# MFMA blocks of the GEMM K-loops aligned to 8 bytes (.p2align 3 ahead of s_setprio 1 / s_barrier)
# baseline (speedup 1.0000x reference)
.Lmy_nb_0:
	s_nop 0
	v_readfirstlane_b32 s86, v152
	v_readfirstlane_b32 s87, v153
	v_readfirstlane_b32 s88, v150
	v_readfirstlane_b32 s89, v151
	v_readfirstlane_b32 s90, v146
	v_readfirstlane_b32 s91, v147
	v_readfirstlane_b32 s92, v148
	v_readfirstlane_b32 s93, v149
	v_readfirstlane_b32 s100, v154
	v_readfirstlane_b32 s101, v138
	v_add_u32_e32 v230, s76, v141
	v_add_u32_e32 v231, s77, v141
	v_add_u32_e32 v232, 0x18000, v141
	v_add_u32_e32 v233, 0x1c000, v141
	s_add_u32 s98, s86, 0xfffc0080
	s_addc_u32 s99, s87, -1
	s_cmp_eq_u32 s7, s100
	s_cselect_b64 s[94:95], s[90:91], s[98:99]
	s_cselect_b64 s[96:97], s[92:93], s[88:89]
	s_add_i32 s51, s7, 2
	s_nop 0
	s_mov_b32 m0, s78
	s_nop 0
	global_load_lds_dwordx4 v144, s[86:87]
	s_mov_b32 m0, s79
	s_nop 0
	global_load_lds_dwordx4 v142, s[86:87]
	ds_read_b128 v[164:167], v230
	ds_read_b128 v[168:171], v230 offset:1024
	ds_read_b128 v[172:175], v230 offset:2048
	ds_read_b128 v[176:179], v230 offset:3072
	ds_read_b128 v[180:183], v231
	ds_read_b128 v[184:187], v231 offset:1024
	ds_read_b128 v[188:191], v231 offset:2048
	ds_read_b128 v[192:195], v231 offset:3072
	ds_read_b128 v[196:199], v160
	ds_read_b128 v[200:203], v160 offset:1024
	ds_read_b128 v[204:207], v160 offset:2048
	ds_read_b128 v[208:211], v160 offset:3072
	ds_read_b128 v[212:215], v160 offset:4096
	ds_read_b128 v[216:219], v160 offset:5120
	ds_read_b128 v[220:223], v160 offset:6144
	ds_read_b128 v[224:227], v160 offset:7168
	s_waitcnt vmcnt(8)
	s_waitcnt lgkmcnt(0)
	.p2align 3
	s_setprio 1
	s_barrier
	v_mfma_f32_16x16x32_bf16 v[122:125], v[164:167], v[196:199], 0
	v_mfma_f32_16x16x32_bf16 v[118:121], v[172:175], v[196:199], 0
	v_mfma_f32_16x16x32_bf16 v[110:113], v[164:167], v[204:207], 0
	v_mfma_f32_16x16x32_bf16 v[102:105], v[172:175], v[204:207], 0
	v_mfma_f32_16x16x32_bf16 v[94:97], v[164:167], v[212:215], 0
	v_mfma_f32_16x16x32_bf16 v[86:89], v[172:175], v[212:215], 0
	v_mfma_f32_16x16x32_bf16 v[78:81], v[164:167], v[220:223], 0
	v_mfma_f32_16x16x32_bf16 v[70:73], v[172:175], v[220:223], 0
	v_mfma_f32_16x16x32_bf16 v[122:125], v[168:171], v[200:203], v[122:125]
	v_mfma_f32_16x16x32_bf16 v[118:121], v[176:179], v[200:203], v[118:121]
	v_mfma_f32_16x16x32_bf16 v[110:113], v[168:171], v[208:211], v[110:113]
	v_mfma_f32_16x16x32_bf16 v[102:105], v[176:179], v[208:211], v[102:105]
	v_mfma_f32_16x16x32_bf16 v[94:97], v[168:171], v[216:219], v[94:97]
	v_mfma_f32_16x16x32_bf16 v[86:89], v[176:179], v[216:219], v[86:89]
	v_mfma_f32_16x16x32_bf16 v[78:81], v[168:171], v[224:227], v[78:81]
	v_mfma_f32_16x16x32_bf16 v[70:73], v[176:179], v[224:227], v[70:73]
	s_setprio 0
	s_setprio 1
	v_mfma_f32_16x16x32_bf16 v[126:129], v[180:183], v[196:199], 0
	v_mfma_f32_16x16x32_bf16 v[114:117], v[188:191], v[196:199], 0
	v_mfma_f32_16x16x32_bf16 v[106:109], v[180:183], v[204:207], 0
	v_mfma_f32_16x16x32_bf16 v[98:101], v[188:191], v[204:207], 0
	v_mfma_f32_16x16x32_bf16 v[90:93], v[180:183], v[212:215], 0
	v_mfma_f32_16x16x32_bf16 v[82:85], v[188:191], v[212:215], 0
	v_mfma_f32_16x16x32_bf16 v[74:77], v[180:183], v[220:223], 0
	v_mfma_f32_16x16x32_bf16 v[66:69], v[188:191], v[220:223], 0
	v_mfma_f32_16x16x32_bf16 v[126:129], v[184:187], v[200:203], v[126:129]
	v_mfma_f32_16x16x32_bf16 v[114:117], v[192:195], v[200:203], v[114:117]
	v_mfma_f32_16x16x32_bf16 v[106:109], v[184:187], v[208:211], v[106:109]
	v_mfma_f32_16x16x32_bf16 v[98:101], v[192:195], v[208:211], v[98:101]
	v_mfma_f32_16x16x32_bf16 v[90:93], v[184:187], v[216:219], v[90:93]
	v_mfma_f32_16x16x32_bf16 v[82:85], v[192:195], v[216:219], v[82:85]
	v_mfma_f32_16x16x32_bf16 v[74:77], v[184:187], v[224:227], v[74:77]
	v_mfma_f32_16x16x32_bf16 v[66:69], v[192:195], v[224:227], v[66:69]
	s_barrier
	s_setprio 0
	s_add_u32 s98, s96, 0x40000
	s_addc_u32 s99, s97, 0
	s_mov_b32 m0, s80
	s_nop 0
	global_load_lds_dwordx4 v132, s[96:97]
	s_mov_b32 m0, s81
	s_add_i32 s7, s77, s47
	global_load_lds_dwordx4 v136, s[96:97]
	s_mov_b32 m0, s7
	s_nop 0
	global_load_lds_dwordx4 v132, s[98:99]
	s_add_i32 m0, s7, 0x2000
	s_nop 0
	global_load_lds_dwordx4 v136, s[98:99]
	s_mov_b32 m0, s57
	s_nop 0
	global_load_lds_dwordx4 v130, s[94:95]
	s_mov_b32 m0, s62
	s_nop 0
	global_load_lds_dwordx4 v134, s[94:95]
	ds_read_b128 v[196:199], v160 offset:16384
	ds_read_b128 v[200:203], v160 offset:17408
	ds_read_b128 v[204:207], v160 offset:18432
	ds_read_b128 v[208:211], v160 offset:19456
	ds_read_b128 v[212:215], v160 offset:20480
	ds_read_b128 v[216:219], v160 offset:21504
	ds_read_b128 v[220:223], v160 offset:22528
	ds_read_b128 v[224:227], v160 offset:23552
	s_waitcnt vmcnt(8)
	s_waitcnt lgkmcnt(0)
	.p2align 3
	s_setprio 1
	s_barrier
	v_mfma_f32_16x16x32_bf16 v[62:65], v[164:167], v[196:199], 0
	v_mfma_f32_16x16x32_bf16 v[54:57], v[172:175], v[196:199], 0
	v_mfma_f32_16x16x32_bf16 v[46:49], v[164:167], v[204:207], 0
	v_mfma_f32_16x16x32_bf16 v[38:41], v[172:175], v[204:207], 0
	v_mfma_f32_16x16x32_bf16 v[30:33], v[164:167], v[212:215], 0
	v_mfma_f32_16x16x32_bf16 v[22:25], v[172:175], v[212:215], 0
	v_mfma_f32_16x16x32_bf16 v[14:17], v[164:167], v[220:223], 0
	v_mfma_f32_16x16x32_bf16 v[6:9], v[172:175], v[220:223], 0
	v_mfma_f32_16x16x32_bf16 v[62:65], v[168:171], v[200:203], v[62:65]
	v_mfma_f32_16x16x32_bf16 v[54:57], v[176:179], v[200:203], v[54:57]
	v_mfma_f32_16x16x32_bf16 v[46:49], v[168:171], v[208:211], v[46:49]
	v_mfma_f32_16x16x32_bf16 v[38:41], v[176:179], v[208:211], v[38:41]
	v_mfma_f32_16x16x32_bf16 v[30:33], v[168:171], v[216:219], v[30:33]
	v_mfma_f32_16x16x32_bf16 v[22:25], v[176:179], v[216:219], v[22:25]
	v_mfma_f32_16x16x32_bf16 v[14:17], v[168:171], v[224:227], v[14:17]
	v_mfma_f32_16x16x32_bf16 v[6:9], v[176:179], v[224:227], v[6:9]
	s_setprio 0
	s_setprio 1
	v_mfma_f32_16x16x32_bf16 v[58:61], v[180:183], v[196:199], 0
	v_mfma_f32_16x16x32_bf16 v[50:53], v[188:191], v[196:199], 0
	v_mfma_f32_16x16x32_bf16 v[42:45], v[180:183], v[204:207], 0
	v_mfma_f32_16x16x32_bf16 v[34:37], v[188:191], v[204:207], 0
	v_mfma_f32_16x16x32_bf16 v[26:29], v[180:183], v[212:215], 0
	v_mfma_f32_16x16x32_bf16 v[18:21], v[188:191], v[212:215], 0
	v_mfma_f32_16x16x32_bf16 v[10:13], v[180:183], v[220:223], 0
	v_mfma_f32_16x16x32_bf16 v[2:5], v[188:191], v[220:223], 0
	v_mfma_f32_16x16x32_bf16 v[58:61], v[184:187], v[200:203], v[58:61]
	v_mfma_f32_16x16x32_bf16 v[50:53], v[192:195], v[200:203], v[50:53]
	v_mfma_f32_16x16x32_bf16 v[42:45], v[184:187], v[208:211], v[42:45]
	v_mfma_f32_16x16x32_bf16 v[34:37], v[192:195], v[208:211], v[34:37]
	v_mfma_f32_16x16x32_bf16 v[26:29], v[184:187], v[216:219], v[26:29]
	v_mfma_f32_16x16x32_bf16 v[18:21], v[192:195], v[216:219], v[18:21]
	v_mfma_f32_16x16x32_bf16 v[10:13], v[184:187], v[224:227], v[10:13]
	v_mfma_f32_16x16x32_bf16 v[2:5], v[192:195], v[224:227], v[2:5]
	s_barrier
	s_setprio 0
	s_add_u32 s98, s94, 0x40000
	s_addc_u32 s99, s95, 0
	s_add_i32 s7, 0, 0x18000
	s_add_i32 s55, 0, 0x1c000
	s_mov_b32 m0, s63
	s_nop 0
	global_load_lds_dwordx4 v130, s[98:99]
	s_mov_b32 m0, s64
	s_nop 0
	global_load_lds_dwordx4 v134, s[98:99]
	ds_read_b128 v[164:167], v232
	ds_read_b128 v[168:171], v232 offset:1024
	ds_read_b128 v[172:175], v232 offset:2048
	ds_read_b128 v[176:179], v232 offset:3072
	ds_read_b128 v[180:183], v233
	ds_read_b128 v[184:187], v233 offset:1024
	ds_read_b128 v[188:191], v233 offset:2048
	ds_read_b128 v[192:195], v233 offset:3072
	ds_read_b128 v[196:199], v160 offset:32768
	ds_read_b128 v[200:203], v160 offset:33792
	ds_read_b128 v[204:207], v160 offset:34816
	ds_read_b128 v[208:211], v160 offset:35840
	ds_read_b128 v[212:215], v160 offset:36864
	ds_read_b128 v[216:219], v160 offset:37888
	ds_read_b128 v[220:223], v160 offset:38912
	ds_read_b128 v[224:227], v160 offset:39936
	s_waitcnt vmcnt(8)
	s_waitcnt lgkmcnt(0)
	.p2align 3
	s_setprio 1
	s_barrier
	v_mfma_f32_16x16x32_bf16 v[122:125], v[164:167], v[196:199], v[122:125]
	v_mfma_f32_16x16x32_bf16 v[118:121], v[172:175], v[196:199], v[118:121]
	v_mfma_f32_16x16x32_bf16 v[110:113], v[164:167], v[204:207], v[110:113]
	v_mfma_f32_16x16x32_bf16 v[102:105], v[172:175], v[204:207], v[102:105]
	v_mfma_f32_16x16x32_bf16 v[94:97], v[164:167], v[212:215], v[94:97]
	v_mfma_f32_16x16x32_bf16 v[86:89], v[172:175], v[212:215], v[86:89]
	v_mfma_f32_16x16x32_bf16 v[78:81], v[164:167], v[220:223], v[78:81]
	v_mfma_f32_16x16x32_bf16 v[70:73], v[172:175], v[220:223], v[70:73]
	v_mfma_f32_16x16x32_bf16 v[122:125], v[168:171], v[200:203], v[122:125]
	v_mfma_f32_16x16x32_bf16 v[118:121], v[176:179], v[200:203], v[118:121]
	v_mfma_f32_16x16x32_bf16 v[110:113], v[168:171], v[208:211], v[110:113]
	v_mfma_f32_16x16x32_bf16 v[102:105], v[176:179], v[208:211], v[102:105]
	v_mfma_f32_16x16x32_bf16 v[94:97], v[168:171], v[216:219], v[94:97]
	v_mfma_f32_16x16x32_bf16 v[86:89], v[176:179], v[216:219], v[86:89]
	v_mfma_f32_16x16x32_bf16 v[78:81], v[168:171], v[224:227], v[78:81]
	v_mfma_f32_16x16x32_bf16 v[70:73], v[176:179], v[224:227], v[70:73]
	s_setprio 0
	s_setprio 1
	v_mfma_f32_16x16x32_bf16 v[126:129], v[180:183], v[196:199], v[126:129]
	v_mfma_f32_16x16x32_bf16 v[114:117], v[188:191], v[196:199], v[114:117]
	v_mfma_f32_16x16x32_bf16 v[106:109], v[180:183], v[204:207], v[106:109]
	v_mfma_f32_16x16x32_bf16 v[98:101], v[188:191], v[204:207], v[98:101]
	v_mfma_f32_16x16x32_bf16 v[90:93], v[180:183], v[212:215], v[90:93]
	v_mfma_f32_16x16x32_bf16 v[82:85], v[188:191], v[212:215], v[82:85]
	v_mfma_f32_16x16x32_bf16 v[74:77], v[180:183], v[220:223], v[74:77]
	v_mfma_f32_16x16x32_bf16 v[66:69], v[188:191], v[220:223], v[66:69]
	v_mfma_f32_16x16x32_bf16 v[126:129], v[184:187], v[200:203], v[126:129]
	v_mfma_f32_16x16x32_bf16 v[114:117], v[192:195], v[200:203], v[114:117]
	v_mfma_f32_16x16x32_bf16 v[106:109], v[184:187], v[208:211], v[106:109]
	v_mfma_f32_16x16x32_bf16 v[98:101], v[192:195], v[208:211], v[98:101]
	v_mfma_f32_16x16x32_bf16 v[90:93], v[184:187], v[216:219], v[90:93]
	v_mfma_f32_16x16x32_bf16 v[82:85], v[192:195], v[216:219], v[82:85]
	v_mfma_f32_16x16x32_bf16 v[74:77], v[184:187], v[224:227], v[74:77]
	v_mfma_f32_16x16x32_bf16 v[66:69], v[192:195], v[224:227], v[66:69]
	s_barrier
	s_setprio 0
	s_add_u32 s96, s96, 0x80
	s_addc_u32 s97, s97, 0
	s_add_u32 s98, s96, 0x40000
	s_addc_u32 s99, s97, 0
	s_add_u32 s94, s94, 0x80
	s_addc_u32 s95, s95, 0
	s_add_i32 s7, s7, s47
	s_mov_b32 m0, s7
	s_nop 0
	global_load_lds_dwordx4 v132, s[96:97]
	s_add_i32 m0, s7, 0x2000
	s_add_i32 s7, s55, s47
	global_load_lds_dwordx4 v136, s[96:97]
	s_mov_b32 m0, s7
	s_nop 0
	global_load_lds_dwordx4 v132, s[98:99]
	s_add_i32 m0, s7, 0x2000
	s_nop 0
	global_load_lds_dwordx4 v136, s[98:99]
	s_mov_b32 m0, s65
	s_nop 0
	global_load_lds_dwordx4 v130, s[94:95]
	s_mov_b32 m0, s66
	s_nop 0
	global_load_lds_dwordx4 v134, s[94:95]
	ds_read_b128 v[196:199], v160 offset:49152
	ds_read_b128 v[200:203], v160 offset:50176
	ds_read_b128 v[204:207], v160 offset:51200
	ds_read_b128 v[208:211], v160 offset:52224
	ds_read_b128 v[212:215], v160 offset:53248
	ds_read_b128 v[216:219], v160 offset:54272
	ds_read_b128 v[220:223], v160 offset:55296
	ds_read_b128 v[224:227], v160 offset:56320
	s_waitcnt vmcnt(8)
	s_waitcnt lgkmcnt(0)
	.p2align 3
	s_setprio 1
	s_barrier
	v_mfma_f32_16x16x32_bf16 v[62:65], v[164:167], v[196:199], v[62:65]
	v_mfma_f32_16x16x32_bf16 v[54:57], v[172:175], v[196:199], v[54:57]
	v_mfma_f32_16x16x32_bf16 v[46:49], v[164:167], v[204:207], v[46:49]
	v_mfma_f32_16x16x32_bf16 v[38:41], v[172:175], v[204:207], v[38:41]
	v_mfma_f32_16x16x32_bf16 v[30:33], v[164:167], v[212:215], v[30:33]
	v_mfma_f32_16x16x32_bf16 v[22:25], v[172:175], v[212:215], v[22:25]
	v_mfma_f32_16x16x32_bf16 v[14:17], v[164:167], v[220:223], v[14:17]
	v_mfma_f32_16x16x32_bf16 v[6:9], v[172:175], v[220:223], v[6:9]
	v_mfma_f32_16x16x32_bf16 v[62:65], v[168:171], v[200:203], v[62:65]
	v_mfma_f32_16x16x32_bf16 v[54:57], v[176:179], v[200:203], v[54:57]
	v_mfma_f32_16x16x32_bf16 v[46:49], v[168:171], v[208:211], v[46:49]
	v_mfma_f32_16x16x32_bf16 v[38:41], v[176:179], v[208:211], v[38:41]
	v_mfma_f32_16x16x32_bf16 v[30:33], v[168:171], v[216:219], v[30:33]
	v_mfma_f32_16x16x32_bf16 v[22:25], v[176:179], v[216:219], v[22:25]
	v_mfma_f32_16x16x32_bf16 v[14:17], v[168:171], v[224:227], v[14:17]
	v_mfma_f32_16x16x32_bf16 v[6:9], v[176:179], v[224:227], v[6:9]
	s_setprio 0
	s_setprio 1
	v_mfma_f32_16x16x32_bf16 v[58:61], v[180:183], v[196:199], v[58:61]
	v_mfma_f32_16x16x32_bf16 v[50:53], v[188:191], v[196:199], v[50:53]
	v_mfma_f32_16x16x32_bf16 v[42:45], v[180:183], v[204:207], v[42:45]
	v_mfma_f32_16x16x32_bf16 v[34:37], v[188:191], v[204:207], v[34:37]
	v_mfma_f32_16x16x32_bf16 v[26:29], v[180:183], v[212:215], v[26:29]
	v_mfma_f32_16x16x32_bf16 v[18:21], v[188:191], v[212:215], v[18:21]
	v_mfma_f32_16x16x32_bf16 v[10:13], v[180:183], v[220:223], v[10:13]
	v_mfma_f32_16x16x32_bf16 v[2:5], v[188:191], v[220:223], v[2:5]
	v_mfma_f32_16x16x32_bf16 v[58:61], v[184:187], v[200:203], v[58:61]
	v_mfma_f32_16x16x32_bf16 v[50:53], v[192:195], v[200:203], v[50:53]
	v_mfma_f32_16x16x32_bf16 v[42:45], v[184:187], v[208:211], v[42:45]
	v_mfma_f32_16x16x32_bf16 v[34:37], v[192:195], v[208:211], v[34:37]
	v_mfma_f32_16x16x32_bf16 v[26:29], v[184:187], v[216:219], v[26:29]
	v_mfma_f32_16x16x32_bf16 v[18:21], v[192:195], v[216:219], v[18:21]
	v_mfma_f32_16x16x32_bf16 v[10:13], v[184:187], v[224:227], v[10:13]
	v_mfma_f32_16x16x32_bf16 v[2:5], v[192:195], v[224:227], v[2:5]
	s_barrier
	s_setprio 0
	s_mov_b32 s7, s51
	s_add_u32 s88, s88, 0x100
	s_addc_u32 s89, s89, 0
	s_add_u32 s86, s86, 0x100
	s_addc_u32 s87, s87, 0
	s_cmp_ge_i32 s51, s101
	s_cbranch_scc1 .Lmy_kexit_0
.LBB0_171:
	s_add_u32 s98, s86, 0xfffc0080
	s_addc_u32 s99, s87, -1
	s_cmp_eq_u32 s7, s100
	s_cselect_b64 s[94:95], s[90:91], s[98:99]
	s_cselect_b64 s[96:97], s[92:93], s[88:89]
	s_add_i32 s51, s7, 2
	s_nop 0
	s_mov_b32 m0, s78
	s_nop 0
	global_load_lds_dwordx4 v144, s[86:87]
	s_mov_b32 m0, s79
	s_nop 0
	global_load_lds_dwordx4 v142, s[86:87]
	ds_read_b128 v[164:167], v230
	ds_read_b128 v[168:171], v230 offset:1024
	ds_read_b128 v[172:175], v230 offset:2048
	ds_read_b128 v[176:179], v230 offset:3072
	ds_read_b128 v[180:183], v231
	ds_read_b128 v[184:187], v231 offset:1024
	ds_read_b128 v[188:191], v231 offset:2048
	ds_read_b128 v[192:195], v231 offset:3072
	ds_read_b128 v[196:199], v160
	ds_read_b128 v[200:203], v160 offset:1024
	ds_read_b128 v[204:207], v160 offset:2048
	ds_read_b128 v[208:211], v160 offset:3072
	ds_read_b128 v[212:215], v160 offset:4096
	ds_read_b128 v[216:219], v160 offset:5120
	ds_read_b128 v[220:223], v160 offset:6144
	ds_read_b128 v[224:227], v160 offset:7168
	s_waitcnt vmcnt(8)
	s_waitcnt lgkmcnt(0)
	.p2align 3
	s_setprio 1
	s_barrier
	v_mfma_f32_16x16x32_bf16 v[122:125], v[164:167], v[196:199], v[122:125]
	v_mfma_f32_16x16x32_bf16 v[118:121], v[172:175], v[196:199], v[118:121]
	v_mfma_f32_16x16x32_bf16 v[110:113], v[164:167], v[204:207], v[110:113]
	v_mfma_f32_16x16x32_bf16 v[102:105], v[172:175], v[204:207], v[102:105]
	v_mfma_f32_16x16x32_bf16 v[94:97], v[164:167], v[212:215], v[94:97]
	v_mfma_f32_16x16x32_bf16 v[86:89], v[172:175], v[212:215], v[86:89]
	v_mfma_f32_16x16x32_bf16 v[78:81], v[164:167], v[220:223], v[78:81]
	v_mfma_f32_16x16x32_bf16 v[70:73], v[172:175], v[220:223], v[70:73]
	v_mfma_f32_16x16x32_bf16 v[122:125], v[168:171], v[200:203], v[122:125]
	v_mfma_f32_16x16x32_bf16 v[118:121], v[176:179], v[200:203], v[118:121]
	v_mfma_f32_16x16x32_bf16 v[110:113], v[168:171], v[208:211], v[110:113]
	v_mfma_f32_16x16x32_bf16 v[102:105], v[176:179], v[208:211], v[102:105]
	v_mfma_f32_16x16x32_bf16 v[94:97], v[168:171], v[216:219], v[94:97]
	v_mfma_f32_16x16x32_bf16 v[86:89], v[176:179], v[216:219], v[86:89]
	v_mfma_f32_16x16x32_bf16 v[78:81], v[168:171], v[224:227], v[78:81]
	v_mfma_f32_16x16x32_bf16 v[70:73], v[176:179], v[224:227], v[70:73]
	s_setprio 0
	s_setprio 1
	v_mfma_f32_16x16x32_bf16 v[126:129], v[180:183], v[196:199], v[126:129]
	v_mfma_f32_16x16x32_bf16 v[114:117], v[188:191], v[196:199], v[114:117]
	v_mfma_f32_16x16x32_bf16 v[106:109], v[180:183], v[204:207], v[106:109]
	v_mfma_f32_16x16x32_bf16 v[98:101], v[188:191], v[204:207], v[98:101]
	v_mfma_f32_16x16x32_bf16 v[90:93], v[180:183], v[212:215], v[90:93]
	v_mfma_f32_16x16x32_bf16 v[82:85], v[188:191], v[212:215], v[82:85]
	v_mfma_f32_16x16x32_bf16 v[74:77], v[180:183], v[220:223], v[74:77]
	v_mfma_f32_16x16x32_bf16 v[66:69], v[188:191], v[220:223], v[66:69]
	v_mfma_f32_16x16x32_bf16 v[126:129], v[184:187], v[200:203], v[126:129]
	v_mfma_f32_16x16x32_bf16 v[114:117], v[192:195], v[200:203], v[114:117]
	v_mfma_f32_16x16x32_bf16 v[106:109], v[184:187], v[208:211], v[106:109]
	v_mfma_f32_16x16x32_bf16 v[98:101], v[192:195], v[208:211], v[98:101]
	v_mfma_f32_16x16x32_bf16 v[90:93], v[184:187], v[216:219], v[90:93]
	v_mfma_f32_16x16x32_bf16 v[82:85], v[192:195], v[216:219], v[82:85]
	v_mfma_f32_16x16x32_bf16 v[74:77], v[184:187], v[224:227], v[74:77]
	v_mfma_f32_16x16x32_bf16 v[66:69], v[192:195], v[224:227], v[66:69]
	s_barrier
	s_setprio 0
	s_add_u32 s98, s96, 0x40000
	s_addc_u32 s99, s97, 0
	s_mov_b32 m0, s80
	s_nop 0
	global_load_lds_dwordx4 v132, s[96:97]
	s_mov_b32 m0, s81
	s_add_i32 s7, s77, s47
	global_load_lds_dwordx4 v136, s[96:97]
	s_mov_b32 m0, s7
	s_nop 0
	global_load_lds_dwordx4 v132, s[98:99]
	s_add_i32 m0, s7, 0x2000
	s_nop 0
	global_load_lds_dwordx4 v136, s[98:99]
	s_mov_b32 m0, s57
	s_nop 0
	global_load_lds_dwordx4 v130, s[94:95]
	s_mov_b32 m0, s62
	s_nop 0
	global_load_lds_dwordx4 v134, s[94:95]
	ds_read_b128 v[196:199], v160 offset:16384
	ds_read_b128 v[200:203], v160 offset:17408
	ds_read_b128 v[204:207], v160 offset:18432
	ds_read_b128 v[208:211], v160 offset:19456
	ds_read_b128 v[212:215], v160 offset:20480
	ds_read_b128 v[216:219], v160 offset:21504
	ds_read_b128 v[220:223], v160 offset:22528
	ds_read_b128 v[224:227], v160 offset:23552
	s_waitcnt vmcnt(8)
	s_waitcnt lgkmcnt(0)
	.p2align 3
	s_setprio 1
	s_barrier
	v_mfma_f32_16x16x32_bf16 v[62:65], v[164:167], v[196:199], v[62:65]
	v_mfma_f32_16x16x32_bf16 v[54:57], v[172:175], v[196:199], v[54:57]
	v_mfma_f32_16x16x32_bf16 v[46:49], v[164:167], v[204:207], v[46:49]
	v_mfma_f32_16x16x32_bf16 v[38:41], v[172:175], v[204:207], v[38:41]
	v_mfma_f32_16x16x32_bf16 v[30:33], v[164:167], v[212:215], v[30:33]
	v_mfma_f32_16x16x32_bf16 v[22:25], v[172:175], v[212:215], v[22:25]
	v_mfma_f32_16x16x32_bf16 v[14:17], v[164:167], v[220:223], v[14:17]
	v_mfma_f32_16x16x32_bf16 v[6:9], v[172:175], v[220:223], v[6:9]
	v_mfma_f32_16x16x32_bf16 v[62:65], v[168:171], v[200:203], v[62:65]
	v_mfma_f32_16x16x32_bf16 v[54:57], v[176:179], v[200:203], v[54:57]
	v_mfma_f32_16x16x32_bf16 v[46:49], v[168:171], v[208:211], v[46:49]
	v_mfma_f32_16x16x32_bf16 v[38:41], v[176:179], v[208:211], v[38:41]
	v_mfma_f32_16x16x32_bf16 v[30:33], v[168:171], v[216:219], v[30:33]
	v_mfma_f32_16x16x32_bf16 v[22:25], v[176:179], v[216:219], v[22:25]
	v_mfma_f32_16x16x32_bf16 v[14:17], v[168:171], v[224:227], v[14:17]
	v_mfma_f32_16x16x32_bf16 v[6:9], v[176:179], v[224:227], v[6:9]
	s_setprio 0
	s_setprio 1
	v_mfma_f32_16x16x32_bf16 v[58:61], v[180:183], v[196:199], v[58:61]
	v_mfma_f32_16x16x32_bf16 v[50:53], v[188:191], v[196:199], v[50:53]
	v_mfma_f32_16x16x32_bf16 v[42:45], v[180:183], v[204:207], v[42:45]
	v_mfma_f32_16x16x32_bf16 v[34:37], v[188:191], v[204:207], v[34:37]
	v_mfma_f32_16x16x32_bf16 v[26:29], v[180:183], v[212:215], v[26:29]
	v_mfma_f32_16x16x32_bf16 v[18:21], v[188:191], v[212:215], v[18:21]
	v_mfma_f32_16x16x32_bf16 v[10:13], v[180:183], v[220:223], v[10:13]
	v_mfma_f32_16x16x32_bf16 v[2:5], v[188:191], v[220:223], v[2:5]
	v_mfma_f32_16x16x32_bf16 v[58:61], v[184:187], v[200:203], v[58:61]
	v_mfma_f32_16x16x32_bf16 v[50:53], v[192:195], v[200:203], v[50:53]
	v_mfma_f32_16x16x32_bf16 v[42:45], v[184:187], v[208:211], v[42:45]
	v_mfma_f32_16x16x32_bf16 v[34:37], v[192:195], v[208:211], v[34:37]
	v_mfma_f32_16x16x32_bf16 v[26:29], v[184:187], v[216:219], v[26:29]
	v_mfma_f32_16x16x32_bf16 v[18:21], v[192:195], v[216:219], v[18:21]
	v_mfma_f32_16x16x32_bf16 v[10:13], v[184:187], v[224:227], v[10:13]
	v_mfma_f32_16x16x32_bf16 v[2:5], v[192:195], v[224:227], v[2:5]
	s_barrier
	s_setprio 0
	s_add_u32 s98, s94, 0x40000
	s_addc_u32 s99, s95, 0
	s_add_i32 s7, 0, 0x18000
	s_add_i32 s55, 0, 0x1c000
	s_mov_b32 m0, s63
	s_nop 0
	global_load_lds_dwordx4 v130, s[98:99]
	s_mov_b32 m0, s64
	s_nop 0
	global_load_lds_dwordx4 v134, s[98:99]
	ds_read_b128 v[164:167], v232
	ds_read_b128 v[168:171], v232 offset:1024
	ds_read_b128 v[172:175], v232 offset:2048
	ds_read_b128 v[176:179], v232 offset:3072
	ds_read_b128 v[180:183], v233
	ds_read_b128 v[184:187], v233 offset:1024
	ds_read_b128 v[188:191], v233 offset:2048
	ds_read_b128 v[192:195], v233 offset:3072
	ds_read_b128 v[196:199], v160 offset:32768
	ds_read_b128 v[200:203], v160 offset:33792
	ds_read_b128 v[204:207], v160 offset:34816
	ds_read_b128 v[208:211], v160 offset:35840
	ds_read_b128 v[212:215], v160 offset:36864
	ds_read_b128 v[216:219], v160 offset:37888
	ds_read_b128 v[220:223], v160 offset:38912
	ds_read_b128 v[224:227], v160 offset:39936
	s_waitcnt vmcnt(8)
	s_waitcnt lgkmcnt(0)
	.p2align 3
	s_setprio 1
	s_barrier
	v_mfma_f32_16x16x32_bf16 v[122:125], v[164:167], v[196:199], v[122:125]
	v_mfma_f32_16x16x32_bf16 v[118:121], v[172:175], v[196:199], v[118:121]
	v_mfma_f32_16x16x32_bf16 v[110:113], v[164:167], v[204:207], v[110:113]
	v_mfma_f32_16x16x32_bf16 v[102:105], v[172:175], v[204:207], v[102:105]
	v_mfma_f32_16x16x32_bf16 v[94:97], v[164:167], v[212:215], v[94:97]
	v_mfma_f32_16x16x32_bf16 v[86:89], v[172:175], v[212:215], v[86:89]
	v_mfma_f32_16x16x32_bf16 v[78:81], v[164:167], v[220:223], v[78:81]
	v_mfma_f32_16x16x32_bf16 v[70:73], v[172:175], v[220:223], v[70:73]
	v_mfma_f32_16x16x32_bf16 v[122:125], v[168:171], v[200:203], v[122:125]
	v_mfma_f32_16x16x32_bf16 v[118:121], v[176:179], v[200:203], v[118:121]
	v_mfma_f32_16x16x32_bf16 v[110:113], v[168:171], v[208:211], v[110:113]
	v_mfma_f32_16x16x32_bf16 v[102:105], v[176:179], v[208:211], v[102:105]
	v_mfma_f32_16x16x32_bf16 v[94:97], v[168:171], v[216:219], v[94:97]
	v_mfma_f32_16x16x32_bf16 v[86:89], v[176:179], v[216:219], v[86:89]
	v_mfma_f32_16x16x32_bf16 v[78:81], v[168:171], v[224:227], v[78:81]
	v_mfma_f32_16x16x32_bf16 v[70:73], v[176:179], v[224:227], v[70:73]
	s_setprio 0
	s_setprio 1
	v_mfma_f32_16x16x32_bf16 v[126:129], v[180:183], v[196:199], v[126:129]
	v_mfma_f32_16x16x32_bf16 v[114:117], v[188:191], v[196:199], v[114:117]
	v_mfma_f32_16x16x32_bf16 v[106:109], v[180:183], v[204:207], v[106:109]
	v_mfma_f32_16x16x32_bf16 v[98:101], v[188:191], v[204:207], v[98:101]
	v_mfma_f32_16x16x32_bf16 v[90:93], v[180:183], v[212:215], v[90:93]
	v_mfma_f32_16x16x32_bf16 v[82:85], v[188:191], v[212:215], v[82:85]
	v_mfma_f32_16x16x32_bf16 v[74:77], v[180:183], v[220:223], v[74:77]
	v_mfma_f32_16x16x32_bf16 v[66:69], v[188:191], v[220:223], v[66:69]
	v_mfma_f32_16x16x32_bf16 v[126:129], v[184:187], v[200:203], v[126:129]
	v_mfma_f32_16x16x32_bf16 v[114:117], v[192:195], v[200:203], v[114:117]
	v_mfma_f32_16x16x32_bf16 v[106:109], v[184:187], v[208:211], v[106:109]
	v_mfma_f32_16x16x32_bf16 v[98:101], v[192:195], v[208:211], v[98:101]
	v_mfma_f32_16x16x32_bf16 v[90:93], v[184:187], v[216:219], v[90:93]
	v_mfma_f32_16x16x32_bf16 v[82:85], v[192:195], v[216:219], v[82:85]
	v_mfma_f32_16x16x32_bf16 v[74:77], v[184:187], v[224:227], v[74:77]
	v_mfma_f32_16x16x32_bf16 v[66:69], v[192:195], v[224:227], v[66:69]
	s_barrier
	s_setprio 0
	s_add_u32 s96, s96, 0x80
	s_addc_u32 s97, s97, 0
	s_add_u32 s98, s96, 0x40000
	s_addc_u32 s99, s97, 0
	s_add_u32 s94, s94, 0x80
	s_addc_u32 s95, s95, 0
	s_add_i32 s7, s7, s47
	s_mov_b32 m0, s7
	s_nop 0
	global_load_lds_dwordx4 v132, s[96:97]
	s_add_i32 m0, s7, 0x2000
	s_add_i32 s7, s55, s47
	global_load_lds_dwordx4 v136, s[96:97]
	s_mov_b32 m0, s7
	s_nop 0
	global_load_lds_dwordx4 v132, s[98:99]
	s_add_i32 m0, s7, 0x2000
	s_nop 0
	global_load_lds_dwordx4 v136, s[98:99]
	s_mov_b32 m0, s65
	s_nop 0
	global_load_lds_dwordx4 v130, s[94:95]
	s_mov_b32 m0, s66
	s_nop 0
	global_load_lds_dwordx4 v134, s[94:95]
	ds_read_b128 v[196:199], v160 offset:49152
	ds_read_b128 v[200:203], v160 offset:50176
	ds_read_b128 v[204:207], v160 offset:51200
	ds_read_b128 v[208:211], v160 offset:52224
	ds_read_b128 v[212:215], v160 offset:53248
	ds_read_b128 v[216:219], v160 offset:54272
	ds_read_b128 v[220:223], v160 offset:55296
	ds_read_b128 v[224:227], v160 offset:56320
	s_waitcnt vmcnt(8)
	s_waitcnt lgkmcnt(0)
	.p2align 3
	s_setprio 1
	s_barrier
	v_mfma_f32_16x16x32_bf16 v[62:65], v[164:167], v[196:199], v[62:65]
	v_mfma_f32_16x16x32_bf16 v[54:57], v[172:175], v[196:199], v[54:57]
	v_mfma_f32_16x16x32_bf16 v[46:49], v[164:167], v[204:207], v[46:49]
	v_mfma_f32_16x16x32_bf16 v[38:41], v[172:175], v[204:207], v[38:41]
	v_mfma_f32_16x16x32_bf16 v[30:33], v[164:167], v[212:215], v[30:33]
	v_mfma_f32_16x16x32_bf16 v[22:25], v[172:175], v[212:215], v[22:25]
	v_mfma_f32_16x16x32_bf16 v[14:17], v[164:167], v[220:223], v[14:17]
	v_mfma_f32_16x16x32_bf16 v[6:9], v[172:175], v[220:223], v[6:9]
	v_mfma_f32_16x16x32_bf16 v[62:65], v[168:171], v[200:203], v[62:65]
	v_mfma_f32_16x16x32_bf16 v[54:57], v[176:179], v[200:203], v[54:57]
	v_mfma_f32_16x16x32_bf16 v[46:49], v[168:171], v[208:211], v[46:49]
	v_mfma_f32_16x16x32_bf16 v[38:41], v[176:179], v[208:211], v[38:41]
	v_mfma_f32_16x16x32_bf16 v[30:33], v[168:171], v[216:219], v[30:33]
	v_mfma_f32_16x16x32_bf16 v[22:25], v[176:179], v[216:219], v[22:25]
	v_mfma_f32_16x16x32_bf16 v[14:17], v[168:171], v[224:227], v[14:17]
	v_mfma_f32_16x16x32_bf16 v[6:9], v[176:179], v[224:227], v[6:9]
	s_setprio 0
	s_setprio 1
	v_mfma_f32_16x16x32_bf16 v[58:61], v[180:183], v[196:199], v[58:61]
	v_mfma_f32_16x16x32_bf16 v[50:53], v[188:191], v[196:199], v[50:53]
	v_mfma_f32_16x16x32_bf16 v[42:45], v[180:183], v[204:207], v[42:45]
	v_mfma_f32_16x16x32_bf16 v[34:37], v[188:191], v[204:207], v[34:37]
	v_mfma_f32_16x16x32_bf16 v[26:29], v[180:183], v[212:215], v[26:29]
	v_mfma_f32_16x16x32_bf16 v[18:21], v[188:191], v[212:215], v[18:21]
	v_mfma_f32_16x16x32_bf16 v[10:13], v[180:183], v[220:223], v[10:13]
	v_mfma_f32_16x16x32_bf16 v[2:5], v[188:191], v[220:223], v[2:5]
	v_mfma_f32_16x16x32_bf16 v[58:61], v[184:187], v[200:203], v[58:61]
	v_mfma_f32_16x16x32_bf16 v[50:53], v[192:195], v[200:203], v[50:53]
	v_mfma_f32_16x16x32_bf16 v[42:45], v[184:187], v[208:211], v[42:45]
	v_mfma_f32_16x16x32_bf16 v[34:37], v[192:195], v[208:211], v[34:37]
	v_mfma_f32_16x16x32_bf16 v[26:29], v[184:187], v[216:219], v[26:29]
	v_mfma_f32_16x16x32_bf16 v[18:21], v[192:195], v[216:219], v[18:21]
	v_mfma_f32_16x16x32_bf16 v[10:13], v[184:187], v[224:227], v[10:13]
	v_mfma_f32_16x16x32_bf16 v[2:5], v[192:195], v[224:227], v[2:5]
	s_barrier
	s_setprio 0
	s_mov_b32 s7, s51
	s_add_u32 s88, s88, 0x100
	s_addc_u32 s89, s89, 0
	s_add_u32 s86, s86, 0x100
	s_addc_u32 s87, s87, 0
	s_cmp_ge_i32 s51, s101
	s_cbranch_scc0 .LBB0_171

.Lmy_nb_1:
	s_nop 0
	v_readfirstlane_b32 s86, v152
	v_readfirstlane_b32 s87, v153
	v_readfirstlane_b32 s88, v154
	v_readfirstlane_b32 s89, v155
	v_readfirstlane_b32 s90, v148
	v_readfirstlane_b32 s91, v149
	v_readfirstlane_b32 s92, v150
	v_readfirstlane_b32 s93, v151
	v_readfirstlane_b32 s100, v138
	v_readfirstlane_b32 s101, v141
	v_add_u32_e32 v230, s69, v160
	v_add_u32_e32 v231, s72, v160
	v_add_u32_e32 v232, 0x18000, v160
	v_add_u32_e32 v233, 0x1c000, v160
	s_add_u32 s98, s86, 0x100
	s_addc_u32 s99, s87, 0
	s_cmp_eq_u32 s8, s100
	s_cselect_b64 s[94:95], s[90:91], s[98:99]
	s_cselect_b64 s[96:97], s[92:93], s[88:89]
	s_add_i32 s9, s8, 2
	s_nop 0
	s_add_i32 m0, s55, 0xc000
	s_nop 0
	global_load_lds_dwordx4 v144, s[86:87]
	s_add_i32 m0, s55, 0xe000
	s_nop 0
	global_load_lds_dwordx4 v142, s[86:87]
	ds_read_b128 v[166:169], v230
	ds_read_b128 v[170:173], v230 offset:1024
	ds_read_b128 v[174:177], v230 offset:2048
	ds_read_b128 v[178:181], v230 offset:3072
	ds_read_b128 v[182:185], v231
	ds_read_b128 v[186:189], v231 offset:1024
	ds_read_b128 v[190:193], v231 offset:2048
	ds_read_b128 v[194:197], v231 offset:3072
	ds_read_b128 v[198:201], v163
	ds_read_b128 v[202:205], v163 offset:1024
	ds_read_b128 v[206:209], v163 offset:2048
	ds_read_b128 v[210:213], v163 offset:3072
	ds_read_b128 v[214:217], v163 offset:4096
	ds_read_b128 v[218:221], v163 offset:5120
	ds_read_b128 v[222:225], v163 offset:6144
	ds_read_b128 v[226:229], v163 offset:7168
	s_waitcnt vmcnt(8)
	s_waitcnt lgkmcnt(0)
	.p2align 3
	s_setprio 1
	s_barrier
	v_mfma_f32_16x16x32_bf16 v[122:125], v[166:169], v[198:201], 0
	v_mfma_f32_16x16x32_bf16 v[118:121], v[174:177], v[198:201], 0
	v_mfma_f32_16x16x32_bf16 v[110:113], v[166:169], v[206:209], 0
	v_mfma_f32_16x16x32_bf16 v[102:105], v[174:177], v[206:209], 0
	v_mfma_f32_16x16x32_bf16 v[94:97], v[166:169], v[214:217], 0
	v_mfma_f32_16x16x32_bf16 v[86:89], v[174:177], v[214:217], 0
	v_mfma_f32_16x16x32_bf16 v[78:81], v[166:169], v[222:225], 0
	v_mfma_f32_16x16x32_bf16 v[70:73], v[174:177], v[222:225], 0
	v_mfma_f32_16x16x32_bf16 v[122:125], v[170:173], v[202:205], v[122:125]
	v_mfma_f32_16x16x32_bf16 v[118:121], v[178:181], v[202:205], v[118:121]
	v_mfma_f32_16x16x32_bf16 v[110:113], v[170:173], v[210:213], v[110:113]
	v_mfma_f32_16x16x32_bf16 v[102:105], v[178:181], v[210:213], v[102:105]
	v_mfma_f32_16x16x32_bf16 v[94:97], v[170:173], v[218:221], v[94:97]
	v_mfma_f32_16x16x32_bf16 v[86:89], v[178:181], v[218:221], v[86:89]
	v_mfma_f32_16x16x32_bf16 v[78:81], v[170:173], v[226:229], v[78:81]
	v_mfma_f32_16x16x32_bf16 v[70:73], v[178:181], v[226:229], v[70:73]
	s_setprio 0
	s_setprio 1
	v_mfma_f32_16x16x32_bf16 v[126:129], v[182:185], v[198:201], 0
	v_mfma_f32_16x16x32_bf16 v[114:117], v[190:193], v[198:201], 0
	v_mfma_f32_16x16x32_bf16 v[106:109], v[182:185], v[206:209], 0
	v_mfma_f32_16x16x32_bf16 v[98:101], v[190:193], v[206:209], 0
	v_mfma_f32_16x16x32_bf16 v[90:93], v[182:185], v[214:217], 0
	v_mfma_f32_16x16x32_bf16 v[82:85], v[190:193], v[214:217], 0
	v_mfma_f32_16x16x32_bf16 v[74:77], v[182:185], v[222:225], 0
	v_mfma_f32_16x16x32_bf16 v[66:69], v[190:193], v[222:225], 0
	v_mfma_f32_16x16x32_bf16 v[126:129], v[186:189], v[202:205], v[126:129]
	v_mfma_f32_16x16x32_bf16 v[114:117], v[194:197], v[202:205], v[114:117]
	v_mfma_f32_16x16x32_bf16 v[106:109], v[186:189], v[210:213], v[106:109]
	v_mfma_f32_16x16x32_bf16 v[98:101], v[194:197], v[210:213], v[98:101]
	v_mfma_f32_16x16x32_bf16 v[90:93], v[186:189], v[218:221], v[90:93]
	v_mfma_f32_16x16x32_bf16 v[82:85], v[194:197], v[218:221], v[82:85]
	v_mfma_f32_16x16x32_bf16 v[74:77], v[186:189], v[226:229], v[74:77]
	v_mfma_f32_16x16x32_bf16 v[66:69], v[194:197], v[226:229], v[66:69]
	s_barrier
	s_setprio 0
	s_add_u32 s98, s96, 0xb0000
	s_addc_u32 s99, s97, 0
	s_add_i32 s8, s69, s54
	s_mov_b32 m0, s8
	s_nop 0
	global_load_lds_dwordx4 v132, s[96:97]
	s_add_i32 m0, s8, 0x2000
	s_add_i32 s8, s72, s54
	global_load_lds_dwordx4 v136, s[96:97]
	s_mov_b32 m0, s8
	s_nop 0
	global_load_lds_dwordx4 v132, s[98:99]
	s_add_i32 m0, s8, 0x2000
	s_nop 0
	global_load_lds_dwordx4 v136, s[98:99]
	s_mov_b32 m0, s55
	s_nop 0
	global_load_lds_dwordx4 v130, s[94:95]
	s_mov_b32 m0, s56
	s_nop 0
	global_load_lds_dwordx4 v134, s[94:95]
	ds_read_b128 v[198:201], v163 offset:16384
	ds_read_b128 v[202:205], v163 offset:17408
	ds_read_b128 v[206:209], v163 offset:18432
	ds_read_b128 v[210:213], v163 offset:19456
	ds_read_b128 v[214:217], v163 offset:20480
	ds_read_b128 v[218:221], v163 offset:21504
	ds_read_b128 v[222:225], v163 offset:22528
	ds_read_b128 v[226:229], v163 offset:23552
	s_waitcnt vmcnt(8)
	s_waitcnt lgkmcnt(0)
	.p2align 3
	s_setprio 1
	s_barrier
	v_mfma_f32_16x16x32_bf16 v[62:65], v[166:169], v[198:201], 0
	v_mfma_f32_16x16x32_bf16 v[54:57], v[174:177], v[198:201], 0
	v_mfma_f32_16x16x32_bf16 v[46:49], v[166:169], v[206:209], 0
	v_mfma_f32_16x16x32_bf16 v[38:41], v[174:177], v[206:209], 0
	v_mfma_f32_16x16x32_bf16 v[30:33], v[166:169], v[214:217], 0
	v_mfma_f32_16x16x32_bf16 v[22:25], v[174:177], v[214:217], 0
	v_mfma_f32_16x16x32_bf16 v[14:17], v[166:169], v[222:225], 0
	v_mfma_f32_16x16x32_bf16 v[6:9], v[174:177], v[222:225], 0
	v_mfma_f32_16x16x32_bf16 v[62:65], v[170:173], v[202:205], v[62:65]
	v_mfma_f32_16x16x32_bf16 v[54:57], v[178:181], v[202:205], v[54:57]
	v_mfma_f32_16x16x32_bf16 v[46:49], v[170:173], v[210:213], v[46:49]
	v_mfma_f32_16x16x32_bf16 v[38:41], v[178:181], v[210:213], v[38:41]
	v_mfma_f32_16x16x32_bf16 v[30:33], v[170:173], v[218:221], v[30:33]
	v_mfma_f32_16x16x32_bf16 v[22:25], v[178:181], v[218:221], v[22:25]
	v_mfma_f32_16x16x32_bf16 v[14:17], v[170:173], v[226:229], v[14:17]
	v_mfma_f32_16x16x32_bf16 v[6:9], v[178:181], v[226:229], v[6:9]
	s_setprio 0
	s_setprio 1
	v_mfma_f32_16x16x32_bf16 v[58:61], v[182:185], v[198:201], 0
	v_mfma_f32_16x16x32_bf16 v[50:53], v[190:193], v[198:201], 0
	v_mfma_f32_16x16x32_bf16 v[42:45], v[182:185], v[206:209], 0
	v_mfma_f32_16x16x32_bf16 v[34:37], v[190:193], v[206:209], 0
	v_mfma_f32_16x16x32_bf16 v[26:29], v[182:185], v[214:217], 0
	v_mfma_f32_16x16x32_bf16 v[18:21], v[190:193], v[214:217], 0
	v_mfma_f32_16x16x32_bf16 v[10:13], v[182:185], v[222:225], 0
	v_mfma_f32_16x16x32_bf16 v[2:5], v[190:193], v[222:225], 0
	v_mfma_f32_16x16x32_bf16 v[58:61], v[186:189], v[202:205], v[58:61]
	v_mfma_f32_16x16x32_bf16 v[50:53], v[194:197], v[202:205], v[50:53]
	v_mfma_f32_16x16x32_bf16 v[42:45], v[186:189], v[210:213], v[42:45]
	v_mfma_f32_16x16x32_bf16 v[34:37], v[194:197], v[210:213], v[34:37]
	v_mfma_f32_16x16x32_bf16 v[26:29], v[186:189], v[218:221], v[26:29]
	v_mfma_f32_16x16x32_bf16 v[18:21], v[194:197], v[218:221], v[18:21]
	v_mfma_f32_16x16x32_bf16 v[10:13], v[186:189], v[226:229], v[10:13]
	v_mfma_f32_16x16x32_bf16 v[2:5], v[194:197], v[226:229], v[2:5]
	s_barrier
	s_setprio 0
	s_add_u32 s98, s94, 0xb0000
	s_addc_u32 s99, s95, 0
	s_add_i32 s8, 0, 0x18000
	s_add_i32 s50, 0, 0x1c000
	s_mov_b32 m0, s57
	s_nop 0
	global_load_lds_dwordx4 v130, s[98:99]
	s_mov_b32 m0, s58
	s_nop 0
	global_load_lds_dwordx4 v134, s[98:99]
	ds_read_b128 v[166:169], v232
	ds_read_b128 v[170:173], v232 offset:1024
	ds_read_b128 v[174:177], v232 offset:2048
	ds_read_b128 v[178:181], v232 offset:3072
	ds_read_b128 v[182:185], v233
	ds_read_b128 v[186:189], v233 offset:1024
	ds_read_b128 v[190:193], v233 offset:2048
	ds_read_b128 v[194:197], v233 offset:3072
	ds_read_b128 v[198:201], v163 offset:32768
	ds_read_b128 v[202:205], v163 offset:33792
	ds_read_b128 v[206:209], v163 offset:34816
	ds_read_b128 v[210:213], v163 offset:35840
	ds_read_b128 v[214:217], v163 offset:36864
	ds_read_b128 v[218:221], v163 offset:37888
	ds_read_b128 v[222:225], v163 offset:38912
	ds_read_b128 v[226:229], v163 offset:39936
	s_waitcnt vmcnt(8)
	s_waitcnt lgkmcnt(0)
	.p2align 3
	s_setprio 1
	s_barrier
	v_mfma_f32_16x16x32_bf16 v[122:125], v[166:169], v[198:201], v[122:125]
	v_mfma_f32_16x16x32_bf16 v[118:121], v[174:177], v[198:201], v[118:121]
	v_mfma_f32_16x16x32_bf16 v[110:113], v[166:169], v[206:209], v[110:113]
	v_mfma_f32_16x16x32_bf16 v[102:105], v[174:177], v[206:209], v[102:105]
	v_mfma_f32_16x16x32_bf16 v[94:97], v[166:169], v[214:217], v[94:97]
	v_mfma_f32_16x16x32_bf16 v[86:89], v[174:177], v[214:217], v[86:89]
	v_mfma_f32_16x16x32_bf16 v[78:81], v[166:169], v[222:225], v[78:81]
	v_mfma_f32_16x16x32_bf16 v[70:73], v[174:177], v[222:225], v[70:73]
	v_mfma_f32_16x16x32_bf16 v[122:125], v[170:173], v[202:205], v[122:125]
	v_mfma_f32_16x16x32_bf16 v[118:121], v[178:181], v[202:205], v[118:121]
	v_mfma_f32_16x16x32_bf16 v[110:113], v[170:173], v[210:213], v[110:113]
	v_mfma_f32_16x16x32_bf16 v[102:105], v[178:181], v[210:213], v[102:105]
	v_mfma_f32_16x16x32_bf16 v[94:97], v[170:173], v[218:221], v[94:97]
	v_mfma_f32_16x16x32_bf16 v[86:89], v[178:181], v[218:221], v[86:89]
	v_mfma_f32_16x16x32_bf16 v[78:81], v[170:173], v[226:229], v[78:81]
	v_mfma_f32_16x16x32_bf16 v[70:73], v[178:181], v[226:229], v[70:73]
	s_setprio 0
	s_setprio 1
	v_mfma_f32_16x16x32_bf16 v[126:129], v[182:185], v[198:201], v[126:129]
	v_mfma_f32_16x16x32_bf16 v[114:117], v[190:193], v[198:201], v[114:117]
	v_mfma_f32_16x16x32_bf16 v[106:109], v[182:185], v[206:209], v[106:109]
	v_mfma_f32_16x16x32_bf16 v[98:101], v[190:193], v[206:209], v[98:101]
	v_mfma_f32_16x16x32_bf16 v[90:93], v[182:185], v[214:217], v[90:93]
	v_mfma_f32_16x16x32_bf16 v[82:85], v[190:193], v[214:217], v[82:85]
	v_mfma_f32_16x16x32_bf16 v[74:77], v[182:185], v[222:225], v[74:77]
	v_mfma_f32_16x16x32_bf16 v[66:69], v[190:193], v[222:225], v[66:69]
	v_mfma_f32_16x16x32_bf16 v[126:129], v[186:189], v[202:205], v[126:129]
	v_mfma_f32_16x16x32_bf16 v[114:117], v[194:197], v[202:205], v[114:117]
	v_mfma_f32_16x16x32_bf16 v[106:109], v[186:189], v[210:213], v[106:109]
	v_mfma_f32_16x16x32_bf16 v[98:101], v[194:197], v[210:213], v[98:101]
	v_mfma_f32_16x16x32_bf16 v[90:93], v[186:189], v[218:221], v[90:93]
	v_mfma_f32_16x16x32_bf16 v[82:85], v[194:197], v[218:221], v[82:85]
	v_mfma_f32_16x16x32_bf16 v[74:77], v[186:189], v[226:229], v[74:77]
	v_mfma_f32_16x16x32_bf16 v[66:69], v[194:197], v[226:229], v[66:69]
	s_barrier
	s_setprio 0
	s_add_u32 s96, s96, 0x80
	s_addc_u32 s97, s97, 0
	s_add_u32 s98, s96, 0xb0000
	s_addc_u32 s99, s97, 0
	s_add_u32 s94, s94, 0x80
	s_addc_u32 s95, s95, 0
	s_add_i32 s8, s8, s54
	s_mov_b32 m0, s8
	s_nop 0
	global_load_lds_dwordx4 v132, s[96:97]
	s_add_i32 m0, s8, 0x2000
	s_add_i32 s8, s50, s54
	global_load_lds_dwordx4 v136, s[96:97]
	s_mov_b32 m0, s8
	s_nop 0
	global_load_lds_dwordx4 v132, s[98:99]
	s_add_i32 m0, s8, 0x2000
	s_nop 0
	global_load_lds_dwordx4 v136, s[98:99]
	s_mov_b32 m0, s64
	s_nop 0
	global_load_lds_dwordx4 v130, s[94:95]
	s_mov_b32 m0, s65
	s_nop 0
	global_load_lds_dwordx4 v134, s[94:95]
	ds_read_b128 v[198:201], v163 offset:49152
	ds_read_b128 v[202:205], v163 offset:50176
	ds_read_b128 v[206:209], v163 offset:51200
	ds_read_b128 v[210:213], v163 offset:52224
	ds_read_b128 v[214:217], v163 offset:53248
	ds_read_b128 v[218:221], v163 offset:54272
	ds_read_b128 v[222:225], v163 offset:55296
	ds_read_b128 v[226:229], v163 offset:56320
	s_waitcnt vmcnt(8)
	s_waitcnt lgkmcnt(0)
	.p2align 3
	s_setprio 1
	s_barrier
	v_mfma_f32_16x16x32_bf16 v[62:65], v[166:169], v[198:201], v[62:65]
	v_mfma_f32_16x16x32_bf16 v[54:57], v[174:177], v[198:201], v[54:57]
	v_mfma_f32_16x16x32_bf16 v[46:49], v[166:169], v[206:209], v[46:49]
	v_mfma_f32_16x16x32_bf16 v[38:41], v[174:177], v[206:209], v[38:41]
	v_mfma_f32_16x16x32_bf16 v[30:33], v[166:169], v[214:217], v[30:33]
	v_mfma_f32_16x16x32_bf16 v[22:25], v[174:177], v[214:217], v[22:25]
	v_mfma_f32_16x16x32_bf16 v[14:17], v[166:169], v[222:225], v[14:17]
	v_mfma_f32_16x16x32_bf16 v[6:9], v[174:177], v[222:225], v[6:9]
	v_mfma_f32_16x16x32_bf16 v[62:65], v[170:173], v[202:205], v[62:65]
	v_mfma_f32_16x16x32_bf16 v[54:57], v[178:181], v[202:205], v[54:57]
	v_mfma_f32_16x16x32_bf16 v[46:49], v[170:173], v[210:213], v[46:49]
	v_mfma_f32_16x16x32_bf16 v[38:41], v[178:181], v[210:213], v[38:41]
	v_mfma_f32_16x16x32_bf16 v[30:33], v[170:173], v[218:221], v[30:33]
	v_mfma_f32_16x16x32_bf16 v[22:25], v[178:181], v[218:221], v[22:25]
	v_mfma_f32_16x16x32_bf16 v[14:17], v[170:173], v[226:229], v[14:17]
	v_mfma_f32_16x16x32_bf16 v[6:9], v[178:181], v[226:229], v[6:9]
	s_setprio 0
	s_setprio 1
	v_mfma_f32_16x16x32_bf16 v[58:61], v[182:185], v[198:201], v[58:61]
	v_mfma_f32_16x16x32_bf16 v[50:53], v[190:193], v[198:201], v[50:53]
	v_mfma_f32_16x16x32_bf16 v[42:45], v[182:185], v[206:209], v[42:45]
	v_mfma_f32_16x16x32_bf16 v[34:37], v[190:193], v[206:209], v[34:37]
	v_mfma_f32_16x16x32_bf16 v[26:29], v[182:185], v[214:217], v[26:29]
	v_mfma_f32_16x16x32_bf16 v[18:21], v[190:193], v[214:217], v[18:21]
	v_mfma_f32_16x16x32_bf16 v[10:13], v[182:185], v[222:225], v[10:13]
	v_mfma_f32_16x16x32_bf16 v[2:5], v[190:193], v[222:225], v[2:5]
	v_mfma_f32_16x16x32_bf16 v[58:61], v[186:189], v[202:205], v[58:61]
	v_mfma_f32_16x16x32_bf16 v[50:53], v[194:197], v[202:205], v[50:53]
	v_mfma_f32_16x16x32_bf16 v[42:45], v[186:189], v[210:213], v[42:45]
	v_mfma_f32_16x16x32_bf16 v[34:37], v[194:197], v[210:213], v[34:37]
	v_mfma_f32_16x16x32_bf16 v[26:29], v[186:189], v[218:221], v[26:29]
	v_mfma_f32_16x16x32_bf16 v[18:21], v[194:197], v[218:221], v[18:21]
	v_mfma_f32_16x16x32_bf16 v[10:13], v[186:189], v[226:229], v[10:13]
	v_mfma_f32_16x16x32_bf16 v[2:5], v[194:197], v[226:229], v[2:5]
	s_barrier
	s_setprio 0
	s_mov_b32 s8, s9
	s_add_u32 s88, s88, 0x100
	s_addc_u32 s89, s89, 0
	s_add_u32 s86, s86, 0x100
	s_addc_u32 s87, s87, 0
	s_cmp_ge_i32 s9, s101
	s_cbranch_scc1 .Lmy_kexit_1
.LBB0_310:
	s_add_u32 s98, s86, 0x100
	s_addc_u32 s99, s87, 0
	s_cmp_eq_u32 s8, s100
	s_cselect_b64 s[94:95], s[90:91], s[98:99]
	s_cselect_b64 s[96:97], s[92:93], s[88:89]
	s_add_i32 s9, s8, 2
	s_nop 0
	s_add_i32 m0, s55, 0xc000
	s_nop 0
	global_load_lds_dwordx4 v144, s[86:87]
	s_add_i32 m0, s55, 0xe000
	s_nop 0
	global_load_lds_dwordx4 v142, s[86:87]
	ds_read_b128 v[166:169], v230
	ds_read_b128 v[170:173], v230 offset:1024
	ds_read_b128 v[174:177], v230 offset:2048
	ds_read_b128 v[178:181], v230 offset:3072
	ds_read_b128 v[182:185], v231
	ds_read_b128 v[186:189], v231 offset:1024
	ds_read_b128 v[190:193], v231 offset:2048
	ds_read_b128 v[194:197], v231 offset:3072
	ds_read_b128 v[198:201], v163
	ds_read_b128 v[202:205], v163 offset:1024
	ds_read_b128 v[206:209], v163 offset:2048
	ds_read_b128 v[210:213], v163 offset:3072
	ds_read_b128 v[214:217], v163 offset:4096
	ds_read_b128 v[218:221], v163 offset:5120
	ds_read_b128 v[222:225], v163 offset:6144
	ds_read_b128 v[226:229], v163 offset:7168
	s_waitcnt vmcnt(8)
	s_waitcnt lgkmcnt(0)
	.p2align 3
	s_setprio 1
	s_barrier
	v_mfma_f32_16x16x32_bf16 v[122:125], v[166:169], v[198:201], v[122:125]
	v_mfma_f32_16x16x32_bf16 v[118:121], v[174:177], v[198:201], v[118:121]
	v_mfma_f32_16x16x32_bf16 v[110:113], v[166:169], v[206:209], v[110:113]
	v_mfma_f32_16x16x32_bf16 v[102:105], v[174:177], v[206:209], v[102:105]
	v_mfma_f32_16x16x32_bf16 v[94:97], v[166:169], v[214:217], v[94:97]
	v_mfma_f32_16x16x32_bf16 v[86:89], v[174:177], v[214:217], v[86:89]
	v_mfma_f32_16x16x32_bf16 v[78:81], v[166:169], v[222:225], v[78:81]
	v_mfma_f32_16x16x32_bf16 v[70:73], v[174:177], v[222:225], v[70:73]
	v_mfma_f32_16x16x32_bf16 v[122:125], v[170:173], v[202:205], v[122:125]
	v_mfma_f32_16x16x32_bf16 v[118:121], v[178:181], v[202:205], v[118:121]
	v_mfma_f32_16x16x32_bf16 v[110:113], v[170:173], v[210:213], v[110:113]
	v_mfma_f32_16x16x32_bf16 v[102:105], v[178:181], v[210:213], v[102:105]
	v_mfma_f32_16x16x32_bf16 v[94:97], v[170:173], v[218:221], v[94:97]
	v_mfma_f32_16x16x32_bf16 v[86:89], v[178:181], v[218:221], v[86:89]
	v_mfma_f32_16x16x32_bf16 v[78:81], v[170:173], v[226:229], v[78:81]
	v_mfma_f32_16x16x32_bf16 v[70:73], v[178:181], v[226:229], v[70:73]
	s_setprio 0
	s_setprio 1
	v_mfma_f32_16x16x32_bf16 v[126:129], v[182:185], v[198:201], v[126:129]
	v_mfma_f32_16x16x32_bf16 v[114:117], v[190:193], v[198:201], v[114:117]
	v_mfma_f32_16x16x32_bf16 v[106:109], v[182:185], v[206:209], v[106:109]
	v_mfma_f32_16x16x32_bf16 v[98:101], v[190:193], v[206:209], v[98:101]
	v_mfma_f32_16x16x32_bf16 v[90:93], v[182:185], v[214:217], v[90:93]
	v_mfma_f32_16x16x32_bf16 v[82:85], v[190:193], v[214:217], v[82:85]
	v_mfma_f32_16x16x32_bf16 v[74:77], v[182:185], v[222:225], v[74:77]
	v_mfma_f32_16x16x32_bf16 v[66:69], v[190:193], v[222:225], v[66:69]
	v_mfma_f32_16x16x32_bf16 v[126:129], v[186:189], v[202:205], v[126:129]
	v_mfma_f32_16x16x32_bf16 v[114:117], v[194:197], v[202:205], v[114:117]
	v_mfma_f32_16x16x32_bf16 v[106:109], v[186:189], v[210:213], v[106:109]
	v_mfma_f32_16x16x32_bf16 v[98:101], v[194:197], v[210:213], v[98:101]
	v_mfma_f32_16x16x32_bf16 v[90:93], v[186:189], v[218:221], v[90:93]
	v_mfma_f32_16x16x32_bf16 v[82:85], v[194:197], v[218:221], v[82:85]
	v_mfma_f32_16x16x32_bf16 v[74:77], v[186:189], v[226:229], v[74:77]
	v_mfma_f32_16x16x32_bf16 v[66:69], v[194:197], v[226:229], v[66:69]
	s_barrier
	s_setprio 0
	s_add_u32 s98, s96, 0xb0000
	s_addc_u32 s99, s97, 0
	s_add_i32 s8, s69, s54
	s_mov_b32 m0, s8
	s_nop 0
	global_load_lds_dwordx4 v132, s[96:97]
	s_add_i32 m0, s8, 0x2000
	s_add_i32 s8, s72, s54
	global_load_lds_dwordx4 v136, s[96:97]
	s_mov_b32 m0, s8
	s_nop 0
	global_load_lds_dwordx4 v132, s[98:99]
	s_add_i32 m0, s8, 0x2000
	s_nop 0
	global_load_lds_dwordx4 v136, s[98:99]
	s_mov_b32 m0, s55
	s_nop 0
	global_load_lds_dwordx4 v130, s[94:95]
	s_mov_b32 m0, s56
	s_nop 0
	global_load_lds_dwordx4 v134, s[94:95]
	ds_read_b128 v[198:201], v163 offset:16384
	ds_read_b128 v[202:205], v163 offset:17408
	ds_read_b128 v[206:209], v163 offset:18432
	ds_read_b128 v[210:213], v163 offset:19456
	ds_read_b128 v[214:217], v163 offset:20480
	ds_read_b128 v[218:221], v163 offset:21504
	ds_read_b128 v[222:225], v163 offset:22528
	ds_read_b128 v[226:229], v163 offset:23552
	s_waitcnt vmcnt(8)
	s_waitcnt lgkmcnt(0)
	.p2align 3
	s_setprio 1
	s_barrier
	v_mfma_f32_16x16x32_bf16 v[62:65], v[166:169], v[198:201], v[62:65]
	v_mfma_f32_16x16x32_bf16 v[54:57], v[174:177], v[198:201], v[54:57]
	v_mfma_f32_16x16x32_bf16 v[46:49], v[166:169], v[206:209], v[46:49]
	v_mfma_f32_16x16x32_bf16 v[38:41], v[174:177], v[206:209], v[38:41]
	v_mfma_f32_16x16x32_bf16 v[30:33], v[166:169], v[214:217], v[30:33]
	v_mfma_f32_16x16x32_bf16 v[22:25], v[174:177], v[214:217], v[22:25]
	v_mfma_f32_16x16x32_bf16 v[14:17], v[166:169], v[222:225], v[14:17]
	v_mfma_f32_16x16x32_bf16 v[6:9], v[174:177], v[222:225], v[6:9]
	v_mfma_f32_16x16x32_bf16 v[62:65], v[170:173], v[202:205], v[62:65]
	v_mfma_f32_16x16x32_bf16 v[54:57], v[178:181], v[202:205], v[54:57]
	v_mfma_f32_16x16x32_bf16 v[46:49], v[170:173], v[210:213], v[46:49]
	v_mfma_f32_16x16x32_bf16 v[38:41], v[178:181], v[210:213], v[38:41]
	v_mfma_f32_16x16x32_bf16 v[30:33], v[170:173], v[218:221], v[30:33]
	v_mfma_f32_16x16x32_bf16 v[22:25], v[178:181], v[218:221], v[22:25]
	v_mfma_f32_16x16x32_bf16 v[14:17], v[170:173], v[226:229], v[14:17]
	v_mfma_f32_16x16x32_bf16 v[6:9], v[178:181], v[226:229], v[6:9]
	s_setprio 0
	s_setprio 1
	v_mfma_f32_16x16x32_bf16 v[58:61], v[182:185], v[198:201], v[58:61]
	v_mfma_f32_16x16x32_bf16 v[50:53], v[190:193], v[198:201], v[50:53]
	v_mfma_f32_16x16x32_bf16 v[42:45], v[182:185], v[206:209], v[42:45]
	v_mfma_f32_16x16x32_bf16 v[34:37], v[190:193], v[206:209], v[34:37]
	v_mfma_f32_16x16x32_bf16 v[26:29], v[182:185], v[214:217], v[26:29]
	v_mfma_f32_16x16x32_bf16 v[18:21], v[190:193], v[214:217], v[18:21]
	v_mfma_f32_16x16x32_bf16 v[10:13], v[182:185], v[222:225], v[10:13]
	v_mfma_f32_16x16x32_bf16 v[2:5], v[190:193], v[222:225], v[2:5]
	v_mfma_f32_16x16x32_bf16 v[58:61], v[186:189], v[202:205], v[58:61]
	v_mfma_f32_16x16x32_bf16 v[50:53], v[194:197], v[202:205], v[50:53]
	v_mfma_f32_16x16x32_bf16 v[42:45], v[186:189], v[210:213], v[42:45]
	v_mfma_f32_16x16x32_bf16 v[34:37], v[194:197], v[210:213], v[34:37]
	v_mfma_f32_16x16x32_bf16 v[26:29], v[186:189], v[218:221], v[26:29]
	v_mfma_f32_16x16x32_bf16 v[18:21], v[194:197], v[218:221], v[18:21]
	v_mfma_f32_16x16x32_bf16 v[10:13], v[186:189], v[226:229], v[10:13]
	v_mfma_f32_16x16x32_bf16 v[2:5], v[194:197], v[226:229], v[2:5]
	s_barrier
	s_setprio 0
	s_add_u32 s98, s94, 0xb0000
	s_addc_u32 s99, s95, 0
	s_add_i32 s8, 0, 0x18000
	s_add_i32 s50, 0, 0x1c000
	s_mov_b32 m0, s57
	s_nop 0
	global_load_lds_dwordx4 v130, s[98:99]
	s_mov_b32 m0, s58
	s_nop 0
	global_load_lds_dwordx4 v134, s[98:99]
	ds_read_b128 v[166:169], v232
	ds_read_b128 v[170:173], v232 offset:1024
	ds_read_b128 v[174:177], v232 offset:2048
	ds_read_b128 v[178:181], v232 offset:3072
	ds_read_b128 v[182:185], v233
	ds_read_b128 v[186:189], v233 offset:1024
	ds_read_b128 v[190:193], v233 offset:2048
	ds_read_b128 v[194:197], v233 offset:3072
	ds_read_b128 v[198:201], v163 offset:32768
	ds_read_b128 v[202:205], v163 offset:33792
	ds_read_b128 v[206:209], v163 offset:34816
	ds_read_b128 v[210:213], v163 offset:35840
	ds_read_b128 v[214:217], v163 offset:36864
	ds_read_b128 v[218:221], v163 offset:37888
	ds_read_b128 v[222:225], v163 offset:38912
	ds_read_b128 v[226:229], v163 offset:39936
	s_waitcnt vmcnt(8)
	s_waitcnt lgkmcnt(0)
	.p2align 3
	s_setprio 1
	s_barrier
	v_mfma_f32_16x16x32_bf16 v[122:125], v[166:169], v[198:201], v[122:125]
	v_mfma_f32_16x16x32_bf16 v[118:121], v[174:177], v[198:201], v[118:121]
	v_mfma_f32_16x16x32_bf16 v[110:113], v[166:169], v[206:209], v[110:113]
	v_mfma_f32_16x16x32_bf16 v[102:105], v[174:177], v[206:209], v[102:105]
	v_mfma_f32_16x16x32_bf16 v[94:97], v[166:169], v[214:217], v[94:97]
	v_mfma_f32_16x16x32_bf16 v[86:89], v[174:177], v[214:217], v[86:89]
	v_mfma_f32_16x16x32_bf16 v[78:81], v[166:169], v[222:225], v[78:81]
	v_mfma_f32_16x16x32_bf16 v[70:73], v[174:177], v[222:225], v[70:73]
	v_mfma_f32_16x16x32_bf16 v[122:125], v[170:173], v[202:205], v[122:125]
	v_mfma_f32_16x16x32_bf16 v[118:121], v[178:181], v[202:205], v[118:121]
	v_mfma_f32_16x16x32_bf16 v[110:113], v[170:173], v[210:213], v[110:113]
	v_mfma_f32_16x16x32_bf16 v[102:105], v[178:181], v[210:213], v[102:105]
	v_mfma_f32_16x16x32_bf16 v[94:97], v[170:173], v[218:221], v[94:97]
	v_mfma_f32_16x16x32_bf16 v[86:89], v[178:181], v[218:221], v[86:89]
	v_mfma_f32_16x16x32_bf16 v[78:81], v[170:173], v[226:229], v[78:81]
	v_mfma_f32_16x16x32_bf16 v[70:73], v[178:181], v[226:229], v[70:73]
	s_setprio 0
	s_setprio 1
	v_mfma_f32_16x16x32_bf16 v[126:129], v[182:185], v[198:201], v[126:129]
	v_mfma_f32_16x16x32_bf16 v[114:117], v[190:193], v[198:201], v[114:117]
	v_mfma_f32_16x16x32_bf16 v[106:109], v[182:185], v[206:209], v[106:109]
	v_mfma_f32_16x16x32_bf16 v[98:101], v[190:193], v[206:209], v[98:101]
	v_mfma_f32_16x16x32_bf16 v[90:93], v[182:185], v[214:217], v[90:93]
	v_mfma_f32_16x16x32_bf16 v[82:85], v[190:193], v[214:217], v[82:85]
	v_mfma_f32_16x16x32_bf16 v[74:77], v[182:185], v[222:225], v[74:77]
	v_mfma_f32_16x16x32_bf16 v[66:69], v[190:193], v[222:225], v[66:69]
	v_mfma_f32_16x16x32_bf16 v[126:129], v[186:189], v[202:205], v[126:129]
	v_mfma_f32_16x16x32_bf16 v[114:117], v[194:197], v[202:205], v[114:117]
	v_mfma_f32_16x16x32_bf16 v[106:109], v[186:189], v[210:213], v[106:109]
	v_mfma_f32_16x16x32_bf16 v[98:101], v[194:197], v[210:213], v[98:101]
	v_mfma_f32_16x16x32_bf16 v[90:93], v[186:189], v[218:221], v[90:93]
	v_mfma_f32_16x16x32_bf16 v[82:85], v[194:197], v[218:221], v[82:85]
	v_mfma_f32_16x16x32_bf16 v[74:77], v[186:189], v[226:229], v[74:77]
	v_mfma_f32_16x16x32_bf16 v[66:69], v[194:197], v[226:229], v[66:69]
	s_barrier
	s_setprio 0
	s_add_u32 s96, s96, 0x80
	s_addc_u32 s97, s97, 0
	s_add_u32 s98, s96, 0xb0000
	s_addc_u32 s99, s97, 0
	s_add_u32 s94, s94, 0x80
	s_addc_u32 s95, s95, 0
	s_add_i32 s8, s8, s54
	s_mov_b32 m0, s8
	s_nop 0
	global_load_lds_dwordx4 v132, s[96:97]
	s_add_i32 m0, s8, 0x2000
	s_add_i32 s8, s50, s54
	global_load_lds_dwordx4 v136, s[96:97]
	s_mov_b32 m0, s8
	s_nop 0
	global_load_lds_dwordx4 v132, s[98:99]
	s_add_i32 m0, s8, 0x2000
	s_nop 0
	global_load_lds_dwordx4 v136, s[98:99]
	s_mov_b32 m0, s64
	s_nop 0
	global_load_lds_dwordx4 v130, s[94:95]
	s_mov_b32 m0, s65
	s_nop 0
	global_load_lds_dwordx4 v134, s[94:95]
	ds_read_b128 v[198:201], v163 offset:49152
	ds_read_b128 v[202:205], v163 offset:50176
	ds_read_b128 v[206:209], v163 offset:51200
	ds_read_b128 v[210:213], v163 offset:52224
	ds_read_b128 v[214:217], v163 offset:53248
	ds_read_b128 v[218:221], v163 offset:54272
	ds_read_b128 v[222:225], v163 offset:55296
	ds_read_b128 v[226:229], v163 offset:56320
	s_waitcnt vmcnt(8)
	s_waitcnt lgkmcnt(0)
	.p2align 3
	s_setprio 1
	s_barrier
	v_mfma_f32_16x16x32_bf16 v[62:65], v[166:169], v[198:201], v[62:65]
	v_mfma_f32_16x16x32_bf16 v[54:57], v[174:177], v[198:201], v[54:57]
	v_mfma_f32_16x16x32_bf16 v[46:49], v[166:169], v[206:209], v[46:49]
	v_mfma_f32_16x16x32_bf16 v[38:41], v[174:177], v[206:209], v[38:41]
	v_mfma_f32_16x16x32_bf16 v[30:33], v[166:169], v[214:217], v[30:33]
	v_mfma_f32_16x16x32_bf16 v[22:25], v[174:177], v[214:217], v[22:25]
	v_mfma_f32_16x16x32_bf16 v[14:17], v[166:169], v[222:225], v[14:17]
	v_mfma_f32_16x16x32_bf16 v[6:9], v[174:177], v[222:225], v[6:9]
	v_mfma_f32_16x16x32_bf16 v[62:65], v[170:173], v[202:205], v[62:65]
	v_mfma_f32_16x16x32_bf16 v[54:57], v[178:181], v[202:205], v[54:57]
	v_mfma_f32_16x16x32_bf16 v[46:49], v[170:173], v[210:213], v[46:49]
	v_mfma_f32_16x16x32_bf16 v[38:41], v[178:181], v[210:213], v[38:41]
	v_mfma_f32_16x16x32_bf16 v[30:33], v[170:173], v[218:221], v[30:33]
	v_mfma_f32_16x16x32_bf16 v[22:25], v[178:181], v[218:221], v[22:25]
	v_mfma_f32_16x16x32_bf16 v[14:17], v[170:173], v[226:229], v[14:17]
	v_mfma_f32_16x16x32_bf16 v[6:9], v[178:181], v[226:229], v[6:9]
	s_setprio 0
	s_setprio 1
	v_mfma_f32_16x16x32_bf16 v[58:61], v[182:185], v[198:201], v[58:61]
	v_mfma_f32_16x16x32_bf16 v[50:53], v[190:193], v[198:201], v[50:53]
	v_mfma_f32_16x16x32_bf16 v[42:45], v[182:185], v[206:209], v[42:45]
	v_mfma_f32_16x16x32_bf16 v[34:37], v[190:193], v[206:209], v[34:37]
	v_mfma_f32_16x16x32_bf16 v[26:29], v[182:185], v[214:217], v[26:29]
	v_mfma_f32_16x16x32_bf16 v[18:21], v[190:193], v[214:217], v[18:21]
	v_mfma_f32_16x16x32_bf16 v[10:13], v[182:185], v[222:225], v[10:13]
	v_mfma_f32_16x16x32_bf16 v[2:5], v[190:193], v[222:225], v[2:5]
	v_mfma_f32_16x16x32_bf16 v[58:61], v[186:189], v[202:205], v[58:61]
	v_mfma_f32_16x16x32_bf16 v[50:53], v[194:197], v[202:205], v[50:53]
	v_mfma_f32_16x16x32_bf16 v[42:45], v[186:189], v[210:213], v[42:45]
	v_mfma_f32_16x16x32_bf16 v[34:37], v[194:197], v[210:213], v[34:37]
	v_mfma_f32_16x16x32_bf16 v[26:29], v[186:189], v[218:221], v[26:29]
	v_mfma_f32_16x16x32_bf16 v[18:21], v[194:197], v[218:221], v[18:21]
	v_mfma_f32_16x16x32_bf16 v[10:13], v[186:189], v[226:229], v[10:13]
	v_mfma_f32_16x16x32_bf16 v[2:5], v[194:197], v[226:229], v[2:5]
	s_barrier
	s_setprio 0
	s_mov_b32 s8, s9
	s_add_u32 s88, s88, 0x100
	s_addc_u32 s89, s89, 0
	s_add_u32 s86, s86, 0x100
	s_addc_u32 s87, s87, 0
	s_cmp_ge_i32 s9, s101
	s_cbranch_scc0 .LBB0_310

.Lmy_nb_2:
	s_nop 0
	v_readfirstlane_b32 s86, v154
	v_readfirstlane_b32 s87, v155
	v_readfirstlane_b32 s88, v152
	v_readfirstlane_b32 s89, v153
	v_readfirstlane_b32 s90, v148
	v_readfirstlane_b32 s91, v149
	v_readfirstlane_b32 s92, v150
	v_readfirstlane_b32 s93, v151
	v_readfirstlane_b32 s100, v138
	v_readfirstlane_b32 s101, v141
	v_add_u32_e32 v230, s77, v160
	v_add_u32_e32 v231, s78, v160
	v_add_u32_e32 v232, 0x18000, v160
	v_add_u32_e32 v233, 0x1c000, v160
	s_add_u32 s98, s86, 0xfffc0080
	s_addc_u32 s99, s87, -1
	s_cmp_eq_u32 s7, s100
	s_cselect_b64 s[94:95], s[90:91], s[98:99]
	s_cselect_b64 s[96:97], s[92:93], s[88:89]
	s_add_i32 s45, s7, 2
	s_nop 0
	s_add_i32 m0, s49, 0xc000
	s_nop 0
	global_load_lds_dwordx4 v144, s[86:87]
	s_add_i32 m0, s49, 0xe000
	s_nop 0
	global_load_lds_dwordx4 v142, s[86:87]
	ds_read_b128 v[156:159], v230
	ds_read_b128 v[166:169], v230 offset:1024
	ds_read_b128 v[170:173], v230 offset:2048
	ds_read_b128 v[174:177], v230 offset:3072
	ds_read_b128 v[178:181], v231
	ds_read_b128 v[182:185], v231 offset:1024
	ds_read_b128 v[186:189], v231 offset:2048
	ds_read_b128 v[190:193], v231 offset:3072
	ds_read_b128 v[194:197], v163
	ds_read_b128 v[198:201], v163 offset:1024
	ds_read_b128 v[202:205], v163 offset:2048
	ds_read_b128 v[206:209], v163 offset:3072
	ds_read_b128 v[210:213], v163 offset:4096
	ds_read_b128 v[214:217], v163 offset:5120
	ds_read_b128 v[218:221], v163 offset:6144
	ds_read_b128 v[222:225], v163 offset:7168
	s_waitcnt vmcnt(8)
	s_waitcnt lgkmcnt(0)
	.p2align 3
	s_setprio 1
	s_barrier
	v_mfma_f32_16x16x32_bf16 v[122:125], v[156:159], v[194:197], 0
	v_mfma_f32_16x16x32_bf16 v[118:121], v[170:173], v[194:197], 0
	v_mfma_f32_16x16x32_bf16 v[110:113], v[156:159], v[202:205], 0
	v_mfma_f32_16x16x32_bf16 v[102:105], v[170:173], v[202:205], 0
	v_mfma_f32_16x16x32_bf16 v[94:97], v[156:159], v[210:213], 0
	v_mfma_f32_16x16x32_bf16 v[86:89], v[170:173], v[210:213], 0
	v_mfma_f32_16x16x32_bf16 v[78:81], v[156:159], v[218:221], 0
	v_mfma_f32_16x16x32_bf16 v[70:73], v[170:173], v[218:221], 0
	v_mfma_f32_16x16x32_bf16 v[122:125], v[166:169], v[198:201], v[122:125]
	v_mfma_f32_16x16x32_bf16 v[118:121], v[174:177], v[198:201], v[118:121]
	v_mfma_f32_16x16x32_bf16 v[110:113], v[166:169], v[206:209], v[110:113]
	v_mfma_f32_16x16x32_bf16 v[102:105], v[174:177], v[206:209], v[102:105]
	v_mfma_f32_16x16x32_bf16 v[94:97], v[166:169], v[214:217], v[94:97]
	v_mfma_f32_16x16x32_bf16 v[86:89], v[174:177], v[214:217], v[86:89]
	v_mfma_f32_16x16x32_bf16 v[78:81], v[166:169], v[222:225], v[78:81]
	v_mfma_f32_16x16x32_bf16 v[70:73], v[174:177], v[222:225], v[70:73]
	s_setprio 0
	s_setprio 1
	v_mfma_f32_16x16x32_bf16 v[126:129], v[178:181], v[194:197], 0
	v_mfma_f32_16x16x32_bf16 v[114:117], v[186:189], v[194:197], 0
	v_mfma_f32_16x16x32_bf16 v[106:109], v[178:181], v[202:205], 0
	v_mfma_f32_16x16x32_bf16 v[98:101], v[186:189], v[202:205], 0
	v_mfma_f32_16x16x32_bf16 v[90:93], v[178:181], v[210:213], 0
	v_mfma_f32_16x16x32_bf16 v[82:85], v[186:189], v[210:213], 0
	v_mfma_f32_16x16x32_bf16 v[74:77], v[178:181], v[218:221], 0
	v_mfma_f32_16x16x32_bf16 v[66:69], v[186:189], v[218:221], 0
	v_mfma_f32_16x16x32_bf16 v[126:129], v[182:185], v[198:201], v[126:129]
	v_mfma_f32_16x16x32_bf16 v[114:117], v[190:193], v[198:201], v[114:117]
	v_mfma_f32_16x16x32_bf16 v[106:109], v[182:185], v[206:209], v[106:109]
	v_mfma_f32_16x16x32_bf16 v[98:101], v[190:193], v[206:209], v[98:101]
	v_mfma_f32_16x16x32_bf16 v[90:93], v[182:185], v[214:217], v[90:93]
	v_mfma_f32_16x16x32_bf16 v[82:85], v[190:193], v[214:217], v[82:85]
	v_mfma_f32_16x16x32_bf16 v[74:77], v[182:185], v[222:225], v[74:77]
	v_mfma_f32_16x16x32_bf16 v[66:69], v[190:193], v[222:225], v[66:69]
	s_barrier
	s_setprio 0
	s_add_u32 s98, s96, 0x40000
	s_addc_u32 s99, s97, 0
	s_add_i32 s7, s77, s25
	s_mov_b32 m0, s7
	s_nop 0
	global_load_lds_dwordx4 v132, s[96:97]
	s_add_i32 m0, s7, 0x2000
	s_add_i32 s7, s78, s25
	global_load_lds_dwordx4 v136, s[96:97]
	s_mov_b32 m0, s7
	s_nop 0
	global_load_lds_dwordx4 v132, s[98:99]
	s_add_i32 m0, s7, 0x2000
	s_nop 0
	global_load_lds_dwordx4 v136, s[98:99]
	s_mov_b32 m0, s49
	s_nop 0
	global_load_lds_dwordx4 v130, s[94:95]
	s_mov_b32 m0, s58
	s_nop 0
	global_load_lds_dwordx4 v134, s[94:95]
	ds_read_b128 v[194:197], v163 offset:16384
	ds_read_b128 v[198:201], v163 offset:17408
	ds_read_b128 v[202:205], v163 offset:18432
	ds_read_b128 v[206:209], v163 offset:19456
	ds_read_b128 v[210:213], v163 offset:20480
	ds_read_b128 v[214:217], v163 offset:21504
	ds_read_b128 v[218:221], v163 offset:22528
	ds_read_b128 v[222:225], v163 offset:23552
	s_waitcnt vmcnt(8)
	s_waitcnt lgkmcnt(0)
	.p2align 3
	s_setprio 1
	s_barrier
	v_mfma_f32_16x16x32_bf16 v[62:65], v[156:159], v[194:197], 0
	v_mfma_f32_16x16x32_bf16 v[54:57], v[170:173], v[194:197], 0
	v_mfma_f32_16x16x32_bf16 v[46:49], v[156:159], v[202:205], 0
	v_mfma_f32_16x16x32_bf16 v[38:41], v[170:173], v[202:205], 0
	v_mfma_f32_16x16x32_bf16 v[30:33], v[156:159], v[210:213], 0
	v_mfma_f32_16x16x32_bf16 v[22:25], v[170:173], v[210:213], 0
	v_mfma_f32_16x16x32_bf16 v[14:17], v[156:159], v[218:221], 0
	v_mfma_f32_16x16x32_bf16 v[6:9], v[170:173], v[218:221], 0
	v_mfma_f32_16x16x32_bf16 v[62:65], v[166:169], v[198:201], v[62:65]
	v_mfma_f32_16x16x32_bf16 v[54:57], v[174:177], v[198:201], v[54:57]
	v_mfma_f32_16x16x32_bf16 v[46:49], v[166:169], v[206:209], v[46:49]
	v_mfma_f32_16x16x32_bf16 v[38:41], v[174:177], v[206:209], v[38:41]
	v_mfma_f32_16x16x32_bf16 v[30:33], v[166:169], v[214:217], v[30:33]
	v_mfma_f32_16x16x32_bf16 v[22:25], v[174:177], v[214:217], v[22:25]
	v_mfma_f32_16x16x32_bf16 v[14:17], v[166:169], v[222:225], v[14:17]
	v_mfma_f32_16x16x32_bf16 v[6:9], v[174:177], v[222:225], v[6:9]
	s_setprio 0
	s_setprio 1
	v_mfma_f32_16x16x32_bf16 v[58:61], v[178:181], v[194:197], 0
	v_mfma_f32_16x16x32_bf16 v[50:53], v[186:189], v[194:197], 0
	v_mfma_f32_16x16x32_bf16 v[42:45], v[178:181], v[202:205], 0
	v_mfma_f32_16x16x32_bf16 v[34:37], v[186:189], v[202:205], 0
	v_mfma_f32_16x16x32_bf16 v[26:29], v[178:181], v[210:213], 0
	v_mfma_f32_16x16x32_bf16 v[18:21], v[186:189], v[210:213], 0
	v_mfma_f32_16x16x32_bf16 v[10:13], v[178:181], v[218:221], 0
	v_mfma_f32_16x16x32_bf16 v[2:5], v[186:189], v[218:221], 0
	v_mfma_f32_16x16x32_bf16 v[58:61], v[182:185], v[198:201], v[58:61]
	v_mfma_f32_16x16x32_bf16 v[50:53], v[190:193], v[198:201], v[50:53]
	v_mfma_f32_16x16x32_bf16 v[42:45], v[182:185], v[206:209], v[42:45]
	v_mfma_f32_16x16x32_bf16 v[34:37], v[190:193], v[206:209], v[34:37]
	v_mfma_f32_16x16x32_bf16 v[26:29], v[182:185], v[214:217], v[26:29]
	v_mfma_f32_16x16x32_bf16 v[18:21], v[190:193], v[214:217], v[18:21]
	v_mfma_f32_16x16x32_bf16 v[10:13], v[182:185], v[222:225], v[10:13]
	v_mfma_f32_16x16x32_bf16 v[2:5], v[190:193], v[222:225], v[2:5]
	s_barrier
	s_setprio 0
	s_add_u32 s98, s94, 0x40000
	s_addc_u32 s99, s95, 0
	s_add_i32 s7, 0, 0x18000
	s_add_i32 s47, 0, 0x1c000
	s_mov_b32 m0, s59
	s_nop 0
	global_load_lds_dwordx4 v130, s[98:99]
	s_mov_b32 m0, s60
	s_nop 0
	global_load_lds_dwordx4 v134, s[98:99]
	ds_read_b128 v[156:159], v232
	ds_read_b128 v[166:169], v232 offset:1024
	ds_read_b128 v[170:173], v232 offset:2048
	ds_read_b128 v[174:177], v232 offset:3072
	ds_read_b128 v[178:181], v233
	ds_read_b128 v[182:185], v233 offset:1024
	ds_read_b128 v[186:189], v233 offset:2048
	ds_read_b128 v[190:193], v233 offset:3072
	ds_read_b128 v[194:197], v163 offset:32768
	ds_read_b128 v[198:201], v163 offset:33792
	ds_read_b128 v[202:205], v163 offset:34816
	ds_read_b128 v[206:209], v163 offset:35840
	ds_read_b128 v[210:213], v163 offset:36864
	ds_read_b128 v[214:217], v163 offset:37888
	ds_read_b128 v[218:221], v163 offset:38912
	ds_read_b128 v[222:225], v163 offset:39936
	s_waitcnt vmcnt(8)
	s_waitcnt lgkmcnt(0)
	.p2align 3
	s_setprio 1
	s_barrier
	v_mfma_f32_16x16x32_bf16 v[122:125], v[156:159], v[194:197], v[122:125]
	v_mfma_f32_16x16x32_bf16 v[118:121], v[170:173], v[194:197], v[118:121]
	v_mfma_f32_16x16x32_bf16 v[110:113], v[156:159], v[202:205], v[110:113]
	v_mfma_f32_16x16x32_bf16 v[102:105], v[170:173], v[202:205], v[102:105]
	v_mfma_f32_16x16x32_bf16 v[94:97], v[156:159], v[210:213], v[94:97]
	v_mfma_f32_16x16x32_bf16 v[86:89], v[170:173], v[210:213], v[86:89]
	v_mfma_f32_16x16x32_bf16 v[78:81], v[156:159], v[218:221], v[78:81]
	v_mfma_f32_16x16x32_bf16 v[70:73], v[170:173], v[218:221], v[70:73]
	v_mfma_f32_16x16x32_bf16 v[122:125], v[166:169], v[198:201], v[122:125]
	v_mfma_f32_16x16x32_bf16 v[118:121], v[174:177], v[198:201], v[118:121]
	v_mfma_f32_16x16x32_bf16 v[110:113], v[166:169], v[206:209], v[110:113]
	v_mfma_f32_16x16x32_bf16 v[102:105], v[174:177], v[206:209], v[102:105]
	v_mfma_f32_16x16x32_bf16 v[94:97], v[166:169], v[214:217], v[94:97]
	v_mfma_f32_16x16x32_bf16 v[86:89], v[174:177], v[214:217], v[86:89]
	v_mfma_f32_16x16x32_bf16 v[78:81], v[166:169], v[222:225], v[78:81]
	v_mfma_f32_16x16x32_bf16 v[70:73], v[174:177], v[222:225], v[70:73]
	s_setprio 0
	s_setprio 1
	v_mfma_f32_16x16x32_bf16 v[126:129], v[178:181], v[194:197], v[126:129]
	v_mfma_f32_16x16x32_bf16 v[114:117], v[186:189], v[194:197], v[114:117]
	v_mfma_f32_16x16x32_bf16 v[106:109], v[178:181], v[202:205], v[106:109]
	v_mfma_f32_16x16x32_bf16 v[98:101], v[186:189], v[202:205], v[98:101]
	v_mfma_f32_16x16x32_bf16 v[90:93], v[178:181], v[210:213], v[90:93]
	v_mfma_f32_16x16x32_bf16 v[82:85], v[186:189], v[210:213], v[82:85]
	v_mfma_f32_16x16x32_bf16 v[74:77], v[178:181], v[218:221], v[74:77]
	v_mfma_f32_16x16x32_bf16 v[66:69], v[186:189], v[218:221], v[66:69]
	v_mfma_f32_16x16x32_bf16 v[126:129], v[182:185], v[198:201], v[126:129]
	v_mfma_f32_16x16x32_bf16 v[114:117], v[190:193], v[198:201], v[114:117]
	v_mfma_f32_16x16x32_bf16 v[106:109], v[182:185], v[206:209], v[106:109]
	v_mfma_f32_16x16x32_bf16 v[98:101], v[190:193], v[206:209], v[98:101]
	v_mfma_f32_16x16x32_bf16 v[90:93], v[182:185], v[214:217], v[90:93]
	v_mfma_f32_16x16x32_bf16 v[82:85], v[190:193], v[214:217], v[82:85]
	v_mfma_f32_16x16x32_bf16 v[74:77], v[182:185], v[222:225], v[74:77]
	v_mfma_f32_16x16x32_bf16 v[66:69], v[190:193], v[222:225], v[66:69]
	s_barrier
	s_setprio 0
	s_add_u32 s96, s96, 0x80
	s_addc_u32 s97, s97, 0
	s_add_u32 s98, s96, 0x40000
	s_addc_u32 s99, s97, 0
	s_add_u32 s94, s94, 0x80
	s_addc_u32 s95, s95, 0
	s_add_i32 s7, s7, s25
	s_mov_b32 m0, s7
	s_nop 0
	global_load_lds_dwordx4 v132, s[96:97]
	s_add_i32 m0, s7, 0x2000
	s_add_i32 s7, s47, s25
	global_load_lds_dwordx4 v136, s[96:97]
	s_mov_b32 m0, s7
	s_nop 0
	global_load_lds_dwordx4 v132, s[98:99]
	s_add_i32 m0, s7, 0x2000
	s_nop 0
	global_load_lds_dwordx4 v136, s[98:99]
	s_mov_b32 m0, s66
	s_nop 0
	global_load_lds_dwordx4 v130, s[94:95]
	s_mov_b32 m0, s67
	s_nop 0
	global_load_lds_dwordx4 v134, s[94:95]
	ds_read_b128 v[194:197], v163 offset:49152
	ds_read_b128 v[198:201], v163 offset:50176
	ds_read_b128 v[202:205], v163 offset:51200
	ds_read_b128 v[206:209], v163 offset:52224
	ds_read_b128 v[210:213], v163 offset:53248
	ds_read_b128 v[214:217], v163 offset:54272
	ds_read_b128 v[218:221], v163 offset:55296
	ds_read_b128 v[222:225], v163 offset:56320
	s_waitcnt vmcnt(8)
	s_waitcnt lgkmcnt(0)
	.p2align 3
	s_setprio 1
	s_barrier
	v_mfma_f32_16x16x32_bf16 v[62:65], v[156:159], v[194:197], v[62:65]
	v_mfma_f32_16x16x32_bf16 v[54:57], v[170:173], v[194:197], v[54:57]
	v_mfma_f32_16x16x32_bf16 v[46:49], v[156:159], v[202:205], v[46:49]
	v_mfma_f32_16x16x32_bf16 v[38:41], v[170:173], v[202:205], v[38:41]
	v_mfma_f32_16x16x32_bf16 v[30:33], v[156:159], v[210:213], v[30:33]
	v_mfma_f32_16x16x32_bf16 v[22:25], v[170:173], v[210:213], v[22:25]
	v_mfma_f32_16x16x32_bf16 v[14:17], v[156:159], v[218:221], v[14:17]
	v_mfma_f32_16x16x32_bf16 v[6:9], v[170:173], v[218:221], v[6:9]
	v_mfma_f32_16x16x32_bf16 v[62:65], v[166:169], v[198:201], v[62:65]
	v_mfma_f32_16x16x32_bf16 v[54:57], v[174:177], v[198:201], v[54:57]
	v_mfma_f32_16x16x32_bf16 v[46:49], v[166:169], v[206:209], v[46:49]
	v_mfma_f32_16x16x32_bf16 v[38:41], v[174:177], v[206:209], v[38:41]
	v_mfma_f32_16x16x32_bf16 v[30:33], v[166:169], v[214:217], v[30:33]
	v_mfma_f32_16x16x32_bf16 v[22:25], v[174:177], v[214:217], v[22:25]
	v_mfma_f32_16x16x32_bf16 v[14:17], v[166:169], v[222:225], v[14:17]
	v_mfma_f32_16x16x32_bf16 v[6:9], v[174:177], v[222:225], v[6:9]
	s_setprio 0
	s_setprio 1
	v_mfma_f32_16x16x32_bf16 v[58:61], v[178:181], v[194:197], v[58:61]
	v_mfma_f32_16x16x32_bf16 v[50:53], v[186:189], v[194:197], v[50:53]
	v_mfma_f32_16x16x32_bf16 v[42:45], v[178:181], v[202:205], v[42:45]
	v_mfma_f32_16x16x32_bf16 v[34:37], v[186:189], v[202:205], v[34:37]
	v_mfma_f32_16x16x32_bf16 v[26:29], v[178:181], v[210:213], v[26:29]
	v_mfma_f32_16x16x32_bf16 v[18:21], v[186:189], v[210:213], v[18:21]
	v_mfma_f32_16x16x32_bf16 v[10:13], v[178:181], v[218:221], v[10:13]
	v_mfma_f32_16x16x32_bf16 v[2:5], v[186:189], v[218:221], v[2:5]
	v_mfma_f32_16x16x32_bf16 v[58:61], v[182:185], v[198:201], v[58:61]
	v_mfma_f32_16x16x32_bf16 v[50:53], v[190:193], v[198:201], v[50:53]
	v_mfma_f32_16x16x32_bf16 v[42:45], v[182:185], v[206:209], v[42:45]
	v_mfma_f32_16x16x32_bf16 v[34:37], v[190:193], v[206:209], v[34:37]
	v_mfma_f32_16x16x32_bf16 v[26:29], v[182:185], v[214:217], v[26:29]
	v_mfma_f32_16x16x32_bf16 v[18:21], v[190:193], v[214:217], v[18:21]
	v_mfma_f32_16x16x32_bf16 v[10:13], v[182:185], v[222:225], v[10:13]
	v_mfma_f32_16x16x32_bf16 v[2:5], v[190:193], v[222:225], v[2:5]
	s_barrier
	s_setprio 0
	s_mov_b32 s7, s45
	s_add_u32 s88, s88, 0x100
	s_addc_u32 s89, s89, 0
	s_add_u32 s86, s86, 0x100
	s_addc_u32 s87, s87, 0
	s_cmp_ge_i32 s45, s101
	s_cbranch_scc1 .Lmy_kexit_2
.LBB0_499:
	s_add_u32 s98, s86, 0xfffc0080
	s_addc_u32 s99, s87, -1
	s_cmp_eq_u32 s7, s100
	s_cselect_b64 s[94:95], s[90:91], s[98:99]
	s_cselect_b64 s[96:97], s[92:93], s[88:89]
	s_add_i32 s45, s7, 2
	s_nop 0
	s_add_i32 m0, s49, 0xc000
	s_nop 0
	global_load_lds_dwordx4 v144, s[86:87]
	s_add_i32 m0, s49, 0xe000
	s_nop 0
	global_load_lds_dwordx4 v142, s[86:87]
	ds_read_b128 v[156:159], v230
	ds_read_b128 v[166:169], v230 offset:1024
	ds_read_b128 v[170:173], v230 offset:2048
	ds_read_b128 v[174:177], v230 offset:3072
	ds_read_b128 v[178:181], v231
	ds_read_b128 v[182:185], v231 offset:1024
	ds_read_b128 v[186:189], v231 offset:2048
	ds_read_b128 v[190:193], v231 offset:3072
	ds_read_b128 v[194:197], v163
	ds_read_b128 v[198:201], v163 offset:1024
	ds_read_b128 v[202:205], v163 offset:2048
	ds_read_b128 v[206:209], v163 offset:3072
	ds_read_b128 v[210:213], v163 offset:4096
	ds_read_b128 v[214:217], v163 offset:5120
	ds_read_b128 v[218:221], v163 offset:6144
	ds_read_b128 v[222:225], v163 offset:7168
	s_waitcnt vmcnt(8)
	s_waitcnt lgkmcnt(0)
	.p2align 3
	s_setprio 1
	s_barrier
	v_mfma_f32_16x16x32_bf16 v[122:125], v[156:159], v[194:197], v[122:125]
	v_mfma_f32_16x16x32_bf16 v[118:121], v[170:173], v[194:197], v[118:121]
	v_mfma_f32_16x16x32_bf16 v[110:113], v[156:159], v[202:205], v[110:113]
	v_mfma_f32_16x16x32_bf16 v[102:105], v[170:173], v[202:205], v[102:105]
	v_mfma_f32_16x16x32_bf16 v[94:97], v[156:159], v[210:213], v[94:97]
	v_mfma_f32_16x16x32_bf16 v[86:89], v[170:173], v[210:213], v[86:89]
	v_mfma_f32_16x16x32_bf16 v[78:81], v[156:159], v[218:221], v[78:81]
	v_mfma_f32_16x16x32_bf16 v[70:73], v[170:173], v[218:221], v[70:73]
	v_mfma_f32_16x16x32_bf16 v[122:125], v[166:169], v[198:201], v[122:125]
	v_mfma_f32_16x16x32_bf16 v[118:121], v[174:177], v[198:201], v[118:121]
	v_mfma_f32_16x16x32_bf16 v[110:113], v[166:169], v[206:209], v[110:113]
	v_mfma_f32_16x16x32_bf16 v[102:105], v[174:177], v[206:209], v[102:105]
	v_mfma_f32_16x16x32_bf16 v[94:97], v[166:169], v[214:217], v[94:97]
	v_mfma_f32_16x16x32_bf16 v[86:89], v[174:177], v[214:217], v[86:89]
	v_mfma_f32_16x16x32_bf16 v[78:81], v[166:169], v[222:225], v[78:81]
	v_mfma_f32_16x16x32_bf16 v[70:73], v[174:177], v[222:225], v[70:73]
	s_setprio 0
	s_setprio 1
	v_mfma_f32_16x16x32_bf16 v[126:129], v[178:181], v[194:197], v[126:129]
	v_mfma_f32_16x16x32_bf16 v[114:117], v[186:189], v[194:197], v[114:117]
	v_mfma_f32_16x16x32_bf16 v[106:109], v[178:181], v[202:205], v[106:109]
	v_mfma_f32_16x16x32_bf16 v[98:101], v[186:189], v[202:205], v[98:101]
	v_mfma_f32_16x16x32_bf16 v[90:93], v[178:181], v[210:213], v[90:93]
	v_mfma_f32_16x16x32_bf16 v[82:85], v[186:189], v[210:213], v[82:85]
	v_mfma_f32_16x16x32_bf16 v[74:77], v[178:181], v[218:221], v[74:77]
	v_mfma_f32_16x16x32_bf16 v[66:69], v[186:189], v[218:221], v[66:69]
	v_mfma_f32_16x16x32_bf16 v[126:129], v[182:185], v[198:201], v[126:129]
	v_mfma_f32_16x16x32_bf16 v[114:117], v[190:193], v[198:201], v[114:117]
	v_mfma_f32_16x16x32_bf16 v[106:109], v[182:185], v[206:209], v[106:109]
	v_mfma_f32_16x16x32_bf16 v[98:101], v[190:193], v[206:209], v[98:101]
	v_mfma_f32_16x16x32_bf16 v[90:93], v[182:185], v[214:217], v[90:93]
	v_mfma_f32_16x16x32_bf16 v[82:85], v[190:193], v[214:217], v[82:85]
	v_mfma_f32_16x16x32_bf16 v[74:77], v[182:185], v[222:225], v[74:77]
	v_mfma_f32_16x16x32_bf16 v[66:69], v[190:193], v[222:225], v[66:69]
	s_barrier
	s_setprio 0
	s_add_u32 s98, s96, 0x40000
	s_addc_u32 s99, s97, 0
	s_add_i32 s7, s77, s25
	s_mov_b32 m0, s7
	s_nop 0
	global_load_lds_dwordx4 v132, s[96:97]
	s_add_i32 m0, s7, 0x2000
	s_add_i32 s7, s78, s25
	global_load_lds_dwordx4 v136, s[96:97]
	s_mov_b32 m0, s7
	s_nop 0
	global_load_lds_dwordx4 v132, s[98:99]
	s_add_i32 m0, s7, 0x2000
	s_nop 0
	global_load_lds_dwordx4 v136, s[98:99]
	s_mov_b32 m0, s49
	s_nop 0
	global_load_lds_dwordx4 v130, s[94:95]
	s_mov_b32 m0, s58
	s_nop 0
	global_load_lds_dwordx4 v134, s[94:95]
	ds_read_b128 v[194:197], v163 offset:16384
	ds_read_b128 v[198:201], v163 offset:17408
	ds_read_b128 v[202:205], v163 offset:18432
	ds_read_b128 v[206:209], v163 offset:19456
	ds_read_b128 v[210:213], v163 offset:20480
	ds_read_b128 v[214:217], v163 offset:21504
	ds_read_b128 v[218:221], v163 offset:22528
	ds_read_b128 v[222:225], v163 offset:23552
	s_waitcnt vmcnt(8)
	s_waitcnt lgkmcnt(0)
	.p2align 3
	s_setprio 1
	s_barrier
	v_mfma_f32_16x16x32_bf16 v[62:65], v[156:159], v[194:197], v[62:65]
	v_mfma_f32_16x16x32_bf16 v[54:57], v[170:173], v[194:197], v[54:57]
	v_mfma_f32_16x16x32_bf16 v[46:49], v[156:159], v[202:205], v[46:49]
	v_mfma_f32_16x16x32_bf16 v[38:41], v[170:173], v[202:205], v[38:41]
	v_mfma_f32_16x16x32_bf16 v[30:33], v[156:159], v[210:213], v[30:33]
	v_mfma_f32_16x16x32_bf16 v[22:25], v[170:173], v[210:213], v[22:25]
	v_mfma_f32_16x16x32_bf16 v[14:17], v[156:159], v[218:221], v[14:17]
	v_mfma_f32_16x16x32_bf16 v[6:9], v[170:173], v[218:221], v[6:9]
	v_mfma_f32_16x16x32_bf16 v[62:65], v[166:169], v[198:201], v[62:65]
	v_mfma_f32_16x16x32_bf16 v[54:57], v[174:177], v[198:201], v[54:57]
	v_mfma_f32_16x16x32_bf16 v[46:49], v[166:169], v[206:209], v[46:49]
	v_mfma_f32_16x16x32_bf16 v[38:41], v[174:177], v[206:209], v[38:41]
	v_mfma_f32_16x16x32_bf16 v[30:33], v[166:169], v[214:217], v[30:33]
	v_mfma_f32_16x16x32_bf16 v[22:25], v[174:177], v[214:217], v[22:25]
	v_mfma_f32_16x16x32_bf16 v[14:17], v[166:169], v[222:225], v[14:17]
	v_mfma_f32_16x16x32_bf16 v[6:9], v[174:177], v[222:225], v[6:9]
	s_setprio 0
	s_setprio 1
	v_mfma_f32_16x16x32_bf16 v[58:61], v[178:181], v[194:197], v[58:61]
	v_mfma_f32_16x16x32_bf16 v[50:53], v[186:189], v[194:197], v[50:53]
	v_mfma_f32_16x16x32_bf16 v[42:45], v[178:181], v[202:205], v[42:45]
	v_mfma_f32_16x16x32_bf16 v[34:37], v[186:189], v[202:205], v[34:37]
	v_mfma_f32_16x16x32_bf16 v[26:29], v[178:181], v[210:213], v[26:29]
	v_mfma_f32_16x16x32_bf16 v[18:21], v[186:189], v[210:213], v[18:21]
	v_mfma_f32_16x16x32_bf16 v[10:13], v[178:181], v[218:221], v[10:13]
	v_mfma_f32_16x16x32_bf16 v[2:5], v[186:189], v[218:221], v[2:5]
	v_mfma_f32_16x16x32_bf16 v[58:61], v[182:185], v[198:201], v[58:61]
	v_mfma_f32_16x16x32_bf16 v[50:53], v[190:193], v[198:201], v[50:53]
	v_mfma_f32_16x16x32_bf16 v[42:45], v[182:185], v[206:209], v[42:45]
	v_mfma_f32_16x16x32_bf16 v[34:37], v[190:193], v[206:209], v[34:37]
	v_mfma_f32_16x16x32_bf16 v[26:29], v[182:185], v[214:217], v[26:29]
	v_mfma_f32_16x16x32_bf16 v[18:21], v[190:193], v[214:217], v[18:21]
	v_mfma_f32_16x16x32_bf16 v[10:13], v[182:185], v[222:225], v[10:13]
	v_mfma_f32_16x16x32_bf16 v[2:5], v[190:193], v[222:225], v[2:5]
	s_barrier
	s_setprio 0
	s_add_u32 s98, s94, 0x40000
	s_addc_u32 s99, s95, 0
	s_add_i32 s7, 0, 0x18000
	s_add_i32 s47, 0, 0x1c000
	s_mov_b32 m0, s59
	s_nop 0
	global_load_lds_dwordx4 v130, s[98:99]
	s_mov_b32 m0, s60
	s_nop 0
	global_load_lds_dwordx4 v134, s[98:99]
	ds_read_b128 v[156:159], v232
	ds_read_b128 v[166:169], v232 offset:1024
	ds_read_b128 v[170:173], v232 offset:2048
	ds_read_b128 v[174:177], v232 offset:3072
	ds_read_b128 v[178:181], v233
	ds_read_b128 v[182:185], v233 offset:1024
	ds_read_b128 v[186:189], v233 offset:2048
	ds_read_b128 v[190:193], v233 offset:3072
	ds_read_b128 v[194:197], v163 offset:32768
	ds_read_b128 v[198:201], v163 offset:33792
	ds_read_b128 v[202:205], v163 offset:34816
	ds_read_b128 v[206:209], v163 offset:35840
	ds_read_b128 v[210:213], v163 offset:36864
	ds_read_b128 v[214:217], v163 offset:37888
	ds_read_b128 v[218:221], v163 offset:38912
	ds_read_b128 v[222:225], v163 offset:39936
	s_waitcnt vmcnt(8)
	s_waitcnt lgkmcnt(0)
	.p2align 3
	s_setprio 1
	s_barrier
	v_mfma_f32_16x16x32_bf16 v[122:125], v[156:159], v[194:197], v[122:125]
	v_mfma_f32_16x16x32_bf16 v[118:121], v[170:173], v[194:197], v[118:121]
	v_mfma_f32_16x16x32_bf16 v[110:113], v[156:159], v[202:205], v[110:113]
	v_mfma_f32_16x16x32_bf16 v[102:105], v[170:173], v[202:205], v[102:105]
	v_mfma_f32_16x16x32_bf16 v[94:97], v[156:159], v[210:213], v[94:97]
	v_mfma_f32_16x16x32_bf16 v[86:89], v[170:173], v[210:213], v[86:89]
	v_mfma_f32_16x16x32_bf16 v[78:81], v[156:159], v[218:221], v[78:81]
	v_mfma_f32_16x16x32_bf16 v[70:73], v[170:173], v[218:221], v[70:73]
	v_mfma_f32_16x16x32_bf16 v[122:125], v[166:169], v[198:201], v[122:125]
	v_mfma_f32_16x16x32_bf16 v[118:121], v[174:177], v[198:201], v[118:121]
	v_mfma_f32_16x16x32_bf16 v[110:113], v[166:169], v[206:209], v[110:113]
	v_mfma_f32_16x16x32_bf16 v[102:105], v[174:177], v[206:209], v[102:105]
	v_mfma_f32_16x16x32_bf16 v[94:97], v[166:169], v[214:217], v[94:97]
	v_mfma_f32_16x16x32_bf16 v[86:89], v[174:177], v[214:217], v[86:89]
	v_mfma_f32_16x16x32_bf16 v[78:81], v[166:169], v[222:225], v[78:81]
	v_mfma_f32_16x16x32_bf16 v[70:73], v[174:177], v[222:225], v[70:73]
	s_setprio 0
	s_setprio 1
	v_mfma_f32_16x16x32_bf16 v[126:129], v[178:181], v[194:197], v[126:129]
	v_mfma_f32_16x16x32_bf16 v[114:117], v[186:189], v[194:197], v[114:117]
	v_mfma_f32_16x16x32_bf16 v[106:109], v[178:181], v[202:205], v[106:109]
	v_mfma_f32_16x16x32_bf16 v[98:101], v[186:189], v[202:205], v[98:101]
	v_mfma_f32_16x16x32_bf16 v[90:93], v[178:181], v[210:213], v[90:93]
	v_mfma_f32_16x16x32_bf16 v[82:85], v[186:189], v[210:213], v[82:85]
	v_mfma_f32_16x16x32_bf16 v[74:77], v[178:181], v[218:221], v[74:77]
	v_mfma_f32_16x16x32_bf16 v[66:69], v[186:189], v[218:221], v[66:69]
	v_mfma_f32_16x16x32_bf16 v[126:129], v[182:185], v[198:201], v[126:129]
	v_mfma_f32_16x16x32_bf16 v[114:117], v[190:193], v[198:201], v[114:117]
	v_mfma_f32_16x16x32_bf16 v[106:109], v[182:185], v[206:209], v[106:109]
	v_mfma_f32_16x16x32_bf16 v[98:101], v[190:193], v[206:209], v[98:101]
	v_mfma_f32_16x16x32_bf16 v[90:93], v[182:185], v[214:217], v[90:93]
	v_mfma_f32_16x16x32_bf16 v[82:85], v[190:193], v[214:217], v[82:85]
	v_mfma_f32_16x16x32_bf16 v[74:77], v[182:185], v[222:225], v[74:77]
	v_mfma_f32_16x16x32_bf16 v[66:69], v[190:193], v[222:225], v[66:69]
	s_barrier
	s_setprio 0
	s_add_u32 s96, s96, 0x80
	s_addc_u32 s97, s97, 0
	s_add_u32 s98, s96, 0x40000
	s_addc_u32 s99, s97, 0
	s_add_u32 s94, s94, 0x80
	s_addc_u32 s95, s95, 0
	s_add_i32 s7, s7, s25
	s_mov_b32 m0, s7
	s_nop 0
	global_load_lds_dwordx4 v132, s[96:97]
	s_add_i32 m0, s7, 0x2000
	s_add_i32 s7, s47, s25
	global_load_lds_dwordx4 v136, s[96:97]
	s_mov_b32 m0, s7
	s_nop 0
	global_load_lds_dwordx4 v132, s[98:99]
	s_add_i32 m0, s7, 0x2000
	s_nop 0
	global_load_lds_dwordx4 v136, s[98:99]
	s_mov_b32 m0, s66
	s_nop 0
	global_load_lds_dwordx4 v130, s[94:95]
	s_mov_b32 m0, s67
	s_nop 0
	global_load_lds_dwordx4 v134, s[94:95]
	ds_read_b128 v[194:197], v163 offset:49152
	ds_read_b128 v[198:201], v163 offset:50176
	ds_read_b128 v[202:205], v163 offset:51200
	ds_read_b128 v[206:209], v163 offset:52224
	ds_read_b128 v[210:213], v163 offset:53248
	ds_read_b128 v[214:217], v163 offset:54272
	ds_read_b128 v[218:221], v163 offset:55296
	ds_read_b128 v[222:225], v163 offset:56320
	s_waitcnt vmcnt(8)
	s_waitcnt lgkmcnt(0)
	.p2align 3
	s_setprio 1
	s_barrier
	v_mfma_f32_16x16x32_bf16 v[62:65], v[156:159], v[194:197], v[62:65]
	v_mfma_f32_16x16x32_bf16 v[54:57], v[170:173], v[194:197], v[54:57]
	v_mfma_f32_16x16x32_bf16 v[46:49], v[156:159], v[202:205], v[46:49]
	v_mfma_f32_16x16x32_bf16 v[38:41], v[170:173], v[202:205], v[38:41]
	v_mfma_f32_16x16x32_bf16 v[30:33], v[156:159], v[210:213], v[30:33]
	v_mfma_f32_16x16x32_bf16 v[22:25], v[170:173], v[210:213], v[22:25]
	v_mfma_f32_16x16x32_bf16 v[14:17], v[156:159], v[218:221], v[14:17]
	v_mfma_f32_16x16x32_bf16 v[6:9], v[170:173], v[218:221], v[6:9]
	v_mfma_f32_16x16x32_bf16 v[62:65], v[166:169], v[198:201], v[62:65]
	v_mfma_f32_16x16x32_bf16 v[54:57], v[174:177], v[198:201], v[54:57]
	v_mfma_f32_16x16x32_bf16 v[46:49], v[166:169], v[206:209], v[46:49]
	v_mfma_f32_16x16x32_bf16 v[38:41], v[174:177], v[206:209], v[38:41]
	v_mfma_f32_16x16x32_bf16 v[30:33], v[166:169], v[214:217], v[30:33]
	v_mfma_f32_16x16x32_bf16 v[22:25], v[174:177], v[214:217], v[22:25]
	v_mfma_f32_16x16x32_bf16 v[14:17], v[166:169], v[222:225], v[14:17]
	v_mfma_f32_16x16x32_bf16 v[6:9], v[174:177], v[222:225], v[6:9]
	s_setprio 0
	s_setprio 1
	v_mfma_f32_16x16x32_bf16 v[58:61], v[178:181], v[194:197], v[58:61]
	v_mfma_f32_16x16x32_bf16 v[50:53], v[186:189], v[194:197], v[50:53]
	v_mfma_f32_16x16x32_bf16 v[42:45], v[178:181], v[202:205], v[42:45]
	v_mfma_f32_16x16x32_bf16 v[34:37], v[186:189], v[202:205], v[34:37]
	v_mfma_f32_16x16x32_bf16 v[26:29], v[178:181], v[210:213], v[26:29]
	v_mfma_f32_16x16x32_bf16 v[18:21], v[186:189], v[210:213], v[18:21]
	v_mfma_f32_16x16x32_bf16 v[10:13], v[178:181], v[218:221], v[10:13]
	v_mfma_f32_16x16x32_bf16 v[2:5], v[186:189], v[218:221], v[2:5]
	v_mfma_f32_16x16x32_bf16 v[58:61], v[182:185], v[198:201], v[58:61]
	v_mfma_f32_16x16x32_bf16 v[50:53], v[190:193], v[198:201], v[50:53]
	v_mfma_f32_16x16x32_bf16 v[42:45], v[182:185], v[206:209], v[42:45]
	v_mfma_f32_16x16x32_bf16 v[34:37], v[190:193], v[206:209], v[34:37]
	v_mfma_f32_16x16x32_bf16 v[26:29], v[182:185], v[214:217], v[26:29]
	v_mfma_f32_16x16x32_bf16 v[18:21], v[190:193], v[214:217], v[18:21]
	v_mfma_f32_16x16x32_bf16 v[10:13], v[182:185], v[222:225], v[10:13]
	v_mfma_f32_16x16x32_bf16 v[2:5], v[190:193], v[222:225], v[2:5]
	s_barrier
	s_setprio 0
	s_mov_b32 s7, s45
	s_add_u32 s88, s88, 0x100
	s_addc_u32 s89, s89, 0
	s_add_u32 s86, s86, 0x100
	s_addc_u32 s87, s87, 0
	s_cmp_ge_i32 s45, s101
	s_cbranch_scc0 .LBB0_499

.Lmy_nb_3:
	s_nop 0
	v_readfirstlane_b32 s86, v152
	v_readfirstlane_b32 s87, v153
	v_readfirstlane_b32 s88, v150
	v_readfirstlane_b32 s89, v151
	v_readfirstlane_b32 s90, v146
	v_readfirstlane_b32 s91, v147
	v_readfirstlane_b32 s92, v148
	v_readfirstlane_b32 s93, v149
	v_readfirstlane_b32 s100, v154
	v_readfirstlane_b32 s101, v138
	v_add_u32_e32 v230, s76, v141
	v_add_u32_e32 v231, s77, v141
	v_add_u32_e32 v232, 0x18000, v141
	v_add_u32_e32 v233, 0x1c000, v141
	s_add_u32 s98, s86, 0xfffc0080
	s_addc_u32 s99, s87, -1
	s_cmp_eq_u32 s7, s100
	s_cselect_b64 s[94:95], s[90:91], s[98:99]
	s_cselect_b64 s[96:97], s[92:93], s[88:89]
	s_add_i32 s45, s7, 2
	s_nop 0
	s_add_i32 m0, s49, 0xc000
	s_nop 0
	global_load_lds_dwordx4 v144, s[86:87]
	s_add_i32 m0, s49, 0xe000
	s_nop 0
	global_load_lds_dwordx4 v142, s[86:87]
	ds_read_b128 v[164:167], v230
	ds_read_b128 v[168:171], v230 offset:1024
	ds_read_b128 v[172:175], v230 offset:2048
	ds_read_b128 v[176:179], v230 offset:3072
	ds_read_b128 v[180:183], v231
	ds_read_b128 v[184:187], v231 offset:1024
	ds_read_b128 v[188:191], v231 offset:2048
	ds_read_b128 v[192:195], v231 offset:3072
	ds_read_b128 v[196:199], v160
	ds_read_b128 v[200:203], v160 offset:1024
	ds_read_b128 v[204:207], v160 offset:2048
	ds_read_b128 v[208:211], v160 offset:3072
	ds_read_b128 v[212:215], v160 offset:4096
	ds_read_b128 v[216:219], v160 offset:5120
	ds_read_b128 v[220:223], v160 offset:6144
	ds_read_b128 v[224:227], v160 offset:7168
	s_waitcnt vmcnt(8)
	s_waitcnt lgkmcnt(0)
	.p2align 3
	s_setprio 1
	s_barrier
	v_mfma_f32_16x16x32_bf16 v[122:125], v[164:167], v[196:199], 0
	v_mfma_f32_16x16x32_bf16 v[118:121], v[172:175], v[196:199], 0
	v_mfma_f32_16x16x32_bf16 v[110:113], v[164:167], v[204:207], 0
	v_mfma_f32_16x16x32_bf16 v[102:105], v[172:175], v[204:207], 0
	v_mfma_f32_16x16x32_bf16 v[94:97], v[164:167], v[212:215], 0
	v_mfma_f32_16x16x32_bf16 v[86:89], v[172:175], v[212:215], 0
	v_mfma_f32_16x16x32_bf16 v[78:81], v[164:167], v[220:223], 0
	v_mfma_f32_16x16x32_bf16 v[70:73], v[172:175], v[220:223], 0
	v_mfma_f32_16x16x32_bf16 v[122:125], v[168:171], v[200:203], v[122:125]
	v_mfma_f32_16x16x32_bf16 v[118:121], v[176:179], v[200:203], v[118:121]
	v_mfma_f32_16x16x32_bf16 v[110:113], v[168:171], v[208:211], v[110:113]
	v_mfma_f32_16x16x32_bf16 v[102:105], v[176:179], v[208:211], v[102:105]
	v_mfma_f32_16x16x32_bf16 v[94:97], v[168:171], v[216:219], v[94:97]
	v_mfma_f32_16x16x32_bf16 v[86:89], v[176:179], v[216:219], v[86:89]
	v_mfma_f32_16x16x32_bf16 v[78:81], v[168:171], v[224:227], v[78:81]
	v_mfma_f32_16x16x32_bf16 v[70:73], v[176:179], v[224:227], v[70:73]
	s_setprio 0
	s_setprio 1
	v_mfma_f32_16x16x32_bf16 v[126:129], v[180:183], v[196:199], 0
	v_mfma_f32_16x16x32_bf16 v[114:117], v[188:191], v[196:199], 0
	v_mfma_f32_16x16x32_bf16 v[106:109], v[180:183], v[204:207], 0
	v_mfma_f32_16x16x32_bf16 v[98:101], v[188:191], v[204:207], 0
	v_mfma_f32_16x16x32_bf16 v[90:93], v[180:183], v[212:215], 0
	v_mfma_f32_16x16x32_bf16 v[82:85], v[188:191], v[212:215], 0
	v_mfma_f32_16x16x32_bf16 v[74:77], v[180:183], v[220:223], 0
	v_mfma_f32_16x16x32_bf16 v[66:69], v[188:191], v[220:223], 0
	v_mfma_f32_16x16x32_bf16 v[126:129], v[184:187], v[200:203], v[126:129]
	v_mfma_f32_16x16x32_bf16 v[114:117], v[192:195], v[200:203], v[114:117]
	v_mfma_f32_16x16x32_bf16 v[106:109], v[184:187], v[208:211], v[106:109]
	v_mfma_f32_16x16x32_bf16 v[98:101], v[192:195], v[208:211], v[98:101]
	v_mfma_f32_16x16x32_bf16 v[90:93], v[184:187], v[216:219], v[90:93]
	v_mfma_f32_16x16x32_bf16 v[82:85], v[192:195], v[216:219], v[82:85]
	v_mfma_f32_16x16x32_bf16 v[74:77], v[184:187], v[224:227], v[74:77]
	v_mfma_f32_16x16x32_bf16 v[66:69], v[192:195], v[224:227], v[66:69]
	s_barrier
	s_setprio 0
	s_add_u32 s98, s96, 0x40000
	s_addc_u32 s99, s97, 0
	s_add_i32 s7, s76, s25
	s_mov_b32 m0, s7
	s_nop 0
	global_load_lds_dwordx4 v132, s[96:97]
	s_add_i32 m0, s7, 0x2000
	s_add_i32 s7, s77, s25
	global_load_lds_dwordx4 v136, s[96:97]
	s_mov_b32 m0, s7
	s_nop 0
	global_load_lds_dwordx4 v132, s[98:99]
	s_add_i32 m0, s7, 0x2000
	s_nop 0
	global_load_lds_dwordx4 v136, s[98:99]
	s_mov_b32 m0, s49
	s_nop 0
	global_load_lds_dwordx4 v130, s[94:95]
	s_mov_b32 m0, s58
	s_nop 0
	global_load_lds_dwordx4 v134, s[94:95]
	ds_read_b128 v[196:199], v160 offset:16384
	ds_read_b128 v[200:203], v160 offset:17408
	ds_read_b128 v[204:207], v160 offset:18432
	ds_read_b128 v[208:211], v160 offset:19456
	ds_read_b128 v[212:215], v160 offset:20480
	ds_read_b128 v[216:219], v160 offset:21504
	ds_read_b128 v[220:223], v160 offset:22528
	ds_read_b128 v[224:227], v160 offset:23552
	s_waitcnt vmcnt(8)
	s_waitcnt lgkmcnt(0)
	.p2align 3
	s_setprio 1
	s_barrier
	v_mfma_f32_16x16x32_bf16 v[62:65], v[164:167], v[196:199], 0
	v_mfma_f32_16x16x32_bf16 v[54:57], v[172:175], v[196:199], 0
	v_mfma_f32_16x16x32_bf16 v[46:49], v[164:167], v[204:207], 0
	v_mfma_f32_16x16x32_bf16 v[38:41], v[172:175], v[204:207], 0
	v_mfma_f32_16x16x32_bf16 v[30:33], v[164:167], v[212:215], 0
	v_mfma_f32_16x16x32_bf16 v[22:25], v[172:175], v[212:215], 0
	v_mfma_f32_16x16x32_bf16 v[14:17], v[164:167], v[220:223], 0
	v_mfma_f32_16x16x32_bf16 v[6:9], v[172:175], v[220:223], 0
	v_mfma_f32_16x16x32_bf16 v[62:65], v[168:171], v[200:203], v[62:65]
	v_mfma_f32_16x16x32_bf16 v[54:57], v[176:179], v[200:203], v[54:57]
	v_mfma_f32_16x16x32_bf16 v[46:49], v[168:171], v[208:211], v[46:49]
	v_mfma_f32_16x16x32_bf16 v[38:41], v[176:179], v[208:211], v[38:41]
	v_mfma_f32_16x16x32_bf16 v[30:33], v[168:171], v[216:219], v[30:33]
	v_mfma_f32_16x16x32_bf16 v[22:25], v[176:179], v[216:219], v[22:25]
	v_mfma_f32_16x16x32_bf16 v[14:17], v[168:171], v[224:227], v[14:17]
	v_mfma_f32_16x16x32_bf16 v[6:9], v[176:179], v[224:227], v[6:9]
	s_setprio 0
	s_setprio 1
	v_mfma_f32_16x16x32_bf16 v[58:61], v[180:183], v[196:199], 0
	v_mfma_f32_16x16x32_bf16 v[50:53], v[188:191], v[196:199], 0
	v_mfma_f32_16x16x32_bf16 v[42:45], v[180:183], v[204:207], 0
	v_mfma_f32_16x16x32_bf16 v[34:37], v[188:191], v[204:207], 0
	v_mfma_f32_16x16x32_bf16 v[26:29], v[180:183], v[212:215], 0
	v_mfma_f32_16x16x32_bf16 v[18:21], v[188:191], v[212:215], 0
	v_mfma_f32_16x16x32_bf16 v[10:13], v[180:183], v[220:223], 0
	v_mfma_f32_16x16x32_bf16 v[2:5], v[188:191], v[220:223], 0
	v_mfma_f32_16x16x32_bf16 v[58:61], v[184:187], v[200:203], v[58:61]
	v_mfma_f32_16x16x32_bf16 v[50:53], v[192:195], v[200:203], v[50:53]
	v_mfma_f32_16x16x32_bf16 v[42:45], v[184:187], v[208:211], v[42:45]
	v_mfma_f32_16x16x32_bf16 v[34:37], v[192:195], v[208:211], v[34:37]
	v_mfma_f32_16x16x32_bf16 v[26:29], v[184:187], v[216:219], v[26:29]
	v_mfma_f32_16x16x32_bf16 v[18:21], v[192:195], v[216:219], v[18:21]
	v_mfma_f32_16x16x32_bf16 v[10:13], v[184:187], v[224:227], v[10:13]
	v_mfma_f32_16x16x32_bf16 v[2:5], v[192:195], v[224:227], v[2:5]
	s_barrier
	s_setprio 0
	s_add_u32 s98, s94, 0x40000
	s_addc_u32 s99, s95, 0
	s_add_i32 s7, 0, 0x18000
	s_add_i32 s47, 0, 0x1c000
	s_mov_b32 m0, s59
	s_nop 0
	global_load_lds_dwordx4 v130, s[98:99]
	s_mov_b32 m0, s60
	s_nop 0
	global_load_lds_dwordx4 v134, s[98:99]
	ds_read_b128 v[164:167], v232
	ds_read_b128 v[168:171], v232 offset:1024
	ds_read_b128 v[172:175], v232 offset:2048
	ds_read_b128 v[176:179], v232 offset:3072
	ds_read_b128 v[180:183], v233
	ds_read_b128 v[184:187], v233 offset:1024
	ds_read_b128 v[188:191], v233 offset:2048
	ds_read_b128 v[192:195], v233 offset:3072
	ds_read_b128 v[196:199], v160 offset:32768
	ds_read_b128 v[200:203], v160 offset:33792
	ds_read_b128 v[204:207], v160 offset:34816
	ds_read_b128 v[208:211], v160 offset:35840
	ds_read_b128 v[212:215], v160 offset:36864
	ds_read_b128 v[216:219], v160 offset:37888
	ds_read_b128 v[220:223], v160 offset:38912
	ds_read_b128 v[224:227], v160 offset:39936
	s_waitcnt vmcnt(8)
	s_waitcnt lgkmcnt(0)
	.p2align 3
	s_setprio 1
	s_barrier
	v_mfma_f32_16x16x32_bf16 v[122:125], v[164:167], v[196:199], v[122:125]
	v_mfma_f32_16x16x32_bf16 v[118:121], v[172:175], v[196:199], v[118:121]
	v_mfma_f32_16x16x32_bf16 v[110:113], v[164:167], v[204:207], v[110:113]
	v_mfma_f32_16x16x32_bf16 v[102:105], v[172:175], v[204:207], v[102:105]
	v_mfma_f32_16x16x32_bf16 v[94:97], v[164:167], v[212:215], v[94:97]
	v_mfma_f32_16x16x32_bf16 v[86:89], v[172:175], v[212:215], v[86:89]
	v_mfma_f32_16x16x32_bf16 v[78:81], v[164:167], v[220:223], v[78:81]
	v_mfma_f32_16x16x32_bf16 v[70:73], v[172:175], v[220:223], v[70:73]
	v_mfma_f32_16x16x32_bf16 v[122:125], v[168:171], v[200:203], v[122:125]
	v_mfma_f32_16x16x32_bf16 v[118:121], v[176:179], v[200:203], v[118:121]
	v_mfma_f32_16x16x32_bf16 v[110:113], v[168:171], v[208:211], v[110:113]
	v_mfma_f32_16x16x32_bf16 v[102:105], v[176:179], v[208:211], v[102:105]
	v_mfma_f32_16x16x32_bf16 v[94:97], v[168:171], v[216:219], v[94:97]
	v_mfma_f32_16x16x32_bf16 v[86:89], v[176:179], v[216:219], v[86:89]
	v_mfma_f32_16x16x32_bf16 v[78:81], v[168:171], v[224:227], v[78:81]
	v_mfma_f32_16x16x32_bf16 v[70:73], v[176:179], v[224:227], v[70:73]
	s_setprio 0
	s_setprio 1
	v_mfma_f32_16x16x32_bf16 v[126:129], v[180:183], v[196:199], v[126:129]
	v_mfma_f32_16x16x32_bf16 v[114:117], v[188:191], v[196:199], v[114:117]
	v_mfma_f32_16x16x32_bf16 v[106:109], v[180:183], v[204:207], v[106:109]
	v_mfma_f32_16x16x32_bf16 v[98:101], v[188:191], v[204:207], v[98:101]
	v_mfma_f32_16x16x32_bf16 v[90:93], v[180:183], v[212:215], v[90:93]
	v_mfma_f32_16x16x32_bf16 v[82:85], v[188:191], v[212:215], v[82:85]
	v_mfma_f32_16x16x32_bf16 v[74:77], v[180:183], v[220:223], v[74:77]
	v_mfma_f32_16x16x32_bf16 v[66:69], v[188:191], v[220:223], v[66:69]
	v_mfma_f32_16x16x32_bf16 v[126:129], v[184:187], v[200:203], v[126:129]
	v_mfma_f32_16x16x32_bf16 v[114:117], v[192:195], v[200:203], v[114:117]
	v_mfma_f32_16x16x32_bf16 v[106:109], v[184:187], v[208:211], v[106:109]
	v_mfma_f32_16x16x32_bf16 v[98:101], v[192:195], v[208:211], v[98:101]
	v_mfma_f32_16x16x32_bf16 v[90:93], v[184:187], v[216:219], v[90:93]
	v_mfma_f32_16x16x32_bf16 v[82:85], v[192:195], v[216:219], v[82:85]
	v_mfma_f32_16x16x32_bf16 v[74:77], v[184:187], v[224:227], v[74:77]
	v_mfma_f32_16x16x32_bf16 v[66:69], v[192:195], v[224:227], v[66:69]
	s_barrier
	s_setprio 0
	s_add_u32 s96, s96, 0x80
	s_addc_u32 s97, s97, 0
	s_add_u32 s98, s96, 0x40000
	s_addc_u32 s99, s97, 0
	s_add_u32 s94, s94, 0x80
	s_addc_u32 s95, s95, 0
	s_add_i32 s7, s7, s25
	s_mov_b32 m0, s7
	s_nop 0
	global_load_lds_dwordx4 v132, s[96:97]
	s_add_i32 m0, s7, 0x2000
	s_add_i32 s7, s47, s25
	global_load_lds_dwordx4 v136, s[96:97]
	s_mov_b32 m0, s7
	s_nop 0
	global_load_lds_dwordx4 v132, s[98:99]
	s_add_i32 m0, s7, 0x2000
	s_nop 0
	global_load_lds_dwordx4 v136, s[98:99]
	s_mov_b32 m0, s66
	s_nop 0
	global_load_lds_dwordx4 v130, s[94:95]
	s_mov_b32 m0, s67
	s_nop 0
	global_load_lds_dwordx4 v134, s[94:95]
	ds_read_b128 v[196:199], v160 offset:49152
	ds_read_b128 v[200:203], v160 offset:50176
	ds_read_b128 v[204:207], v160 offset:51200
	ds_read_b128 v[208:211], v160 offset:52224
	ds_read_b128 v[212:215], v160 offset:53248
	ds_read_b128 v[216:219], v160 offset:54272
	ds_read_b128 v[220:223], v160 offset:55296
	ds_read_b128 v[224:227], v160 offset:56320
	s_waitcnt vmcnt(8)
	s_waitcnt lgkmcnt(0)
	.p2align 3
	s_setprio 1
	s_barrier
	v_mfma_f32_16x16x32_bf16 v[62:65], v[164:167], v[196:199], v[62:65]
	v_mfma_f32_16x16x32_bf16 v[54:57], v[172:175], v[196:199], v[54:57]
	v_mfma_f32_16x16x32_bf16 v[46:49], v[164:167], v[204:207], v[46:49]
	v_mfma_f32_16x16x32_bf16 v[38:41], v[172:175], v[204:207], v[38:41]
	v_mfma_f32_16x16x32_bf16 v[30:33], v[164:167], v[212:215], v[30:33]
	v_mfma_f32_16x16x32_bf16 v[22:25], v[172:175], v[212:215], v[22:25]
	v_mfma_f32_16x16x32_bf16 v[14:17], v[164:167], v[220:223], v[14:17]
	v_mfma_f32_16x16x32_bf16 v[6:9], v[172:175], v[220:223], v[6:9]
	v_mfma_f32_16x16x32_bf16 v[62:65], v[168:171], v[200:203], v[62:65]
	v_mfma_f32_16x16x32_bf16 v[54:57], v[176:179], v[200:203], v[54:57]
	v_mfma_f32_16x16x32_bf16 v[46:49], v[168:171], v[208:211], v[46:49]
	v_mfma_f32_16x16x32_bf16 v[38:41], v[176:179], v[208:211], v[38:41]
	v_mfma_f32_16x16x32_bf16 v[30:33], v[168:171], v[216:219], v[30:33]
	v_mfma_f32_16x16x32_bf16 v[22:25], v[176:179], v[216:219], v[22:25]
	v_mfma_f32_16x16x32_bf16 v[14:17], v[168:171], v[224:227], v[14:17]
	v_mfma_f32_16x16x32_bf16 v[6:9], v[176:179], v[224:227], v[6:9]
	s_setprio 0
	s_setprio 1
	v_mfma_f32_16x16x32_bf16 v[58:61], v[180:183], v[196:199], v[58:61]
	v_mfma_f32_16x16x32_bf16 v[50:53], v[188:191], v[196:199], v[50:53]
	v_mfma_f32_16x16x32_bf16 v[42:45], v[180:183], v[204:207], v[42:45]
	v_mfma_f32_16x16x32_bf16 v[34:37], v[188:191], v[204:207], v[34:37]
	v_mfma_f32_16x16x32_bf16 v[26:29], v[180:183], v[212:215], v[26:29]
	v_mfma_f32_16x16x32_bf16 v[18:21], v[188:191], v[212:215], v[18:21]
	v_mfma_f32_16x16x32_bf16 v[10:13], v[180:183], v[220:223], v[10:13]
	v_mfma_f32_16x16x32_bf16 v[2:5], v[188:191], v[220:223], v[2:5]
	v_mfma_f32_16x16x32_bf16 v[58:61], v[184:187], v[200:203], v[58:61]
	v_mfma_f32_16x16x32_bf16 v[50:53], v[192:195], v[200:203], v[50:53]
	v_mfma_f32_16x16x32_bf16 v[42:45], v[184:187], v[208:211], v[42:45]
	v_mfma_f32_16x16x32_bf16 v[34:37], v[192:195], v[208:211], v[34:37]
	v_mfma_f32_16x16x32_bf16 v[26:29], v[184:187], v[216:219], v[26:29]
	v_mfma_f32_16x16x32_bf16 v[18:21], v[192:195], v[216:219], v[18:21]
	v_mfma_f32_16x16x32_bf16 v[10:13], v[184:187], v[224:227], v[10:13]
	v_mfma_f32_16x16x32_bf16 v[2:5], v[192:195], v[224:227], v[2:5]
	s_barrier
	s_setprio 0
	s_mov_b32 s7, s45
	s_add_u32 s88, s88, 0x100
	s_addc_u32 s89, s89, 0
	s_add_u32 s86, s86, 0x100
	s_addc_u32 s87, s87, 0
	s_cmp_ge_i32 s45, s101
	s_cbranch_scc1 .Lmy_kexit_3
.LBB0_768:
	s_add_u32 s98, s86, 0xfffc0080
	s_addc_u32 s99, s87, -1
	s_cmp_eq_u32 s7, s100
	s_cselect_b64 s[94:95], s[90:91], s[98:99]
	s_cselect_b64 s[96:97], s[92:93], s[88:89]
	s_add_i32 s45, s7, 2
	s_nop 0
	s_add_i32 m0, s49, 0xc000
	s_nop 0
	global_load_lds_dwordx4 v144, s[86:87]
	s_add_i32 m0, s49, 0xe000
	s_nop 0
	global_load_lds_dwordx4 v142, s[86:87]
	ds_read_b128 v[164:167], v230
	ds_read_b128 v[168:171], v230 offset:1024
	ds_read_b128 v[172:175], v230 offset:2048
	ds_read_b128 v[176:179], v230 offset:3072
	ds_read_b128 v[180:183], v231
	ds_read_b128 v[184:187], v231 offset:1024
	ds_read_b128 v[188:191], v231 offset:2048
	ds_read_b128 v[192:195], v231 offset:3072
	ds_read_b128 v[196:199], v160
	ds_read_b128 v[200:203], v160 offset:1024
	ds_read_b128 v[204:207], v160 offset:2048
	ds_read_b128 v[208:211], v160 offset:3072
	ds_read_b128 v[212:215], v160 offset:4096
	ds_read_b128 v[216:219], v160 offset:5120
	ds_read_b128 v[220:223], v160 offset:6144
	ds_read_b128 v[224:227], v160 offset:7168
	s_waitcnt vmcnt(8)
	s_waitcnt lgkmcnt(0)
	.p2align 3
	s_setprio 1
	s_barrier
	v_mfma_f32_16x16x32_bf16 v[122:125], v[164:167], v[196:199], v[122:125]
	v_mfma_f32_16x16x32_bf16 v[118:121], v[172:175], v[196:199], v[118:121]
	v_mfma_f32_16x16x32_bf16 v[110:113], v[164:167], v[204:207], v[110:113]
	v_mfma_f32_16x16x32_bf16 v[102:105], v[172:175], v[204:207], v[102:105]
	v_mfma_f32_16x16x32_bf16 v[94:97], v[164:167], v[212:215], v[94:97]
	v_mfma_f32_16x16x32_bf16 v[86:89], v[172:175], v[212:215], v[86:89]
	v_mfma_f32_16x16x32_bf16 v[78:81], v[164:167], v[220:223], v[78:81]
	v_mfma_f32_16x16x32_bf16 v[70:73], v[172:175], v[220:223], v[70:73]
	v_mfma_f32_16x16x32_bf16 v[122:125], v[168:171], v[200:203], v[122:125]
	v_mfma_f32_16x16x32_bf16 v[118:121], v[176:179], v[200:203], v[118:121]
	v_mfma_f32_16x16x32_bf16 v[110:113], v[168:171], v[208:211], v[110:113]
	v_mfma_f32_16x16x32_bf16 v[102:105], v[176:179], v[208:211], v[102:105]
	v_mfma_f32_16x16x32_bf16 v[94:97], v[168:171], v[216:219], v[94:97]
	v_mfma_f32_16x16x32_bf16 v[86:89], v[176:179], v[216:219], v[86:89]
	v_mfma_f32_16x16x32_bf16 v[78:81], v[168:171], v[224:227], v[78:81]
	v_mfma_f32_16x16x32_bf16 v[70:73], v[176:179], v[224:227], v[70:73]
	s_setprio 0
	s_setprio 1
	v_mfma_f32_16x16x32_bf16 v[126:129], v[180:183], v[196:199], v[126:129]
	v_mfma_f32_16x16x32_bf16 v[114:117], v[188:191], v[196:199], v[114:117]
	v_mfma_f32_16x16x32_bf16 v[106:109], v[180:183], v[204:207], v[106:109]
	v_mfma_f32_16x16x32_bf16 v[98:101], v[188:191], v[204:207], v[98:101]
	v_mfma_f32_16x16x32_bf16 v[90:93], v[180:183], v[212:215], v[90:93]
	v_mfma_f32_16x16x32_bf16 v[82:85], v[188:191], v[212:215], v[82:85]
	v_mfma_f32_16x16x32_bf16 v[74:77], v[180:183], v[220:223], v[74:77]
	v_mfma_f32_16x16x32_bf16 v[66:69], v[188:191], v[220:223], v[66:69]
	v_mfma_f32_16x16x32_bf16 v[126:129], v[184:187], v[200:203], v[126:129]
	v_mfma_f32_16x16x32_bf16 v[114:117], v[192:195], v[200:203], v[114:117]
	v_mfma_f32_16x16x32_bf16 v[106:109], v[184:187], v[208:211], v[106:109]
	v_mfma_f32_16x16x32_bf16 v[98:101], v[192:195], v[208:211], v[98:101]
	v_mfma_f32_16x16x32_bf16 v[90:93], v[184:187], v[216:219], v[90:93]
	v_mfma_f32_16x16x32_bf16 v[82:85], v[192:195], v[216:219], v[82:85]
	v_mfma_f32_16x16x32_bf16 v[74:77], v[184:187], v[224:227], v[74:77]
	v_mfma_f32_16x16x32_bf16 v[66:69], v[192:195], v[224:227], v[66:69]
	s_barrier
	s_setprio 0
	s_add_u32 s98, s96, 0x40000
	s_addc_u32 s99, s97, 0
	s_add_i32 s7, s76, s25
	s_mov_b32 m0, s7
	s_nop 0
	global_load_lds_dwordx4 v132, s[96:97]
	s_add_i32 m0, s7, 0x2000
	s_add_i32 s7, s77, s25
	global_load_lds_dwordx4 v136, s[96:97]
	s_mov_b32 m0, s7
	s_nop 0
	global_load_lds_dwordx4 v132, s[98:99]
	s_add_i32 m0, s7, 0x2000
	s_nop 0
	global_load_lds_dwordx4 v136, s[98:99]
	s_mov_b32 m0, s49
	s_nop 0
	global_load_lds_dwordx4 v130, s[94:95]
	s_mov_b32 m0, s58
	s_nop 0
	global_load_lds_dwordx4 v134, s[94:95]
	ds_read_b128 v[196:199], v160 offset:16384
	ds_read_b128 v[200:203], v160 offset:17408
	ds_read_b128 v[204:207], v160 offset:18432
	ds_read_b128 v[208:211], v160 offset:19456
	ds_read_b128 v[212:215], v160 offset:20480
	ds_read_b128 v[216:219], v160 offset:21504
	ds_read_b128 v[220:223], v160 offset:22528
	ds_read_b128 v[224:227], v160 offset:23552
	s_waitcnt vmcnt(8)
	s_waitcnt lgkmcnt(0)
	.p2align 3
	s_setprio 1
	s_barrier
	v_mfma_f32_16x16x32_bf16 v[62:65], v[164:167], v[196:199], v[62:65]
	v_mfma_f32_16x16x32_bf16 v[54:57], v[172:175], v[196:199], v[54:57]
	v_mfma_f32_16x16x32_bf16 v[46:49], v[164:167], v[204:207], v[46:49]
	v_mfma_f32_16x16x32_bf16 v[38:41], v[172:175], v[204:207], v[38:41]
	v_mfma_f32_16x16x32_bf16 v[30:33], v[164:167], v[212:215], v[30:33]
	v_mfma_f32_16x16x32_bf16 v[22:25], v[172:175], v[212:215], v[22:25]
	v_mfma_f32_16x16x32_bf16 v[14:17], v[164:167], v[220:223], v[14:17]
	v_mfma_f32_16x16x32_bf16 v[6:9], v[172:175], v[220:223], v[6:9]
	v_mfma_f32_16x16x32_bf16 v[62:65], v[168:171], v[200:203], v[62:65]
	v_mfma_f32_16x16x32_bf16 v[54:57], v[176:179], v[200:203], v[54:57]
	v_mfma_f32_16x16x32_bf16 v[46:49], v[168:171], v[208:211], v[46:49]
	v_mfma_f32_16x16x32_bf16 v[38:41], v[176:179], v[208:211], v[38:41]
	v_mfma_f32_16x16x32_bf16 v[30:33], v[168:171], v[216:219], v[30:33]
	v_mfma_f32_16x16x32_bf16 v[22:25], v[176:179], v[216:219], v[22:25]
	v_mfma_f32_16x16x32_bf16 v[14:17], v[168:171], v[224:227], v[14:17]
	v_mfma_f32_16x16x32_bf16 v[6:9], v[176:179], v[224:227], v[6:9]
	s_setprio 0
	s_setprio 1
	v_mfma_f32_16x16x32_bf16 v[58:61], v[180:183], v[196:199], v[58:61]
	v_mfma_f32_16x16x32_bf16 v[50:53], v[188:191], v[196:199], v[50:53]
	v_mfma_f32_16x16x32_bf16 v[42:45], v[180:183], v[204:207], v[42:45]
	v_mfma_f32_16x16x32_bf16 v[34:37], v[188:191], v[204:207], v[34:37]
	v_mfma_f32_16x16x32_bf16 v[26:29], v[180:183], v[212:215], v[26:29]
	v_mfma_f32_16x16x32_bf16 v[18:21], v[188:191], v[212:215], v[18:21]
	v_mfma_f32_16x16x32_bf16 v[10:13], v[180:183], v[220:223], v[10:13]
	v_mfma_f32_16x16x32_bf16 v[2:5], v[188:191], v[220:223], v[2:5]
	v_mfma_f32_16x16x32_bf16 v[58:61], v[184:187], v[200:203], v[58:61]
	v_mfma_f32_16x16x32_bf16 v[50:53], v[192:195], v[200:203], v[50:53]
	v_mfma_f32_16x16x32_bf16 v[42:45], v[184:187], v[208:211], v[42:45]
	v_mfma_f32_16x16x32_bf16 v[34:37], v[192:195], v[208:211], v[34:37]
	v_mfma_f32_16x16x32_bf16 v[26:29], v[184:187], v[216:219], v[26:29]
	v_mfma_f32_16x16x32_bf16 v[18:21], v[192:195], v[216:219], v[18:21]
	v_mfma_f32_16x16x32_bf16 v[10:13], v[184:187], v[224:227], v[10:13]
	v_mfma_f32_16x16x32_bf16 v[2:5], v[192:195], v[224:227], v[2:5]
	s_barrier
	s_setprio 0
	s_add_u32 s98, s94, 0x40000
	s_addc_u32 s99, s95, 0
	s_add_i32 s7, 0, 0x18000
	s_add_i32 s47, 0, 0x1c000
	s_mov_b32 m0, s59
	s_nop 0
	global_load_lds_dwordx4 v130, s[98:99]
	s_mov_b32 m0, s60
	s_nop 0
	global_load_lds_dwordx4 v134, s[98:99]
	ds_read_b128 v[164:167], v232
	ds_read_b128 v[168:171], v232 offset:1024
	ds_read_b128 v[172:175], v232 offset:2048
	ds_read_b128 v[176:179], v232 offset:3072
	ds_read_b128 v[180:183], v233
	ds_read_b128 v[184:187], v233 offset:1024
	ds_read_b128 v[188:191], v233 offset:2048
	ds_read_b128 v[192:195], v233 offset:3072
	ds_read_b128 v[196:199], v160 offset:32768
	ds_read_b128 v[200:203], v160 offset:33792
	ds_read_b128 v[204:207], v160 offset:34816
	ds_read_b128 v[208:211], v160 offset:35840
	ds_read_b128 v[212:215], v160 offset:36864
	ds_read_b128 v[216:219], v160 offset:37888
	ds_read_b128 v[220:223], v160 offset:38912
	ds_read_b128 v[224:227], v160 offset:39936
	s_waitcnt vmcnt(8)
	s_waitcnt lgkmcnt(0)
	.p2align 3
	s_setprio 1
	s_barrier
	v_mfma_f32_16x16x32_bf16 v[122:125], v[164:167], v[196:199], v[122:125]
	v_mfma_f32_16x16x32_bf16 v[118:121], v[172:175], v[196:199], v[118:121]
	v_mfma_f32_16x16x32_bf16 v[110:113], v[164:167], v[204:207], v[110:113]
	v_mfma_f32_16x16x32_bf16 v[102:105], v[172:175], v[204:207], v[102:105]
	v_mfma_f32_16x16x32_bf16 v[94:97], v[164:167], v[212:215], v[94:97]
	v_mfma_f32_16x16x32_bf16 v[86:89], v[172:175], v[212:215], v[86:89]
	v_mfma_f32_16x16x32_bf16 v[78:81], v[164:167], v[220:223], v[78:81]
	v_mfma_f32_16x16x32_bf16 v[70:73], v[172:175], v[220:223], v[70:73]
	v_mfma_f32_16x16x32_bf16 v[122:125], v[168:171], v[200:203], v[122:125]
	v_mfma_f32_16x16x32_bf16 v[118:121], v[176:179], v[200:203], v[118:121]
	v_mfma_f32_16x16x32_bf16 v[110:113], v[168:171], v[208:211], v[110:113]
	v_mfma_f32_16x16x32_bf16 v[102:105], v[176:179], v[208:211], v[102:105]
	v_mfma_f32_16x16x32_bf16 v[94:97], v[168:171], v[216:219], v[94:97]
	v_mfma_f32_16x16x32_bf16 v[86:89], v[176:179], v[216:219], v[86:89]
	v_mfma_f32_16x16x32_bf16 v[78:81], v[168:171], v[224:227], v[78:81]
	v_mfma_f32_16x16x32_bf16 v[70:73], v[176:179], v[224:227], v[70:73]
	s_setprio 0
	s_setprio 1
	v_mfma_f32_16x16x32_bf16 v[126:129], v[180:183], v[196:199], v[126:129]
	v_mfma_f32_16x16x32_bf16 v[114:117], v[188:191], v[196:199], v[114:117]
	v_mfma_f32_16x16x32_bf16 v[106:109], v[180:183], v[204:207], v[106:109]
	v_mfma_f32_16x16x32_bf16 v[98:101], v[188:191], v[204:207], v[98:101]
	v_mfma_f32_16x16x32_bf16 v[90:93], v[180:183], v[212:215], v[90:93]
	v_mfma_f32_16x16x32_bf16 v[82:85], v[188:191], v[212:215], v[82:85]
	v_mfma_f32_16x16x32_bf16 v[74:77], v[180:183], v[220:223], v[74:77]
	v_mfma_f32_16x16x32_bf16 v[66:69], v[188:191], v[220:223], v[66:69]
	v_mfma_f32_16x16x32_bf16 v[126:129], v[184:187], v[200:203], v[126:129]
	v_mfma_f32_16x16x32_bf16 v[114:117], v[192:195], v[200:203], v[114:117]
	v_mfma_f32_16x16x32_bf16 v[106:109], v[184:187], v[208:211], v[106:109]
	v_mfma_f32_16x16x32_bf16 v[98:101], v[192:195], v[208:211], v[98:101]
	v_mfma_f32_16x16x32_bf16 v[90:93], v[184:187], v[216:219], v[90:93]
	v_mfma_f32_16x16x32_bf16 v[82:85], v[192:195], v[216:219], v[82:85]
	v_mfma_f32_16x16x32_bf16 v[74:77], v[184:187], v[224:227], v[74:77]
	v_mfma_f32_16x16x32_bf16 v[66:69], v[192:195], v[224:227], v[66:69]
	s_barrier
	s_setprio 0
	s_add_u32 s96, s96, 0x80
	s_addc_u32 s97, s97, 0
	s_add_u32 s98, s96, 0x40000
	s_addc_u32 s99, s97, 0
	s_add_u32 s94, s94, 0x80
	s_addc_u32 s95, s95, 0
	s_add_i32 s7, s7, s25
	s_mov_b32 m0, s7
	s_nop 0
	global_load_lds_dwordx4 v132, s[96:97]
	s_add_i32 m0, s7, 0x2000
	s_add_i32 s7, s47, s25
	global_load_lds_dwordx4 v136, s[96:97]
	s_mov_b32 m0, s7
	s_nop 0
	global_load_lds_dwordx4 v132, s[98:99]
	s_add_i32 m0, s7, 0x2000
	s_nop 0
	global_load_lds_dwordx4 v136, s[98:99]
	s_mov_b32 m0, s66
	s_nop 0
	global_load_lds_dwordx4 v130, s[94:95]
	s_mov_b32 m0, s67
	s_nop 0
	global_load_lds_dwordx4 v134, s[94:95]
	ds_read_b128 v[196:199], v160 offset:49152
	ds_read_b128 v[200:203], v160 offset:50176
	ds_read_b128 v[204:207], v160 offset:51200
	ds_read_b128 v[208:211], v160 offset:52224
	ds_read_b128 v[212:215], v160 offset:53248
	ds_read_b128 v[216:219], v160 offset:54272
	ds_read_b128 v[220:223], v160 offset:55296
	ds_read_b128 v[224:227], v160 offset:56320
	s_waitcnt vmcnt(8)
	s_waitcnt lgkmcnt(0)
	.p2align 3
	s_setprio 1
	s_barrier
	v_mfma_f32_16x16x32_bf16 v[62:65], v[164:167], v[196:199], v[62:65]
	v_mfma_f32_16x16x32_bf16 v[54:57], v[172:175], v[196:199], v[54:57]
	v_mfma_f32_16x16x32_bf16 v[46:49], v[164:167], v[204:207], v[46:49]
	v_mfma_f32_16x16x32_bf16 v[38:41], v[172:175], v[204:207], v[38:41]
	v_mfma_f32_16x16x32_bf16 v[30:33], v[164:167], v[212:215], v[30:33]
	v_mfma_f32_16x16x32_bf16 v[22:25], v[172:175], v[212:215], v[22:25]
	v_mfma_f32_16x16x32_bf16 v[14:17], v[164:167], v[220:223], v[14:17]
	v_mfma_f32_16x16x32_bf16 v[6:9], v[172:175], v[220:223], v[6:9]
	v_mfma_f32_16x16x32_bf16 v[62:65], v[168:171], v[200:203], v[62:65]
	v_mfma_f32_16x16x32_bf16 v[54:57], v[176:179], v[200:203], v[54:57]
	v_mfma_f32_16x16x32_bf16 v[46:49], v[168:171], v[208:211], v[46:49]
	v_mfma_f32_16x16x32_bf16 v[38:41], v[176:179], v[208:211], v[38:41]
	v_mfma_f32_16x16x32_bf16 v[30:33], v[168:171], v[216:219], v[30:33]
	v_mfma_f32_16x16x32_bf16 v[22:25], v[176:179], v[216:219], v[22:25]
	v_mfma_f32_16x16x32_bf16 v[14:17], v[168:171], v[224:227], v[14:17]
	v_mfma_f32_16x16x32_bf16 v[6:9], v[176:179], v[224:227], v[6:9]
	s_setprio 0
	s_setprio 1
	v_mfma_f32_16x16x32_bf16 v[58:61], v[180:183], v[196:199], v[58:61]
	v_mfma_f32_16x16x32_bf16 v[50:53], v[188:191], v[196:199], v[50:53]
	v_mfma_f32_16x16x32_bf16 v[42:45], v[180:183], v[204:207], v[42:45]
	v_mfma_f32_16x16x32_bf16 v[34:37], v[188:191], v[204:207], v[34:37]
	v_mfma_f32_16x16x32_bf16 v[26:29], v[180:183], v[212:215], v[26:29]
	v_mfma_f32_16x16x32_bf16 v[18:21], v[188:191], v[212:215], v[18:21]
	v_mfma_f32_16x16x32_bf16 v[10:13], v[180:183], v[220:223], v[10:13]
	v_mfma_f32_16x16x32_bf16 v[2:5], v[188:191], v[220:223], v[2:5]
	v_mfma_f32_16x16x32_bf16 v[58:61], v[184:187], v[200:203], v[58:61]
	v_mfma_f32_16x16x32_bf16 v[50:53], v[192:195], v[200:203], v[50:53]
	v_mfma_f32_16x16x32_bf16 v[42:45], v[184:187], v[208:211], v[42:45]
	v_mfma_f32_16x16x32_bf16 v[34:37], v[192:195], v[208:211], v[34:37]
	v_mfma_f32_16x16x32_bf16 v[26:29], v[184:187], v[216:219], v[26:29]
	v_mfma_f32_16x16x32_bf16 v[18:21], v[192:195], v[216:219], v[18:21]
	v_mfma_f32_16x16x32_bf16 v[10:13], v[184:187], v[224:227], v[10:13]
	v_mfma_f32_16x16x32_bf16 v[2:5], v[192:195], v[224:227], v[2:5]
	s_barrier
	s_setprio 0
	s_mov_b32 s7, s45
	s_add_u32 s88, s88, 0x100
	s_addc_u32 s89, s89, 0
	s_add_u32 s86, s86, 0x100
	s_addc_u32 s87, s87, 0
	s_cmp_ge_i32 s45, s101
	s_cbranch_scc0 .LBB0_768

.Lmy_nb_4:
	s_nop 0
	v_readfirstlane_b32 s86, v152
	v_readfirstlane_b32 s87, v153
	v_readfirstlane_b32 s88, v150
	v_readfirstlane_b32 s89, v151
	v_readfirstlane_b32 s90, v146
	v_readfirstlane_b32 s91, v147
	v_readfirstlane_b32 s92, v148
	v_readfirstlane_b32 s93, v149
	v_readfirstlane_b32 s100, v154
	v_readfirstlane_b32 s101, v138
	v_add_u32_e32 v230, s74, v141
	v_add_u32_e32 v231, s75, v141
	v_add_u32_e32 v232, 0x18000, v141
	v_add_u32_e32 v233, 0x1c000, v141
	s_add_u32 s98, s86, 0xfffc0080
	s_addc_u32 s99, s87, -1
	s_cmp_eq_u32 s7, s100
	s_cselect_b64 s[94:95], s[90:91], s[98:99]
	s_cselect_b64 s[96:97], s[92:93], s[88:89]
	s_add_i32 s47, s7, 2
	s_nop 0
	s_mov_b32 m0, s76
	s_nop 0
	global_load_lds_dwordx4 v144, s[86:87]
	s_mov_b32 m0, s77
	s_nop 0
	global_load_lds_dwordx4 v142, s[86:87]
	ds_read_b128 v[164:167], v230
	ds_read_b128 v[168:171], v230 offset:1024
	ds_read_b128 v[172:175], v230 offset:2048
	ds_read_b128 v[176:179], v230 offset:3072
	ds_read_b128 v[180:183], v231
	ds_read_b128 v[184:187], v231 offset:1024
	ds_read_b128 v[188:191], v231 offset:2048
	ds_read_b128 v[192:195], v231 offset:3072
	ds_read_b128 v[196:199], v160
	ds_read_b128 v[200:203], v160 offset:1024
	ds_read_b128 v[204:207], v160 offset:2048
	ds_read_b128 v[208:211], v160 offset:3072
	ds_read_b128 v[212:215], v160 offset:4096
	ds_read_b128 v[216:219], v160 offset:5120
	ds_read_b128 v[220:223], v160 offset:6144
	ds_read_b128 v[224:227], v160 offset:7168
	s_waitcnt vmcnt(8)
	s_waitcnt lgkmcnt(0)
	.p2align 3
	s_setprio 1
	s_barrier
	v_mfma_f32_16x16x32_bf16 v[122:125], v[164:167], v[196:199], 0
	v_mfma_f32_16x16x32_bf16 v[118:121], v[172:175], v[196:199], 0
	v_mfma_f32_16x16x32_bf16 v[110:113], v[164:167], v[204:207], 0
	v_mfma_f32_16x16x32_bf16 v[102:105], v[172:175], v[204:207], 0
	v_mfma_f32_16x16x32_bf16 v[94:97], v[164:167], v[212:215], 0
	v_mfma_f32_16x16x32_bf16 v[86:89], v[172:175], v[212:215], 0
	v_mfma_f32_16x16x32_bf16 v[78:81], v[164:167], v[220:223], 0
	v_mfma_f32_16x16x32_bf16 v[70:73], v[172:175], v[220:223], 0
	v_mfma_f32_16x16x32_bf16 v[122:125], v[168:171], v[200:203], v[122:125]
	v_mfma_f32_16x16x32_bf16 v[118:121], v[176:179], v[200:203], v[118:121]
	v_mfma_f32_16x16x32_bf16 v[110:113], v[168:171], v[208:211], v[110:113]
	v_mfma_f32_16x16x32_bf16 v[102:105], v[176:179], v[208:211], v[102:105]
	v_mfma_f32_16x16x32_bf16 v[94:97], v[168:171], v[216:219], v[94:97]
	v_mfma_f32_16x16x32_bf16 v[86:89], v[176:179], v[216:219], v[86:89]
	v_mfma_f32_16x16x32_bf16 v[78:81], v[168:171], v[224:227], v[78:81]
	v_mfma_f32_16x16x32_bf16 v[70:73], v[176:179], v[224:227], v[70:73]
	s_setprio 0
	s_setprio 1
	v_mfma_f32_16x16x32_bf16 v[126:129], v[180:183], v[196:199], 0
	v_mfma_f32_16x16x32_bf16 v[114:117], v[188:191], v[196:199], 0
	v_mfma_f32_16x16x32_bf16 v[106:109], v[180:183], v[204:207], 0
	v_mfma_f32_16x16x32_bf16 v[98:101], v[188:191], v[204:207], 0
	v_mfma_f32_16x16x32_bf16 v[90:93], v[180:183], v[212:215], 0
	v_mfma_f32_16x16x32_bf16 v[82:85], v[188:191], v[212:215], 0
	v_mfma_f32_16x16x32_bf16 v[74:77], v[180:183], v[220:223], 0
	v_mfma_f32_16x16x32_bf16 v[66:69], v[188:191], v[220:223], 0
	v_mfma_f32_16x16x32_bf16 v[126:129], v[184:187], v[200:203], v[126:129]
	v_mfma_f32_16x16x32_bf16 v[114:117], v[192:195], v[200:203], v[114:117]
	v_mfma_f32_16x16x32_bf16 v[106:109], v[184:187], v[208:211], v[106:109]
	v_mfma_f32_16x16x32_bf16 v[98:101], v[192:195], v[208:211], v[98:101]
	v_mfma_f32_16x16x32_bf16 v[90:93], v[184:187], v[216:219], v[90:93]
	v_mfma_f32_16x16x32_bf16 v[82:85], v[192:195], v[216:219], v[82:85]
	v_mfma_f32_16x16x32_bf16 v[74:77], v[184:187], v[224:227], v[74:77]
	v_mfma_f32_16x16x32_bf16 v[66:69], v[192:195], v[224:227], v[66:69]
	s_barrier
	s_setprio 0
	s_add_u32 s98, s96, 0x40000
	s_addc_u32 s99, s97, 0
	s_mov_b32 m0, s78
	s_nop 0
	global_load_lds_dwordx4 v132, s[96:97]
	s_mov_b32 m0, s79
	s_add_i32 s7, s75, s29
	global_load_lds_dwordx4 v136, s[96:97]
	s_mov_b32 m0, s7
	s_nop 0
	global_load_lds_dwordx4 v132, s[98:99]
	s_add_i32 m0, s7, 0x2000
	s_nop 0
	global_load_lds_dwordx4 v136, s[98:99]
	s_mov_b32 m0, s51
	s_nop 0
	global_load_lds_dwordx4 v130, s[94:95]
	s_mov_b32 m0, s60
	s_nop 0
	global_load_lds_dwordx4 v134, s[94:95]
	ds_read_b128 v[196:199], v160 offset:16384
	ds_read_b128 v[200:203], v160 offset:17408
	ds_read_b128 v[204:207], v160 offset:18432
	ds_read_b128 v[208:211], v160 offset:19456
	ds_read_b128 v[212:215], v160 offset:20480
	ds_read_b128 v[216:219], v160 offset:21504
	ds_read_b128 v[220:223], v160 offset:22528
	ds_read_b128 v[224:227], v160 offset:23552
	s_waitcnt vmcnt(8)
	s_waitcnt lgkmcnt(0)
	.p2align 3
	s_setprio 1
	s_barrier
	v_mfma_f32_16x16x32_bf16 v[62:65], v[164:167], v[196:199], 0
	v_mfma_f32_16x16x32_bf16 v[54:57], v[172:175], v[196:199], 0
	v_mfma_f32_16x16x32_bf16 v[46:49], v[164:167], v[204:207], 0
	v_mfma_f32_16x16x32_bf16 v[38:41], v[172:175], v[204:207], 0
	v_mfma_f32_16x16x32_bf16 v[30:33], v[164:167], v[212:215], 0
	v_mfma_f32_16x16x32_bf16 v[22:25], v[172:175], v[212:215], 0
	v_mfma_f32_16x16x32_bf16 v[14:17], v[164:167], v[220:223], 0
	v_mfma_f32_16x16x32_bf16 v[6:9], v[172:175], v[220:223], 0
	v_mfma_f32_16x16x32_bf16 v[62:65], v[168:171], v[200:203], v[62:65]
	v_mfma_f32_16x16x32_bf16 v[54:57], v[176:179], v[200:203], v[54:57]
	v_mfma_f32_16x16x32_bf16 v[46:49], v[168:171], v[208:211], v[46:49]
	v_mfma_f32_16x16x32_bf16 v[38:41], v[176:179], v[208:211], v[38:41]
	v_mfma_f32_16x16x32_bf16 v[30:33], v[168:171], v[216:219], v[30:33]
	v_mfma_f32_16x16x32_bf16 v[22:25], v[176:179], v[216:219], v[22:25]
	v_mfma_f32_16x16x32_bf16 v[14:17], v[168:171], v[224:227], v[14:17]
	v_mfma_f32_16x16x32_bf16 v[6:9], v[176:179], v[224:227], v[6:9]
	s_setprio 0
	s_setprio 1
	v_mfma_f32_16x16x32_bf16 v[58:61], v[180:183], v[196:199], 0
	v_mfma_f32_16x16x32_bf16 v[50:53], v[188:191], v[196:199], 0
	v_mfma_f32_16x16x32_bf16 v[42:45], v[180:183], v[204:207], 0
	v_mfma_f32_16x16x32_bf16 v[34:37], v[188:191], v[204:207], 0
	v_mfma_f32_16x16x32_bf16 v[26:29], v[180:183], v[212:215], 0
	v_mfma_f32_16x16x32_bf16 v[18:21], v[188:191], v[212:215], 0
	v_mfma_f32_16x16x32_bf16 v[10:13], v[180:183], v[220:223], 0
	v_mfma_f32_16x16x32_bf16 v[2:5], v[188:191], v[220:223], 0
	v_mfma_f32_16x16x32_bf16 v[58:61], v[184:187], v[200:203], v[58:61]
	v_mfma_f32_16x16x32_bf16 v[50:53], v[192:195], v[200:203], v[50:53]
	v_mfma_f32_16x16x32_bf16 v[42:45], v[184:187], v[208:211], v[42:45]
	v_mfma_f32_16x16x32_bf16 v[34:37], v[192:195], v[208:211], v[34:37]
	v_mfma_f32_16x16x32_bf16 v[26:29], v[184:187], v[216:219], v[26:29]
	v_mfma_f32_16x16x32_bf16 v[18:21], v[192:195], v[216:219], v[18:21]
	v_mfma_f32_16x16x32_bf16 v[10:13], v[184:187], v[224:227], v[10:13]
	v_mfma_f32_16x16x32_bf16 v[2:5], v[192:195], v[224:227], v[2:5]
	s_barrier
	s_setprio 0
	s_add_u32 s98, s94, 0x40000
	s_addc_u32 s99, s95, 0
	s_add_i32 s7, 0, 0x18000
	s_add_i32 s49, 0, 0x1c000
	s_mov_b32 m0, s61
	s_nop 0
	global_load_lds_dwordx4 v130, s[98:99]
	s_mov_b32 m0, s62
	s_nop 0
	global_load_lds_dwordx4 v134, s[98:99]
	ds_read_b128 v[164:167], v232
	ds_read_b128 v[168:171], v232 offset:1024
	ds_read_b128 v[172:175], v232 offset:2048
	ds_read_b128 v[176:179], v232 offset:3072
	ds_read_b128 v[180:183], v233
	ds_read_b128 v[184:187], v233 offset:1024
	ds_read_b128 v[188:191], v233 offset:2048
	ds_read_b128 v[192:195], v233 offset:3072
	ds_read_b128 v[196:199], v160 offset:32768
	ds_read_b128 v[200:203], v160 offset:33792
	ds_read_b128 v[204:207], v160 offset:34816
	ds_read_b128 v[208:211], v160 offset:35840
	ds_read_b128 v[212:215], v160 offset:36864
	ds_read_b128 v[216:219], v160 offset:37888
	ds_read_b128 v[220:223], v160 offset:38912
	ds_read_b128 v[224:227], v160 offset:39936
	s_waitcnt vmcnt(8)
	s_waitcnt lgkmcnt(0)
	.p2align 3
	s_setprio 1
	s_barrier
	v_mfma_f32_16x16x32_bf16 v[122:125], v[164:167], v[196:199], v[122:125]
	v_mfma_f32_16x16x32_bf16 v[118:121], v[172:175], v[196:199], v[118:121]
	v_mfma_f32_16x16x32_bf16 v[110:113], v[164:167], v[204:207], v[110:113]
	v_mfma_f32_16x16x32_bf16 v[102:105], v[172:175], v[204:207], v[102:105]
	v_mfma_f32_16x16x32_bf16 v[94:97], v[164:167], v[212:215], v[94:97]
	v_mfma_f32_16x16x32_bf16 v[86:89], v[172:175], v[212:215], v[86:89]
	v_mfma_f32_16x16x32_bf16 v[78:81], v[164:167], v[220:223], v[78:81]
	v_mfma_f32_16x16x32_bf16 v[70:73], v[172:175], v[220:223], v[70:73]
	v_mfma_f32_16x16x32_bf16 v[122:125], v[168:171], v[200:203], v[122:125]
	v_mfma_f32_16x16x32_bf16 v[118:121], v[176:179], v[200:203], v[118:121]
	v_mfma_f32_16x16x32_bf16 v[110:113], v[168:171], v[208:211], v[110:113]
	v_mfma_f32_16x16x32_bf16 v[102:105], v[176:179], v[208:211], v[102:105]
	v_mfma_f32_16x16x32_bf16 v[94:97], v[168:171], v[216:219], v[94:97]
	v_mfma_f32_16x16x32_bf16 v[86:89], v[176:179], v[216:219], v[86:89]
	v_mfma_f32_16x16x32_bf16 v[78:81], v[168:171], v[224:227], v[78:81]
	v_mfma_f32_16x16x32_bf16 v[70:73], v[176:179], v[224:227], v[70:73]
	s_setprio 0
	s_setprio 1
	v_mfma_f32_16x16x32_bf16 v[126:129], v[180:183], v[196:199], v[126:129]
	v_mfma_f32_16x16x32_bf16 v[114:117], v[188:191], v[196:199], v[114:117]
	v_mfma_f32_16x16x32_bf16 v[106:109], v[180:183], v[204:207], v[106:109]
	v_mfma_f32_16x16x32_bf16 v[98:101], v[188:191], v[204:207], v[98:101]
	v_mfma_f32_16x16x32_bf16 v[90:93], v[180:183], v[212:215], v[90:93]
	v_mfma_f32_16x16x32_bf16 v[82:85], v[188:191], v[212:215], v[82:85]
	v_mfma_f32_16x16x32_bf16 v[74:77], v[180:183], v[220:223], v[74:77]
	v_mfma_f32_16x16x32_bf16 v[66:69], v[188:191], v[220:223], v[66:69]
	v_mfma_f32_16x16x32_bf16 v[126:129], v[184:187], v[200:203], v[126:129]
	v_mfma_f32_16x16x32_bf16 v[114:117], v[192:195], v[200:203], v[114:117]
	v_mfma_f32_16x16x32_bf16 v[106:109], v[184:187], v[208:211], v[106:109]
	v_mfma_f32_16x16x32_bf16 v[98:101], v[192:195], v[208:211], v[98:101]
	v_mfma_f32_16x16x32_bf16 v[90:93], v[184:187], v[216:219], v[90:93]
	v_mfma_f32_16x16x32_bf16 v[82:85], v[192:195], v[216:219], v[82:85]
	v_mfma_f32_16x16x32_bf16 v[74:77], v[184:187], v[224:227], v[74:77]
	v_mfma_f32_16x16x32_bf16 v[66:69], v[192:195], v[224:227], v[66:69]
	s_barrier
	s_setprio 0
	s_add_u32 s96, s96, 0x80
	s_addc_u32 s97, s97, 0
	s_add_u32 s98, s96, 0x40000
	s_addc_u32 s99, s97, 0
	s_add_u32 s94, s94, 0x80
	s_addc_u32 s95, s95, 0
	s_add_i32 s7, s7, s29
	s_mov_b32 m0, s7
	s_nop 0
	global_load_lds_dwordx4 v132, s[96:97]
	s_add_i32 m0, s7, 0x2000
	s_add_i32 s7, s49, s29
	global_load_lds_dwordx4 v136, s[96:97]
	s_mov_b32 m0, s7
	s_nop 0
	global_load_lds_dwordx4 v132, s[98:99]
	s_add_i32 m0, s7, 0x2000
	s_nop 0
	global_load_lds_dwordx4 v136, s[98:99]
	s_mov_b32 m0, s63
	s_nop 0
	global_load_lds_dwordx4 v130, s[94:95]
	s_mov_b32 m0, s64
	s_nop 0
	global_load_lds_dwordx4 v134, s[94:95]
	ds_read_b128 v[196:199], v160 offset:49152
	ds_read_b128 v[200:203], v160 offset:50176
	ds_read_b128 v[204:207], v160 offset:51200
	ds_read_b128 v[208:211], v160 offset:52224
	ds_read_b128 v[212:215], v160 offset:53248
	ds_read_b128 v[216:219], v160 offset:54272
	ds_read_b128 v[220:223], v160 offset:55296
	ds_read_b128 v[224:227], v160 offset:56320
	s_waitcnt vmcnt(8)
	s_waitcnt lgkmcnt(0)
	.p2align 3
	s_setprio 1
	s_barrier
	v_mfma_f32_16x16x32_bf16 v[62:65], v[164:167], v[196:199], v[62:65]
	v_mfma_f32_16x16x32_bf16 v[54:57], v[172:175], v[196:199], v[54:57]
	v_mfma_f32_16x16x32_bf16 v[46:49], v[164:167], v[204:207], v[46:49]
	v_mfma_f32_16x16x32_bf16 v[38:41], v[172:175], v[204:207], v[38:41]
	v_mfma_f32_16x16x32_bf16 v[30:33], v[164:167], v[212:215], v[30:33]
	v_mfma_f32_16x16x32_bf16 v[22:25], v[172:175], v[212:215], v[22:25]
	v_mfma_f32_16x16x32_bf16 v[14:17], v[164:167], v[220:223], v[14:17]
	v_mfma_f32_16x16x32_bf16 v[6:9], v[172:175], v[220:223], v[6:9]
	v_mfma_f32_16x16x32_bf16 v[62:65], v[168:171], v[200:203], v[62:65]
	v_mfma_f32_16x16x32_bf16 v[54:57], v[176:179], v[200:203], v[54:57]
	v_mfma_f32_16x16x32_bf16 v[46:49], v[168:171], v[208:211], v[46:49]
	v_mfma_f32_16x16x32_bf16 v[38:41], v[176:179], v[208:211], v[38:41]
	v_mfma_f32_16x16x32_bf16 v[30:33], v[168:171], v[216:219], v[30:33]
	v_mfma_f32_16x16x32_bf16 v[22:25], v[176:179], v[216:219], v[22:25]
	v_mfma_f32_16x16x32_bf16 v[14:17], v[168:171], v[224:227], v[14:17]
	v_mfma_f32_16x16x32_bf16 v[6:9], v[176:179], v[224:227], v[6:9]
	s_setprio 0
	s_setprio 1
	v_mfma_f32_16x16x32_bf16 v[58:61], v[180:183], v[196:199], v[58:61]
	v_mfma_f32_16x16x32_bf16 v[50:53], v[188:191], v[196:199], v[50:53]
	v_mfma_f32_16x16x32_bf16 v[42:45], v[180:183], v[204:207], v[42:45]
	v_mfma_f32_16x16x32_bf16 v[34:37], v[188:191], v[204:207], v[34:37]
	v_mfma_f32_16x16x32_bf16 v[26:29], v[180:183], v[212:215], v[26:29]
	v_mfma_f32_16x16x32_bf16 v[18:21], v[188:191], v[212:215], v[18:21]
	v_mfma_f32_16x16x32_bf16 v[10:13], v[180:183], v[220:223], v[10:13]
	v_mfma_f32_16x16x32_bf16 v[2:5], v[188:191], v[220:223], v[2:5]
	v_mfma_f32_16x16x32_bf16 v[58:61], v[184:187], v[200:203], v[58:61]
	v_mfma_f32_16x16x32_bf16 v[50:53], v[192:195], v[200:203], v[50:53]
	v_mfma_f32_16x16x32_bf16 v[42:45], v[184:187], v[208:211], v[42:45]
	v_mfma_f32_16x16x32_bf16 v[34:37], v[192:195], v[208:211], v[34:37]
	v_mfma_f32_16x16x32_bf16 v[26:29], v[184:187], v[216:219], v[26:29]
	v_mfma_f32_16x16x32_bf16 v[18:21], v[192:195], v[216:219], v[18:21]
	v_mfma_f32_16x16x32_bf16 v[10:13], v[184:187], v[224:227], v[10:13]
	v_mfma_f32_16x16x32_bf16 v[2:5], v[192:195], v[224:227], v[2:5]
	s_barrier
	s_setprio 0
	s_mov_b32 s7, s47
	s_add_u32 s88, s88, 0x100
	s_addc_u32 s89, s89, 0
	s_add_u32 s86, s86, 0x100
	s_addc_u32 s87, s87, 0
	s_cmp_ge_i32 s47, s101
	s_cbranch_scc1 .Lmy_kexit_4
.LBB0_949:
	s_add_u32 s98, s86, 0xfffc0080
	s_addc_u32 s99, s87, -1
	s_cmp_eq_u32 s7, s100
	s_cselect_b64 s[94:95], s[90:91], s[98:99]
	s_cselect_b64 s[96:97], s[92:93], s[88:89]
	s_add_i32 s47, s7, 2
	s_nop 0
	s_mov_b32 m0, s76
	s_nop 0
	global_load_lds_dwordx4 v144, s[86:87]
	s_mov_b32 m0, s77
	s_nop 0
	global_load_lds_dwordx4 v142, s[86:87]
	ds_read_b128 v[164:167], v230
	ds_read_b128 v[168:171], v230 offset:1024
	ds_read_b128 v[172:175], v230 offset:2048
	ds_read_b128 v[176:179], v230 offset:3072
	ds_read_b128 v[180:183], v231
	ds_read_b128 v[184:187], v231 offset:1024
	ds_read_b128 v[188:191], v231 offset:2048
	ds_read_b128 v[192:195], v231 offset:3072
	ds_read_b128 v[196:199], v160
	ds_read_b128 v[200:203], v160 offset:1024
	ds_read_b128 v[204:207], v160 offset:2048
	ds_read_b128 v[208:211], v160 offset:3072
	ds_read_b128 v[212:215], v160 offset:4096
	ds_read_b128 v[216:219], v160 offset:5120
	ds_read_b128 v[220:223], v160 offset:6144
	ds_read_b128 v[224:227], v160 offset:7168
	s_waitcnt vmcnt(8)
	s_waitcnt lgkmcnt(0)
	.p2align 3
	s_setprio 1
	s_barrier
	v_mfma_f32_16x16x32_bf16 v[122:125], v[164:167], v[196:199], v[122:125]
	v_mfma_f32_16x16x32_bf16 v[118:121], v[172:175], v[196:199], v[118:121]
	v_mfma_f32_16x16x32_bf16 v[110:113], v[164:167], v[204:207], v[110:113]
	v_mfma_f32_16x16x32_bf16 v[102:105], v[172:175], v[204:207], v[102:105]
	v_mfma_f32_16x16x32_bf16 v[94:97], v[164:167], v[212:215], v[94:97]
	v_mfma_f32_16x16x32_bf16 v[86:89], v[172:175], v[212:215], v[86:89]
	v_mfma_f32_16x16x32_bf16 v[78:81], v[164:167], v[220:223], v[78:81]
	v_mfma_f32_16x16x32_bf16 v[70:73], v[172:175], v[220:223], v[70:73]
	v_mfma_f32_16x16x32_bf16 v[122:125], v[168:171], v[200:203], v[122:125]
	v_mfma_f32_16x16x32_bf16 v[118:121], v[176:179], v[200:203], v[118:121]
	v_mfma_f32_16x16x32_bf16 v[110:113], v[168:171], v[208:211], v[110:113]
	v_mfma_f32_16x16x32_bf16 v[102:105], v[176:179], v[208:211], v[102:105]
	v_mfma_f32_16x16x32_bf16 v[94:97], v[168:171], v[216:219], v[94:97]
	v_mfma_f32_16x16x32_bf16 v[86:89], v[176:179], v[216:219], v[86:89]
	v_mfma_f32_16x16x32_bf16 v[78:81], v[168:171], v[224:227], v[78:81]
	v_mfma_f32_16x16x32_bf16 v[70:73], v[176:179], v[224:227], v[70:73]
	s_setprio 0
	s_setprio 1
	v_mfma_f32_16x16x32_bf16 v[126:129], v[180:183], v[196:199], v[126:129]
	v_mfma_f32_16x16x32_bf16 v[114:117], v[188:191], v[196:199], v[114:117]
	v_mfma_f32_16x16x32_bf16 v[106:109], v[180:183], v[204:207], v[106:109]
	v_mfma_f32_16x16x32_bf16 v[98:101], v[188:191], v[204:207], v[98:101]
	v_mfma_f32_16x16x32_bf16 v[90:93], v[180:183], v[212:215], v[90:93]
	v_mfma_f32_16x16x32_bf16 v[82:85], v[188:191], v[212:215], v[82:85]
	v_mfma_f32_16x16x32_bf16 v[74:77], v[180:183], v[220:223], v[74:77]
	v_mfma_f32_16x16x32_bf16 v[66:69], v[188:191], v[220:223], v[66:69]
	v_mfma_f32_16x16x32_bf16 v[126:129], v[184:187], v[200:203], v[126:129]
	v_mfma_f32_16x16x32_bf16 v[114:117], v[192:195], v[200:203], v[114:117]
	v_mfma_f32_16x16x32_bf16 v[106:109], v[184:187], v[208:211], v[106:109]
	v_mfma_f32_16x16x32_bf16 v[98:101], v[192:195], v[208:211], v[98:101]
	v_mfma_f32_16x16x32_bf16 v[90:93], v[184:187], v[216:219], v[90:93]
	v_mfma_f32_16x16x32_bf16 v[82:85], v[192:195], v[216:219], v[82:85]
	v_mfma_f32_16x16x32_bf16 v[74:77], v[184:187], v[224:227], v[74:77]
	v_mfma_f32_16x16x32_bf16 v[66:69], v[192:195], v[224:227], v[66:69]
	s_barrier
	s_setprio 0
	s_add_u32 s98, s96, 0x40000
	s_addc_u32 s99, s97, 0
	s_mov_b32 m0, s78
	s_nop 0
	global_load_lds_dwordx4 v132, s[96:97]
	s_mov_b32 m0, s79
	s_add_i32 s7, s75, s29
	global_load_lds_dwordx4 v136, s[96:97]
	s_mov_b32 m0, s7
	s_nop 0
	global_load_lds_dwordx4 v132, s[98:99]
	s_add_i32 m0, s7, 0x2000
	s_nop 0
	global_load_lds_dwordx4 v136, s[98:99]
	s_mov_b32 m0, s51
	s_nop 0
	global_load_lds_dwordx4 v130, s[94:95]
	s_mov_b32 m0, s60
	s_nop 0
	global_load_lds_dwordx4 v134, s[94:95]
	ds_read_b128 v[196:199], v160 offset:16384
	ds_read_b128 v[200:203], v160 offset:17408
	ds_read_b128 v[204:207], v160 offset:18432
	ds_read_b128 v[208:211], v160 offset:19456
	ds_read_b128 v[212:215], v160 offset:20480
	ds_read_b128 v[216:219], v160 offset:21504
	ds_read_b128 v[220:223], v160 offset:22528
	ds_read_b128 v[224:227], v160 offset:23552
	s_waitcnt vmcnt(8)
	s_waitcnt lgkmcnt(0)
	.p2align 3
	s_setprio 1
	s_barrier
	v_mfma_f32_16x16x32_bf16 v[62:65], v[164:167], v[196:199], v[62:65]
	v_mfma_f32_16x16x32_bf16 v[54:57], v[172:175], v[196:199], v[54:57]
	v_mfma_f32_16x16x32_bf16 v[46:49], v[164:167], v[204:207], v[46:49]
	v_mfma_f32_16x16x32_bf16 v[38:41], v[172:175], v[204:207], v[38:41]
	v_mfma_f32_16x16x32_bf16 v[30:33], v[164:167], v[212:215], v[30:33]
	v_mfma_f32_16x16x32_bf16 v[22:25], v[172:175], v[212:215], v[22:25]
	v_mfma_f32_16x16x32_bf16 v[14:17], v[164:167], v[220:223], v[14:17]
	v_mfma_f32_16x16x32_bf16 v[6:9], v[172:175], v[220:223], v[6:9]
	v_mfma_f32_16x16x32_bf16 v[62:65], v[168:171], v[200:203], v[62:65]
	v_mfma_f32_16x16x32_bf16 v[54:57], v[176:179], v[200:203], v[54:57]
	v_mfma_f32_16x16x32_bf16 v[46:49], v[168:171], v[208:211], v[46:49]
	v_mfma_f32_16x16x32_bf16 v[38:41], v[176:179], v[208:211], v[38:41]
	v_mfma_f32_16x16x32_bf16 v[30:33], v[168:171], v[216:219], v[30:33]
	v_mfma_f32_16x16x32_bf16 v[22:25], v[176:179], v[216:219], v[22:25]
	v_mfma_f32_16x16x32_bf16 v[14:17], v[168:171], v[224:227], v[14:17]
	v_mfma_f32_16x16x32_bf16 v[6:9], v[176:179], v[224:227], v[6:9]
	s_setprio 0
	s_setprio 1
	v_mfma_f32_16x16x32_bf16 v[58:61], v[180:183], v[196:199], v[58:61]
	v_mfma_f32_16x16x32_bf16 v[50:53], v[188:191], v[196:199], v[50:53]
	v_mfma_f32_16x16x32_bf16 v[42:45], v[180:183], v[204:207], v[42:45]
	v_mfma_f32_16x16x32_bf16 v[34:37], v[188:191], v[204:207], v[34:37]
	v_mfma_f32_16x16x32_bf16 v[26:29], v[180:183], v[212:215], v[26:29]
	v_mfma_f32_16x16x32_bf16 v[18:21], v[188:191], v[212:215], v[18:21]
	v_mfma_f32_16x16x32_bf16 v[10:13], v[180:183], v[220:223], v[10:13]
	v_mfma_f32_16x16x32_bf16 v[2:5], v[188:191], v[220:223], v[2:5]
	v_mfma_f32_16x16x32_bf16 v[58:61], v[184:187], v[200:203], v[58:61]
	v_mfma_f32_16x16x32_bf16 v[50:53], v[192:195], v[200:203], v[50:53]
	v_mfma_f32_16x16x32_bf16 v[42:45], v[184:187], v[208:211], v[42:45]
	v_mfma_f32_16x16x32_bf16 v[34:37], v[192:195], v[208:211], v[34:37]
	v_mfma_f32_16x16x32_bf16 v[26:29], v[184:187], v[216:219], v[26:29]
	v_mfma_f32_16x16x32_bf16 v[18:21], v[192:195], v[216:219], v[18:21]
	v_mfma_f32_16x16x32_bf16 v[10:13], v[184:187], v[224:227], v[10:13]
	v_mfma_f32_16x16x32_bf16 v[2:5], v[192:195], v[224:227], v[2:5]
	s_barrier
	s_setprio 0
	s_add_u32 s98, s94, 0x40000
	s_addc_u32 s99, s95, 0
	s_add_i32 s7, 0, 0x18000
	s_add_i32 s49, 0, 0x1c000
	s_mov_b32 m0, s61
	s_nop 0
	global_load_lds_dwordx4 v130, s[98:99]
	s_mov_b32 m0, s62
	s_nop 0
	global_load_lds_dwordx4 v134, s[98:99]
	ds_read_b128 v[164:167], v232
	ds_read_b128 v[168:171], v232 offset:1024
	ds_read_b128 v[172:175], v232 offset:2048
	ds_read_b128 v[176:179], v232 offset:3072
	ds_read_b128 v[180:183], v233
	ds_read_b128 v[184:187], v233 offset:1024
	ds_read_b128 v[188:191], v233 offset:2048
	ds_read_b128 v[192:195], v233 offset:3072
	ds_read_b128 v[196:199], v160 offset:32768
	ds_read_b128 v[200:203], v160 offset:33792
	ds_read_b128 v[204:207], v160 offset:34816
	ds_read_b128 v[208:211], v160 offset:35840
	ds_read_b128 v[212:215], v160 offset:36864
	ds_read_b128 v[216:219], v160 offset:37888
	ds_read_b128 v[220:223], v160 offset:38912
	ds_read_b128 v[224:227], v160 offset:39936
	s_waitcnt vmcnt(8)
	s_waitcnt lgkmcnt(0)
	.p2align 3
	s_setprio 1
	s_barrier
	v_mfma_f32_16x16x32_bf16 v[122:125], v[164:167], v[196:199], v[122:125]
	v_mfma_f32_16x16x32_bf16 v[118:121], v[172:175], v[196:199], v[118:121]
	v_mfma_f32_16x16x32_bf16 v[110:113], v[164:167], v[204:207], v[110:113]
	v_mfma_f32_16x16x32_bf16 v[102:105], v[172:175], v[204:207], v[102:105]
	v_mfma_f32_16x16x32_bf16 v[94:97], v[164:167], v[212:215], v[94:97]
	v_mfma_f32_16x16x32_bf16 v[86:89], v[172:175], v[212:215], v[86:89]
	v_mfma_f32_16x16x32_bf16 v[78:81], v[164:167], v[220:223], v[78:81]
	v_mfma_f32_16x16x32_bf16 v[70:73], v[172:175], v[220:223], v[70:73]
	v_mfma_f32_16x16x32_bf16 v[122:125], v[168:171], v[200:203], v[122:125]
	v_mfma_f32_16x16x32_bf16 v[118:121], v[176:179], v[200:203], v[118:121]
	v_mfma_f32_16x16x32_bf16 v[110:113], v[168:171], v[208:211], v[110:113]
	v_mfma_f32_16x16x32_bf16 v[102:105], v[176:179], v[208:211], v[102:105]
	v_mfma_f32_16x16x32_bf16 v[94:97], v[168:171], v[216:219], v[94:97]
	v_mfma_f32_16x16x32_bf16 v[86:89], v[176:179], v[216:219], v[86:89]
	v_mfma_f32_16x16x32_bf16 v[78:81], v[168:171], v[224:227], v[78:81]
	v_mfma_f32_16x16x32_bf16 v[70:73], v[176:179], v[224:227], v[70:73]
	s_setprio 0
	s_setprio 1
	v_mfma_f32_16x16x32_bf16 v[126:129], v[180:183], v[196:199], v[126:129]
	v_mfma_f32_16x16x32_bf16 v[114:117], v[188:191], v[196:199], v[114:117]
	v_mfma_f32_16x16x32_bf16 v[106:109], v[180:183], v[204:207], v[106:109]
	v_mfma_f32_16x16x32_bf16 v[98:101], v[188:191], v[204:207], v[98:101]
	v_mfma_f32_16x16x32_bf16 v[90:93], v[180:183], v[212:215], v[90:93]
	v_mfma_f32_16x16x32_bf16 v[82:85], v[188:191], v[212:215], v[82:85]
	v_mfma_f32_16x16x32_bf16 v[74:77], v[180:183], v[220:223], v[74:77]
	v_mfma_f32_16x16x32_bf16 v[66:69], v[188:191], v[220:223], v[66:69]
	v_mfma_f32_16x16x32_bf16 v[126:129], v[184:187], v[200:203], v[126:129]
	v_mfma_f32_16x16x32_bf16 v[114:117], v[192:195], v[200:203], v[114:117]
	v_mfma_f32_16x16x32_bf16 v[106:109], v[184:187], v[208:211], v[106:109]
	v_mfma_f32_16x16x32_bf16 v[98:101], v[192:195], v[208:211], v[98:101]
	v_mfma_f32_16x16x32_bf16 v[90:93], v[184:187], v[216:219], v[90:93]
	v_mfma_f32_16x16x32_bf16 v[82:85], v[192:195], v[216:219], v[82:85]
	v_mfma_f32_16x16x32_bf16 v[74:77], v[184:187], v[224:227], v[74:77]
	v_mfma_f32_16x16x32_bf16 v[66:69], v[192:195], v[224:227], v[66:69]
	s_barrier
	s_setprio 0
	s_add_u32 s96, s96, 0x80
	s_addc_u32 s97, s97, 0
	s_add_u32 s98, s96, 0x40000
	s_addc_u32 s99, s97, 0
	s_add_u32 s94, s94, 0x80
	s_addc_u32 s95, s95, 0
	s_add_i32 s7, s7, s29
	s_mov_b32 m0, s7
	s_nop 0
	global_load_lds_dwordx4 v132, s[96:97]
	s_add_i32 m0, s7, 0x2000
	s_add_i32 s7, s49, s29
	global_load_lds_dwordx4 v136, s[96:97]
	s_mov_b32 m0, s7
	s_nop 0
	global_load_lds_dwordx4 v132, s[98:99]
	s_add_i32 m0, s7, 0x2000
	s_nop 0
	global_load_lds_dwordx4 v136, s[98:99]
	s_mov_b32 m0, s63
	s_nop 0
	global_load_lds_dwordx4 v130, s[94:95]
	s_mov_b32 m0, s64
	s_nop 0
	global_load_lds_dwordx4 v134, s[94:95]
	ds_read_b128 v[196:199], v160 offset:49152
	ds_read_b128 v[200:203], v160 offset:50176
	ds_read_b128 v[204:207], v160 offset:51200
	ds_read_b128 v[208:211], v160 offset:52224
	ds_read_b128 v[212:215], v160 offset:53248
	ds_read_b128 v[216:219], v160 offset:54272
	ds_read_b128 v[220:223], v160 offset:55296
	ds_read_b128 v[224:227], v160 offset:56320
	s_waitcnt vmcnt(8)
	s_waitcnt lgkmcnt(0)
	.p2align 3
	s_setprio 1
	s_barrier
	v_mfma_f32_16x16x32_bf16 v[62:65], v[164:167], v[196:199], v[62:65]
	v_mfma_f32_16x16x32_bf16 v[54:57], v[172:175], v[196:199], v[54:57]
	v_mfma_f32_16x16x32_bf16 v[46:49], v[164:167], v[204:207], v[46:49]
	v_mfma_f32_16x16x32_bf16 v[38:41], v[172:175], v[204:207], v[38:41]
	v_mfma_f32_16x16x32_bf16 v[30:33], v[164:167], v[212:215], v[30:33]
	v_mfma_f32_16x16x32_bf16 v[22:25], v[172:175], v[212:215], v[22:25]
	v_mfma_f32_16x16x32_bf16 v[14:17], v[164:167], v[220:223], v[14:17]
	v_mfma_f32_16x16x32_bf16 v[6:9], v[172:175], v[220:223], v[6:9]
	v_mfma_f32_16x16x32_bf16 v[62:65], v[168:171], v[200:203], v[62:65]
	v_mfma_f32_16x16x32_bf16 v[54:57], v[176:179], v[200:203], v[54:57]
	v_mfma_f32_16x16x32_bf16 v[46:49], v[168:171], v[208:211], v[46:49]
	v_mfma_f32_16x16x32_bf16 v[38:41], v[176:179], v[208:211], v[38:41]
	v_mfma_f32_16x16x32_bf16 v[30:33], v[168:171], v[216:219], v[30:33]
	v_mfma_f32_16x16x32_bf16 v[22:25], v[176:179], v[216:219], v[22:25]
	v_mfma_f32_16x16x32_bf16 v[14:17], v[168:171], v[224:227], v[14:17]
	v_mfma_f32_16x16x32_bf16 v[6:9], v[176:179], v[224:227], v[6:9]
	s_setprio 0
	s_setprio 1
	v_mfma_f32_16x16x32_bf16 v[58:61], v[180:183], v[196:199], v[58:61]
	v_mfma_f32_16x16x32_bf16 v[50:53], v[188:191], v[196:199], v[50:53]
	v_mfma_f32_16x16x32_bf16 v[42:45], v[180:183], v[204:207], v[42:45]
	v_mfma_f32_16x16x32_bf16 v[34:37], v[188:191], v[204:207], v[34:37]
	v_mfma_f32_16x16x32_bf16 v[26:29], v[180:183], v[212:215], v[26:29]
	v_mfma_f32_16x16x32_bf16 v[18:21], v[188:191], v[212:215], v[18:21]
	v_mfma_f32_16x16x32_bf16 v[10:13], v[180:183], v[220:223], v[10:13]
	v_mfma_f32_16x16x32_bf16 v[2:5], v[188:191], v[220:223], v[2:5]
	v_mfma_f32_16x16x32_bf16 v[58:61], v[184:187], v[200:203], v[58:61]
	v_mfma_f32_16x16x32_bf16 v[50:53], v[192:195], v[200:203], v[50:53]
	v_mfma_f32_16x16x32_bf16 v[42:45], v[184:187], v[208:211], v[42:45]
	v_mfma_f32_16x16x32_bf16 v[34:37], v[192:195], v[208:211], v[34:37]
	v_mfma_f32_16x16x32_bf16 v[26:29], v[184:187], v[216:219], v[26:29]
	v_mfma_f32_16x16x32_bf16 v[18:21], v[192:195], v[216:219], v[18:21]
	v_mfma_f32_16x16x32_bf16 v[10:13], v[184:187], v[224:227], v[10:13]
	v_mfma_f32_16x16x32_bf16 v[2:5], v[192:195], v[224:227], v[2:5]
	s_barrier
	s_setprio 0
	s_mov_b32 s7, s47
	s_add_u32 s88, s88, 0x100
	s_addc_u32 s89, s89, 0
	s_add_u32 s86, s86, 0x100
	s_addc_u32 s87, s87, 0
	s_cmp_ge_i32 s47, s101
	s_cbranch_scc0 .LBB0_949

.Lmy_nb_5:
	s_nop 0
	v_readfirstlane_b32 s86, v150
	v_readfirstlane_b32 s87, v151
	v_readfirstlane_b32 s88, v152
	v_readfirstlane_b32 s89, v153
	v_readfirstlane_b32 s90, v146
	v_readfirstlane_b32 s91, v147
	v_readfirstlane_b32 s92, v148
	v_readfirstlane_b32 s93, v149
	v_readfirstlane_b32 s100, v138
	v_readfirstlane_b32 s101, v156
	v_add_u32_e32 v230, s67, v141
	v_add_u32_e32 v231, s68, v141
	v_add_u32_e32 v232, 0x18000, v141
	v_add_u32_e32 v233, 0x1c000, v141
	s_add_u32 s98, s86, 0x100
	s_addc_u32 s99, s87, 0
	s_cmp_eq_u32 s6, s100
	s_cselect_b64 s[94:95], s[90:91], s[98:99]
	s_cselect_b64 s[96:97], s[92:93], s[88:89]
	s_add_i32 s7, s6, 2
	s_nop 0
	s_add_i32 m0, s46, 0xc000
	s_nop 0
	global_load_lds_dwordx4 v144, s[86:87]
	s_add_i32 m0, s46, 0xe000
	s_nop 0
	global_load_lds_dwordx4 v142, s[86:87]
	ds_read_b128 v[164:167], v230
	ds_read_b128 v[168:171], v230 offset:1024
	ds_read_b128 v[172:175], v230 offset:2048
	ds_read_b128 v[176:179], v230 offset:3072
	ds_read_b128 v[180:183], v231
	ds_read_b128 v[184:187], v231 offset:1024
	ds_read_b128 v[188:191], v231 offset:2048
	ds_read_b128 v[192:195], v231 offset:3072
	ds_read_b128 v[196:199], v160
	ds_read_b128 v[200:203], v160 offset:1024
	ds_read_b128 v[204:207], v160 offset:2048
	ds_read_b128 v[208:211], v160 offset:3072
	ds_read_b128 v[212:215], v160 offset:4096
	ds_read_b128 v[216:219], v160 offset:5120
	ds_read_b128 v[220:223], v160 offset:6144
	ds_read_b128 v[224:227], v160 offset:7168
	s_waitcnt vmcnt(8)
	s_waitcnt lgkmcnt(0)
	.p2align 3
	s_setprio 1
	s_barrier
	v_mfma_f32_16x16x32_bf16 v[122:125], v[164:167], v[196:199], 0
	v_mfma_f32_16x16x32_bf16 v[118:121], v[172:175], v[196:199], 0
	v_mfma_f32_16x16x32_bf16 v[110:113], v[164:167], v[204:207], 0
	v_mfma_f32_16x16x32_bf16 v[102:105], v[172:175], v[204:207], 0
	v_mfma_f32_16x16x32_bf16 v[94:97], v[164:167], v[212:215], 0
	v_mfma_f32_16x16x32_bf16 v[86:89], v[172:175], v[212:215], 0
	v_mfma_f32_16x16x32_bf16 v[78:81], v[164:167], v[220:223], 0
	v_mfma_f32_16x16x32_bf16 v[70:73], v[172:175], v[220:223], 0
	v_mfma_f32_16x16x32_bf16 v[122:125], v[168:171], v[200:203], v[122:125]
	v_mfma_f32_16x16x32_bf16 v[118:121], v[176:179], v[200:203], v[118:121]
	v_mfma_f32_16x16x32_bf16 v[110:113], v[168:171], v[208:211], v[110:113]
	v_mfma_f32_16x16x32_bf16 v[102:105], v[176:179], v[208:211], v[102:105]
	v_mfma_f32_16x16x32_bf16 v[94:97], v[168:171], v[216:219], v[94:97]
	v_mfma_f32_16x16x32_bf16 v[86:89], v[176:179], v[216:219], v[86:89]
	v_mfma_f32_16x16x32_bf16 v[78:81], v[168:171], v[224:227], v[78:81]
	v_mfma_f32_16x16x32_bf16 v[70:73], v[176:179], v[224:227], v[70:73]
	s_setprio 0
	s_setprio 1
	v_mfma_f32_16x16x32_bf16 v[126:129], v[180:183], v[196:199], 0
	v_mfma_f32_16x16x32_bf16 v[114:117], v[188:191], v[196:199], 0
	v_mfma_f32_16x16x32_bf16 v[106:109], v[180:183], v[204:207], 0
	v_mfma_f32_16x16x32_bf16 v[98:101], v[188:191], v[204:207], 0
	v_mfma_f32_16x16x32_bf16 v[90:93], v[180:183], v[212:215], 0
	v_mfma_f32_16x16x32_bf16 v[82:85], v[188:191], v[212:215], 0
	v_mfma_f32_16x16x32_bf16 v[74:77], v[180:183], v[220:223], 0
	v_mfma_f32_16x16x32_bf16 v[66:69], v[188:191], v[220:223], 0
	v_mfma_f32_16x16x32_bf16 v[126:129], v[184:187], v[200:203], v[126:129]
	v_mfma_f32_16x16x32_bf16 v[114:117], v[192:195], v[200:203], v[114:117]
	v_mfma_f32_16x16x32_bf16 v[106:109], v[184:187], v[208:211], v[106:109]
	v_mfma_f32_16x16x32_bf16 v[98:101], v[192:195], v[208:211], v[98:101]
	v_mfma_f32_16x16x32_bf16 v[90:93], v[184:187], v[216:219], v[90:93]
	v_mfma_f32_16x16x32_bf16 v[82:85], v[192:195], v[216:219], v[82:85]
	v_mfma_f32_16x16x32_bf16 v[74:77], v[184:187], v[224:227], v[74:77]
	v_mfma_f32_16x16x32_bf16 v[66:69], v[192:195], v[224:227], v[66:69]
	s_barrier
	s_setprio 0
	s_add_u32 s98, s96, 0xb0000
	s_addc_u32 s99, s97, 0
	s_add_i32 s6, s67, s23
	s_mov_b32 m0, s6
	s_nop 0
	global_load_lds_dwordx4 v132, s[96:97]
	s_add_i32 m0, s6, 0x2000
	s_add_i32 s6, s68, s23
	global_load_lds_dwordx4 v136, s[96:97]
	s_mov_b32 m0, s6
	s_nop 0
	global_load_lds_dwordx4 v132, s[98:99]
	s_add_i32 m0, s6, 0x2000
	s_nop 0
	global_load_lds_dwordx4 v136, s[98:99]
	s_mov_b32 m0, s46
	s_nop 0
	global_load_lds_dwordx4 v130, s[94:95]
	s_mov_b32 m0, s47
	s_nop 0
	global_load_lds_dwordx4 v134, s[94:95]
	ds_read_b128 v[196:199], v160 offset:16384
	ds_read_b128 v[200:203], v160 offset:17408
	ds_read_b128 v[204:207], v160 offset:18432
	ds_read_b128 v[208:211], v160 offset:19456
	ds_read_b128 v[212:215], v160 offset:20480
	ds_read_b128 v[216:219], v160 offset:21504
	ds_read_b128 v[220:223], v160 offset:22528
	ds_read_b128 v[224:227], v160 offset:23552
	s_waitcnt vmcnt(8)
	s_waitcnt lgkmcnt(0)
	.p2align 3
	s_setprio 1
	s_barrier
	v_mfma_f32_16x16x32_bf16 v[62:65], v[164:167], v[196:199], 0
	v_mfma_f32_16x16x32_bf16 v[54:57], v[172:175], v[196:199], 0
	v_mfma_f32_16x16x32_bf16 v[46:49], v[164:167], v[204:207], 0
	v_mfma_f32_16x16x32_bf16 v[38:41], v[172:175], v[204:207], 0
	v_mfma_f32_16x16x32_bf16 v[30:33], v[164:167], v[212:215], 0
	v_mfma_f32_16x16x32_bf16 v[22:25], v[172:175], v[212:215], 0
	v_mfma_f32_16x16x32_bf16 v[14:17], v[164:167], v[220:223], 0
	v_mfma_f32_16x16x32_bf16 v[6:9], v[172:175], v[220:223], 0
	v_mfma_f32_16x16x32_bf16 v[62:65], v[168:171], v[200:203], v[62:65]
	v_mfma_f32_16x16x32_bf16 v[54:57], v[176:179], v[200:203], v[54:57]
	v_mfma_f32_16x16x32_bf16 v[46:49], v[168:171], v[208:211], v[46:49]
	v_mfma_f32_16x16x32_bf16 v[38:41], v[176:179], v[208:211], v[38:41]
	v_mfma_f32_16x16x32_bf16 v[30:33], v[168:171], v[216:219], v[30:33]
	v_mfma_f32_16x16x32_bf16 v[22:25], v[176:179], v[216:219], v[22:25]
	v_mfma_f32_16x16x32_bf16 v[14:17], v[168:171], v[224:227], v[14:17]
	v_mfma_f32_16x16x32_bf16 v[6:9], v[176:179], v[224:227], v[6:9]
	s_setprio 0
	s_setprio 1
	v_mfma_f32_16x16x32_bf16 v[58:61], v[180:183], v[196:199], 0
	v_mfma_f32_16x16x32_bf16 v[50:53], v[188:191], v[196:199], 0
	v_mfma_f32_16x16x32_bf16 v[42:45], v[180:183], v[204:207], 0
	v_mfma_f32_16x16x32_bf16 v[34:37], v[188:191], v[204:207], 0
	v_mfma_f32_16x16x32_bf16 v[26:29], v[180:183], v[212:215], 0
	v_mfma_f32_16x16x32_bf16 v[18:21], v[188:191], v[212:215], 0
	v_mfma_f32_16x16x32_bf16 v[10:13], v[180:183], v[220:223], 0
	v_mfma_f32_16x16x32_bf16 v[2:5], v[188:191], v[220:223], 0
	v_mfma_f32_16x16x32_bf16 v[58:61], v[184:187], v[200:203], v[58:61]
	v_mfma_f32_16x16x32_bf16 v[50:53], v[192:195], v[200:203], v[50:53]
	v_mfma_f32_16x16x32_bf16 v[42:45], v[184:187], v[208:211], v[42:45]
	v_mfma_f32_16x16x32_bf16 v[34:37], v[192:195], v[208:211], v[34:37]
	v_mfma_f32_16x16x32_bf16 v[26:29], v[184:187], v[216:219], v[26:29]
	v_mfma_f32_16x16x32_bf16 v[18:21], v[192:195], v[216:219], v[18:21]
	v_mfma_f32_16x16x32_bf16 v[10:13], v[184:187], v[224:227], v[10:13]
	v_mfma_f32_16x16x32_bf16 v[2:5], v[192:195], v[224:227], v[2:5]
	s_barrier
	s_setprio 0
	s_add_u32 s98, s94, 0xb0000
	s_addc_u32 s99, s95, 0
	s_add_i32 s6, 0, 0x18000
	s_add_i32 s29, 0, 0x1c000
	s_mov_b32 m0, s48
	s_nop 0
	global_load_lds_dwordx4 v130, s[98:99]
	s_mov_b32 m0, s49
	s_nop 0
	global_load_lds_dwordx4 v134, s[98:99]
	ds_read_b128 v[164:167], v232
	ds_read_b128 v[168:171], v232 offset:1024
	ds_read_b128 v[172:175], v232 offset:2048
	ds_read_b128 v[176:179], v232 offset:3072
	ds_read_b128 v[180:183], v233
	ds_read_b128 v[184:187], v233 offset:1024
	ds_read_b128 v[188:191], v233 offset:2048
	ds_read_b128 v[192:195], v233 offset:3072
	ds_read_b128 v[196:199], v160 offset:32768
	ds_read_b128 v[200:203], v160 offset:33792
	ds_read_b128 v[204:207], v160 offset:34816
	ds_read_b128 v[208:211], v160 offset:35840
	ds_read_b128 v[212:215], v160 offset:36864
	ds_read_b128 v[216:219], v160 offset:37888
	ds_read_b128 v[220:223], v160 offset:38912
	ds_read_b128 v[224:227], v160 offset:39936
	s_waitcnt vmcnt(8)
	s_waitcnt lgkmcnt(0)
	.p2align 3
	s_setprio 1
	s_barrier
	v_mfma_f32_16x16x32_bf16 v[122:125], v[164:167], v[196:199], v[122:125]
	v_mfma_f32_16x16x32_bf16 v[118:121], v[172:175], v[196:199], v[118:121]
	v_mfma_f32_16x16x32_bf16 v[110:113], v[164:167], v[204:207], v[110:113]
	v_mfma_f32_16x16x32_bf16 v[102:105], v[172:175], v[204:207], v[102:105]
	v_mfma_f32_16x16x32_bf16 v[94:97], v[164:167], v[212:215], v[94:97]
	v_mfma_f32_16x16x32_bf16 v[86:89], v[172:175], v[212:215], v[86:89]
	v_mfma_f32_16x16x32_bf16 v[78:81], v[164:167], v[220:223], v[78:81]
	v_mfma_f32_16x16x32_bf16 v[70:73], v[172:175], v[220:223], v[70:73]
	v_mfma_f32_16x16x32_bf16 v[122:125], v[168:171], v[200:203], v[122:125]
	v_mfma_f32_16x16x32_bf16 v[118:121], v[176:179], v[200:203], v[118:121]
	v_mfma_f32_16x16x32_bf16 v[110:113], v[168:171], v[208:211], v[110:113]
	v_mfma_f32_16x16x32_bf16 v[102:105], v[176:179], v[208:211], v[102:105]
	v_mfma_f32_16x16x32_bf16 v[94:97], v[168:171], v[216:219], v[94:97]
	v_mfma_f32_16x16x32_bf16 v[86:89], v[176:179], v[216:219], v[86:89]
	v_mfma_f32_16x16x32_bf16 v[78:81], v[168:171], v[224:227], v[78:81]
	v_mfma_f32_16x16x32_bf16 v[70:73], v[176:179], v[224:227], v[70:73]
	s_setprio 0
	s_setprio 1
	v_mfma_f32_16x16x32_bf16 v[126:129], v[180:183], v[196:199], v[126:129]
	v_mfma_f32_16x16x32_bf16 v[114:117], v[188:191], v[196:199], v[114:117]
	v_mfma_f32_16x16x32_bf16 v[106:109], v[180:183], v[204:207], v[106:109]
	v_mfma_f32_16x16x32_bf16 v[98:101], v[188:191], v[204:207], v[98:101]
	v_mfma_f32_16x16x32_bf16 v[90:93], v[180:183], v[212:215], v[90:93]
	v_mfma_f32_16x16x32_bf16 v[82:85], v[188:191], v[212:215], v[82:85]
	v_mfma_f32_16x16x32_bf16 v[74:77], v[180:183], v[220:223], v[74:77]
	v_mfma_f32_16x16x32_bf16 v[66:69], v[188:191], v[220:223], v[66:69]
	v_mfma_f32_16x16x32_bf16 v[126:129], v[184:187], v[200:203], v[126:129]
	v_mfma_f32_16x16x32_bf16 v[114:117], v[192:195], v[200:203], v[114:117]
	v_mfma_f32_16x16x32_bf16 v[106:109], v[184:187], v[208:211], v[106:109]
	v_mfma_f32_16x16x32_bf16 v[98:101], v[192:195], v[208:211], v[98:101]
	v_mfma_f32_16x16x32_bf16 v[90:93], v[184:187], v[216:219], v[90:93]
	v_mfma_f32_16x16x32_bf16 v[82:85], v[192:195], v[216:219], v[82:85]
	v_mfma_f32_16x16x32_bf16 v[74:77], v[184:187], v[224:227], v[74:77]
	v_mfma_f32_16x16x32_bf16 v[66:69], v[192:195], v[224:227], v[66:69]
	s_barrier
	s_setprio 0
	s_add_u32 s96, s96, 0x80
	s_addc_u32 s97, s97, 0
	s_add_u32 s98, s96, 0xb0000
	s_addc_u32 s99, s97, 0
	s_add_u32 s94, s94, 0x80
	s_addc_u32 s95, s95, 0
	s_add_i32 s6, s6, s23
	s_mov_b32 m0, s6
	s_nop 0
	global_load_lds_dwordx4 v132, s[96:97]
	s_add_i32 m0, s6, 0x2000
	s_add_i32 s6, s29, s23
	global_load_lds_dwordx4 v136, s[96:97]
	s_mov_b32 m0, s6
	s_nop 0
	global_load_lds_dwordx4 v132, s[98:99]
	s_add_i32 m0, s6, 0x2000
	s_nop 0
	global_load_lds_dwordx4 v136, s[98:99]
	s_mov_b32 m0, s59
	s_nop 0
	global_load_lds_dwordx4 v130, s[94:95]
	s_mov_b32 m0, s60
	s_nop 0
	global_load_lds_dwordx4 v134, s[94:95]
	ds_read_b128 v[196:199], v160 offset:49152
	ds_read_b128 v[200:203], v160 offset:50176
	ds_read_b128 v[204:207], v160 offset:51200
	ds_read_b128 v[208:211], v160 offset:52224
	ds_read_b128 v[212:215], v160 offset:53248
	ds_read_b128 v[216:219], v160 offset:54272
	ds_read_b128 v[220:223], v160 offset:55296
	ds_read_b128 v[224:227], v160 offset:56320
	s_waitcnt vmcnt(8)
	s_waitcnt lgkmcnt(0)
	.p2align 3
	s_setprio 1
	s_barrier
	v_mfma_f32_16x16x32_bf16 v[62:65], v[164:167], v[196:199], v[62:65]
	v_mfma_f32_16x16x32_bf16 v[54:57], v[172:175], v[196:199], v[54:57]
	v_mfma_f32_16x16x32_bf16 v[46:49], v[164:167], v[204:207], v[46:49]
	v_mfma_f32_16x16x32_bf16 v[38:41], v[172:175], v[204:207], v[38:41]
	v_mfma_f32_16x16x32_bf16 v[30:33], v[164:167], v[212:215], v[30:33]
	v_mfma_f32_16x16x32_bf16 v[22:25], v[172:175], v[212:215], v[22:25]
	v_mfma_f32_16x16x32_bf16 v[14:17], v[164:167], v[220:223], v[14:17]
	v_mfma_f32_16x16x32_bf16 v[6:9], v[172:175], v[220:223], v[6:9]
	v_mfma_f32_16x16x32_bf16 v[62:65], v[168:171], v[200:203], v[62:65]
	v_mfma_f32_16x16x32_bf16 v[54:57], v[176:179], v[200:203], v[54:57]
	v_mfma_f32_16x16x32_bf16 v[46:49], v[168:171], v[208:211], v[46:49]
	v_mfma_f32_16x16x32_bf16 v[38:41], v[176:179], v[208:211], v[38:41]
	v_mfma_f32_16x16x32_bf16 v[30:33], v[168:171], v[216:219], v[30:33]
	v_mfma_f32_16x16x32_bf16 v[22:25], v[176:179], v[216:219], v[22:25]
	v_mfma_f32_16x16x32_bf16 v[14:17], v[168:171], v[224:227], v[14:17]
	v_mfma_f32_16x16x32_bf16 v[6:9], v[176:179], v[224:227], v[6:9]
	s_setprio 0
	s_setprio 1
	v_mfma_f32_16x16x32_bf16 v[58:61], v[180:183], v[196:199], v[58:61]
	v_mfma_f32_16x16x32_bf16 v[50:53], v[188:191], v[196:199], v[50:53]
	v_mfma_f32_16x16x32_bf16 v[42:45], v[180:183], v[204:207], v[42:45]
	v_mfma_f32_16x16x32_bf16 v[34:37], v[188:191], v[204:207], v[34:37]
	v_mfma_f32_16x16x32_bf16 v[26:29], v[180:183], v[212:215], v[26:29]
	v_mfma_f32_16x16x32_bf16 v[18:21], v[188:191], v[212:215], v[18:21]
	v_mfma_f32_16x16x32_bf16 v[10:13], v[180:183], v[220:223], v[10:13]
	v_mfma_f32_16x16x32_bf16 v[2:5], v[188:191], v[220:223], v[2:5]
	v_mfma_f32_16x16x32_bf16 v[58:61], v[184:187], v[200:203], v[58:61]
	v_mfma_f32_16x16x32_bf16 v[50:53], v[192:195], v[200:203], v[50:53]
	v_mfma_f32_16x16x32_bf16 v[42:45], v[184:187], v[208:211], v[42:45]
	v_mfma_f32_16x16x32_bf16 v[34:37], v[192:195], v[208:211], v[34:37]
	v_mfma_f32_16x16x32_bf16 v[26:29], v[184:187], v[216:219], v[26:29]
	v_mfma_f32_16x16x32_bf16 v[18:21], v[192:195], v[216:219], v[18:21]
	v_mfma_f32_16x16x32_bf16 v[10:13], v[184:187], v[224:227], v[10:13]
	v_mfma_f32_16x16x32_bf16 v[2:5], v[192:195], v[224:227], v[2:5]
	s_barrier
	s_setprio 0
	s_mov_b32 s6, s7
	s_add_u32 s88, s88, 0x100
	s_addc_u32 s89, s89, 0
	s_add_u32 s86, s86, 0x100
	s_addc_u32 s87, s87, 0
	s_cmp_ge_i32 s7, s101
	s_cbranch_scc1 .Lmy_kexit_5
.LBB0_1080:
	s_add_u32 s98, s86, 0x100
	s_addc_u32 s99, s87, 0
	s_cmp_eq_u32 s6, s100
	s_cselect_b64 s[94:95], s[90:91], s[98:99]
	s_cselect_b64 s[96:97], s[92:93], s[88:89]
	s_add_i32 s7, s6, 2
	s_nop 0
	s_add_i32 m0, s46, 0xc000
	s_nop 0
	global_load_lds_dwordx4 v144, s[86:87]
	s_add_i32 m0, s46, 0xe000
	s_nop 0
	global_load_lds_dwordx4 v142, s[86:87]
	ds_read_b128 v[164:167], v230
	ds_read_b128 v[168:171], v230 offset:1024
	ds_read_b128 v[172:175], v230 offset:2048
	ds_read_b128 v[176:179], v230 offset:3072
	ds_read_b128 v[180:183], v231
	ds_read_b128 v[184:187], v231 offset:1024
	ds_read_b128 v[188:191], v231 offset:2048
	ds_read_b128 v[192:195], v231 offset:3072
	ds_read_b128 v[196:199], v160
	ds_read_b128 v[200:203], v160 offset:1024
	ds_read_b128 v[204:207], v160 offset:2048
	ds_read_b128 v[208:211], v160 offset:3072
	ds_read_b128 v[212:215], v160 offset:4096
	ds_read_b128 v[216:219], v160 offset:5120
	ds_read_b128 v[220:223], v160 offset:6144
	ds_read_b128 v[224:227], v160 offset:7168
	s_waitcnt vmcnt(8)
	s_waitcnt lgkmcnt(0)
	.p2align 3
	s_setprio 1
	s_barrier
	v_mfma_f32_16x16x32_bf16 v[122:125], v[164:167], v[196:199], v[122:125]
	v_mfma_f32_16x16x32_bf16 v[118:121], v[172:175], v[196:199], v[118:121]
	v_mfma_f32_16x16x32_bf16 v[110:113], v[164:167], v[204:207], v[110:113]
	v_mfma_f32_16x16x32_bf16 v[102:105], v[172:175], v[204:207], v[102:105]
	v_mfma_f32_16x16x32_bf16 v[94:97], v[164:167], v[212:215], v[94:97]
	v_mfma_f32_16x16x32_bf16 v[86:89], v[172:175], v[212:215], v[86:89]
	v_mfma_f32_16x16x32_bf16 v[78:81], v[164:167], v[220:223], v[78:81]
	v_mfma_f32_16x16x32_bf16 v[70:73], v[172:175], v[220:223], v[70:73]
	v_mfma_f32_16x16x32_bf16 v[122:125], v[168:171], v[200:203], v[122:125]
	v_mfma_f32_16x16x32_bf16 v[118:121], v[176:179], v[200:203], v[118:121]
	v_mfma_f32_16x16x32_bf16 v[110:113], v[168:171], v[208:211], v[110:113]
	v_mfma_f32_16x16x32_bf16 v[102:105], v[176:179], v[208:211], v[102:105]
	v_mfma_f32_16x16x32_bf16 v[94:97], v[168:171], v[216:219], v[94:97]
	v_mfma_f32_16x16x32_bf16 v[86:89], v[176:179], v[216:219], v[86:89]
	v_mfma_f32_16x16x32_bf16 v[78:81], v[168:171], v[224:227], v[78:81]
	v_mfma_f32_16x16x32_bf16 v[70:73], v[176:179], v[224:227], v[70:73]
	s_setprio 0
	s_setprio 1
	v_mfma_f32_16x16x32_bf16 v[126:129], v[180:183], v[196:199], v[126:129]
	v_mfma_f32_16x16x32_bf16 v[114:117], v[188:191], v[196:199], v[114:117]
	v_mfma_f32_16x16x32_bf16 v[106:109], v[180:183], v[204:207], v[106:109]
	v_mfma_f32_16x16x32_bf16 v[98:101], v[188:191], v[204:207], v[98:101]
	v_mfma_f32_16x16x32_bf16 v[90:93], v[180:183], v[212:215], v[90:93]
	v_mfma_f32_16x16x32_bf16 v[82:85], v[188:191], v[212:215], v[82:85]
	v_mfma_f32_16x16x32_bf16 v[74:77], v[180:183], v[220:223], v[74:77]
	v_mfma_f32_16x16x32_bf16 v[66:69], v[188:191], v[220:223], v[66:69]
	v_mfma_f32_16x16x32_bf16 v[126:129], v[184:187], v[200:203], v[126:129]
	v_mfma_f32_16x16x32_bf16 v[114:117], v[192:195], v[200:203], v[114:117]
	v_mfma_f32_16x16x32_bf16 v[106:109], v[184:187], v[208:211], v[106:109]
	v_mfma_f32_16x16x32_bf16 v[98:101], v[192:195], v[208:211], v[98:101]
	v_mfma_f32_16x16x32_bf16 v[90:93], v[184:187], v[216:219], v[90:93]
	v_mfma_f32_16x16x32_bf16 v[82:85], v[192:195], v[216:219], v[82:85]
	v_mfma_f32_16x16x32_bf16 v[74:77], v[184:187], v[224:227], v[74:77]
	v_mfma_f32_16x16x32_bf16 v[66:69], v[192:195], v[224:227], v[66:69]
	s_barrier
	s_setprio 0
	s_add_u32 s98, s96, 0xb0000
	s_addc_u32 s99, s97, 0
	s_add_i32 s6, s67, s23
	s_mov_b32 m0, s6
	s_nop 0
	global_load_lds_dwordx4 v132, s[96:97]
	s_add_i32 m0, s6, 0x2000
	s_add_i32 s6, s68, s23
	global_load_lds_dwordx4 v136, s[96:97]
	s_mov_b32 m0, s6
	s_nop 0
	global_load_lds_dwordx4 v132, s[98:99]
	s_add_i32 m0, s6, 0x2000
	s_nop 0
	global_load_lds_dwordx4 v136, s[98:99]
	s_mov_b32 m0, s46
	s_nop 0
	global_load_lds_dwordx4 v130, s[94:95]
	s_mov_b32 m0, s47
	s_nop 0
	global_load_lds_dwordx4 v134, s[94:95]
	ds_read_b128 v[196:199], v160 offset:16384
	ds_read_b128 v[200:203], v160 offset:17408
	ds_read_b128 v[204:207], v160 offset:18432
	ds_read_b128 v[208:211], v160 offset:19456
	ds_read_b128 v[212:215], v160 offset:20480
	ds_read_b128 v[216:219], v160 offset:21504
	ds_read_b128 v[220:223], v160 offset:22528
	ds_read_b128 v[224:227], v160 offset:23552
	s_waitcnt vmcnt(8)
	s_waitcnt lgkmcnt(0)
	.p2align 3
	s_setprio 1
	s_barrier
	v_mfma_f32_16x16x32_bf16 v[62:65], v[164:167], v[196:199], v[62:65]
	v_mfma_f32_16x16x32_bf16 v[54:57], v[172:175], v[196:199], v[54:57]
	v_mfma_f32_16x16x32_bf16 v[46:49], v[164:167], v[204:207], v[46:49]
	v_mfma_f32_16x16x32_bf16 v[38:41], v[172:175], v[204:207], v[38:41]
	v_mfma_f32_16x16x32_bf16 v[30:33], v[164:167], v[212:215], v[30:33]
	v_mfma_f32_16x16x32_bf16 v[22:25], v[172:175], v[212:215], v[22:25]
	v_mfma_f32_16x16x32_bf16 v[14:17], v[164:167], v[220:223], v[14:17]
	v_mfma_f32_16x16x32_bf16 v[6:9], v[172:175], v[220:223], v[6:9]
	v_mfma_f32_16x16x32_bf16 v[62:65], v[168:171], v[200:203], v[62:65]
	v_mfma_f32_16x16x32_bf16 v[54:57], v[176:179], v[200:203], v[54:57]
	v_mfma_f32_16x16x32_bf16 v[46:49], v[168:171], v[208:211], v[46:49]
	v_mfma_f32_16x16x32_bf16 v[38:41], v[176:179], v[208:211], v[38:41]
	v_mfma_f32_16x16x32_bf16 v[30:33], v[168:171], v[216:219], v[30:33]
	v_mfma_f32_16x16x32_bf16 v[22:25], v[176:179], v[216:219], v[22:25]
	v_mfma_f32_16x16x32_bf16 v[14:17], v[168:171], v[224:227], v[14:17]
	v_mfma_f32_16x16x32_bf16 v[6:9], v[176:179], v[224:227], v[6:9]
	s_setprio 0
	s_setprio 1
	v_mfma_f32_16x16x32_bf16 v[58:61], v[180:183], v[196:199], v[58:61]
	v_mfma_f32_16x16x32_bf16 v[50:53], v[188:191], v[196:199], v[50:53]
	v_mfma_f32_16x16x32_bf16 v[42:45], v[180:183], v[204:207], v[42:45]
	v_mfma_f32_16x16x32_bf16 v[34:37], v[188:191], v[204:207], v[34:37]
	v_mfma_f32_16x16x32_bf16 v[26:29], v[180:183], v[212:215], v[26:29]
	v_mfma_f32_16x16x32_bf16 v[18:21], v[188:191], v[212:215], v[18:21]
	v_mfma_f32_16x16x32_bf16 v[10:13], v[180:183], v[220:223], v[10:13]
	v_mfma_f32_16x16x32_bf16 v[2:5], v[188:191], v[220:223], v[2:5]
	v_mfma_f32_16x16x32_bf16 v[58:61], v[184:187], v[200:203], v[58:61]
	v_mfma_f32_16x16x32_bf16 v[50:53], v[192:195], v[200:203], v[50:53]
	v_mfma_f32_16x16x32_bf16 v[42:45], v[184:187], v[208:211], v[42:45]
	v_mfma_f32_16x16x32_bf16 v[34:37], v[192:195], v[208:211], v[34:37]
	v_mfma_f32_16x16x32_bf16 v[26:29], v[184:187], v[216:219], v[26:29]
	v_mfma_f32_16x16x32_bf16 v[18:21], v[192:195], v[216:219], v[18:21]
	v_mfma_f32_16x16x32_bf16 v[10:13], v[184:187], v[224:227], v[10:13]
	v_mfma_f32_16x16x32_bf16 v[2:5], v[192:195], v[224:227], v[2:5]
	s_barrier
	s_setprio 0
	s_add_u32 s98, s94, 0xb0000
	s_addc_u32 s99, s95, 0
	s_add_i32 s6, 0, 0x18000
	s_add_i32 s29, 0, 0x1c000
	s_mov_b32 m0, s48
	s_nop 0
	global_load_lds_dwordx4 v130, s[98:99]
	s_mov_b32 m0, s49
	s_nop 0
	global_load_lds_dwordx4 v134, s[98:99]
	ds_read_b128 v[164:167], v232
	ds_read_b128 v[168:171], v232 offset:1024
	ds_read_b128 v[172:175], v232 offset:2048
	ds_read_b128 v[176:179], v232 offset:3072
	ds_read_b128 v[180:183], v233
	ds_read_b128 v[184:187], v233 offset:1024
	ds_read_b128 v[188:191], v233 offset:2048
	ds_read_b128 v[192:195], v233 offset:3072
	ds_read_b128 v[196:199], v160 offset:32768
	ds_read_b128 v[200:203], v160 offset:33792
	ds_read_b128 v[204:207], v160 offset:34816
	ds_read_b128 v[208:211], v160 offset:35840
	ds_read_b128 v[212:215], v160 offset:36864
	ds_read_b128 v[216:219], v160 offset:37888
	ds_read_b128 v[220:223], v160 offset:38912
	ds_read_b128 v[224:227], v160 offset:39936
	s_waitcnt vmcnt(8)
	s_waitcnt lgkmcnt(0)
	.p2align 3
	s_setprio 1
	s_barrier
	v_mfma_f32_16x16x32_bf16 v[122:125], v[164:167], v[196:199], v[122:125]
	v_mfma_f32_16x16x32_bf16 v[118:121], v[172:175], v[196:199], v[118:121]
	v_mfma_f32_16x16x32_bf16 v[110:113], v[164:167], v[204:207], v[110:113]
	v_mfma_f32_16x16x32_bf16 v[102:105], v[172:175], v[204:207], v[102:105]
	v_mfma_f32_16x16x32_bf16 v[94:97], v[164:167], v[212:215], v[94:97]
	v_mfma_f32_16x16x32_bf16 v[86:89], v[172:175], v[212:215], v[86:89]
	v_mfma_f32_16x16x32_bf16 v[78:81], v[164:167], v[220:223], v[78:81]
	v_mfma_f32_16x16x32_bf16 v[70:73], v[172:175], v[220:223], v[70:73]
	v_mfma_f32_16x16x32_bf16 v[122:125], v[168:171], v[200:203], v[122:125]
	v_mfma_f32_16x16x32_bf16 v[118:121], v[176:179], v[200:203], v[118:121]
	v_mfma_f32_16x16x32_bf16 v[110:113], v[168:171], v[208:211], v[110:113]
	v_mfma_f32_16x16x32_bf16 v[102:105], v[176:179], v[208:211], v[102:105]
	v_mfma_f32_16x16x32_bf16 v[94:97], v[168:171], v[216:219], v[94:97]
	v_mfma_f32_16x16x32_bf16 v[86:89], v[176:179], v[216:219], v[86:89]
	v_mfma_f32_16x16x32_bf16 v[78:81], v[168:171], v[224:227], v[78:81]
	v_mfma_f32_16x16x32_bf16 v[70:73], v[176:179], v[224:227], v[70:73]
	s_setprio 0
	s_setprio 1
	v_mfma_f32_16x16x32_bf16 v[126:129], v[180:183], v[196:199], v[126:129]
	v_mfma_f32_16x16x32_bf16 v[114:117], v[188:191], v[196:199], v[114:117]
	v_mfma_f32_16x16x32_bf16 v[106:109], v[180:183], v[204:207], v[106:109]
	v_mfma_f32_16x16x32_bf16 v[98:101], v[188:191], v[204:207], v[98:101]
	v_mfma_f32_16x16x32_bf16 v[90:93], v[180:183], v[212:215], v[90:93]
	v_mfma_f32_16x16x32_bf16 v[82:85], v[188:191], v[212:215], v[82:85]
	v_mfma_f32_16x16x32_bf16 v[74:77], v[180:183], v[220:223], v[74:77]
	v_mfma_f32_16x16x32_bf16 v[66:69], v[188:191], v[220:223], v[66:69]
	v_mfma_f32_16x16x32_bf16 v[126:129], v[184:187], v[200:203], v[126:129]
	v_mfma_f32_16x16x32_bf16 v[114:117], v[192:195], v[200:203], v[114:117]
	v_mfma_f32_16x16x32_bf16 v[106:109], v[184:187], v[208:211], v[106:109]
	v_mfma_f32_16x16x32_bf16 v[98:101], v[192:195], v[208:211], v[98:101]
	v_mfma_f32_16x16x32_bf16 v[90:93], v[184:187], v[216:219], v[90:93]
	v_mfma_f32_16x16x32_bf16 v[82:85], v[192:195], v[216:219], v[82:85]
	v_mfma_f32_16x16x32_bf16 v[74:77], v[184:187], v[224:227], v[74:77]
	v_mfma_f32_16x16x32_bf16 v[66:69], v[192:195], v[224:227], v[66:69]
	s_barrier
	s_setprio 0
	s_add_u32 s96, s96, 0x80
	s_addc_u32 s97, s97, 0
	s_add_u32 s98, s96, 0xb0000
	s_addc_u32 s99, s97, 0
	s_add_u32 s94, s94, 0x80
	s_addc_u32 s95, s95, 0
	s_add_i32 s6, s6, s23
	s_mov_b32 m0, s6
	s_nop 0
	global_load_lds_dwordx4 v132, s[96:97]
	s_add_i32 m0, s6, 0x2000
	s_add_i32 s6, s29, s23
	global_load_lds_dwordx4 v136, s[96:97]
	s_mov_b32 m0, s6
	s_nop 0
	global_load_lds_dwordx4 v132, s[98:99]
	s_add_i32 m0, s6, 0x2000
	s_nop 0
	global_load_lds_dwordx4 v136, s[98:99]
	s_mov_b32 m0, s59
	s_nop 0
	global_load_lds_dwordx4 v130, s[94:95]
	s_mov_b32 m0, s60
	s_nop 0
	global_load_lds_dwordx4 v134, s[94:95]
	ds_read_b128 v[196:199], v160 offset:49152
	ds_read_b128 v[200:203], v160 offset:50176
	ds_read_b128 v[204:207], v160 offset:51200
	ds_read_b128 v[208:211], v160 offset:52224
	ds_read_b128 v[212:215], v160 offset:53248
	ds_read_b128 v[216:219], v160 offset:54272
	ds_read_b128 v[220:223], v160 offset:55296
	ds_read_b128 v[224:227], v160 offset:56320
	s_waitcnt vmcnt(8)
	s_waitcnt lgkmcnt(0)
	.p2align 3
	s_setprio 1
	s_barrier
	v_mfma_f32_16x16x32_bf16 v[62:65], v[164:167], v[196:199], v[62:65]
	v_mfma_f32_16x16x32_bf16 v[54:57], v[172:175], v[196:199], v[54:57]
	v_mfma_f32_16x16x32_bf16 v[46:49], v[164:167], v[204:207], v[46:49]
	v_mfma_f32_16x16x32_bf16 v[38:41], v[172:175], v[204:207], v[38:41]
	v_mfma_f32_16x16x32_bf16 v[30:33], v[164:167], v[212:215], v[30:33]
	v_mfma_f32_16x16x32_bf16 v[22:25], v[172:175], v[212:215], v[22:25]
	v_mfma_f32_16x16x32_bf16 v[14:17], v[164:167], v[220:223], v[14:17]
	v_mfma_f32_16x16x32_bf16 v[6:9], v[172:175], v[220:223], v[6:9]
	v_mfma_f32_16x16x32_bf16 v[62:65], v[168:171], v[200:203], v[62:65]
	v_mfma_f32_16x16x32_bf16 v[54:57], v[176:179], v[200:203], v[54:57]
	v_mfma_f32_16x16x32_bf16 v[46:49], v[168:171], v[208:211], v[46:49]
	v_mfma_f32_16x16x32_bf16 v[38:41], v[176:179], v[208:211], v[38:41]
	v_mfma_f32_16x16x32_bf16 v[30:33], v[168:171], v[216:219], v[30:33]
	v_mfma_f32_16x16x32_bf16 v[22:25], v[176:179], v[216:219], v[22:25]
	v_mfma_f32_16x16x32_bf16 v[14:17], v[168:171], v[224:227], v[14:17]
	v_mfma_f32_16x16x32_bf16 v[6:9], v[176:179], v[224:227], v[6:9]
	s_setprio 0
	s_setprio 1
	v_mfma_f32_16x16x32_bf16 v[58:61], v[180:183], v[196:199], v[58:61]
	v_mfma_f32_16x16x32_bf16 v[50:53], v[188:191], v[196:199], v[50:53]
	v_mfma_f32_16x16x32_bf16 v[42:45], v[180:183], v[204:207], v[42:45]
	v_mfma_f32_16x16x32_bf16 v[34:37], v[188:191], v[204:207], v[34:37]
	v_mfma_f32_16x16x32_bf16 v[26:29], v[180:183], v[212:215], v[26:29]
	v_mfma_f32_16x16x32_bf16 v[18:21], v[188:191], v[212:215], v[18:21]
	v_mfma_f32_16x16x32_bf16 v[10:13], v[180:183], v[220:223], v[10:13]
	v_mfma_f32_16x16x32_bf16 v[2:5], v[188:191], v[220:223], v[2:5]
	v_mfma_f32_16x16x32_bf16 v[58:61], v[184:187], v[200:203], v[58:61]
	v_mfma_f32_16x16x32_bf16 v[50:53], v[192:195], v[200:203], v[50:53]
	v_mfma_f32_16x16x32_bf16 v[42:45], v[184:187], v[208:211], v[42:45]
	v_mfma_f32_16x16x32_bf16 v[34:37], v[192:195], v[208:211], v[34:37]
	v_mfma_f32_16x16x32_bf16 v[26:29], v[184:187], v[216:219], v[26:29]
	v_mfma_f32_16x16x32_bf16 v[18:21], v[192:195], v[216:219], v[18:21]
	v_mfma_f32_16x16x32_bf16 v[10:13], v[184:187], v[224:227], v[10:13]
	v_mfma_f32_16x16x32_bf16 v[2:5], v[192:195], v[224:227], v[2:5]
	s_barrier
	s_setprio 0
	s_mov_b32 s6, s7
	s_add_u32 s88, s88, 0x100
	s_addc_u32 s89, s89, 0
	s_add_u32 s86, s86, 0x100
	s_addc_u32 s87, s87, 0
	s_cmp_ge_i32 s7, s101
	s_cbranch_scc0 .LBB0_1080

.Lmy_nb_7:
	s_nop 0
	v_readfirstlane_b32 s86, v150
	v_readfirstlane_b32 s87, v151
	v_readfirstlane_b32 s88, v152
	v_readfirstlane_b32 s89, v153
	v_readfirstlane_b32 s90, v146
	v_readfirstlane_b32 s91, v147
	v_readfirstlane_b32 s92, v148
	v_readfirstlane_b32 s93, v149
	v_readfirstlane_b32 s100, v138
	v_readfirstlane_b32 s101, v156
	v_add_u32_e32 v230, s67, v141
	v_add_u32_e32 v231, s70, v141
	v_add_u32_e32 v232, 0x18000, v141
	v_add_u32_e32 v233, 0x1c000, v141
	s_add_u32 s98, s86, 0x100
	s_addc_u32 s99, s87, 0
	s_cmp_eq_u32 s6, s100
	s_cselect_b64 s[94:95], s[90:91], s[98:99]
	s_cselect_b64 s[96:97], s[92:93], s[88:89]
	s_add_i32 s7, s6, 2
	s_nop 0
	s_add_i32 m0, s46, 0xc000
	s_nop 0
	global_load_lds_dwordx4 v144, s[86:87]
	s_add_i32 m0, s46, 0xe000
	s_nop 0
	global_load_lds_dwordx4 v142, s[86:87]
	ds_read_b128 v[164:167], v230
	ds_read_b128 v[168:171], v230 offset:1024
	ds_read_b128 v[172:175], v230 offset:2048
	ds_read_b128 v[176:179], v230 offset:3072
	ds_read_b128 v[180:183], v231
	ds_read_b128 v[184:187], v231 offset:1024
	ds_read_b128 v[188:191], v231 offset:2048
	ds_read_b128 v[192:195], v231 offset:3072
	ds_read_b128 v[196:199], v160
	ds_read_b128 v[200:203], v160 offset:1024
	ds_read_b128 v[204:207], v160 offset:2048
	ds_read_b128 v[208:211], v160 offset:3072
	ds_read_b128 v[212:215], v160 offset:4096
	ds_read_b128 v[216:219], v160 offset:5120
	ds_read_b128 v[220:223], v160 offset:6144
	ds_read_b128 v[224:227], v160 offset:7168
	s_waitcnt vmcnt(8)
	s_waitcnt lgkmcnt(0)
	.p2align 3
	s_setprio 1
	s_barrier
	v_mfma_f32_16x16x32_bf16 v[122:125], v[164:167], v[196:199], 0
	v_mfma_f32_16x16x32_bf16 v[118:121], v[172:175], v[196:199], 0
	v_mfma_f32_16x16x32_bf16 v[110:113], v[164:167], v[204:207], 0
	v_mfma_f32_16x16x32_bf16 v[102:105], v[172:175], v[204:207], 0
	v_mfma_f32_16x16x32_bf16 v[94:97], v[164:167], v[212:215], 0
	v_mfma_f32_16x16x32_bf16 v[86:89], v[172:175], v[212:215], 0
	v_mfma_f32_16x16x32_bf16 v[78:81], v[164:167], v[220:223], 0
	v_mfma_f32_16x16x32_bf16 v[70:73], v[172:175], v[220:223], 0
	v_mfma_f32_16x16x32_bf16 v[122:125], v[168:171], v[200:203], v[122:125]
	v_mfma_f32_16x16x32_bf16 v[118:121], v[176:179], v[200:203], v[118:121]
	v_mfma_f32_16x16x32_bf16 v[110:113], v[168:171], v[208:211], v[110:113]
	v_mfma_f32_16x16x32_bf16 v[102:105], v[176:179], v[208:211], v[102:105]
	v_mfma_f32_16x16x32_bf16 v[94:97], v[168:171], v[216:219], v[94:97]
	v_mfma_f32_16x16x32_bf16 v[86:89], v[176:179], v[216:219], v[86:89]
	v_mfma_f32_16x16x32_bf16 v[78:81], v[168:171], v[224:227], v[78:81]
	v_mfma_f32_16x16x32_bf16 v[70:73], v[176:179], v[224:227], v[70:73]
	s_setprio 0
	s_setprio 1
	v_mfma_f32_16x16x32_bf16 v[126:129], v[180:183], v[196:199], 0
	v_mfma_f32_16x16x32_bf16 v[114:117], v[188:191], v[196:199], 0
	v_mfma_f32_16x16x32_bf16 v[106:109], v[180:183], v[204:207], 0
	v_mfma_f32_16x16x32_bf16 v[98:101], v[188:191], v[204:207], 0
	v_mfma_f32_16x16x32_bf16 v[90:93], v[180:183], v[212:215], 0
	v_mfma_f32_16x16x32_bf16 v[82:85], v[188:191], v[212:215], 0
	v_mfma_f32_16x16x32_bf16 v[74:77], v[180:183], v[220:223], 0
	v_mfma_f32_16x16x32_bf16 v[66:69], v[188:191], v[220:223], 0
	v_mfma_f32_16x16x32_bf16 v[126:129], v[184:187], v[200:203], v[126:129]
	v_mfma_f32_16x16x32_bf16 v[114:117], v[192:195], v[200:203], v[114:117]
	v_mfma_f32_16x16x32_bf16 v[106:109], v[184:187], v[208:211], v[106:109]
	v_mfma_f32_16x16x32_bf16 v[98:101], v[192:195], v[208:211], v[98:101]
	v_mfma_f32_16x16x32_bf16 v[90:93], v[184:187], v[216:219], v[90:93]
	v_mfma_f32_16x16x32_bf16 v[82:85], v[192:195], v[216:219], v[82:85]
	v_mfma_f32_16x16x32_bf16 v[74:77], v[184:187], v[224:227], v[74:77]
	v_mfma_f32_16x16x32_bf16 v[66:69], v[192:195], v[224:227], v[66:69]
	s_barrier
	s_setprio 0
	s_add_u32 s98, s96, 0xb0000
	s_addc_u32 s99, s97, 0
	s_add_i32 s6, s67, s23
	s_mov_b32 m0, s6
	s_nop 0
	global_load_lds_dwordx4 v132, s[96:97]
	s_add_i32 m0, s6, 0x2000
	s_add_i32 s6, s70, s23
	global_load_lds_dwordx4 v136, s[96:97]
	s_mov_b32 m0, s6
	s_nop 0
	global_load_lds_dwordx4 v132, s[98:99]
	s_add_i32 m0, s6, 0x2000
	s_nop 0
	global_load_lds_dwordx4 v136, s[98:99]
	s_mov_b32 m0, s46
	s_nop 0
	global_load_lds_dwordx4 v130, s[94:95]
	s_mov_b32 m0, s47
	s_nop 0
	global_load_lds_dwordx4 v134, s[94:95]
	ds_read_b128 v[196:199], v160 offset:16384
	ds_read_b128 v[200:203], v160 offset:17408
	ds_read_b128 v[204:207], v160 offset:18432
	ds_read_b128 v[208:211], v160 offset:19456
	ds_read_b128 v[212:215], v160 offset:20480
	ds_read_b128 v[216:219], v160 offset:21504
	ds_read_b128 v[220:223], v160 offset:22528
	ds_read_b128 v[224:227], v160 offset:23552
	s_waitcnt vmcnt(8)
	s_waitcnt lgkmcnt(0)
	.p2align 3
	s_setprio 1
	s_barrier
	v_mfma_f32_16x16x32_bf16 v[62:65], v[164:167], v[196:199], 0
	v_mfma_f32_16x16x32_bf16 v[54:57], v[172:175], v[196:199], 0
	v_mfma_f32_16x16x32_bf16 v[46:49], v[164:167], v[204:207], 0
	v_mfma_f32_16x16x32_bf16 v[38:41], v[172:175], v[204:207], 0
	v_mfma_f32_16x16x32_bf16 v[30:33], v[164:167], v[212:215], 0
	v_mfma_f32_16x16x32_bf16 v[22:25], v[172:175], v[212:215], 0
	v_mfma_f32_16x16x32_bf16 v[14:17], v[164:167], v[220:223], 0
	v_mfma_f32_16x16x32_bf16 v[6:9], v[172:175], v[220:223], 0
	v_mfma_f32_16x16x32_bf16 v[62:65], v[168:171], v[200:203], v[62:65]
	v_mfma_f32_16x16x32_bf16 v[54:57], v[176:179], v[200:203], v[54:57]
	v_mfma_f32_16x16x32_bf16 v[46:49], v[168:171], v[208:211], v[46:49]
	v_mfma_f32_16x16x32_bf16 v[38:41], v[176:179], v[208:211], v[38:41]
	v_mfma_f32_16x16x32_bf16 v[30:33], v[168:171], v[216:219], v[30:33]
	v_mfma_f32_16x16x32_bf16 v[22:25], v[176:179], v[216:219], v[22:25]
	v_mfma_f32_16x16x32_bf16 v[14:17], v[168:171], v[224:227], v[14:17]
	v_mfma_f32_16x16x32_bf16 v[6:9], v[176:179], v[224:227], v[6:9]
	s_setprio 0
	s_setprio 1
	v_mfma_f32_16x16x32_bf16 v[58:61], v[180:183], v[196:199], 0
	v_mfma_f32_16x16x32_bf16 v[50:53], v[188:191], v[196:199], 0
	v_mfma_f32_16x16x32_bf16 v[42:45], v[180:183], v[204:207], 0
	v_mfma_f32_16x16x32_bf16 v[34:37], v[188:191], v[204:207], 0
	v_mfma_f32_16x16x32_bf16 v[26:29], v[180:183], v[212:215], 0
	v_mfma_f32_16x16x32_bf16 v[18:21], v[188:191], v[212:215], 0
	v_mfma_f32_16x16x32_bf16 v[10:13], v[180:183], v[220:223], 0
	v_mfma_f32_16x16x32_bf16 v[2:5], v[188:191], v[220:223], 0
	v_mfma_f32_16x16x32_bf16 v[58:61], v[184:187], v[200:203], v[58:61]
	v_mfma_f32_16x16x32_bf16 v[50:53], v[192:195], v[200:203], v[50:53]
	v_mfma_f32_16x16x32_bf16 v[42:45], v[184:187], v[208:211], v[42:45]
	v_mfma_f32_16x16x32_bf16 v[34:37], v[192:195], v[208:211], v[34:37]
	v_mfma_f32_16x16x32_bf16 v[26:29], v[184:187], v[216:219], v[26:29]
	v_mfma_f32_16x16x32_bf16 v[18:21], v[192:195], v[216:219], v[18:21]
	v_mfma_f32_16x16x32_bf16 v[10:13], v[184:187], v[224:227], v[10:13]
	v_mfma_f32_16x16x32_bf16 v[2:5], v[192:195], v[224:227], v[2:5]
	s_barrier
	s_setprio 0
	s_add_u32 s98, s94, 0xb0000
	s_addc_u32 s99, s95, 0
	s_add_i32 s6, 0, 0x18000
	s_add_i32 s29, 0, 0x1c000
	s_mov_b32 m0, s48
	s_nop 0
	global_load_lds_dwordx4 v130, s[98:99]
	s_mov_b32 m0, s49
	s_nop 0
	global_load_lds_dwordx4 v134, s[98:99]
	ds_read_b128 v[164:167], v232
	ds_read_b128 v[168:171], v232 offset:1024
	ds_read_b128 v[172:175], v232 offset:2048
	ds_read_b128 v[176:179], v232 offset:3072
	ds_read_b128 v[180:183], v233
	ds_read_b128 v[184:187], v233 offset:1024
	ds_read_b128 v[188:191], v233 offset:2048
	ds_read_b128 v[192:195], v233 offset:3072
	ds_read_b128 v[196:199], v160 offset:32768
	ds_read_b128 v[200:203], v160 offset:33792
	ds_read_b128 v[204:207], v160 offset:34816
	ds_read_b128 v[208:211], v160 offset:35840
	ds_read_b128 v[212:215], v160 offset:36864
	ds_read_b128 v[216:219], v160 offset:37888
	ds_read_b128 v[220:223], v160 offset:38912
	ds_read_b128 v[224:227], v160 offset:39936
	s_waitcnt vmcnt(8)
	s_waitcnt lgkmcnt(0)
	.p2align 3
	s_setprio 1
	s_barrier
	v_mfma_f32_16x16x32_bf16 v[122:125], v[164:167], v[196:199], v[122:125]
	v_mfma_f32_16x16x32_bf16 v[118:121], v[172:175], v[196:199], v[118:121]
	v_mfma_f32_16x16x32_bf16 v[110:113], v[164:167], v[204:207], v[110:113]
	v_mfma_f32_16x16x32_bf16 v[102:105], v[172:175], v[204:207], v[102:105]
	v_mfma_f32_16x16x32_bf16 v[94:97], v[164:167], v[212:215], v[94:97]
	v_mfma_f32_16x16x32_bf16 v[86:89], v[172:175], v[212:215], v[86:89]
	v_mfma_f32_16x16x32_bf16 v[78:81], v[164:167], v[220:223], v[78:81]
	v_mfma_f32_16x16x32_bf16 v[70:73], v[172:175], v[220:223], v[70:73]
	v_mfma_f32_16x16x32_bf16 v[122:125], v[168:171], v[200:203], v[122:125]
	v_mfma_f32_16x16x32_bf16 v[118:121], v[176:179], v[200:203], v[118:121]
	v_mfma_f32_16x16x32_bf16 v[110:113], v[168:171], v[208:211], v[110:113]
	v_mfma_f32_16x16x32_bf16 v[102:105], v[176:179], v[208:211], v[102:105]
	v_mfma_f32_16x16x32_bf16 v[94:97], v[168:171], v[216:219], v[94:97]
	v_mfma_f32_16x16x32_bf16 v[86:89], v[176:179], v[216:219], v[86:89]
	v_mfma_f32_16x16x32_bf16 v[78:81], v[168:171], v[224:227], v[78:81]
	v_mfma_f32_16x16x32_bf16 v[70:73], v[176:179], v[224:227], v[70:73]
	s_setprio 0
	s_setprio 1
	v_mfma_f32_16x16x32_bf16 v[126:129], v[180:183], v[196:199], v[126:129]
	v_mfma_f32_16x16x32_bf16 v[114:117], v[188:191], v[196:199], v[114:117]
	v_mfma_f32_16x16x32_bf16 v[106:109], v[180:183], v[204:207], v[106:109]
	v_mfma_f32_16x16x32_bf16 v[98:101], v[188:191], v[204:207], v[98:101]
	v_mfma_f32_16x16x32_bf16 v[90:93], v[180:183], v[212:215], v[90:93]
	v_mfma_f32_16x16x32_bf16 v[82:85], v[188:191], v[212:215], v[82:85]
	v_mfma_f32_16x16x32_bf16 v[74:77], v[180:183], v[220:223], v[74:77]
	v_mfma_f32_16x16x32_bf16 v[66:69], v[188:191], v[220:223], v[66:69]
	v_mfma_f32_16x16x32_bf16 v[126:129], v[184:187], v[200:203], v[126:129]
	v_mfma_f32_16x16x32_bf16 v[114:117], v[192:195], v[200:203], v[114:117]
	v_mfma_f32_16x16x32_bf16 v[106:109], v[184:187], v[208:211], v[106:109]
	v_mfma_f32_16x16x32_bf16 v[98:101], v[192:195], v[208:211], v[98:101]
	v_mfma_f32_16x16x32_bf16 v[90:93], v[184:187], v[216:219], v[90:93]
	v_mfma_f32_16x16x32_bf16 v[82:85], v[192:195], v[216:219], v[82:85]
	v_mfma_f32_16x16x32_bf16 v[74:77], v[184:187], v[224:227], v[74:77]
	v_mfma_f32_16x16x32_bf16 v[66:69], v[192:195], v[224:227], v[66:69]
	s_barrier
	s_setprio 0
	s_add_u32 s96, s96, 0x80
	s_addc_u32 s97, s97, 0
	s_add_u32 s98, s96, 0xb0000
	s_addc_u32 s99, s97, 0
	s_add_u32 s94, s94, 0x80
	s_addc_u32 s95, s95, 0
	s_add_i32 s6, s6, s23
	s_mov_b32 m0, s6
	s_nop 0
	global_load_lds_dwordx4 v132, s[96:97]
	s_add_i32 m0, s6, 0x2000
	s_add_i32 s6, s29, s23
	global_load_lds_dwordx4 v136, s[96:97]
	s_mov_b32 m0, s6
	s_nop 0
	global_load_lds_dwordx4 v132, s[98:99]
	s_add_i32 m0, s6, 0x2000
	s_nop 0
	global_load_lds_dwordx4 v136, s[98:99]
	s_mov_b32 m0, s59
	s_nop 0
	global_load_lds_dwordx4 v130, s[94:95]
	s_mov_b32 m0, s60
	s_nop 0
	global_load_lds_dwordx4 v134, s[94:95]
	ds_read_b128 v[196:199], v160 offset:49152
	ds_read_b128 v[200:203], v160 offset:50176
	ds_read_b128 v[204:207], v160 offset:51200
	ds_read_b128 v[208:211], v160 offset:52224
	ds_read_b128 v[212:215], v160 offset:53248
	ds_read_b128 v[216:219], v160 offset:54272
	ds_read_b128 v[220:223], v160 offset:55296
	ds_read_b128 v[224:227], v160 offset:56320
	s_waitcnt vmcnt(8)
	s_waitcnt lgkmcnt(0)
	.p2align 3
	s_setprio 1
	s_barrier
	v_mfma_f32_16x16x32_bf16 v[62:65], v[164:167], v[196:199], v[62:65]
	v_mfma_f32_16x16x32_bf16 v[54:57], v[172:175], v[196:199], v[54:57]
	v_mfma_f32_16x16x32_bf16 v[46:49], v[164:167], v[204:207], v[46:49]
	v_mfma_f32_16x16x32_bf16 v[38:41], v[172:175], v[204:207], v[38:41]
	v_mfma_f32_16x16x32_bf16 v[30:33], v[164:167], v[212:215], v[30:33]
	v_mfma_f32_16x16x32_bf16 v[22:25], v[172:175], v[212:215], v[22:25]
	v_mfma_f32_16x16x32_bf16 v[14:17], v[164:167], v[220:223], v[14:17]
	v_mfma_f32_16x16x32_bf16 v[6:9], v[172:175], v[220:223], v[6:9]
	v_mfma_f32_16x16x32_bf16 v[62:65], v[168:171], v[200:203], v[62:65]
	v_mfma_f32_16x16x32_bf16 v[54:57], v[176:179], v[200:203], v[54:57]
	v_mfma_f32_16x16x32_bf16 v[46:49], v[168:171], v[208:211], v[46:49]
	v_mfma_f32_16x16x32_bf16 v[38:41], v[176:179], v[208:211], v[38:41]
	v_mfma_f32_16x16x32_bf16 v[30:33], v[168:171], v[216:219], v[30:33]
	v_mfma_f32_16x16x32_bf16 v[22:25], v[176:179], v[216:219], v[22:25]
	v_mfma_f32_16x16x32_bf16 v[14:17], v[168:171], v[224:227], v[14:17]
	v_mfma_f32_16x16x32_bf16 v[6:9], v[176:179], v[224:227], v[6:9]
	s_setprio 0
	s_setprio 1
	v_mfma_f32_16x16x32_bf16 v[58:61], v[180:183], v[196:199], v[58:61]
	v_mfma_f32_16x16x32_bf16 v[50:53], v[188:191], v[196:199], v[50:53]
	v_mfma_f32_16x16x32_bf16 v[42:45], v[180:183], v[204:207], v[42:45]
	v_mfma_f32_16x16x32_bf16 v[34:37], v[188:191], v[204:207], v[34:37]
	v_mfma_f32_16x16x32_bf16 v[26:29], v[180:183], v[212:215], v[26:29]
	v_mfma_f32_16x16x32_bf16 v[18:21], v[188:191], v[212:215], v[18:21]
	v_mfma_f32_16x16x32_bf16 v[10:13], v[180:183], v[220:223], v[10:13]
	v_mfma_f32_16x16x32_bf16 v[2:5], v[188:191], v[220:223], v[2:5]
	v_mfma_f32_16x16x32_bf16 v[58:61], v[184:187], v[200:203], v[58:61]
	v_mfma_f32_16x16x32_bf16 v[50:53], v[192:195], v[200:203], v[50:53]
	v_mfma_f32_16x16x32_bf16 v[42:45], v[184:187], v[208:211], v[42:45]
	v_mfma_f32_16x16x32_bf16 v[34:37], v[192:195], v[208:211], v[34:37]
	v_mfma_f32_16x16x32_bf16 v[26:29], v[184:187], v[216:219], v[26:29]
	v_mfma_f32_16x16x32_bf16 v[18:21], v[192:195], v[216:219], v[18:21]
	v_mfma_f32_16x16x32_bf16 v[10:13], v[184:187], v[224:227], v[10:13]
	v_mfma_f32_16x16x32_bf16 v[2:5], v[192:195], v[224:227], v[2:5]
	s_barrier
	s_setprio 0
	s_mov_b32 s6, s7
	s_add_u32 s88, s88, 0x100
	s_addc_u32 s89, s89, 0
	s_add_u32 s86, s86, 0x100
	s_addc_u32 s87, s87, 0
	s_cmp_ge_i32 s7, s101
	s_cbranch_scc1 .Lmy_kexit_7
.LBB0_1392:
	s_add_u32 s98, s86, 0x100
	s_addc_u32 s99, s87, 0
	s_cmp_eq_u32 s6, s100
	s_cselect_b64 s[94:95], s[90:91], s[98:99]
	s_cselect_b64 s[96:97], s[92:93], s[88:89]
	s_add_i32 s7, s6, 2
	s_nop 0
	s_add_i32 m0, s46, 0xc000
	s_nop 0
	global_load_lds_dwordx4 v144, s[86:87]
	s_add_i32 m0, s46, 0xe000
	s_nop 0
	global_load_lds_dwordx4 v142, s[86:87]
	ds_read_b128 v[164:167], v230
	ds_read_b128 v[168:171], v230 offset:1024
	ds_read_b128 v[172:175], v230 offset:2048
	ds_read_b128 v[176:179], v230 offset:3072
	ds_read_b128 v[180:183], v231
	ds_read_b128 v[184:187], v231 offset:1024
	ds_read_b128 v[188:191], v231 offset:2048
	ds_read_b128 v[192:195], v231 offset:3072
	ds_read_b128 v[196:199], v160
	ds_read_b128 v[200:203], v160 offset:1024
	ds_read_b128 v[204:207], v160 offset:2048
	ds_read_b128 v[208:211], v160 offset:3072
	ds_read_b128 v[212:215], v160 offset:4096
	ds_read_b128 v[216:219], v160 offset:5120
	ds_read_b128 v[220:223], v160 offset:6144
	ds_read_b128 v[224:227], v160 offset:7168
	s_waitcnt vmcnt(8)
	s_waitcnt lgkmcnt(0)
	.p2align 3
	s_setprio 1
	s_barrier
	v_mfma_f32_16x16x32_bf16 v[122:125], v[164:167], v[196:199], v[122:125]
	v_mfma_f32_16x16x32_bf16 v[118:121], v[172:175], v[196:199], v[118:121]
	v_mfma_f32_16x16x32_bf16 v[110:113], v[164:167], v[204:207], v[110:113]
	v_mfma_f32_16x16x32_bf16 v[102:105], v[172:175], v[204:207], v[102:105]
	v_mfma_f32_16x16x32_bf16 v[94:97], v[164:167], v[212:215], v[94:97]
	v_mfma_f32_16x16x32_bf16 v[86:89], v[172:175], v[212:215], v[86:89]
	v_mfma_f32_16x16x32_bf16 v[78:81], v[164:167], v[220:223], v[78:81]
	v_mfma_f32_16x16x32_bf16 v[70:73], v[172:175], v[220:223], v[70:73]
	v_mfma_f32_16x16x32_bf16 v[122:125], v[168:171], v[200:203], v[122:125]
	v_mfma_f32_16x16x32_bf16 v[118:121], v[176:179], v[200:203], v[118:121]
	v_mfma_f32_16x16x32_bf16 v[110:113], v[168:171], v[208:211], v[110:113]
	v_mfma_f32_16x16x32_bf16 v[102:105], v[176:179], v[208:211], v[102:105]
	v_mfma_f32_16x16x32_bf16 v[94:97], v[168:171], v[216:219], v[94:97]
	v_mfma_f32_16x16x32_bf16 v[86:89], v[176:179], v[216:219], v[86:89]
	v_mfma_f32_16x16x32_bf16 v[78:81], v[168:171], v[224:227], v[78:81]
	v_mfma_f32_16x16x32_bf16 v[70:73], v[176:179], v[224:227], v[70:73]
	s_setprio 0
	s_setprio 1
	v_mfma_f32_16x16x32_bf16 v[126:129], v[180:183], v[196:199], v[126:129]
	v_mfma_f32_16x16x32_bf16 v[114:117], v[188:191], v[196:199], v[114:117]
	v_mfma_f32_16x16x32_bf16 v[106:109], v[180:183], v[204:207], v[106:109]
	v_mfma_f32_16x16x32_bf16 v[98:101], v[188:191], v[204:207], v[98:101]
	v_mfma_f32_16x16x32_bf16 v[90:93], v[180:183], v[212:215], v[90:93]
	v_mfma_f32_16x16x32_bf16 v[82:85], v[188:191], v[212:215], v[82:85]
	v_mfma_f32_16x16x32_bf16 v[74:77], v[180:183], v[220:223], v[74:77]
	v_mfma_f32_16x16x32_bf16 v[66:69], v[188:191], v[220:223], v[66:69]
	v_mfma_f32_16x16x32_bf16 v[126:129], v[184:187], v[200:203], v[126:129]
	v_mfma_f32_16x16x32_bf16 v[114:117], v[192:195], v[200:203], v[114:117]
	v_mfma_f32_16x16x32_bf16 v[106:109], v[184:187], v[208:211], v[106:109]
	v_mfma_f32_16x16x32_bf16 v[98:101], v[192:195], v[208:211], v[98:101]
	v_mfma_f32_16x16x32_bf16 v[90:93], v[184:187], v[216:219], v[90:93]
	v_mfma_f32_16x16x32_bf16 v[82:85], v[192:195], v[216:219], v[82:85]
	v_mfma_f32_16x16x32_bf16 v[74:77], v[184:187], v[224:227], v[74:77]
	v_mfma_f32_16x16x32_bf16 v[66:69], v[192:195], v[224:227], v[66:69]
	s_barrier
	s_setprio 0
	s_add_u32 s98, s96, 0xb0000
	s_addc_u32 s99, s97, 0
	s_add_i32 s6, s67, s23
	s_mov_b32 m0, s6
	s_nop 0
	global_load_lds_dwordx4 v132, s[96:97]
	s_add_i32 m0, s6, 0x2000
	s_add_i32 s6, s70, s23
	global_load_lds_dwordx4 v136, s[96:97]
	s_mov_b32 m0, s6
	s_nop 0
	global_load_lds_dwordx4 v132, s[98:99]
	s_add_i32 m0, s6, 0x2000
	s_nop 0
	global_load_lds_dwordx4 v136, s[98:99]
	s_mov_b32 m0, s46
	s_nop 0
	global_load_lds_dwordx4 v130, s[94:95]
	s_mov_b32 m0, s47
	s_nop 0
	global_load_lds_dwordx4 v134, s[94:95]
	ds_read_b128 v[196:199], v160 offset:16384
	ds_read_b128 v[200:203], v160 offset:17408
	ds_read_b128 v[204:207], v160 offset:18432
	ds_read_b128 v[208:211], v160 offset:19456
	ds_read_b128 v[212:215], v160 offset:20480
	ds_read_b128 v[216:219], v160 offset:21504
	ds_read_b128 v[220:223], v160 offset:22528
	ds_read_b128 v[224:227], v160 offset:23552
	s_waitcnt vmcnt(8)
	s_waitcnt lgkmcnt(0)
	.p2align 3
	s_setprio 1
	s_barrier
	v_mfma_f32_16x16x32_bf16 v[62:65], v[164:167], v[196:199], v[62:65]
	v_mfma_f32_16x16x32_bf16 v[54:57], v[172:175], v[196:199], v[54:57]
	v_mfma_f32_16x16x32_bf16 v[46:49], v[164:167], v[204:207], v[46:49]
	v_mfma_f32_16x16x32_bf16 v[38:41], v[172:175], v[204:207], v[38:41]
	v_mfma_f32_16x16x32_bf16 v[30:33], v[164:167], v[212:215], v[30:33]
	v_mfma_f32_16x16x32_bf16 v[22:25], v[172:175], v[212:215], v[22:25]
	v_mfma_f32_16x16x32_bf16 v[14:17], v[164:167], v[220:223], v[14:17]
	v_mfma_f32_16x16x32_bf16 v[6:9], v[172:175], v[220:223], v[6:9]
	v_mfma_f32_16x16x32_bf16 v[62:65], v[168:171], v[200:203], v[62:65]
	v_mfma_f32_16x16x32_bf16 v[54:57], v[176:179], v[200:203], v[54:57]
	v_mfma_f32_16x16x32_bf16 v[46:49], v[168:171], v[208:211], v[46:49]
	v_mfma_f32_16x16x32_bf16 v[38:41], v[176:179], v[208:211], v[38:41]
	v_mfma_f32_16x16x32_bf16 v[30:33], v[168:171], v[216:219], v[30:33]
	v_mfma_f32_16x16x32_bf16 v[22:25], v[176:179], v[216:219], v[22:25]
	v_mfma_f32_16x16x32_bf16 v[14:17], v[168:171], v[224:227], v[14:17]
	v_mfma_f32_16x16x32_bf16 v[6:9], v[176:179], v[224:227], v[6:9]
	s_setprio 0
	s_setprio 1
	v_mfma_f32_16x16x32_bf16 v[58:61], v[180:183], v[196:199], v[58:61]
	v_mfma_f32_16x16x32_bf16 v[50:53], v[188:191], v[196:199], v[50:53]
	v_mfma_f32_16x16x32_bf16 v[42:45], v[180:183], v[204:207], v[42:45]
	v_mfma_f32_16x16x32_bf16 v[34:37], v[188:191], v[204:207], v[34:37]
	v_mfma_f32_16x16x32_bf16 v[26:29], v[180:183], v[212:215], v[26:29]
	v_mfma_f32_16x16x32_bf16 v[18:21], v[188:191], v[212:215], v[18:21]
	v_mfma_f32_16x16x32_bf16 v[10:13], v[180:183], v[220:223], v[10:13]
	v_mfma_f32_16x16x32_bf16 v[2:5], v[188:191], v[220:223], v[2:5]
	v_mfma_f32_16x16x32_bf16 v[58:61], v[184:187], v[200:203], v[58:61]
	v_mfma_f32_16x16x32_bf16 v[50:53], v[192:195], v[200:203], v[50:53]
	v_mfma_f32_16x16x32_bf16 v[42:45], v[184:187], v[208:211], v[42:45]
	v_mfma_f32_16x16x32_bf16 v[34:37], v[192:195], v[208:211], v[34:37]
	v_mfma_f32_16x16x32_bf16 v[26:29], v[184:187], v[216:219], v[26:29]
	v_mfma_f32_16x16x32_bf16 v[18:21], v[192:195], v[216:219], v[18:21]
	v_mfma_f32_16x16x32_bf16 v[10:13], v[184:187], v[224:227], v[10:13]
	v_mfma_f32_16x16x32_bf16 v[2:5], v[192:195], v[224:227], v[2:5]
	s_barrier
	s_setprio 0
	s_add_u32 s98, s94, 0xb0000
	s_addc_u32 s99, s95, 0
	s_add_i32 s6, 0, 0x18000
	s_add_i32 s29, 0, 0x1c000
	s_mov_b32 m0, s48
	s_nop 0
	global_load_lds_dwordx4 v130, s[98:99]
	s_mov_b32 m0, s49
	s_nop 0
	global_load_lds_dwordx4 v134, s[98:99]
	ds_read_b128 v[164:167], v232
	ds_read_b128 v[168:171], v232 offset:1024
	ds_read_b128 v[172:175], v232 offset:2048
	ds_read_b128 v[176:179], v232 offset:3072
	ds_read_b128 v[180:183], v233
	ds_read_b128 v[184:187], v233 offset:1024
	ds_read_b128 v[188:191], v233 offset:2048
	ds_read_b128 v[192:195], v233 offset:3072
	ds_read_b128 v[196:199], v160 offset:32768
	ds_read_b128 v[200:203], v160 offset:33792
	ds_read_b128 v[204:207], v160 offset:34816
	ds_read_b128 v[208:211], v160 offset:35840
	ds_read_b128 v[212:215], v160 offset:36864
	ds_read_b128 v[216:219], v160 offset:37888
	ds_read_b128 v[220:223], v160 offset:38912
	ds_read_b128 v[224:227], v160 offset:39936
	s_waitcnt vmcnt(8)
	s_waitcnt lgkmcnt(0)
	.p2align 3
	s_setprio 1
	s_barrier
	v_mfma_f32_16x16x32_bf16 v[122:125], v[164:167], v[196:199], v[122:125]
	v_mfma_f32_16x16x32_bf16 v[118:121], v[172:175], v[196:199], v[118:121]
	v_mfma_f32_16x16x32_bf16 v[110:113], v[164:167], v[204:207], v[110:113]
	v_mfma_f32_16x16x32_bf16 v[102:105], v[172:175], v[204:207], v[102:105]
	v_mfma_f32_16x16x32_bf16 v[94:97], v[164:167], v[212:215], v[94:97]
	v_mfma_f32_16x16x32_bf16 v[86:89], v[172:175], v[212:215], v[86:89]
	v_mfma_f32_16x16x32_bf16 v[78:81], v[164:167], v[220:223], v[78:81]
	v_mfma_f32_16x16x32_bf16 v[70:73], v[172:175], v[220:223], v[70:73]
	v_mfma_f32_16x16x32_bf16 v[122:125], v[168:171], v[200:203], v[122:125]
	v_mfma_f32_16x16x32_bf16 v[118:121], v[176:179], v[200:203], v[118:121]
	v_mfma_f32_16x16x32_bf16 v[110:113], v[168:171], v[208:211], v[110:113]
	v_mfma_f32_16x16x32_bf16 v[102:105], v[176:179], v[208:211], v[102:105]
	v_mfma_f32_16x16x32_bf16 v[94:97], v[168:171], v[216:219], v[94:97]
	v_mfma_f32_16x16x32_bf16 v[86:89], v[176:179], v[216:219], v[86:89]
	v_mfma_f32_16x16x32_bf16 v[78:81], v[168:171], v[224:227], v[78:81]
	v_mfma_f32_16x16x32_bf16 v[70:73], v[176:179], v[224:227], v[70:73]
	s_setprio 0
	s_setprio 1
	v_mfma_f32_16x16x32_bf16 v[126:129], v[180:183], v[196:199], v[126:129]
	v_mfma_f32_16x16x32_bf16 v[114:117], v[188:191], v[196:199], v[114:117]
	v_mfma_f32_16x16x32_bf16 v[106:109], v[180:183], v[204:207], v[106:109]
	v_mfma_f32_16x16x32_bf16 v[98:101], v[188:191], v[204:207], v[98:101]
	v_mfma_f32_16x16x32_bf16 v[90:93], v[180:183], v[212:215], v[90:93]
	v_mfma_f32_16x16x32_bf16 v[82:85], v[188:191], v[212:215], v[82:85]
	v_mfma_f32_16x16x32_bf16 v[74:77], v[180:183], v[220:223], v[74:77]
	v_mfma_f32_16x16x32_bf16 v[66:69], v[188:191], v[220:223], v[66:69]
	v_mfma_f32_16x16x32_bf16 v[126:129], v[184:187], v[200:203], v[126:129]
	v_mfma_f32_16x16x32_bf16 v[114:117], v[192:195], v[200:203], v[114:117]
	v_mfma_f32_16x16x32_bf16 v[106:109], v[184:187], v[208:211], v[106:109]
	v_mfma_f32_16x16x32_bf16 v[98:101], v[192:195], v[208:211], v[98:101]
	v_mfma_f32_16x16x32_bf16 v[90:93], v[184:187], v[216:219], v[90:93]
	v_mfma_f32_16x16x32_bf16 v[82:85], v[192:195], v[216:219], v[82:85]
	v_mfma_f32_16x16x32_bf16 v[74:77], v[184:187], v[224:227], v[74:77]
	v_mfma_f32_16x16x32_bf16 v[66:69], v[192:195], v[224:227], v[66:69]
	s_barrier
	s_setprio 0
	s_add_u32 s96, s96, 0x80
	s_addc_u32 s97, s97, 0
	s_add_u32 s98, s96, 0xb0000
	s_addc_u32 s99, s97, 0
	s_add_u32 s94, s94, 0x80
	s_addc_u32 s95, s95, 0
	s_add_i32 s6, s6, s23
	s_mov_b32 m0, s6
	s_nop 0
	global_load_lds_dwordx4 v132, s[96:97]
	s_add_i32 m0, s6, 0x2000
	s_add_i32 s6, s29, s23
	global_load_lds_dwordx4 v136, s[96:97]
	s_mov_b32 m0, s6
	s_nop 0
	global_load_lds_dwordx4 v132, s[98:99]
	s_add_i32 m0, s6, 0x2000
	s_nop 0
	global_load_lds_dwordx4 v136, s[98:99]
	s_mov_b32 m0, s59
	s_nop 0
	global_load_lds_dwordx4 v130, s[94:95]
	s_mov_b32 m0, s60
	s_nop 0
	global_load_lds_dwordx4 v134, s[94:95]
	ds_read_b128 v[196:199], v160 offset:49152
	ds_read_b128 v[200:203], v160 offset:50176
	ds_read_b128 v[204:207], v160 offset:51200
	ds_read_b128 v[208:211], v160 offset:52224
	ds_read_b128 v[212:215], v160 offset:53248
	ds_read_b128 v[216:219], v160 offset:54272
	ds_read_b128 v[220:223], v160 offset:55296
	ds_read_b128 v[224:227], v160 offset:56320
	s_waitcnt vmcnt(8)
	s_waitcnt lgkmcnt(0)
	.p2align 3
	s_setprio 1
	s_barrier
	v_mfma_f32_16x16x32_bf16 v[62:65], v[164:167], v[196:199], v[62:65]
	v_mfma_f32_16x16x32_bf16 v[54:57], v[172:175], v[196:199], v[54:57]
	v_mfma_f32_16x16x32_bf16 v[46:49], v[164:167], v[204:207], v[46:49]
	v_mfma_f32_16x16x32_bf16 v[38:41], v[172:175], v[204:207], v[38:41]
	v_mfma_f32_16x16x32_bf16 v[30:33], v[164:167], v[212:215], v[30:33]
	v_mfma_f32_16x16x32_bf16 v[22:25], v[172:175], v[212:215], v[22:25]
	v_mfma_f32_16x16x32_bf16 v[14:17], v[164:167], v[220:223], v[14:17]
	v_mfma_f32_16x16x32_bf16 v[6:9], v[172:175], v[220:223], v[6:9]
	v_mfma_f32_16x16x32_bf16 v[62:65], v[168:171], v[200:203], v[62:65]
	v_mfma_f32_16x16x32_bf16 v[54:57], v[176:179], v[200:203], v[54:57]
	v_mfma_f32_16x16x32_bf16 v[46:49], v[168:171], v[208:211], v[46:49]
	v_mfma_f32_16x16x32_bf16 v[38:41], v[176:179], v[208:211], v[38:41]
	v_mfma_f32_16x16x32_bf16 v[30:33], v[168:171], v[216:219], v[30:33]
	v_mfma_f32_16x16x32_bf16 v[22:25], v[176:179], v[216:219], v[22:25]
	v_mfma_f32_16x16x32_bf16 v[14:17], v[168:171], v[224:227], v[14:17]
	v_mfma_f32_16x16x32_bf16 v[6:9], v[176:179], v[224:227], v[6:9]
	s_setprio 0
	s_setprio 1
	v_mfma_f32_16x16x32_bf16 v[58:61], v[180:183], v[196:199], v[58:61]
	v_mfma_f32_16x16x32_bf16 v[50:53], v[188:191], v[196:199], v[50:53]
	v_mfma_f32_16x16x32_bf16 v[42:45], v[180:183], v[204:207], v[42:45]
	v_mfma_f32_16x16x32_bf16 v[34:37], v[188:191], v[204:207], v[34:37]
	v_mfma_f32_16x16x32_bf16 v[26:29], v[180:183], v[212:215], v[26:29]
	v_mfma_f32_16x16x32_bf16 v[18:21], v[188:191], v[212:215], v[18:21]
	v_mfma_f32_16x16x32_bf16 v[10:13], v[180:183], v[220:223], v[10:13]
	v_mfma_f32_16x16x32_bf16 v[2:5], v[188:191], v[220:223], v[2:5]
	v_mfma_f32_16x16x32_bf16 v[58:61], v[184:187], v[200:203], v[58:61]
	v_mfma_f32_16x16x32_bf16 v[50:53], v[192:195], v[200:203], v[50:53]
	v_mfma_f32_16x16x32_bf16 v[42:45], v[184:187], v[208:211], v[42:45]
	v_mfma_f32_16x16x32_bf16 v[34:37], v[192:195], v[208:211], v[34:37]
	v_mfma_f32_16x16x32_bf16 v[26:29], v[184:187], v[216:219], v[26:29]
	v_mfma_f32_16x16x32_bf16 v[18:21], v[192:195], v[216:219], v[18:21]
	v_mfma_f32_16x16x32_bf16 v[10:13], v[184:187], v[224:227], v[10:13]
	v_mfma_f32_16x16x32_bf16 v[2:5], v[192:195], v[224:227], v[2:5]
	s_barrier
	s_setprio 0
	s_mov_b32 s6, s7
	s_add_u32 s88, s88, 0x100
	s_addc_u32 s89, s89, 0
	s_add_u32 s86, s86, 0x100
	s_addc_u32 s87, s87, 0
	s_cmp_ge_i32 s7, s101
	s_cbranch_scc0 .LBB0_1392

.Lmy_nb_8:
	s_nop 0
	v_readfirstlane_b32 s86, v154
	v_readfirstlane_b32 s87, v155
	v_readfirstlane_b32 s88, v152
	v_readfirstlane_b32 s89, v153
	v_readfirstlane_b32 s90, v148
	v_readfirstlane_b32 s91, v149
	v_readfirstlane_b32 s92, v150
	v_readfirstlane_b32 s93, v151
	v_readfirstlane_b32 s100, v138
	v_readfirstlane_b32 s101, v141
	v_add_u32_e32 v230, s71, v160
	v_add_u32_e32 v231, s72, v160
	v_add_u32_e32 v232, 0x18000, v160
	v_add_u32_e32 v233, 0x1c000, v160
	s_add_u32 s98, s86, 0xfffc0080
	s_addc_u32 s99, s87, -1
	s_cmp_eq_u32 s7, s100
	s_cselect_b64 s[94:95], s[90:91], s[98:99]
	s_cselect_b64 s[96:97], s[92:93], s[88:89]
	s_add_i32 s47, s7, 2
	s_nop 0
	s_mov_b32 m0, s74
	s_nop 0
	global_load_lds_dwordx4 v144, s[86:87]
	s_mov_b32 m0, s75
	s_nop 0
	global_load_lds_dwordx4 v142, s[86:87]
	ds_read_b128 v[156:159], v230
	ds_read_b128 v[166:169], v230 offset:1024
	ds_read_b128 v[170:173], v230 offset:2048
	ds_read_b128 v[174:177], v230 offset:3072
	ds_read_b128 v[178:181], v231
	ds_read_b128 v[182:185], v231 offset:1024
	ds_read_b128 v[186:189], v231 offset:2048
	ds_read_b128 v[190:193], v231 offset:3072
	ds_read_b128 v[194:197], v163
	ds_read_b128 v[198:201], v163 offset:1024
	ds_read_b128 v[202:205], v163 offset:2048
	ds_read_b128 v[206:209], v163 offset:3072
	ds_read_b128 v[210:213], v163 offset:4096
	ds_read_b128 v[214:217], v163 offset:5120
	ds_read_b128 v[218:221], v163 offset:6144
	ds_read_b128 v[222:225], v163 offset:7168
	s_waitcnt vmcnt(8)
	s_waitcnt lgkmcnt(0)
	.p2align 3
	s_setprio 1
	s_barrier
	v_mfma_f32_16x16x32_bf16 v[122:125], v[156:159], v[194:197], 0
	v_mfma_f32_16x16x32_bf16 v[118:121], v[170:173], v[194:197], 0
	v_mfma_f32_16x16x32_bf16 v[110:113], v[156:159], v[202:205], 0
	v_mfma_f32_16x16x32_bf16 v[102:105], v[170:173], v[202:205], 0
	v_mfma_f32_16x16x32_bf16 v[94:97], v[156:159], v[210:213], 0
	v_mfma_f32_16x16x32_bf16 v[86:89], v[170:173], v[210:213], 0
	v_mfma_f32_16x16x32_bf16 v[78:81], v[156:159], v[218:221], 0
	v_mfma_f32_16x16x32_bf16 v[70:73], v[170:173], v[218:221], 0
	v_mfma_f32_16x16x32_bf16 v[122:125], v[166:169], v[198:201], v[122:125]
	v_mfma_f32_16x16x32_bf16 v[118:121], v[174:177], v[198:201], v[118:121]
	v_mfma_f32_16x16x32_bf16 v[110:113], v[166:169], v[206:209], v[110:113]
	v_mfma_f32_16x16x32_bf16 v[102:105], v[174:177], v[206:209], v[102:105]
	v_mfma_f32_16x16x32_bf16 v[94:97], v[166:169], v[214:217], v[94:97]
	v_mfma_f32_16x16x32_bf16 v[86:89], v[174:177], v[214:217], v[86:89]
	v_mfma_f32_16x16x32_bf16 v[78:81], v[166:169], v[222:225], v[78:81]
	v_mfma_f32_16x16x32_bf16 v[70:73], v[174:177], v[222:225], v[70:73]
	s_setprio 0
	s_setprio 1
	v_mfma_f32_16x16x32_bf16 v[126:129], v[178:181], v[194:197], 0
	v_mfma_f32_16x16x32_bf16 v[114:117], v[186:189], v[194:197], 0
	v_mfma_f32_16x16x32_bf16 v[106:109], v[178:181], v[202:205], 0
	v_mfma_f32_16x16x32_bf16 v[98:101], v[186:189], v[202:205], 0
	v_mfma_f32_16x16x32_bf16 v[90:93], v[178:181], v[210:213], 0
	v_mfma_f32_16x16x32_bf16 v[82:85], v[186:189], v[210:213], 0
	v_mfma_f32_16x16x32_bf16 v[74:77], v[178:181], v[218:221], 0
	v_mfma_f32_16x16x32_bf16 v[66:69], v[186:189], v[218:221], 0
	v_mfma_f32_16x16x32_bf16 v[126:129], v[182:185], v[198:201], v[126:129]
	v_mfma_f32_16x16x32_bf16 v[114:117], v[190:193], v[198:201], v[114:117]
	v_mfma_f32_16x16x32_bf16 v[106:109], v[182:185], v[206:209], v[106:109]
	v_mfma_f32_16x16x32_bf16 v[98:101], v[190:193], v[206:209], v[98:101]
	v_mfma_f32_16x16x32_bf16 v[90:93], v[182:185], v[214:217], v[90:93]
	v_mfma_f32_16x16x32_bf16 v[82:85], v[190:193], v[214:217], v[82:85]
	v_mfma_f32_16x16x32_bf16 v[74:77], v[182:185], v[222:225], v[74:77]
	v_mfma_f32_16x16x32_bf16 v[66:69], v[190:193], v[222:225], v[66:69]
	s_barrier
	s_setprio 0
	s_add_u32 s98, s96, 0x40000
	s_addc_u32 s99, s97, 0
	s_add_i32 s7, s71, s29
	s_mov_b32 m0, s7
	s_nop 0
	global_load_lds_dwordx4 v132, s[96:97]
	s_add_i32 m0, s7, 0x2000
	s_add_i32 s7, s72, s29
	global_load_lds_dwordx4 v136, s[96:97]
	s_mov_b32 m0, s7
	s_nop 0
	global_load_lds_dwordx4 v132, s[98:99]
	s_add_i32 m0, s7, 0x2000
	s_nop 0
	global_load_lds_dwordx4 v136, s[98:99]
	s_mov_b32 m0, s51
	s_nop 0
	global_load_lds_dwordx4 v130, s[94:95]
	s_mov_b32 m0, s60
	s_nop 0
	global_load_lds_dwordx4 v134, s[94:95]
	ds_read_b128 v[194:197], v163 offset:16384
	ds_read_b128 v[198:201], v163 offset:17408
	ds_read_b128 v[202:205], v163 offset:18432
	ds_read_b128 v[206:209], v163 offset:19456
	ds_read_b128 v[210:213], v163 offset:20480
	ds_read_b128 v[214:217], v163 offset:21504
	ds_read_b128 v[218:221], v163 offset:22528
	ds_read_b128 v[222:225], v163 offset:23552
	s_waitcnt vmcnt(8)
	s_waitcnt lgkmcnt(0)
	.p2align 3
	s_setprio 1
	s_barrier
	v_mfma_f32_16x16x32_bf16 v[62:65], v[156:159], v[194:197], 0
	v_mfma_f32_16x16x32_bf16 v[54:57], v[170:173], v[194:197], 0
	v_mfma_f32_16x16x32_bf16 v[46:49], v[156:159], v[202:205], 0
	v_mfma_f32_16x16x32_bf16 v[38:41], v[170:173], v[202:205], 0
	v_mfma_f32_16x16x32_bf16 v[30:33], v[156:159], v[210:213], 0
	v_mfma_f32_16x16x32_bf16 v[22:25], v[170:173], v[210:213], 0
	v_mfma_f32_16x16x32_bf16 v[14:17], v[156:159], v[218:221], 0
	v_mfma_f32_16x16x32_bf16 v[6:9], v[170:173], v[218:221], 0
	v_mfma_f32_16x16x32_bf16 v[62:65], v[166:169], v[198:201], v[62:65]
	v_mfma_f32_16x16x32_bf16 v[54:57], v[174:177], v[198:201], v[54:57]
	v_mfma_f32_16x16x32_bf16 v[46:49], v[166:169], v[206:209], v[46:49]
	v_mfma_f32_16x16x32_bf16 v[38:41], v[174:177], v[206:209], v[38:41]
	v_mfma_f32_16x16x32_bf16 v[30:33], v[166:169], v[214:217], v[30:33]
	v_mfma_f32_16x16x32_bf16 v[22:25], v[174:177], v[214:217], v[22:25]
	v_mfma_f32_16x16x32_bf16 v[14:17], v[166:169], v[222:225], v[14:17]
	v_mfma_f32_16x16x32_bf16 v[6:9], v[174:177], v[222:225], v[6:9]
	s_setprio 0
	s_setprio 1
	v_mfma_f32_16x16x32_bf16 v[58:61], v[178:181], v[194:197], 0
	v_mfma_f32_16x16x32_bf16 v[50:53], v[186:189], v[194:197], 0
	v_mfma_f32_16x16x32_bf16 v[42:45], v[178:181], v[202:205], 0
	v_mfma_f32_16x16x32_bf16 v[34:37], v[186:189], v[202:205], 0
	v_mfma_f32_16x16x32_bf16 v[26:29], v[178:181], v[210:213], 0
	v_mfma_f32_16x16x32_bf16 v[18:21], v[186:189], v[210:213], 0
	v_mfma_f32_16x16x32_bf16 v[10:13], v[178:181], v[218:221], 0
	v_mfma_f32_16x16x32_bf16 v[2:5], v[186:189], v[218:221], 0
	v_mfma_f32_16x16x32_bf16 v[58:61], v[182:185], v[198:201], v[58:61]
	v_mfma_f32_16x16x32_bf16 v[50:53], v[190:193], v[198:201], v[50:53]
	v_mfma_f32_16x16x32_bf16 v[42:45], v[182:185], v[206:209], v[42:45]
	v_mfma_f32_16x16x32_bf16 v[34:37], v[190:193], v[206:209], v[34:37]
	v_mfma_f32_16x16x32_bf16 v[26:29], v[182:185], v[214:217], v[26:29]
	v_mfma_f32_16x16x32_bf16 v[18:21], v[190:193], v[214:217], v[18:21]
	v_mfma_f32_16x16x32_bf16 v[10:13], v[182:185], v[222:225], v[10:13]
	v_mfma_f32_16x16x32_bf16 v[2:5], v[190:193], v[222:225], v[2:5]
	s_barrier
	s_setprio 0
	s_add_u32 s98, s94, 0x40000
	s_addc_u32 s99, s95, 0
	s_add_i32 s7, 0, 0x18000
	s_add_i32 s49, 0, 0x1c000
	s_mov_b32 m0, s61
	s_nop 0
	global_load_lds_dwordx4 v130, s[98:99]
	s_mov_b32 m0, s62
	s_nop 0
	global_load_lds_dwordx4 v134, s[98:99]
	ds_read_b128 v[156:159], v232
	ds_read_b128 v[166:169], v232 offset:1024
	ds_read_b128 v[170:173], v232 offset:2048
	ds_read_b128 v[174:177], v232 offset:3072
	ds_read_b128 v[178:181], v233
	ds_read_b128 v[182:185], v233 offset:1024
	ds_read_b128 v[186:189], v233 offset:2048
	ds_read_b128 v[190:193], v233 offset:3072
	ds_read_b128 v[194:197], v163 offset:32768
	ds_read_b128 v[198:201], v163 offset:33792
	ds_read_b128 v[202:205], v163 offset:34816
	ds_read_b128 v[206:209], v163 offset:35840
	ds_read_b128 v[210:213], v163 offset:36864
	ds_read_b128 v[214:217], v163 offset:37888
	ds_read_b128 v[218:221], v163 offset:38912
	ds_read_b128 v[222:225], v163 offset:39936
	s_waitcnt vmcnt(8)
	s_waitcnt lgkmcnt(0)
	.p2align 3
	s_setprio 1
	s_barrier
	v_mfma_f32_16x16x32_bf16 v[122:125], v[156:159], v[194:197], v[122:125]
	v_mfma_f32_16x16x32_bf16 v[118:121], v[170:173], v[194:197], v[118:121]
	v_mfma_f32_16x16x32_bf16 v[110:113], v[156:159], v[202:205], v[110:113]
	v_mfma_f32_16x16x32_bf16 v[102:105], v[170:173], v[202:205], v[102:105]
	v_mfma_f32_16x16x32_bf16 v[94:97], v[156:159], v[210:213], v[94:97]
	v_mfma_f32_16x16x32_bf16 v[86:89], v[170:173], v[210:213], v[86:89]
	v_mfma_f32_16x16x32_bf16 v[78:81], v[156:159], v[218:221], v[78:81]
	v_mfma_f32_16x16x32_bf16 v[70:73], v[170:173], v[218:221], v[70:73]
	v_mfma_f32_16x16x32_bf16 v[122:125], v[166:169], v[198:201], v[122:125]
	v_mfma_f32_16x16x32_bf16 v[118:121], v[174:177], v[198:201], v[118:121]
	v_mfma_f32_16x16x32_bf16 v[110:113], v[166:169], v[206:209], v[110:113]
	v_mfma_f32_16x16x32_bf16 v[102:105], v[174:177], v[206:209], v[102:105]
	v_mfma_f32_16x16x32_bf16 v[94:97], v[166:169], v[214:217], v[94:97]
	v_mfma_f32_16x16x32_bf16 v[86:89], v[174:177], v[214:217], v[86:89]
	v_mfma_f32_16x16x32_bf16 v[78:81], v[166:169], v[222:225], v[78:81]
	v_mfma_f32_16x16x32_bf16 v[70:73], v[174:177], v[222:225], v[70:73]
	s_setprio 0
	s_setprio 1
	v_mfma_f32_16x16x32_bf16 v[126:129], v[178:181], v[194:197], v[126:129]
	v_mfma_f32_16x16x32_bf16 v[114:117], v[186:189], v[194:197], v[114:117]
	v_mfma_f32_16x16x32_bf16 v[106:109], v[178:181], v[202:205], v[106:109]
	v_mfma_f32_16x16x32_bf16 v[98:101], v[186:189], v[202:205], v[98:101]
	v_mfma_f32_16x16x32_bf16 v[90:93], v[178:181], v[210:213], v[90:93]
	v_mfma_f32_16x16x32_bf16 v[82:85], v[186:189], v[210:213], v[82:85]
	v_mfma_f32_16x16x32_bf16 v[74:77], v[178:181], v[218:221], v[74:77]
	v_mfma_f32_16x16x32_bf16 v[66:69], v[186:189], v[218:221], v[66:69]
	v_mfma_f32_16x16x32_bf16 v[126:129], v[182:185], v[198:201], v[126:129]
	v_mfma_f32_16x16x32_bf16 v[114:117], v[190:193], v[198:201], v[114:117]
	v_mfma_f32_16x16x32_bf16 v[106:109], v[182:185], v[206:209], v[106:109]
	v_mfma_f32_16x16x32_bf16 v[98:101], v[190:193], v[206:209], v[98:101]
	v_mfma_f32_16x16x32_bf16 v[90:93], v[182:185], v[214:217], v[90:93]
	v_mfma_f32_16x16x32_bf16 v[82:85], v[190:193], v[214:217], v[82:85]
	v_mfma_f32_16x16x32_bf16 v[74:77], v[182:185], v[222:225], v[74:77]
	v_mfma_f32_16x16x32_bf16 v[66:69], v[190:193], v[222:225], v[66:69]
	s_barrier
	s_setprio 0
	s_add_u32 s96, s96, 0x80
	s_addc_u32 s97, s97, 0
	s_add_u32 s98, s96, 0x40000
	s_addc_u32 s99, s97, 0
	s_add_u32 s94, s94, 0x80
	s_addc_u32 s95, s95, 0
	s_add_i32 s7, s7, s29
	s_mov_b32 m0, s7
	s_nop 0
	global_load_lds_dwordx4 v132, s[96:97]
	s_add_i32 m0, s7, 0x2000
	s_add_i32 s7, s49, s29
	global_load_lds_dwordx4 v136, s[96:97]
	s_mov_b32 m0, s7
	s_nop 0
	global_load_lds_dwordx4 v132, s[98:99]
	s_add_i32 m0, s7, 0x2000
	s_nop 0
	global_load_lds_dwordx4 v136, s[98:99]
	s_mov_b32 m0, s63
	s_nop 0
	global_load_lds_dwordx4 v130, s[94:95]
	s_mov_b32 m0, s64
	s_nop 0
	global_load_lds_dwordx4 v134, s[94:95]
	ds_read_b128 v[194:197], v163 offset:49152
	ds_read_b128 v[198:201], v163 offset:50176
	ds_read_b128 v[202:205], v163 offset:51200
	ds_read_b128 v[206:209], v163 offset:52224
	ds_read_b128 v[210:213], v163 offset:53248
	ds_read_b128 v[214:217], v163 offset:54272
	ds_read_b128 v[218:221], v163 offset:55296
	ds_read_b128 v[222:225], v163 offset:56320
	s_waitcnt vmcnt(8)
	s_waitcnt lgkmcnt(0)
	.p2align 3
	s_setprio 1
	s_barrier
	v_mfma_f32_16x16x32_bf16 v[62:65], v[156:159], v[194:197], v[62:65]
	v_mfma_f32_16x16x32_bf16 v[54:57], v[170:173], v[194:197], v[54:57]
	v_mfma_f32_16x16x32_bf16 v[46:49], v[156:159], v[202:205], v[46:49]
	v_mfma_f32_16x16x32_bf16 v[38:41], v[170:173], v[202:205], v[38:41]
	v_mfma_f32_16x16x32_bf16 v[30:33], v[156:159], v[210:213], v[30:33]
	v_mfma_f32_16x16x32_bf16 v[22:25], v[170:173], v[210:213], v[22:25]
	v_mfma_f32_16x16x32_bf16 v[14:17], v[156:159], v[218:221], v[14:17]
	v_mfma_f32_16x16x32_bf16 v[6:9], v[170:173], v[218:221], v[6:9]
	v_mfma_f32_16x16x32_bf16 v[62:65], v[166:169], v[198:201], v[62:65]
	v_mfma_f32_16x16x32_bf16 v[54:57], v[174:177], v[198:201], v[54:57]
	v_mfma_f32_16x16x32_bf16 v[46:49], v[166:169], v[206:209], v[46:49]
	v_mfma_f32_16x16x32_bf16 v[38:41], v[174:177], v[206:209], v[38:41]
	v_mfma_f32_16x16x32_bf16 v[30:33], v[166:169], v[214:217], v[30:33]
	v_mfma_f32_16x16x32_bf16 v[22:25], v[174:177], v[214:217], v[22:25]
	v_mfma_f32_16x16x32_bf16 v[14:17], v[166:169], v[222:225], v[14:17]
	v_mfma_f32_16x16x32_bf16 v[6:9], v[174:177], v[222:225], v[6:9]
	s_setprio 0
	s_setprio 1
	v_mfma_f32_16x16x32_bf16 v[58:61], v[178:181], v[194:197], v[58:61]
	v_mfma_f32_16x16x32_bf16 v[50:53], v[186:189], v[194:197], v[50:53]
	v_mfma_f32_16x16x32_bf16 v[42:45], v[178:181], v[202:205], v[42:45]
	v_mfma_f32_16x16x32_bf16 v[34:37], v[186:189], v[202:205], v[34:37]
	v_mfma_f32_16x16x32_bf16 v[26:29], v[178:181], v[210:213], v[26:29]
	v_mfma_f32_16x16x32_bf16 v[18:21], v[186:189], v[210:213], v[18:21]
	v_mfma_f32_16x16x32_bf16 v[10:13], v[178:181], v[218:221], v[10:13]
	v_mfma_f32_16x16x32_bf16 v[2:5], v[186:189], v[218:221], v[2:5]
	v_mfma_f32_16x16x32_bf16 v[58:61], v[182:185], v[198:201], v[58:61]
	v_mfma_f32_16x16x32_bf16 v[50:53], v[190:193], v[198:201], v[50:53]
	v_mfma_f32_16x16x32_bf16 v[42:45], v[182:185], v[206:209], v[42:45]
	v_mfma_f32_16x16x32_bf16 v[34:37], v[190:193], v[206:209], v[34:37]
	v_mfma_f32_16x16x32_bf16 v[26:29], v[182:185], v[214:217], v[26:29]
	v_mfma_f32_16x16x32_bf16 v[18:21], v[190:193], v[214:217], v[18:21]
	v_mfma_f32_16x16x32_bf16 v[10:13], v[182:185], v[222:225], v[10:13]
	v_mfma_f32_16x16x32_bf16 v[2:5], v[190:193], v[222:225], v[2:5]
	s_barrier
	s_setprio 0
	s_mov_b32 s7, s47
	s_add_u32 s88, s88, 0x100
	s_addc_u32 s89, s89, 0
	s_add_u32 s86, s86, 0x100
	s_addc_u32 s87, s87, 0
	s_cmp_ge_i32 s47, s101
	s_cbranch_scc1 .Lmy_kexit_8
.LBB0_1573:
	s_add_u32 s98, s86, 0xfffc0080
	s_addc_u32 s99, s87, -1
	s_cmp_eq_u32 s7, s100
	s_cselect_b64 s[94:95], s[90:91], s[98:99]
	s_cselect_b64 s[96:97], s[92:93], s[88:89]
	s_add_i32 s47, s7, 2
	s_nop 0
	s_mov_b32 m0, s74
	s_nop 0
	global_load_lds_dwordx4 v144, s[86:87]
	s_mov_b32 m0, s75
	s_nop 0
	global_load_lds_dwordx4 v142, s[86:87]
	ds_read_b128 v[156:159], v230
	ds_read_b128 v[166:169], v230 offset:1024
	ds_read_b128 v[170:173], v230 offset:2048
	ds_read_b128 v[174:177], v230 offset:3072
	ds_read_b128 v[178:181], v231
	ds_read_b128 v[182:185], v231 offset:1024
	ds_read_b128 v[186:189], v231 offset:2048
	ds_read_b128 v[190:193], v231 offset:3072
	ds_read_b128 v[194:197], v163
	ds_read_b128 v[198:201], v163 offset:1024
	ds_read_b128 v[202:205], v163 offset:2048
	ds_read_b128 v[206:209], v163 offset:3072
	ds_read_b128 v[210:213], v163 offset:4096
	ds_read_b128 v[214:217], v163 offset:5120
	ds_read_b128 v[218:221], v163 offset:6144
	ds_read_b128 v[222:225], v163 offset:7168
	s_waitcnt vmcnt(8)
	s_waitcnt lgkmcnt(0)
	.p2align 3
	s_setprio 1
	s_barrier
	v_mfma_f32_16x16x32_bf16 v[122:125], v[156:159], v[194:197], v[122:125]
	v_mfma_f32_16x16x32_bf16 v[118:121], v[170:173], v[194:197], v[118:121]
	v_mfma_f32_16x16x32_bf16 v[110:113], v[156:159], v[202:205], v[110:113]
	v_mfma_f32_16x16x32_bf16 v[102:105], v[170:173], v[202:205], v[102:105]
	v_mfma_f32_16x16x32_bf16 v[94:97], v[156:159], v[210:213], v[94:97]
	v_mfma_f32_16x16x32_bf16 v[86:89], v[170:173], v[210:213], v[86:89]
	v_mfma_f32_16x16x32_bf16 v[78:81], v[156:159], v[218:221], v[78:81]
	v_mfma_f32_16x16x32_bf16 v[70:73], v[170:173], v[218:221], v[70:73]
	v_mfma_f32_16x16x32_bf16 v[122:125], v[166:169], v[198:201], v[122:125]
	v_mfma_f32_16x16x32_bf16 v[118:121], v[174:177], v[198:201], v[118:121]
	v_mfma_f32_16x16x32_bf16 v[110:113], v[166:169], v[206:209], v[110:113]
	v_mfma_f32_16x16x32_bf16 v[102:105], v[174:177], v[206:209], v[102:105]
	v_mfma_f32_16x16x32_bf16 v[94:97], v[166:169], v[214:217], v[94:97]
	v_mfma_f32_16x16x32_bf16 v[86:89], v[174:177], v[214:217], v[86:89]
	v_mfma_f32_16x16x32_bf16 v[78:81], v[166:169], v[222:225], v[78:81]
	v_mfma_f32_16x16x32_bf16 v[70:73], v[174:177], v[222:225], v[70:73]
	s_setprio 0
	s_setprio 1
	v_mfma_f32_16x16x32_bf16 v[126:129], v[178:181], v[194:197], v[126:129]
	v_mfma_f32_16x16x32_bf16 v[114:117], v[186:189], v[194:197], v[114:117]
	v_mfma_f32_16x16x32_bf16 v[106:109], v[178:181], v[202:205], v[106:109]
	v_mfma_f32_16x16x32_bf16 v[98:101], v[186:189], v[202:205], v[98:101]
	v_mfma_f32_16x16x32_bf16 v[90:93], v[178:181], v[210:213], v[90:93]
	v_mfma_f32_16x16x32_bf16 v[82:85], v[186:189], v[210:213], v[82:85]
	v_mfma_f32_16x16x32_bf16 v[74:77], v[178:181], v[218:221], v[74:77]
	v_mfma_f32_16x16x32_bf16 v[66:69], v[186:189], v[218:221], v[66:69]
	v_mfma_f32_16x16x32_bf16 v[126:129], v[182:185], v[198:201], v[126:129]
	v_mfma_f32_16x16x32_bf16 v[114:117], v[190:193], v[198:201], v[114:117]
	v_mfma_f32_16x16x32_bf16 v[106:109], v[182:185], v[206:209], v[106:109]
	v_mfma_f32_16x16x32_bf16 v[98:101], v[190:193], v[206:209], v[98:101]
	v_mfma_f32_16x16x32_bf16 v[90:93], v[182:185], v[214:217], v[90:93]
	v_mfma_f32_16x16x32_bf16 v[82:85], v[190:193], v[214:217], v[82:85]
	v_mfma_f32_16x16x32_bf16 v[74:77], v[182:185], v[222:225], v[74:77]
	v_mfma_f32_16x16x32_bf16 v[66:69], v[190:193], v[222:225], v[66:69]
	s_barrier
	s_setprio 0
	s_add_u32 s98, s96, 0x40000
	s_addc_u32 s99, s97, 0
	s_add_i32 s7, s71, s29
	s_mov_b32 m0, s7
	s_nop 0
	global_load_lds_dwordx4 v132, s[96:97]
	s_add_i32 m0, s7, 0x2000
	s_add_i32 s7, s72, s29
	global_load_lds_dwordx4 v136, s[96:97]
	s_mov_b32 m0, s7
	s_nop 0
	global_load_lds_dwordx4 v132, s[98:99]
	s_add_i32 m0, s7, 0x2000
	s_nop 0
	global_load_lds_dwordx4 v136, s[98:99]
	s_mov_b32 m0, s51
	s_nop 0
	global_load_lds_dwordx4 v130, s[94:95]
	s_mov_b32 m0, s60
	s_nop 0
	global_load_lds_dwordx4 v134, s[94:95]
	ds_read_b128 v[194:197], v163 offset:16384
	ds_read_b128 v[198:201], v163 offset:17408
	ds_read_b128 v[202:205], v163 offset:18432
	ds_read_b128 v[206:209], v163 offset:19456
	ds_read_b128 v[210:213], v163 offset:20480
	ds_read_b128 v[214:217], v163 offset:21504
	ds_read_b128 v[218:221], v163 offset:22528
	ds_read_b128 v[222:225], v163 offset:23552
	s_waitcnt vmcnt(8)
	s_waitcnt lgkmcnt(0)
	.p2align 3
	s_setprio 1
	s_barrier
	v_mfma_f32_16x16x32_bf16 v[62:65], v[156:159], v[194:197], v[62:65]
	v_mfma_f32_16x16x32_bf16 v[54:57], v[170:173], v[194:197], v[54:57]
	v_mfma_f32_16x16x32_bf16 v[46:49], v[156:159], v[202:205], v[46:49]
	v_mfma_f32_16x16x32_bf16 v[38:41], v[170:173], v[202:205], v[38:41]
	v_mfma_f32_16x16x32_bf16 v[30:33], v[156:159], v[210:213], v[30:33]
	v_mfma_f32_16x16x32_bf16 v[22:25], v[170:173], v[210:213], v[22:25]
	v_mfma_f32_16x16x32_bf16 v[14:17], v[156:159], v[218:221], v[14:17]
	v_mfma_f32_16x16x32_bf16 v[6:9], v[170:173], v[218:221], v[6:9]
	v_mfma_f32_16x16x32_bf16 v[62:65], v[166:169], v[198:201], v[62:65]
	v_mfma_f32_16x16x32_bf16 v[54:57], v[174:177], v[198:201], v[54:57]
	v_mfma_f32_16x16x32_bf16 v[46:49], v[166:169], v[206:209], v[46:49]
	v_mfma_f32_16x16x32_bf16 v[38:41], v[174:177], v[206:209], v[38:41]
	v_mfma_f32_16x16x32_bf16 v[30:33], v[166:169], v[214:217], v[30:33]
	v_mfma_f32_16x16x32_bf16 v[22:25], v[174:177], v[214:217], v[22:25]
	v_mfma_f32_16x16x32_bf16 v[14:17], v[166:169], v[222:225], v[14:17]
	v_mfma_f32_16x16x32_bf16 v[6:9], v[174:177], v[222:225], v[6:9]
	s_setprio 0
	s_setprio 1
	v_mfma_f32_16x16x32_bf16 v[58:61], v[178:181], v[194:197], v[58:61]
	v_mfma_f32_16x16x32_bf16 v[50:53], v[186:189], v[194:197], v[50:53]
	v_mfma_f32_16x16x32_bf16 v[42:45], v[178:181], v[202:205], v[42:45]
	v_mfma_f32_16x16x32_bf16 v[34:37], v[186:189], v[202:205], v[34:37]
	v_mfma_f32_16x16x32_bf16 v[26:29], v[178:181], v[210:213], v[26:29]
	v_mfma_f32_16x16x32_bf16 v[18:21], v[186:189], v[210:213], v[18:21]
	v_mfma_f32_16x16x32_bf16 v[10:13], v[178:181], v[218:221], v[10:13]
	v_mfma_f32_16x16x32_bf16 v[2:5], v[186:189], v[218:221], v[2:5]
	v_mfma_f32_16x16x32_bf16 v[58:61], v[182:185], v[198:201], v[58:61]
	v_mfma_f32_16x16x32_bf16 v[50:53], v[190:193], v[198:201], v[50:53]
	v_mfma_f32_16x16x32_bf16 v[42:45], v[182:185], v[206:209], v[42:45]
	v_mfma_f32_16x16x32_bf16 v[34:37], v[190:193], v[206:209], v[34:37]
	v_mfma_f32_16x16x32_bf16 v[26:29], v[182:185], v[214:217], v[26:29]
	v_mfma_f32_16x16x32_bf16 v[18:21], v[190:193], v[214:217], v[18:21]
	v_mfma_f32_16x16x32_bf16 v[10:13], v[182:185], v[222:225], v[10:13]
	v_mfma_f32_16x16x32_bf16 v[2:5], v[190:193], v[222:225], v[2:5]
	s_barrier
	s_setprio 0
	s_add_u32 s98, s94, 0x40000
	s_addc_u32 s99, s95, 0
	s_add_i32 s7, 0, 0x18000
	s_add_i32 s49, 0, 0x1c000
	s_mov_b32 m0, s61
	s_nop 0
	global_load_lds_dwordx4 v130, s[98:99]
	s_mov_b32 m0, s62
	s_nop 0
	global_load_lds_dwordx4 v134, s[98:99]
	ds_read_b128 v[156:159], v232
	ds_read_b128 v[166:169], v232 offset:1024
	ds_read_b128 v[170:173], v232 offset:2048
	ds_read_b128 v[174:177], v232 offset:3072
	ds_read_b128 v[178:181], v233
	ds_read_b128 v[182:185], v233 offset:1024
	ds_read_b128 v[186:189], v233 offset:2048
	ds_read_b128 v[190:193], v233 offset:3072
	ds_read_b128 v[194:197], v163 offset:32768
	ds_read_b128 v[198:201], v163 offset:33792
	ds_read_b128 v[202:205], v163 offset:34816
	ds_read_b128 v[206:209], v163 offset:35840
	ds_read_b128 v[210:213], v163 offset:36864
	ds_read_b128 v[214:217], v163 offset:37888
	ds_read_b128 v[218:221], v163 offset:38912
	ds_read_b128 v[222:225], v163 offset:39936
	s_waitcnt vmcnt(8)
	s_waitcnt lgkmcnt(0)
	.p2align 3
	s_setprio 1
	s_barrier
	v_mfma_f32_16x16x32_bf16 v[122:125], v[156:159], v[194:197], v[122:125]
	v_mfma_f32_16x16x32_bf16 v[118:121], v[170:173], v[194:197], v[118:121]
	v_mfma_f32_16x16x32_bf16 v[110:113], v[156:159], v[202:205], v[110:113]
	v_mfma_f32_16x16x32_bf16 v[102:105], v[170:173], v[202:205], v[102:105]
	v_mfma_f32_16x16x32_bf16 v[94:97], v[156:159], v[210:213], v[94:97]
	v_mfma_f32_16x16x32_bf16 v[86:89], v[170:173], v[210:213], v[86:89]
	v_mfma_f32_16x16x32_bf16 v[78:81], v[156:159], v[218:221], v[78:81]
	v_mfma_f32_16x16x32_bf16 v[70:73], v[170:173], v[218:221], v[70:73]
	v_mfma_f32_16x16x32_bf16 v[122:125], v[166:169], v[198:201], v[122:125]
	v_mfma_f32_16x16x32_bf16 v[118:121], v[174:177], v[198:201], v[118:121]
	v_mfma_f32_16x16x32_bf16 v[110:113], v[166:169], v[206:209], v[110:113]
	v_mfma_f32_16x16x32_bf16 v[102:105], v[174:177], v[206:209], v[102:105]
	v_mfma_f32_16x16x32_bf16 v[94:97], v[166:169], v[214:217], v[94:97]
	v_mfma_f32_16x16x32_bf16 v[86:89], v[174:177], v[214:217], v[86:89]
	v_mfma_f32_16x16x32_bf16 v[78:81], v[166:169], v[222:225], v[78:81]
	v_mfma_f32_16x16x32_bf16 v[70:73], v[174:177], v[222:225], v[70:73]
	s_setprio 0
	s_setprio 1
	v_mfma_f32_16x16x32_bf16 v[126:129], v[178:181], v[194:197], v[126:129]
	v_mfma_f32_16x16x32_bf16 v[114:117], v[186:189], v[194:197], v[114:117]
	v_mfma_f32_16x16x32_bf16 v[106:109], v[178:181], v[202:205], v[106:109]
	v_mfma_f32_16x16x32_bf16 v[98:101], v[186:189], v[202:205], v[98:101]
	v_mfma_f32_16x16x32_bf16 v[90:93], v[178:181], v[210:213], v[90:93]
	v_mfma_f32_16x16x32_bf16 v[82:85], v[186:189], v[210:213], v[82:85]
	v_mfma_f32_16x16x32_bf16 v[74:77], v[178:181], v[218:221], v[74:77]
	v_mfma_f32_16x16x32_bf16 v[66:69], v[186:189], v[218:221], v[66:69]
	v_mfma_f32_16x16x32_bf16 v[126:129], v[182:185], v[198:201], v[126:129]
	v_mfma_f32_16x16x32_bf16 v[114:117], v[190:193], v[198:201], v[114:117]
	v_mfma_f32_16x16x32_bf16 v[106:109], v[182:185], v[206:209], v[106:109]
	v_mfma_f32_16x16x32_bf16 v[98:101], v[190:193], v[206:209], v[98:101]
	v_mfma_f32_16x16x32_bf16 v[90:93], v[182:185], v[214:217], v[90:93]
	v_mfma_f32_16x16x32_bf16 v[82:85], v[190:193], v[214:217], v[82:85]
	v_mfma_f32_16x16x32_bf16 v[74:77], v[182:185], v[222:225], v[74:77]
	v_mfma_f32_16x16x32_bf16 v[66:69], v[190:193], v[222:225], v[66:69]
	s_barrier
	s_setprio 0
	s_add_u32 s96, s96, 0x80
	s_addc_u32 s97, s97, 0
	s_add_u32 s98, s96, 0x40000
	s_addc_u32 s99, s97, 0
	s_add_u32 s94, s94, 0x80
	s_addc_u32 s95, s95, 0
	s_add_i32 s7, s7, s29
	s_mov_b32 m0, s7
	s_nop 0
	global_load_lds_dwordx4 v132, s[96:97]
	s_add_i32 m0, s7, 0x2000
	s_add_i32 s7, s49, s29
	global_load_lds_dwordx4 v136, s[96:97]
	s_mov_b32 m0, s7
	s_nop 0
	global_load_lds_dwordx4 v132, s[98:99]
	s_add_i32 m0, s7, 0x2000
	s_nop 0
	global_load_lds_dwordx4 v136, s[98:99]
	s_mov_b32 m0, s63
	s_nop 0
	global_load_lds_dwordx4 v130, s[94:95]
	s_mov_b32 m0, s64
	s_nop 0
	global_load_lds_dwordx4 v134, s[94:95]
	ds_read_b128 v[194:197], v163 offset:49152
	ds_read_b128 v[198:201], v163 offset:50176
	ds_read_b128 v[202:205], v163 offset:51200
	ds_read_b128 v[206:209], v163 offset:52224
	ds_read_b128 v[210:213], v163 offset:53248
	ds_read_b128 v[214:217], v163 offset:54272
	ds_read_b128 v[218:221], v163 offset:55296
	ds_read_b128 v[222:225], v163 offset:56320
	s_waitcnt vmcnt(8)
	s_waitcnt lgkmcnt(0)
	.p2align 3
	s_setprio 1
	s_barrier
	v_mfma_f32_16x16x32_bf16 v[62:65], v[156:159], v[194:197], v[62:65]
	v_mfma_f32_16x16x32_bf16 v[54:57], v[170:173], v[194:197], v[54:57]
	v_mfma_f32_16x16x32_bf16 v[46:49], v[156:159], v[202:205], v[46:49]
	v_mfma_f32_16x16x32_bf16 v[38:41], v[170:173], v[202:205], v[38:41]
	v_mfma_f32_16x16x32_bf16 v[30:33], v[156:159], v[210:213], v[30:33]
	v_mfma_f32_16x16x32_bf16 v[22:25], v[170:173], v[210:213], v[22:25]
	v_mfma_f32_16x16x32_bf16 v[14:17], v[156:159], v[218:221], v[14:17]
	v_mfma_f32_16x16x32_bf16 v[6:9], v[170:173], v[218:221], v[6:9]
	v_mfma_f32_16x16x32_bf16 v[62:65], v[166:169], v[198:201], v[62:65]
	v_mfma_f32_16x16x32_bf16 v[54:57], v[174:177], v[198:201], v[54:57]
	v_mfma_f32_16x16x32_bf16 v[46:49], v[166:169], v[206:209], v[46:49]
	v_mfma_f32_16x16x32_bf16 v[38:41], v[174:177], v[206:209], v[38:41]
	v_mfma_f32_16x16x32_bf16 v[30:33], v[166:169], v[214:217], v[30:33]
	v_mfma_f32_16x16x32_bf16 v[22:25], v[174:177], v[214:217], v[22:25]
	v_mfma_f32_16x16x32_bf16 v[14:17], v[166:169], v[222:225], v[14:17]
	v_mfma_f32_16x16x32_bf16 v[6:9], v[174:177], v[222:225], v[6:9]
	s_setprio 0
	s_setprio 1
	v_mfma_f32_16x16x32_bf16 v[58:61], v[178:181], v[194:197], v[58:61]
	v_mfma_f32_16x16x32_bf16 v[50:53], v[186:189], v[194:197], v[50:53]
	v_mfma_f32_16x16x32_bf16 v[42:45], v[178:181], v[202:205], v[42:45]
	v_mfma_f32_16x16x32_bf16 v[34:37], v[186:189], v[202:205], v[34:37]
	v_mfma_f32_16x16x32_bf16 v[26:29], v[178:181], v[210:213], v[26:29]
	v_mfma_f32_16x16x32_bf16 v[18:21], v[186:189], v[210:213], v[18:21]
	v_mfma_f32_16x16x32_bf16 v[10:13], v[178:181], v[218:221], v[10:13]
	v_mfma_f32_16x16x32_bf16 v[2:5], v[186:189], v[218:221], v[2:5]
	v_mfma_f32_16x16x32_bf16 v[58:61], v[182:185], v[198:201], v[58:61]
	v_mfma_f32_16x16x32_bf16 v[50:53], v[190:193], v[198:201], v[50:53]
	v_mfma_f32_16x16x32_bf16 v[42:45], v[182:185], v[206:209], v[42:45]
	v_mfma_f32_16x16x32_bf16 v[34:37], v[190:193], v[206:209], v[34:37]
	v_mfma_f32_16x16x32_bf16 v[26:29], v[182:185], v[214:217], v[26:29]
	v_mfma_f32_16x16x32_bf16 v[18:21], v[190:193], v[214:217], v[18:21]
	v_mfma_f32_16x16x32_bf16 v[10:13], v[182:185], v[222:225], v[10:13]
	v_mfma_f32_16x16x32_bf16 v[2:5], v[190:193], v[222:225], v[2:5]
	s_barrier
	s_setprio 0
	s_mov_b32 s7, s47
	s_add_u32 s88, s88, 0x100
	s_addc_u32 s89, s89, 0
	s_add_u32 s86, s86, 0x100
	s_addc_u32 s87, s87, 0
	s_cmp_ge_i32 s47, s101
	s_cbranch_scc0 .LBB0_1573

.Lmy_nb_9:
	s_nop 0
	v_readfirstlane_b32 s86, v152
	v_readfirstlane_b32 s87, v153
	v_readfirstlane_b32 s88, v150
	v_readfirstlane_b32 s89, v151
	v_readfirstlane_b32 s90, v146
	v_readfirstlane_b32 s91, v147
	v_readfirstlane_b32 s92, v148
	v_readfirstlane_b32 s93, v149
	v_readfirstlane_b32 s100, v154
	v_readfirstlane_b32 s101, v138
	v_add_u32_e32 v230, s74, v141
	v_add_u32_e32 v231, s75, v141
	v_add_u32_e32 v232, 0x18000, v141
	v_add_u32_e32 v233, 0x1c000, v141
	s_add_u32 s98, s86, 0xfffc0080
	s_addc_u32 s99, s87, -1
	s_cmp_eq_u32 s5, s100
	s_cselect_b64 s[94:95], s[90:91], s[98:99]
	s_cselect_b64 s[96:97], s[92:93], s[88:89]
	s_add_i32 s29, s5, 2
	s_nop 0
	s_add_i32 m0, s47, 0xc000
	s_nop 0
	global_load_lds_dwordx4 v144, s[86:87]
	s_add_i32 m0, s47, 0xe000
	s_nop 0
	global_load_lds_dwordx4 v142, s[86:87]
	ds_read_b128 v[164:167], v230
	ds_read_b128 v[168:171], v230 offset:1024
	ds_read_b128 v[172:175], v230 offset:2048
	ds_read_b128 v[176:179], v230 offset:3072
	ds_read_b128 v[180:183], v231
	ds_read_b128 v[184:187], v231 offset:1024
	ds_read_b128 v[188:191], v231 offset:2048
	ds_read_b128 v[192:195], v231 offset:3072
	ds_read_b128 v[196:199], v160
	ds_read_b128 v[200:203], v160 offset:1024
	ds_read_b128 v[204:207], v160 offset:2048
	ds_read_b128 v[208:211], v160 offset:3072
	ds_read_b128 v[212:215], v160 offset:4096
	ds_read_b128 v[216:219], v160 offset:5120
	ds_read_b128 v[220:223], v160 offset:6144
	ds_read_b128 v[224:227], v160 offset:7168
	s_waitcnt vmcnt(8)
	s_waitcnt lgkmcnt(0)
	.p2align 3
	s_setprio 1
	s_barrier
	v_mfma_f32_16x16x32_bf16 v[122:125], v[164:167], v[196:199], 0
	v_mfma_f32_16x16x32_bf16 v[118:121], v[172:175], v[196:199], 0
	v_mfma_f32_16x16x32_bf16 v[110:113], v[164:167], v[204:207], 0
	v_mfma_f32_16x16x32_bf16 v[102:105], v[172:175], v[204:207], 0
	v_mfma_f32_16x16x32_bf16 v[94:97], v[164:167], v[212:215], 0
	v_mfma_f32_16x16x32_bf16 v[86:89], v[172:175], v[212:215], 0
	v_mfma_f32_16x16x32_bf16 v[78:81], v[164:167], v[220:223], 0
	v_mfma_f32_16x16x32_bf16 v[70:73], v[172:175], v[220:223], 0
	v_mfma_f32_16x16x32_bf16 v[122:125], v[168:171], v[200:203], v[122:125]
	v_mfma_f32_16x16x32_bf16 v[118:121], v[176:179], v[200:203], v[118:121]
	v_mfma_f32_16x16x32_bf16 v[110:113], v[168:171], v[208:211], v[110:113]
	v_mfma_f32_16x16x32_bf16 v[102:105], v[176:179], v[208:211], v[102:105]
	v_mfma_f32_16x16x32_bf16 v[94:97], v[168:171], v[216:219], v[94:97]
	v_mfma_f32_16x16x32_bf16 v[86:89], v[176:179], v[216:219], v[86:89]
	v_mfma_f32_16x16x32_bf16 v[78:81], v[168:171], v[224:227], v[78:81]
	v_mfma_f32_16x16x32_bf16 v[70:73], v[176:179], v[224:227], v[70:73]
	s_setprio 0
	s_setprio 1
	v_mfma_f32_16x16x32_bf16 v[126:129], v[180:183], v[196:199], 0
	v_mfma_f32_16x16x32_bf16 v[114:117], v[188:191], v[196:199], 0
	v_mfma_f32_16x16x32_bf16 v[106:109], v[180:183], v[204:207], 0
	v_mfma_f32_16x16x32_bf16 v[98:101], v[188:191], v[204:207], 0
	v_mfma_f32_16x16x32_bf16 v[90:93], v[180:183], v[212:215], 0
	v_mfma_f32_16x16x32_bf16 v[82:85], v[188:191], v[212:215], 0
	v_mfma_f32_16x16x32_bf16 v[74:77], v[180:183], v[220:223], 0
	v_mfma_f32_16x16x32_bf16 v[66:69], v[188:191], v[220:223], 0
	v_mfma_f32_16x16x32_bf16 v[126:129], v[184:187], v[200:203], v[126:129]
	v_mfma_f32_16x16x32_bf16 v[114:117], v[192:195], v[200:203], v[114:117]
	v_mfma_f32_16x16x32_bf16 v[106:109], v[184:187], v[208:211], v[106:109]
	v_mfma_f32_16x16x32_bf16 v[98:101], v[192:195], v[208:211], v[98:101]
	v_mfma_f32_16x16x32_bf16 v[90:93], v[184:187], v[216:219], v[90:93]
	v_mfma_f32_16x16x32_bf16 v[82:85], v[192:195], v[216:219], v[82:85]
	v_mfma_f32_16x16x32_bf16 v[74:77], v[184:187], v[224:227], v[74:77]
	v_mfma_f32_16x16x32_bf16 v[66:69], v[192:195], v[224:227], v[66:69]
	s_barrier
	s_setprio 0
	s_add_u32 s98, s96, 0x40000
	s_addc_u32 s99, s97, 0
	s_add_i32 s5, s74, s23
	s_mov_b32 m0, s5
	s_nop 0
	global_load_lds_dwordx4 v132, s[96:97]
	s_add_i32 m0, s5, 0x2000
	s_add_i32 s5, s75, s23
	global_load_lds_dwordx4 v136, s[96:97]
	s_mov_b32 m0, s5
	s_nop 0
	global_load_lds_dwordx4 v132, s[98:99]
	s_add_i32 m0, s5, 0x2000
	s_nop 0
	global_load_lds_dwordx4 v136, s[98:99]
	s_mov_b32 m0, s47
	s_nop 0
	global_load_lds_dwordx4 v130, s[94:95]
	s_mov_b32 m0, s56
	s_nop 0
	global_load_lds_dwordx4 v134, s[94:95]
	ds_read_b128 v[196:199], v160 offset:16384
	ds_read_b128 v[200:203], v160 offset:17408
	ds_read_b128 v[204:207], v160 offset:18432
	ds_read_b128 v[208:211], v160 offset:19456
	ds_read_b128 v[212:215], v160 offset:20480
	ds_read_b128 v[216:219], v160 offset:21504
	ds_read_b128 v[220:223], v160 offset:22528
	ds_read_b128 v[224:227], v160 offset:23552
	s_waitcnt vmcnt(8)
	s_waitcnt lgkmcnt(0)
	.p2align 3
	s_setprio 1
	s_barrier
	v_mfma_f32_16x16x32_bf16 v[62:65], v[164:167], v[196:199], 0
	v_mfma_f32_16x16x32_bf16 v[54:57], v[172:175], v[196:199], 0
	v_mfma_f32_16x16x32_bf16 v[46:49], v[164:167], v[204:207], 0
	v_mfma_f32_16x16x32_bf16 v[38:41], v[172:175], v[204:207], 0
	v_mfma_f32_16x16x32_bf16 v[30:33], v[164:167], v[212:215], 0
	v_mfma_f32_16x16x32_bf16 v[22:25], v[172:175], v[212:215], 0
	v_mfma_f32_16x16x32_bf16 v[14:17], v[164:167], v[220:223], 0
	v_mfma_f32_16x16x32_bf16 v[6:9], v[172:175], v[220:223], 0
	v_mfma_f32_16x16x32_bf16 v[62:65], v[168:171], v[200:203], v[62:65]
	v_mfma_f32_16x16x32_bf16 v[54:57], v[176:179], v[200:203], v[54:57]
	v_mfma_f32_16x16x32_bf16 v[46:49], v[168:171], v[208:211], v[46:49]
	v_mfma_f32_16x16x32_bf16 v[38:41], v[176:179], v[208:211], v[38:41]
	v_mfma_f32_16x16x32_bf16 v[30:33], v[168:171], v[216:219], v[30:33]
	v_mfma_f32_16x16x32_bf16 v[22:25], v[176:179], v[216:219], v[22:25]
	v_mfma_f32_16x16x32_bf16 v[14:17], v[168:171], v[224:227], v[14:17]
	v_mfma_f32_16x16x32_bf16 v[6:9], v[176:179], v[224:227], v[6:9]
	s_setprio 0
	s_setprio 1
	v_mfma_f32_16x16x32_bf16 v[58:61], v[180:183], v[196:199], 0
	v_mfma_f32_16x16x32_bf16 v[50:53], v[188:191], v[196:199], 0
	v_mfma_f32_16x16x32_bf16 v[42:45], v[180:183], v[204:207], 0
	v_mfma_f32_16x16x32_bf16 v[34:37], v[188:191], v[204:207], 0
	v_mfma_f32_16x16x32_bf16 v[26:29], v[180:183], v[212:215], 0
	v_mfma_f32_16x16x32_bf16 v[18:21], v[188:191], v[212:215], 0
	v_mfma_f32_16x16x32_bf16 v[10:13], v[180:183], v[220:223], 0
	v_mfma_f32_16x16x32_bf16 v[2:5], v[188:191], v[220:223], 0
	v_mfma_f32_16x16x32_bf16 v[58:61], v[184:187], v[200:203], v[58:61]
	v_mfma_f32_16x16x32_bf16 v[50:53], v[192:195], v[200:203], v[50:53]
	v_mfma_f32_16x16x32_bf16 v[42:45], v[184:187], v[208:211], v[42:45]
	v_mfma_f32_16x16x32_bf16 v[34:37], v[192:195], v[208:211], v[34:37]
	v_mfma_f32_16x16x32_bf16 v[26:29], v[184:187], v[216:219], v[26:29]
	v_mfma_f32_16x16x32_bf16 v[18:21], v[192:195], v[216:219], v[18:21]
	v_mfma_f32_16x16x32_bf16 v[10:13], v[184:187], v[224:227], v[10:13]
	v_mfma_f32_16x16x32_bf16 v[2:5], v[192:195], v[224:227], v[2:5]
	s_barrier
	s_setprio 0
	s_add_u32 s98, s94, 0x40000
	s_addc_u32 s99, s95, 0
	s_add_i32 s5, 0, 0x18000
	s_add_i32 s45, 0, 0x1c000
	s_mov_b32 m0, s57
	s_nop 0
	global_load_lds_dwordx4 v130, s[98:99]
	s_mov_b32 m0, s58
	s_nop 0
	global_load_lds_dwordx4 v134, s[98:99]
	ds_read_b128 v[164:167], v232
	ds_read_b128 v[168:171], v232 offset:1024
	ds_read_b128 v[172:175], v232 offset:2048
	ds_read_b128 v[176:179], v232 offset:3072
	ds_read_b128 v[180:183], v233
	ds_read_b128 v[184:187], v233 offset:1024
	ds_read_b128 v[188:191], v233 offset:2048
	ds_read_b128 v[192:195], v233 offset:3072
	ds_read_b128 v[196:199], v160 offset:32768
	ds_read_b128 v[200:203], v160 offset:33792
	ds_read_b128 v[204:207], v160 offset:34816
	ds_read_b128 v[208:211], v160 offset:35840
	ds_read_b128 v[212:215], v160 offset:36864
	ds_read_b128 v[216:219], v160 offset:37888
	ds_read_b128 v[220:223], v160 offset:38912
	ds_read_b128 v[224:227], v160 offset:39936
	s_waitcnt vmcnt(8)
	s_waitcnt lgkmcnt(0)
	.p2align 3
	s_setprio 1
	s_barrier
	v_mfma_f32_16x16x32_bf16 v[122:125], v[164:167], v[196:199], v[122:125]
	v_mfma_f32_16x16x32_bf16 v[118:121], v[172:175], v[196:199], v[118:121]
	v_mfma_f32_16x16x32_bf16 v[110:113], v[164:167], v[204:207], v[110:113]
	v_mfma_f32_16x16x32_bf16 v[102:105], v[172:175], v[204:207], v[102:105]
	v_mfma_f32_16x16x32_bf16 v[94:97], v[164:167], v[212:215], v[94:97]
	v_mfma_f32_16x16x32_bf16 v[86:89], v[172:175], v[212:215], v[86:89]
	v_mfma_f32_16x16x32_bf16 v[78:81], v[164:167], v[220:223], v[78:81]
	v_mfma_f32_16x16x32_bf16 v[70:73], v[172:175], v[220:223], v[70:73]
	v_mfma_f32_16x16x32_bf16 v[122:125], v[168:171], v[200:203], v[122:125]
	v_mfma_f32_16x16x32_bf16 v[118:121], v[176:179], v[200:203], v[118:121]
	v_mfma_f32_16x16x32_bf16 v[110:113], v[168:171], v[208:211], v[110:113]
	v_mfma_f32_16x16x32_bf16 v[102:105], v[176:179], v[208:211], v[102:105]
	v_mfma_f32_16x16x32_bf16 v[94:97], v[168:171], v[216:219], v[94:97]
	v_mfma_f32_16x16x32_bf16 v[86:89], v[176:179], v[216:219], v[86:89]
	v_mfma_f32_16x16x32_bf16 v[78:81], v[168:171], v[224:227], v[78:81]
	v_mfma_f32_16x16x32_bf16 v[70:73], v[176:179], v[224:227], v[70:73]
	s_setprio 0
	s_setprio 1
	v_mfma_f32_16x16x32_bf16 v[126:129], v[180:183], v[196:199], v[126:129]
	v_mfma_f32_16x16x32_bf16 v[114:117], v[188:191], v[196:199], v[114:117]
	v_mfma_f32_16x16x32_bf16 v[106:109], v[180:183], v[204:207], v[106:109]
	v_mfma_f32_16x16x32_bf16 v[98:101], v[188:191], v[204:207], v[98:101]
	v_mfma_f32_16x16x32_bf16 v[90:93], v[180:183], v[212:215], v[90:93]
	v_mfma_f32_16x16x32_bf16 v[82:85], v[188:191], v[212:215], v[82:85]
	v_mfma_f32_16x16x32_bf16 v[74:77], v[180:183], v[220:223], v[74:77]
	v_mfma_f32_16x16x32_bf16 v[66:69], v[188:191], v[220:223], v[66:69]
	v_mfma_f32_16x16x32_bf16 v[126:129], v[184:187], v[200:203], v[126:129]
	v_mfma_f32_16x16x32_bf16 v[114:117], v[192:195], v[200:203], v[114:117]
	v_mfma_f32_16x16x32_bf16 v[106:109], v[184:187], v[208:211], v[106:109]
	v_mfma_f32_16x16x32_bf16 v[98:101], v[192:195], v[208:211], v[98:101]
	v_mfma_f32_16x16x32_bf16 v[90:93], v[184:187], v[216:219], v[90:93]
	v_mfma_f32_16x16x32_bf16 v[82:85], v[192:195], v[216:219], v[82:85]
	v_mfma_f32_16x16x32_bf16 v[74:77], v[184:187], v[224:227], v[74:77]
	v_mfma_f32_16x16x32_bf16 v[66:69], v[192:195], v[224:227], v[66:69]
	s_barrier
	s_setprio 0
	s_add_u32 s96, s96, 0x80
	s_addc_u32 s97, s97, 0
	s_add_u32 s98, s96, 0x40000
	s_addc_u32 s99, s97, 0
	s_add_u32 s94, s94, 0x80
	s_addc_u32 s95, s95, 0
	s_add_i32 s5, s5, s23
	s_mov_b32 m0, s5
	s_nop 0
	global_load_lds_dwordx4 v132, s[96:97]
	s_add_i32 m0, s5, 0x2000
	s_add_i32 s5, s45, s23
	global_load_lds_dwordx4 v136, s[96:97]
	s_mov_b32 m0, s5
	s_nop 0
	global_load_lds_dwordx4 v132, s[98:99]
	s_add_i32 m0, s5, 0x2000
	s_nop 0
	global_load_lds_dwordx4 v136, s[98:99]
	s_mov_b32 m0, s64
	s_nop 0
	global_load_lds_dwordx4 v130, s[94:95]
	s_mov_b32 m0, s65
	s_nop 0
	global_load_lds_dwordx4 v134, s[94:95]
	ds_read_b128 v[196:199], v160 offset:49152
	ds_read_b128 v[200:203], v160 offset:50176
	ds_read_b128 v[204:207], v160 offset:51200
	ds_read_b128 v[208:211], v160 offset:52224
	ds_read_b128 v[212:215], v160 offset:53248
	ds_read_b128 v[216:219], v160 offset:54272
	ds_read_b128 v[220:223], v160 offset:55296
	ds_read_b128 v[224:227], v160 offset:56320
	s_waitcnt vmcnt(8)
	s_waitcnt lgkmcnt(0)
	.p2align 3
	s_setprio 1
	s_barrier
	v_mfma_f32_16x16x32_bf16 v[62:65], v[164:167], v[196:199], v[62:65]
	v_mfma_f32_16x16x32_bf16 v[54:57], v[172:175], v[196:199], v[54:57]
	v_mfma_f32_16x16x32_bf16 v[46:49], v[164:167], v[204:207], v[46:49]
	v_mfma_f32_16x16x32_bf16 v[38:41], v[172:175], v[204:207], v[38:41]
	v_mfma_f32_16x16x32_bf16 v[30:33], v[164:167], v[212:215], v[30:33]
	v_mfma_f32_16x16x32_bf16 v[22:25], v[172:175], v[212:215], v[22:25]
	v_mfma_f32_16x16x32_bf16 v[14:17], v[164:167], v[220:223], v[14:17]
	v_mfma_f32_16x16x32_bf16 v[6:9], v[172:175], v[220:223], v[6:9]
	v_mfma_f32_16x16x32_bf16 v[62:65], v[168:171], v[200:203], v[62:65]
	v_mfma_f32_16x16x32_bf16 v[54:57], v[176:179], v[200:203], v[54:57]
	v_mfma_f32_16x16x32_bf16 v[46:49], v[168:171], v[208:211], v[46:49]
	v_mfma_f32_16x16x32_bf16 v[38:41], v[176:179], v[208:211], v[38:41]
	v_mfma_f32_16x16x32_bf16 v[30:33], v[168:171], v[216:219], v[30:33]
	v_mfma_f32_16x16x32_bf16 v[22:25], v[176:179], v[216:219], v[22:25]
	v_mfma_f32_16x16x32_bf16 v[14:17], v[168:171], v[224:227], v[14:17]
	v_mfma_f32_16x16x32_bf16 v[6:9], v[176:179], v[224:227], v[6:9]
	s_setprio 0
	s_setprio 1
	v_mfma_f32_16x16x32_bf16 v[58:61], v[180:183], v[196:199], v[58:61]
	v_mfma_f32_16x16x32_bf16 v[50:53], v[188:191], v[196:199], v[50:53]
	v_mfma_f32_16x16x32_bf16 v[42:45], v[180:183], v[204:207], v[42:45]
	v_mfma_f32_16x16x32_bf16 v[34:37], v[188:191], v[204:207], v[34:37]
	v_mfma_f32_16x16x32_bf16 v[26:29], v[180:183], v[212:215], v[26:29]
	v_mfma_f32_16x16x32_bf16 v[18:21], v[188:191], v[212:215], v[18:21]
	v_mfma_f32_16x16x32_bf16 v[10:13], v[180:183], v[220:223], v[10:13]
	v_mfma_f32_16x16x32_bf16 v[2:5], v[188:191], v[220:223], v[2:5]
	v_mfma_f32_16x16x32_bf16 v[58:61], v[184:187], v[200:203], v[58:61]
	v_mfma_f32_16x16x32_bf16 v[50:53], v[192:195], v[200:203], v[50:53]
	v_mfma_f32_16x16x32_bf16 v[42:45], v[184:187], v[208:211], v[42:45]
	v_mfma_f32_16x16x32_bf16 v[34:37], v[192:195], v[208:211], v[34:37]
	v_mfma_f32_16x16x32_bf16 v[26:29], v[184:187], v[216:219], v[26:29]
	v_mfma_f32_16x16x32_bf16 v[18:21], v[192:195], v[216:219], v[18:21]
	v_mfma_f32_16x16x32_bf16 v[10:13], v[184:187], v[224:227], v[10:13]
	v_mfma_f32_16x16x32_bf16 v[2:5], v[192:195], v[224:227], v[2:5]
	s_barrier
	s_setprio 0
	s_mov_b32 s5, s29
	s_add_u32 s88, s88, 0x100
	s_addc_u32 s89, s89, 0
	s_add_u32 s86, s86, 0x100
	s_addc_u32 s87, s87, 0
	s_cmp_ge_i32 s29, s101
	s_cbranch_scc1 .Lmy_kexit_9
.LBB0_1763:
	s_add_u32 s98, s86, 0xfffc0080
	s_addc_u32 s99, s87, -1
	s_cmp_eq_u32 s5, s100
	s_cselect_b64 s[94:95], s[90:91], s[98:99]
	s_cselect_b64 s[96:97], s[92:93], s[88:89]
	s_add_i32 s29, s5, 2
	s_nop 0
	s_add_i32 m0, s47, 0xc000
	s_nop 0
	global_load_lds_dwordx4 v144, s[86:87]
	s_add_i32 m0, s47, 0xe000
	s_nop 0
	global_load_lds_dwordx4 v142, s[86:87]
	ds_read_b128 v[164:167], v230
	ds_read_b128 v[168:171], v230 offset:1024
	ds_read_b128 v[172:175], v230 offset:2048
	ds_read_b128 v[176:179], v230 offset:3072
	ds_read_b128 v[180:183], v231
	ds_read_b128 v[184:187], v231 offset:1024
	ds_read_b128 v[188:191], v231 offset:2048
	ds_read_b128 v[192:195], v231 offset:3072
	ds_read_b128 v[196:199], v160
	ds_read_b128 v[200:203], v160 offset:1024
	ds_read_b128 v[204:207], v160 offset:2048
	ds_read_b128 v[208:211], v160 offset:3072
	ds_read_b128 v[212:215], v160 offset:4096
	ds_read_b128 v[216:219], v160 offset:5120
	ds_read_b128 v[220:223], v160 offset:6144
	ds_read_b128 v[224:227], v160 offset:7168
	s_waitcnt vmcnt(8)
	s_waitcnt lgkmcnt(0)
	.p2align 3
	s_setprio 1
	s_barrier
	v_mfma_f32_16x16x32_bf16 v[122:125], v[164:167], v[196:199], v[122:125]
	v_mfma_f32_16x16x32_bf16 v[118:121], v[172:175], v[196:199], v[118:121]
	v_mfma_f32_16x16x32_bf16 v[110:113], v[164:167], v[204:207], v[110:113]
	v_mfma_f32_16x16x32_bf16 v[102:105], v[172:175], v[204:207], v[102:105]
	v_mfma_f32_16x16x32_bf16 v[94:97], v[164:167], v[212:215], v[94:97]
	v_mfma_f32_16x16x32_bf16 v[86:89], v[172:175], v[212:215], v[86:89]
	v_mfma_f32_16x16x32_bf16 v[78:81], v[164:167], v[220:223], v[78:81]
	v_mfma_f32_16x16x32_bf16 v[70:73], v[172:175], v[220:223], v[70:73]
	v_mfma_f32_16x16x32_bf16 v[122:125], v[168:171], v[200:203], v[122:125]
	v_mfma_f32_16x16x32_bf16 v[118:121], v[176:179], v[200:203], v[118:121]
	v_mfma_f32_16x16x32_bf16 v[110:113], v[168:171], v[208:211], v[110:113]
	v_mfma_f32_16x16x32_bf16 v[102:105], v[176:179], v[208:211], v[102:105]
	v_mfma_f32_16x16x32_bf16 v[94:97], v[168:171], v[216:219], v[94:97]
	v_mfma_f32_16x16x32_bf16 v[86:89], v[176:179], v[216:219], v[86:89]
	v_mfma_f32_16x16x32_bf16 v[78:81], v[168:171], v[224:227], v[78:81]
	v_mfma_f32_16x16x32_bf16 v[70:73], v[176:179], v[224:227], v[70:73]
	s_setprio 0
	s_setprio 1
	v_mfma_f32_16x16x32_bf16 v[126:129], v[180:183], v[196:199], v[126:129]
	v_mfma_f32_16x16x32_bf16 v[114:117], v[188:191], v[196:199], v[114:117]
	v_mfma_f32_16x16x32_bf16 v[106:109], v[180:183], v[204:207], v[106:109]
	v_mfma_f32_16x16x32_bf16 v[98:101], v[188:191], v[204:207], v[98:101]
	v_mfma_f32_16x16x32_bf16 v[90:93], v[180:183], v[212:215], v[90:93]
	v_mfma_f32_16x16x32_bf16 v[82:85], v[188:191], v[212:215], v[82:85]
	v_mfma_f32_16x16x32_bf16 v[74:77], v[180:183], v[220:223], v[74:77]
	v_mfma_f32_16x16x32_bf16 v[66:69], v[188:191], v[220:223], v[66:69]
	v_mfma_f32_16x16x32_bf16 v[126:129], v[184:187], v[200:203], v[126:129]
	v_mfma_f32_16x16x32_bf16 v[114:117], v[192:195], v[200:203], v[114:117]
	v_mfma_f32_16x16x32_bf16 v[106:109], v[184:187], v[208:211], v[106:109]
	v_mfma_f32_16x16x32_bf16 v[98:101], v[192:195], v[208:211], v[98:101]
	v_mfma_f32_16x16x32_bf16 v[90:93], v[184:187], v[216:219], v[90:93]
	v_mfma_f32_16x16x32_bf16 v[82:85], v[192:195], v[216:219], v[82:85]
	v_mfma_f32_16x16x32_bf16 v[74:77], v[184:187], v[224:227], v[74:77]
	v_mfma_f32_16x16x32_bf16 v[66:69], v[192:195], v[224:227], v[66:69]
	s_barrier
	s_setprio 0
	s_add_u32 s98, s96, 0x40000
	s_addc_u32 s99, s97, 0
	s_add_i32 s5, s74, s23
	s_mov_b32 m0, s5
	s_nop 0
	global_load_lds_dwordx4 v132, s[96:97]
	s_add_i32 m0, s5, 0x2000
	s_add_i32 s5, s75, s23
	global_load_lds_dwordx4 v136, s[96:97]
	s_mov_b32 m0, s5
	s_nop 0
	global_load_lds_dwordx4 v132, s[98:99]
	s_add_i32 m0, s5, 0x2000
	s_nop 0
	global_load_lds_dwordx4 v136, s[98:99]
	s_mov_b32 m0, s47
	s_nop 0
	global_load_lds_dwordx4 v130, s[94:95]
	s_mov_b32 m0, s56
	s_nop 0
	global_load_lds_dwordx4 v134, s[94:95]
	ds_read_b128 v[196:199], v160 offset:16384
	ds_read_b128 v[200:203], v160 offset:17408
	ds_read_b128 v[204:207], v160 offset:18432
	ds_read_b128 v[208:211], v160 offset:19456
	ds_read_b128 v[212:215], v160 offset:20480
	ds_read_b128 v[216:219], v160 offset:21504
	ds_read_b128 v[220:223], v160 offset:22528
	ds_read_b128 v[224:227], v160 offset:23552
	s_waitcnt vmcnt(8)
	s_waitcnt lgkmcnt(0)
	.p2align 3
	s_setprio 1
	s_barrier
	v_mfma_f32_16x16x32_bf16 v[62:65], v[164:167], v[196:199], v[62:65]
	v_mfma_f32_16x16x32_bf16 v[54:57], v[172:175], v[196:199], v[54:57]
	v_mfma_f32_16x16x32_bf16 v[46:49], v[164:167], v[204:207], v[46:49]
	v_mfma_f32_16x16x32_bf16 v[38:41], v[172:175], v[204:207], v[38:41]
	v_mfma_f32_16x16x32_bf16 v[30:33], v[164:167], v[212:215], v[30:33]
	v_mfma_f32_16x16x32_bf16 v[22:25], v[172:175], v[212:215], v[22:25]
	v_mfma_f32_16x16x32_bf16 v[14:17], v[164:167], v[220:223], v[14:17]
	v_mfma_f32_16x16x32_bf16 v[6:9], v[172:175], v[220:223], v[6:9]
	v_mfma_f32_16x16x32_bf16 v[62:65], v[168:171], v[200:203], v[62:65]
	v_mfma_f32_16x16x32_bf16 v[54:57], v[176:179], v[200:203], v[54:57]
	v_mfma_f32_16x16x32_bf16 v[46:49], v[168:171], v[208:211], v[46:49]
	v_mfma_f32_16x16x32_bf16 v[38:41], v[176:179], v[208:211], v[38:41]
	v_mfma_f32_16x16x32_bf16 v[30:33], v[168:171], v[216:219], v[30:33]
	v_mfma_f32_16x16x32_bf16 v[22:25], v[176:179], v[216:219], v[22:25]
	v_mfma_f32_16x16x32_bf16 v[14:17], v[168:171], v[224:227], v[14:17]
	v_mfma_f32_16x16x32_bf16 v[6:9], v[176:179], v[224:227], v[6:9]
	s_setprio 0
	s_setprio 1
	v_mfma_f32_16x16x32_bf16 v[58:61], v[180:183], v[196:199], v[58:61]
	v_mfma_f32_16x16x32_bf16 v[50:53], v[188:191], v[196:199], v[50:53]
	v_mfma_f32_16x16x32_bf16 v[42:45], v[180:183], v[204:207], v[42:45]
	v_mfma_f32_16x16x32_bf16 v[34:37], v[188:191], v[204:207], v[34:37]
	v_mfma_f32_16x16x32_bf16 v[26:29], v[180:183], v[212:215], v[26:29]
	v_mfma_f32_16x16x32_bf16 v[18:21], v[188:191], v[212:215], v[18:21]
	v_mfma_f32_16x16x32_bf16 v[10:13], v[180:183], v[220:223], v[10:13]
	v_mfma_f32_16x16x32_bf16 v[2:5], v[188:191], v[220:223], v[2:5]
	v_mfma_f32_16x16x32_bf16 v[58:61], v[184:187], v[200:203], v[58:61]
	v_mfma_f32_16x16x32_bf16 v[50:53], v[192:195], v[200:203], v[50:53]
	v_mfma_f32_16x16x32_bf16 v[42:45], v[184:187], v[208:211], v[42:45]
	v_mfma_f32_16x16x32_bf16 v[34:37], v[192:195], v[208:211], v[34:37]
	v_mfma_f32_16x16x32_bf16 v[26:29], v[184:187], v[216:219], v[26:29]
	v_mfma_f32_16x16x32_bf16 v[18:21], v[192:195], v[216:219], v[18:21]
	v_mfma_f32_16x16x32_bf16 v[10:13], v[184:187], v[224:227], v[10:13]
	v_mfma_f32_16x16x32_bf16 v[2:5], v[192:195], v[224:227], v[2:5]
	s_barrier
	s_setprio 0
	s_add_u32 s98, s94, 0x40000
	s_addc_u32 s99, s95, 0
	s_add_i32 s5, 0, 0x18000
	s_add_i32 s45, 0, 0x1c000
	s_mov_b32 m0, s57
	s_nop 0
	global_load_lds_dwordx4 v130, s[98:99]
	s_mov_b32 m0, s58
	s_nop 0
	global_load_lds_dwordx4 v134, s[98:99]
	ds_read_b128 v[164:167], v232
	ds_read_b128 v[168:171], v232 offset:1024
	ds_read_b128 v[172:175], v232 offset:2048
	ds_read_b128 v[176:179], v232 offset:3072
	ds_read_b128 v[180:183], v233
	ds_read_b128 v[184:187], v233 offset:1024
	ds_read_b128 v[188:191], v233 offset:2048
	ds_read_b128 v[192:195], v233 offset:3072
	ds_read_b128 v[196:199], v160 offset:32768
	ds_read_b128 v[200:203], v160 offset:33792
	ds_read_b128 v[204:207], v160 offset:34816
	ds_read_b128 v[208:211], v160 offset:35840
	ds_read_b128 v[212:215], v160 offset:36864
	ds_read_b128 v[216:219], v160 offset:37888
	ds_read_b128 v[220:223], v160 offset:38912
	ds_read_b128 v[224:227], v160 offset:39936
	s_waitcnt vmcnt(8)
	s_waitcnt lgkmcnt(0)
	.p2align 3
	s_setprio 1
	s_barrier
	v_mfma_f32_16x16x32_bf16 v[122:125], v[164:167], v[196:199], v[122:125]
	v_mfma_f32_16x16x32_bf16 v[118:121], v[172:175], v[196:199], v[118:121]
	v_mfma_f32_16x16x32_bf16 v[110:113], v[164:167], v[204:207], v[110:113]
	v_mfma_f32_16x16x32_bf16 v[102:105], v[172:175], v[204:207], v[102:105]
	v_mfma_f32_16x16x32_bf16 v[94:97], v[164:167], v[212:215], v[94:97]
	v_mfma_f32_16x16x32_bf16 v[86:89], v[172:175], v[212:215], v[86:89]
	v_mfma_f32_16x16x32_bf16 v[78:81], v[164:167], v[220:223], v[78:81]
	v_mfma_f32_16x16x32_bf16 v[70:73], v[172:175], v[220:223], v[70:73]
	v_mfma_f32_16x16x32_bf16 v[122:125], v[168:171], v[200:203], v[122:125]
	v_mfma_f32_16x16x32_bf16 v[118:121], v[176:179], v[200:203], v[118:121]
	v_mfma_f32_16x16x32_bf16 v[110:113], v[168:171], v[208:211], v[110:113]
	v_mfma_f32_16x16x32_bf16 v[102:105], v[176:179], v[208:211], v[102:105]
	v_mfma_f32_16x16x32_bf16 v[94:97], v[168:171], v[216:219], v[94:97]
	v_mfma_f32_16x16x32_bf16 v[86:89], v[176:179], v[216:219], v[86:89]
	v_mfma_f32_16x16x32_bf16 v[78:81], v[168:171], v[224:227], v[78:81]
	v_mfma_f32_16x16x32_bf16 v[70:73], v[176:179], v[224:227], v[70:73]
	s_setprio 0
	s_setprio 1
	v_mfma_f32_16x16x32_bf16 v[126:129], v[180:183], v[196:199], v[126:129]
	v_mfma_f32_16x16x32_bf16 v[114:117], v[188:191], v[196:199], v[114:117]
	v_mfma_f32_16x16x32_bf16 v[106:109], v[180:183], v[204:207], v[106:109]
	v_mfma_f32_16x16x32_bf16 v[98:101], v[188:191], v[204:207], v[98:101]
	v_mfma_f32_16x16x32_bf16 v[90:93], v[180:183], v[212:215], v[90:93]
	v_mfma_f32_16x16x32_bf16 v[82:85], v[188:191], v[212:215], v[82:85]
	v_mfma_f32_16x16x32_bf16 v[74:77], v[180:183], v[220:223], v[74:77]
	v_mfma_f32_16x16x32_bf16 v[66:69], v[188:191], v[220:223], v[66:69]
	v_mfma_f32_16x16x32_bf16 v[126:129], v[184:187], v[200:203], v[126:129]
	v_mfma_f32_16x16x32_bf16 v[114:117], v[192:195], v[200:203], v[114:117]
	v_mfma_f32_16x16x32_bf16 v[106:109], v[184:187], v[208:211], v[106:109]
	v_mfma_f32_16x16x32_bf16 v[98:101], v[192:195], v[208:211], v[98:101]
	v_mfma_f32_16x16x32_bf16 v[90:93], v[184:187], v[216:219], v[90:93]
	v_mfma_f32_16x16x32_bf16 v[82:85], v[192:195], v[216:219], v[82:85]
	v_mfma_f32_16x16x32_bf16 v[74:77], v[184:187], v[224:227], v[74:77]
	v_mfma_f32_16x16x32_bf16 v[66:69], v[192:195], v[224:227], v[66:69]
	s_barrier
	s_setprio 0
	s_add_u32 s96, s96, 0x80
	s_addc_u32 s97, s97, 0
	s_add_u32 s98, s96, 0x40000
	s_addc_u32 s99, s97, 0
	s_add_u32 s94, s94, 0x80
	s_addc_u32 s95, s95, 0
	s_add_i32 s5, s5, s23
	s_mov_b32 m0, s5
	s_nop 0
	global_load_lds_dwordx4 v132, s[96:97]
	s_add_i32 m0, s5, 0x2000
	s_add_i32 s5, s45, s23
	global_load_lds_dwordx4 v136, s[96:97]
	s_mov_b32 m0, s5
	s_nop 0
	global_load_lds_dwordx4 v132, s[98:99]
	s_add_i32 m0, s5, 0x2000
	s_nop 0
	global_load_lds_dwordx4 v136, s[98:99]
	s_mov_b32 m0, s64
	s_nop 0
	global_load_lds_dwordx4 v130, s[94:95]
	s_mov_b32 m0, s65
	s_nop 0
	global_load_lds_dwordx4 v134, s[94:95]
	ds_read_b128 v[196:199], v160 offset:49152
	ds_read_b128 v[200:203], v160 offset:50176
	ds_read_b128 v[204:207], v160 offset:51200
	ds_read_b128 v[208:211], v160 offset:52224
	ds_read_b128 v[212:215], v160 offset:53248
	ds_read_b128 v[216:219], v160 offset:54272
	ds_read_b128 v[220:223], v160 offset:55296
	ds_read_b128 v[224:227], v160 offset:56320
	s_waitcnt vmcnt(8)
	s_waitcnt lgkmcnt(0)
	.p2align 3
	s_setprio 1
	s_barrier
	v_mfma_f32_16x16x32_bf16 v[62:65], v[164:167], v[196:199], v[62:65]
	v_mfma_f32_16x16x32_bf16 v[54:57], v[172:175], v[196:199], v[54:57]
	v_mfma_f32_16x16x32_bf16 v[46:49], v[164:167], v[204:207], v[46:49]
	v_mfma_f32_16x16x32_bf16 v[38:41], v[172:175], v[204:207], v[38:41]
	v_mfma_f32_16x16x32_bf16 v[30:33], v[164:167], v[212:215], v[30:33]
	v_mfma_f32_16x16x32_bf16 v[22:25], v[172:175], v[212:215], v[22:25]
	v_mfma_f32_16x16x32_bf16 v[14:17], v[164:167], v[220:223], v[14:17]
	v_mfma_f32_16x16x32_bf16 v[6:9], v[172:175], v[220:223], v[6:9]
	v_mfma_f32_16x16x32_bf16 v[62:65], v[168:171], v[200:203], v[62:65]
	v_mfma_f32_16x16x32_bf16 v[54:57], v[176:179], v[200:203], v[54:57]
	v_mfma_f32_16x16x32_bf16 v[46:49], v[168:171], v[208:211], v[46:49]
	v_mfma_f32_16x16x32_bf16 v[38:41], v[176:179], v[208:211], v[38:41]
	v_mfma_f32_16x16x32_bf16 v[30:33], v[168:171], v[216:219], v[30:33]
	v_mfma_f32_16x16x32_bf16 v[22:25], v[176:179], v[216:219], v[22:25]
	v_mfma_f32_16x16x32_bf16 v[14:17], v[168:171], v[224:227], v[14:17]
	v_mfma_f32_16x16x32_bf16 v[6:9], v[176:179], v[224:227], v[6:9]
	s_setprio 0
	s_setprio 1
	v_mfma_f32_16x16x32_bf16 v[58:61], v[180:183], v[196:199], v[58:61]
	v_mfma_f32_16x16x32_bf16 v[50:53], v[188:191], v[196:199], v[50:53]
	v_mfma_f32_16x16x32_bf16 v[42:45], v[180:183], v[204:207], v[42:45]
	v_mfma_f32_16x16x32_bf16 v[34:37], v[188:191], v[204:207], v[34:37]
	v_mfma_f32_16x16x32_bf16 v[26:29], v[180:183], v[212:215], v[26:29]
	v_mfma_f32_16x16x32_bf16 v[18:21], v[188:191], v[212:215], v[18:21]
	v_mfma_f32_16x16x32_bf16 v[10:13], v[180:183], v[220:223], v[10:13]
	v_mfma_f32_16x16x32_bf16 v[2:5], v[188:191], v[220:223], v[2:5]
	v_mfma_f32_16x16x32_bf16 v[58:61], v[184:187], v[200:203], v[58:61]
	v_mfma_f32_16x16x32_bf16 v[50:53], v[192:195], v[200:203], v[50:53]
	v_mfma_f32_16x16x32_bf16 v[42:45], v[184:187], v[208:211], v[42:45]
	v_mfma_f32_16x16x32_bf16 v[34:37], v[192:195], v[208:211], v[34:37]
	v_mfma_f32_16x16x32_bf16 v[26:29], v[184:187], v[216:219], v[26:29]
	v_mfma_f32_16x16x32_bf16 v[18:21], v[192:195], v[216:219], v[18:21]
	v_mfma_f32_16x16x32_bf16 v[10:13], v[184:187], v[224:227], v[10:13]
	v_mfma_f32_16x16x32_bf16 v[2:5], v[192:195], v[224:227], v[2:5]
	s_barrier
	s_setprio 0
	s_mov_b32 s5, s29
	s_add_u32 s88, s88, 0x100
	s_addc_u32 s89, s89, 0
	s_add_u32 s86, s86, 0x100
	s_addc_u32 s87, s87, 0
	s_cmp_ge_i32 s29, s101
	s_cbranch_scc0 .LBB0_1763

.Lmy_nb_10:
	s_nop 0
	v_readfirstlane_b32 s86, v152
	v_readfirstlane_b32 s87, v153
	v_readfirstlane_b32 s88, v150
	v_readfirstlane_b32 s89, v151
	v_readfirstlane_b32 s90, v146
	v_readfirstlane_b32 s91, v147
	v_readfirstlane_b32 s92, v148
	v_readfirstlane_b32 s93, v149
	v_readfirstlane_b32 s100, v154
	v_readfirstlane_b32 s101, v138
	v_add_u32_e32 v230, s72, v141
	v_add_u32_e32 v231, s73, v141
	v_add_u32_e32 v232, 0x18000, v141
	v_add_u32_e32 v233, 0x1c000, v141
	s_add_u32 s98, s86, 0xfffc0080
	s_addc_u32 s99, s87, -1
	s_cmp_eq_u32 s5, s100
	s_cselect_b64 s[94:95], s[90:91], s[98:99]
	s_cselect_b64 s[96:97], s[92:93], s[88:89]
	s_add_i32 s45, s5, 2
	s_nop 0
	s_mov_b32 m0, s74
	s_nop 0
	global_load_lds_dwordx4 v144, s[86:87]
	s_mov_b32 m0, s75
	s_nop 0
	global_load_lds_dwordx4 v142, s[86:87]
	ds_read_b128 v[164:167], v230
	ds_read_b128 v[168:171], v230 offset:1024
	ds_read_b128 v[172:175], v230 offset:2048
	ds_read_b128 v[176:179], v230 offset:3072
	ds_read_b128 v[180:183], v231
	ds_read_b128 v[184:187], v231 offset:1024
	ds_read_b128 v[188:191], v231 offset:2048
	ds_read_b128 v[192:195], v231 offset:3072
	ds_read_b128 v[196:199], v160
	ds_read_b128 v[200:203], v160 offset:1024
	ds_read_b128 v[204:207], v160 offset:2048
	ds_read_b128 v[208:211], v160 offset:3072
	ds_read_b128 v[212:215], v160 offset:4096
	ds_read_b128 v[216:219], v160 offset:5120
	ds_read_b128 v[220:223], v160 offset:6144
	ds_read_b128 v[224:227], v160 offset:7168
	s_waitcnt vmcnt(8)
	s_waitcnt lgkmcnt(0)
	.p2align 3
	s_setprio 1
	s_barrier
	v_mfma_f32_16x16x32_bf16 v[122:125], v[164:167], v[196:199], 0
	v_mfma_f32_16x16x32_bf16 v[118:121], v[172:175], v[196:199], 0
	v_mfma_f32_16x16x32_bf16 v[110:113], v[164:167], v[204:207], 0
	v_mfma_f32_16x16x32_bf16 v[102:105], v[172:175], v[204:207], 0
	v_mfma_f32_16x16x32_bf16 v[94:97], v[164:167], v[212:215], 0
	v_mfma_f32_16x16x32_bf16 v[86:89], v[172:175], v[212:215], 0
	v_mfma_f32_16x16x32_bf16 v[78:81], v[164:167], v[220:223], 0
	v_mfma_f32_16x16x32_bf16 v[70:73], v[172:175], v[220:223], 0
	v_mfma_f32_16x16x32_bf16 v[122:125], v[168:171], v[200:203], v[122:125]
	v_mfma_f32_16x16x32_bf16 v[118:121], v[176:179], v[200:203], v[118:121]
	v_mfma_f32_16x16x32_bf16 v[110:113], v[168:171], v[208:211], v[110:113]
	v_mfma_f32_16x16x32_bf16 v[102:105], v[176:179], v[208:211], v[102:105]
	v_mfma_f32_16x16x32_bf16 v[94:97], v[168:171], v[216:219], v[94:97]
	v_mfma_f32_16x16x32_bf16 v[86:89], v[176:179], v[216:219], v[86:89]
	v_mfma_f32_16x16x32_bf16 v[78:81], v[168:171], v[224:227], v[78:81]
	v_mfma_f32_16x16x32_bf16 v[70:73], v[176:179], v[224:227], v[70:73]
	s_setprio 0
	s_setprio 1
	v_mfma_f32_16x16x32_bf16 v[126:129], v[180:183], v[196:199], 0
	v_mfma_f32_16x16x32_bf16 v[114:117], v[188:191], v[196:199], 0
	v_mfma_f32_16x16x32_bf16 v[106:109], v[180:183], v[204:207], 0
	v_mfma_f32_16x16x32_bf16 v[98:101], v[188:191], v[204:207], 0
	v_mfma_f32_16x16x32_bf16 v[90:93], v[180:183], v[212:215], 0
	v_mfma_f32_16x16x32_bf16 v[82:85], v[188:191], v[212:215], 0
	v_mfma_f32_16x16x32_bf16 v[74:77], v[180:183], v[220:223], 0
	v_mfma_f32_16x16x32_bf16 v[66:69], v[188:191], v[220:223], 0
	v_mfma_f32_16x16x32_bf16 v[126:129], v[184:187], v[200:203], v[126:129]
	v_mfma_f32_16x16x32_bf16 v[114:117], v[192:195], v[200:203], v[114:117]
	v_mfma_f32_16x16x32_bf16 v[106:109], v[184:187], v[208:211], v[106:109]
	v_mfma_f32_16x16x32_bf16 v[98:101], v[192:195], v[208:211], v[98:101]
	v_mfma_f32_16x16x32_bf16 v[90:93], v[184:187], v[216:219], v[90:93]
	v_mfma_f32_16x16x32_bf16 v[82:85], v[192:195], v[216:219], v[82:85]
	v_mfma_f32_16x16x32_bf16 v[74:77], v[184:187], v[224:227], v[74:77]
	v_mfma_f32_16x16x32_bf16 v[66:69], v[192:195], v[224:227], v[66:69]
	s_barrier
	s_setprio 0
	s_add_u32 s98, s96, 0x40000
	s_addc_u32 s99, s97, 0
	s_mov_b32 m0, s76
	s_nop 0
	global_load_lds_dwordx4 v132, s[96:97]
	s_mov_b32 m0, s77
	s_add_i32 s5, s73, s25
	global_load_lds_dwordx4 v136, s[96:97]
	s_mov_b32 m0, s5
	s_nop 0
	global_load_lds_dwordx4 v132, s[98:99]
	s_add_i32 m0, s5, 0x2000
	s_nop 0
	global_load_lds_dwordx4 v136, s[98:99]
	s_mov_b32 m0, s49
	s_nop 0
	global_load_lds_dwordx4 v130, s[94:95]
	s_mov_b32 m0, s58
	s_nop 0
	global_load_lds_dwordx4 v134, s[94:95]
	ds_read_b128 v[196:199], v160 offset:16384
	ds_read_b128 v[200:203], v160 offset:17408
	ds_read_b128 v[204:207], v160 offset:18432
	ds_read_b128 v[208:211], v160 offset:19456
	ds_read_b128 v[212:215], v160 offset:20480
	ds_read_b128 v[216:219], v160 offset:21504
	ds_read_b128 v[220:223], v160 offset:22528
	ds_read_b128 v[224:227], v160 offset:23552
	s_waitcnt vmcnt(8)
	s_waitcnt lgkmcnt(0)
	.p2align 3
	s_setprio 1
	s_barrier
	v_mfma_f32_16x16x32_bf16 v[62:65], v[164:167], v[196:199], 0
	v_mfma_f32_16x16x32_bf16 v[54:57], v[172:175], v[196:199], 0
	v_mfma_f32_16x16x32_bf16 v[46:49], v[164:167], v[204:207], 0
	v_mfma_f32_16x16x32_bf16 v[38:41], v[172:175], v[204:207], 0
	v_mfma_f32_16x16x32_bf16 v[30:33], v[164:167], v[212:215], 0
	v_mfma_f32_16x16x32_bf16 v[22:25], v[172:175], v[212:215], 0
	v_mfma_f32_16x16x32_bf16 v[14:17], v[164:167], v[220:223], 0
	v_mfma_f32_16x16x32_bf16 v[6:9], v[172:175], v[220:223], 0
	v_mfma_f32_16x16x32_bf16 v[62:65], v[168:171], v[200:203], v[62:65]
	v_mfma_f32_16x16x32_bf16 v[54:57], v[176:179], v[200:203], v[54:57]
	v_mfma_f32_16x16x32_bf16 v[46:49], v[168:171], v[208:211], v[46:49]
	v_mfma_f32_16x16x32_bf16 v[38:41], v[176:179], v[208:211], v[38:41]
	v_mfma_f32_16x16x32_bf16 v[30:33], v[168:171], v[216:219], v[30:33]
	v_mfma_f32_16x16x32_bf16 v[22:25], v[176:179], v[216:219], v[22:25]
	v_mfma_f32_16x16x32_bf16 v[14:17], v[168:171], v[224:227], v[14:17]
	v_mfma_f32_16x16x32_bf16 v[6:9], v[176:179], v[224:227], v[6:9]
	s_setprio 0
	s_setprio 1
	v_mfma_f32_16x16x32_bf16 v[58:61], v[180:183], v[196:199], 0
	v_mfma_f32_16x16x32_bf16 v[50:53], v[188:191], v[196:199], 0
	v_mfma_f32_16x16x32_bf16 v[42:45], v[180:183], v[204:207], 0
	v_mfma_f32_16x16x32_bf16 v[34:37], v[188:191], v[204:207], 0
	v_mfma_f32_16x16x32_bf16 v[26:29], v[180:183], v[212:215], 0
	v_mfma_f32_16x16x32_bf16 v[18:21], v[188:191], v[212:215], 0
	v_mfma_f32_16x16x32_bf16 v[10:13], v[180:183], v[220:223], 0
	v_mfma_f32_16x16x32_bf16 v[2:5], v[188:191], v[220:223], 0
	v_mfma_f32_16x16x32_bf16 v[58:61], v[184:187], v[200:203], v[58:61]
	v_mfma_f32_16x16x32_bf16 v[50:53], v[192:195], v[200:203], v[50:53]
	v_mfma_f32_16x16x32_bf16 v[42:45], v[184:187], v[208:211], v[42:45]
	v_mfma_f32_16x16x32_bf16 v[34:37], v[192:195], v[208:211], v[34:37]
	v_mfma_f32_16x16x32_bf16 v[26:29], v[184:187], v[216:219], v[26:29]
	v_mfma_f32_16x16x32_bf16 v[18:21], v[192:195], v[216:219], v[18:21]
	v_mfma_f32_16x16x32_bf16 v[10:13], v[184:187], v[224:227], v[10:13]
	v_mfma_f32_16x16x32_bf16 v[2:5], v[192:195], v[224:227], v[2:5]
	s_barrier
	s_setprio 0
	s_add_u32 s98, s94, 0x40000
	s_addc_u32 s99, s95, 0
	s_add_i32 s5, 0, 0x18000
	s_add_i32 s47, 0, 0x1c000
	s_mov_b32 m0, s59
	s_nop 0
	global_load_lds_dwordx4 v130, s[98:99]
	s_mov_b32 m0, s60
	s_nop 0
	global_load_lds_dwordx4 v134, s[98:99]
	ds_read_b128 v[164:167], v232
	ds_read_b128 v[168:171], v232 offset:1024
	ds_read_b128 v[172:175], v232 offset:2048
	ds_read_b128 v[176:179], v232 offset:3072
	ds_read_b128 v[180:183], v233
	ds_read_b128 v[184:187], v233 offset:1024
	ds_read_b128 v[188:191], v233 offset:2048
	ds_read_b128 v[192:195], v233 offset:3072
	ds_read_b128 v[196:199], v160 offset:32768
	ds_read_b128 v[200:203], v160 offset:33792
	ds_read_b128 v[204:207], v160 offset:34816
	ds_read_b128 v[208:211], v160 offset:35840
	ds_read_b128 v[212:215], v160 offset:36864
	ds_read_b128 v[216:219], v160 offset:37888
	ds_read_b128 v[220:223], v160 offset:38912
	ds_read_b128 v[224:227], v160 offset:39936
	s_waitcnt vmcnt(8)
	s_waitcnt lgkmcnt(0)
	.p2align 3
	s_setprio 1
	s_barrier
	v_mfma_f32_16x16x32_bf16 v[122:125], v[164:167], v[196:199], v[122:125]
	v_mfma_f32_16x16x32_bf16 v[118:121], v[172:175], v[196:199], v[118:121]
	v_mfma_f32_16x16x32_bf16 v[110:113], v[164:167], v[204:207], v[110:113]
	v_mfma_f32_16x16x32_bf16 v[102:105], v[172:175], v[204:207], v[102:105]
	v_mfma_f32_16x16x32_bf16 v[94:97], v[164:167], v[212:215], v[94:97]
	v_mfma_f32_16x16x32_bf16 v[86:89], v[172:175], v[212:215], v[86:89]
	v_mfma_f32_16x16x32_bf16 v[78:81], v[164:167], v[220:223], v[78:81]
	v_mfma_f32_16x16x32_bf16 v[70:73], v[172:175], v[220:223], v[70:73]
	v_mfma_f32_16x16x32_bf16 v[122:125], v[168:171], v[200:203], v[122:125]
	v_mfma_f32_16x16x32_bf16 v[118:121], v[176:179], v[200:203], v[118:121]
	v_mfma_f32_16x16x32_bf16 v[110:113], v[168:171], v[208:211], v[110:113]
	v_mfma_f32_16x16x32_bf16 v[102:105], v[176:179], v[208:211], v[102:105]
	v_mfma_f32_16x16x32_bf16 v[94:97], v[168:171], v[216:219], v[94:97]
	v_mfma_f32_16x16x32_bf16 v[86:89], v[176:179], v[216:219], v[86:89]
	v_mfma_f32_16x16x32_bf16 v[78:81], v[168:171], v[224:227], v[78:81]
	v_mfma_f32_16x16x32_bf16 v[70:73], v[176:179], v[224:227], v[70:73]
	s_setprio 0
	s_setprio 1
	v_mfma_f32_16x16x32_bf16 v[126:129], v[180:183], v[196:199], v[126:129]
	v_mfma_f32_16x16x32_bf16 v[114:117], v[188:191], v[196:199], v[114:117]
	v_mfma_f32_16x16x32_bf16 v[106:109], v[180:183], v[204:207], v[106:109]
	v_mfma_f32_16x16x32_bf16 v[98:101], v[188:191], v[204:207], v[98:101]
	v_mfma_f32_16x16x32_bf16 v[90:93], v[180:183], v[212:215], v[90:93]
	v_mfma_f32_16x16x32_bf16 v[82:85], v[188:191], v[212:215], v[82:85]
	v_mfma_f32_16x16x32_bf16 v[74:77], v[180:183], v[220:223], v[74:77]
	v_mfma_f32_16x16x32_bf16 v[66:69], v[188:191], v[220:223], v[66:69]
	v_mfma_f32_16x16x32_bf16 v[126:129], v[184:187], v[200:203], v[126:129]
	v_mfma_f32_16x16x32_bf16 v[114:117], v[192:195], v[200:203], v[114:117]
	v_mfma_f32_16x16x32_bf16 v[106:109], v[184:187], v[208:211], v[106:109]
	v_mfma_f32_16x16x32_bf16 v[98:101], v[192:195], v[208:211], v[98:101]
	v_mfma_f32_16x16x32_bf16 v[90:93], v[184:187], v[216:219], v[90:93]
	v_mfma_f32_16x16x32_bf16 v[82:85], v[192:195], v[216:219], v[82:85]
	v_mfma_f32_16x16x32_bf16 v[74:77], v[184:187], v[224:227], v[74:77]
	v_mfma_f32_16x16x32_bf16 v[66:69], v[192:195], v[224:227], v[66:69]
	s_barrier
	s_setprio 0
	s_add_u32 s96, s96, 0x80
	s_addc_u32 s97, s97, 0
	s_add_u32 s98, s96, 0x40000
	s_addc_u32 s99, s97, 0
	s_add_u32 s94, s94, 0x80
	s_addc_u32 s95, s95, 0
	s_add_i32 s5, s5, s25
	s_mov_b32 m0, s5
	s_nop 0
	global_load_lds_dwordx4 v132, s[96:97]
	s_add_i32 m0, s5, 0x2000
	s_add_i32 s5, s47, s25
	global_load_lds_dwordx4 v136, s[96:97]
	s_mov_b32 m0, s5
	s_nop 0
	global_load_lds_dwordx4 v132, s[98:99]
	s_add_i32 m0, s5, 0x2000
	s_nop 0
	global_load_lds_dwordx4 v136, s[98:99]
	s_mov_b32 m0, s61
	s_nop 0
	global_load_lds_dwordx4 v130, s[94:95]
	s_mov_b32 m0, s62
	s_nop 0
	global_load_lds_dwordx4 v134, s[94:95]
	ds_read_b128 v[196:199], v160 offset:49152
	ds_read_b128 v[200:203], v160 offset:50176
	ds_read_b128 v[204:207], v160 offset:51200
	ds_read_b128 v[208:211], v160 offset:52224
	ds_read_b128 v[212:215], v160 offset:53248
	ds_read_b128 v[216:219], v160 offset:54272
	ds_read_b128 v[220:223], v160 offset:55296
	ds_read_b128 v[224:227], v160 offset:56320
	s_waitcnt vmcnt(8)
	s_waitcnt lgkmcnt(0)
	.p2align 3
	s_setprio 1
	s_barrier
	v_mfma_f32_16x16x32_bf16 v[62:65], v[164:167], v[196:199], v[62:65]
	v_mfma_f32_16x16x32_bf16 v[54:57], v[172:175], v[196:199], v[54:57]
	v_mfma_f32_16x16x32_bf16 v[46:49], v[164:167], v[204:207], v[46:49]
	v_mfma_f32_16x16x32_bf16 v[38:41], v[172:175], v[204:207], v[38:41]
	v_mfma_f32_16x16x32_bf16 v[30:33], v[164:167], v[212:215], v[30:33]
	v_mfma_f32_16x16x32_bf16 v[22:25], v[172:175], v[212:215], v[22:25]
	v_mfma_f32_16x16x32_bf16 v[14:17], v[164:167], v[220:223], v[14:17]
	v_mfma_f32_16x16x32_bf16 v[6:9], v[172:175], v[220:223], v[6:9]
	v_mfma_f32_16x16x32_bf16 v[62:65], v[168:171], v[200:203], v[62:65]
	v_mfma_f32_16x16x32_bf16 v[54:57], v[176:179], v[200:203], v[54:57]
	v_mfma_f32_16x16x32_bf16 v[46:49], v[168:171], v[208:211], v[46:49]
	v_mfma_f32_16x16x32_bf16 v[38:41], v[176:179], v[208:211], v[38:41]
	v_mfma_f32_16x16x32_bf16 v[30:33], v[168:171], v[216:219], v[30:33]
	v_mfma_f32_16x16x32_bf16 v[22:25], v[176:179], v[216:219], v[22:25]
	v_mfma_f32_16x16x32_bf16 v[14:17], v[168:171], v[224:227], v[14:17]
	v_mfma_f32_16x16x32_bf16 v[6:9], v[176:179], v[224:227], v[6:9]
	s_setprio 0
	s_setprio 1
	v_mfma_f32_16x16x32_bf16 v[58:61], v[180:183], v[196:199], v[58:61]
	v_mfma_f32_16x16x32_bf16 v[50:53], v[188:191], v[196:199], v[50:53]
	v_mfma_f32_16x16x32_bf16 v[42:45], v[180:183], v[204:207], v[42:45]
	v_mfma_f32_16x16x32_bf16 v[34:37], v[188:191], v[204:207], v[34:37]
	v_mfma_f32_16x16x32_bf16 v[26:29], v[180:183], v[212:215], v[26:29]
	v_mfma_f32_16x16x32_bf16 v[18:21], v[188:191], v[212:215], v[18:21]
	v_mfma_f32_16x16x32_bf16 v[10:13], v[180:183], v[220:223], v[10:13]
	v_mfma_f32_16x16x32_bf16 v[2:5], v[188:191], v[220:223], v[2:5]
	v_mfma_f32_16x16x32_bf16 v[58:61], v[184:187], v[200:203], v[58:61]
	v_mfma_f32_16x16x32_bf16 v[50:53], v[192:195], v[200:203], v[50:53]
	v_mfma_f32_16x16x32_bf16 v[42:45], v[184:187], v[208:211], v[42:45]
	v_mfma_f32_16x16x32_bf16 v[34:37], v[192:195], v[208:211], v[34:37]
	v_mfma_f32_16x16x32_bf16 v[26:29], v[184:187], v[216:219], v[26:29]
	v_mfma_f32_16x16x32_bf16 v[18:21], v[192:195], v[216:219], v[18:21]
	v_mfma_f32_16x16x32_bf16 v[10:13], v[184:187], v[224:227], v[10:13]
	v_mfma_f32_16x16x32_bf16 v[2:5], v[192:195], v[224:227], v[2:5]
	s_barrier
	s_setprio 0
	s_mov_b32 s5, s45
	s_add_u32 s88, s88, 0x100
	s_addc_u32 s89, s89, 0
	s_add_u32 s86, s86, 0x100
	s_addc_u32 s87, s87, 0
	s_cmp_ge_i32 s45, s101
	s_cbranch_scc1 .Lmy_kexit_10
.LBB0_1944:
	s_add_u32 s98, s86, 0xfffc0080
	s_addc_u32 s99, s87, -1
	s_cmp_eq_u32 s5, s100
	s_cselect_b64 s[94:95], s[90:91], s[98:99]
	s_cselect_b64 s[96:97], s[92:93], s[88:89]
	s_add_i32 s45, s5, 2
	s_nop 0
	s_mov_b32 m0, s74
	s_nop 0
	global_load_lds_dwordx4 v144, s[86:87]
	s_mov_b32 m0, s75
	s_nop 0
	global_load_lds_dwordx4 v142, s[86:87]
	ds_read_b128 v[164:167], v230
	ds_read_b128 v[168:171], v230 offset:1024
	ds_read_b128 v[172:175], v230 offset:2048
	ds_read_b128 v[176:179], v230 offset:3072
	ds_read_b128 v[180:183], v231
	ds_read_b128 v[184:187], v231 offset:1024
	ds_read_b128 v[188:191], v231 offset:2048
	ds_read_b128 v[192:195], v231 offset:3072
	ds_read_b128 v[196:199], v160
	ds_read_b128 v[200:203], v160 offset:1024
	ds_read_b128 v[204:207], v160 offset:2048
	ds_read_b128 v[208:211], v160 offset:3072
	ds_read_b128 v[212:215], v160 offset:4096
	ds_read_b128 v[216:219], v160 offset:5120
	ds_read_b128 v[220:223], v160 offset:6144
	ds_read_b128 v[224:227], v160 offset:7168
	s_waitcnt vmcnt(8)
	s_waitcnt lgkmcnt(0)
	.p2align 3
	s_setprio 1
	s_barrier
	v_mfma_f32_16x16x32_bf16 v[122:125], v[164:167], v[196:199], v[122:125]
	v_mfma_f32_16x16x32_bf16 v[118:121], v[172:175], v[196:199], v[118:121]
	v_mfma_f32_16x16x32_bf16 v[110:113], v[164:167], v[204:207], v[110:113]
	v_mfma_f32_16x16x32_bf16 v[102:105], v[172:175], v[204:207], v[102:105]
	v_mfma_f32_16x16x32_bf16 v[94:97], v[164:167], v[212:215], v[94:97]
	v_mfma_f32_16x16x32_bf16 v[86:89], v[172:175], v[212:215], v[86:89]
	v_mfma_f32_16x16x32_bf16 v[78:81], v[164:167], v[220:223], v[78:81]
	v_mfma_f32_16x16x32_bf16 v[70:73], v[172:175], v[220:223], v[70:73]
	v_mfma_f32_16x16x32_bf16 v[122:125], v[168:171], v[200:203], v[122:125]
	v_mfma_f32_16x16x32_bf16 v[118:121], v[176:179], v[200:203], v[118:121]
	v_mfma_f32_16x16x32_bf16 v[110:113], v[168:171], v[208:211], v[110:113]
	v_mfma_f32_16x16x32_bf16 v[102:105], v[176:179], v[208:211], v[102:105]
	v_mfma_f32_16x16x32_bf16 v[94:97], v[168:171], v[216:219], v[94:97]
	v_mfma_f32_16x16x32_bf16 v[86:89], v[176:179], v[216:219], v[86:89]
	v_mfma_f32_16x16x32_bf16 v[78:81], v[168:171], v[224:227], v[78:81]
	v_mfma_f32_16x16x32_bf16 v[70:73], v[176:179], v[224:227], v[70:73]
	s_setprio 0
	s_setprio 1
	v_mfma_f32_16x16x32_bf16 v[126:129], v[180:183], v[196:199], v[126:129]
	v_mfma_f32_16x16x32_bf16 v[114:117], v[188:191], v[196:199], v[114:117]
	v_mfma_f32_16x16x32_bf16 v[106:109], v[180:183], v[204:207], v[106:109]
	v_mfma_f32_16x16x32_bf16 v[98:101], v[188:191], v[204:207], v[98:101]
	v_mfma_f32_16x16x32_bf16 v[90:93], v[180:183], v[212:215], v[90:93]
	v_mfma_f32_16x16x32_bf16 v[82:85], v[188:191], v[212:215], v[82:85]
	v_mfma_f32_16x16x32_bf16 v[74:77], v[180:183], v[220:223], v[74:77]
	v_mfma_f32_16x16x32_bf16 v[66:69], v[188:191], v[220:223], v[66:69]
	v_mfma_f32_16x16x32_bf16 v[126:129], v[184:187], v[200:203], v[126:129]
	v_mfma_f32_16x16x32_bf16 v[114:117], v[192:195], v[200:203], v[114:117]
	v_mfma_f32_16x16x32_bf16 v[106:109], v[184:187], v[208:211], v[106:109]
	v_mfma_f32_16x16x32_bf16 v[98:101], v[192:195], v[208:211], v[98:101]
	v_mfma_f32_16x16x32_bf16 v[90:93], v[184:187], v[216:219], v[90:93]
	v_mfma_f32_16x16x32_bf16 v[82:85], v[192:195], v[216:219], v[82:85]
	v_mfma_f32_16x16x32_bf16 v[74:77], v[184:187], v[224:227], v[74:77]
	v_mfma_f32_16x16x32_bf16 v[66:69], v[192:195], v[224:227], v[66:69]
	s_barrier
	s_setprio 0
	s_add_u32 s98, s96, 0x40000
	s_addc_u32 s99, s97, 0
	s_mov_b32 m0, s76
	s_nop 0
	global_load_lds_dwordx4 v132, s[96:97]
	s_mov_b32 m0, s77
	s_add_i32 s5, s73, s25
	global_load_lds_dwordx4 v136, s[96:97]
	s_mov_b32 m0, s5
	s_nop 0
	global_load_lds_dwordx4 v132, s[98:99]
	s_add_i32 m0, s5, 0x2000
	s_nop 0
	global_load_lds_dwordx4 v136, s[98:99]
	s_mov_b32 m0, s49
	s_nop 0
	global_load_lds_dwordx4 v130, s[94:95]
	s_mov_b32 m0, s58
	s_nop 0
	global_load_lds_dwordx4 v134, s[94:95]
	ds_read_b128 v[196:199], v160 offset:16384
	ds_read_b128 v[200:203], v160 offset:17408
	ds_read_b128 v[204:207], v160 offset:18432
	ds_read_b128 v[208:211], v160 offset:19456
	ds_read_b128 v[212:215], v160 offset:20480
	ds_read_b128 v[216:219], v160 offset:21504
	ds_read_b128 v[220:223], v160 offset:22528
	ds_read_b128 v[224:227], v160 offset:23552
	s_waitcnt vmcnt(8)
	s_waitcnt lgkmcnt(0)
	.p2align 3
	s_setprio 1
	s_barrier
	v_mfma_f32_16x16x32_bf16 v[62:65], v[164:167], v[196:199], v[62:65]
	v_mfma_f32_16x16x32_bf16 v[54:57], v[172:175], v[196:199], v[54:57]
	v_mfma_f32_16x16x32_bf16 v[46:49], v[164:167], v[204:207], v[46:49]
	v_mfma_f32_16x16x32_bf16 v[38:41], v[172:175], v[204:207], v[38:41]
	v_mfma_f32_16x16x32_bf16 v[30:33], v[164:167], v[212:215], v[30:33]
	v_mfma_f32_16x16x32_bf16 v[22:25], v[172:175], v[212:215], v[22:25]
	v_mfma_f32_16x16x32_bf16 v[14:17], v[164:167], v[220:223], v[14:17]
	v_mfma_f32_16x16x32_bf16 v[6:9], v[172:175], v[220:223], v[6:9]
	v_mfma_f32_16x16x32_bf16 v[62:65], v[168:171], v[200:203], v[62:65]
	v_mfma_f32_16x16x32_bf16 v[54:57], v[176:179], v[200:203], v[54:57]
	v_mfma_f32_16x16x32_bf16 v[46:49], v[168:171], v[208:211], v[46:49]
	v_mfma_f32_16x16x32_bf16 v[38:41], v[176:179], v[208:211], v[38:41]
	v_mfma_f32_16x16x32_bf16 v[30:33], v[168:171], v[216:219], v[30:33]
	v_mfma_f32_16x16x32_bf16 v[22:25], v[176:179], v[216:219], v[22:25]
	v_mfma_f32_16x16x32_bf16 v[14:17], v[168:171], v[224:227], v[14:17]
	v_mfma_f32_16x16x32_bf16 v[6:9], v[176:179], v[224:227], v[6:9]
	s_setprio 0
	s_setprio 1
	v_mfma_f32_16x16x32_bf16 v[58:61], v[180:183], v[196:199], v[58:61]
	v_mfma_f32_16x16x32_bf16 v[50:53], v[188:191], v[196:199], v[50:53]
	v_mfma_f32_16x16x32_bf16 v[42:45], v[180:183], v[204:207], v[42:45]
	v_mfma_f32_16x16x32_bf16 v[34:37], v[188:191], v[204:207], v[34:37]
	v_mfma_f32_16x16x32_bf16 v[26:29], v[180:183], v[212:215], v[26:29]
	v_mfma_f32_16x16x32_bf16 v[18:21], v[188:191], v[212:215], v[18:21]
	v_mfma_f32_16x16x32_bf16 v[10:13], v[180:183], v[220:223], v[10:13]
	v_mfma_f32_16x16x32_bf16 v[2:5], v[188:191], v[220:223], v[2:5]
	v_mfma_f32_16x16x32_bf16 v[58:61], v[184:187], v[200:203], v[58:61]
	v_mfma_f32_16x16x32_bf16 v[50:53], v[192:195], v[200:203], v[50:53]
	v_mfma_f32_16x16x32_bf16 v[42:45], v[184:187], v[208:211], v[42:45]
	v_mfma_f32_16x16x32_bf16 v[34:37], v[192:195], v[208:211], v[34:37]
	v_mfma_f32_16x16x32_bf16 v[26:29], v[184:187], v[216:219], v[26:29]
	v_mfma_f32_16x16x32_bf16 v[18:21], v[192:195], v[216:219], v[18:21]
	v_mfma_f32_16x16x32_bf16 v[10:13], v[184:187], v[224:227], v[10:13]
	v_mfma_f32_16x16x32_bf16 v[2:5], v[192:195], v[224:227], v[2:5]
	s_barrier
	s_setprio 0
	s_add_u32 s98, s94, 0x40000
	s_addc_u32 s99, s95, 0
	s_add_i32 s5, 0, 0x18000
	s_add_i32 s47, 0, 0x1c000
	s_mov_b32 m0, s59
	s_nop 0
	global_load_lds_dwordx4 v130, s[98:99]
	s_mov_b32 m0, s60
	s_nop 0
	global_load_lds_dwordx4 v134, s[98:99]
	ds_read_b128 v[164:167], v232
	ds_read_b128 v[168:171], v232 offset:1024
	ds_read_b128 v[172:175], v232 offset:2048
	ds_read_b128 v[176:179], v232 offset:3072
	ds_read_b128 v[180:183], v233
	ds_read_b128 v[184:187], v233 offset:1024
	ds_read_b128 v[188:191], v233 offset:2048
	ds_read_b128 v[192:195], v233 offset:3072
	ds_read_b128 v[196:199], v160 offset:32768
	ds_read_b128 v[200:203], v160 offset:33792
	ds_read_b128 v[204:207], v160 offset:34816
	ds_read_b128 v[208:211], v160 offset:35840
	ds_read_b128 v[212:215], v160 offset:36864
	ds_read_b128 v[216:219], v160 offset:37888
	ds_read_b128 v[220:223], v160 offset:38912
	ds_read_b128 v[224:227], v160 offset:39936
	s_waitcnt vmcnt(8)
	s_waitcnt lgkmcnt(0)
	.p2align 3
	s_setprio 1
	s_barrier
	v_mfma_f32_16x16x32_bf16 v[122:125], v[164:167], v[196:199], v[122:125]
	v_mfma_f32_16x16x32_bf16 v[118:121], v[172:175], v[196:199], v[118:121]
	v_mfma_f32_16x16x32_bf16 v[110:113], v[164:167], v[204:207], v[110:113]
	v_mfma_f32_16x16x32_bf16 v[102:105], v[172:175], v[204:207], v[102:105]
	v_mfma_f32_16x16x32_bf16 v[94:97], v[164:167], v[212:215], v[94:97]
	v_mfma_f32_16x16x32_bf16 v[86:89], v[172:175], v[212:215], v[86:89]
	v_mfma_f32_16x16x32_bf16 v[78:81], v[164:167], v[220:223], v[78:81]
	v_mfma_f32_16x16x32_bf16 v[70:73], v[172:175], v[220:223], v[70:73]
	v_mfma_f32_16x16x32_bf16 v[122:125], v[168:171], v[200:203], v[122:125]
	v_mfma_f32_16x16x32_bf16 v[118:121], v[176:179], v[200:203], v[118:121]
	v_mfma_f32_16x16x32_bf16 v[110:113], v[168:171], v[208:211], v[110:113]
	v_mfma_f32_16x16x32_bf16 v[102:105], v[176:179], v[208:211], v[102:105]
	v_mfma_f32_16x16x32_bf16 v[94:97], v[168:171], v[216:219], v[94:97]
	v_mfma_f32_16x16x32_bf16 v[86:89], v[176:179], v[216:219], v[86:89]
	v_mfma_f32_16x16x32_bf16 v[78:81], v[168:171], v[224:227], v[78:81]
	v_mfma_f32_16x16x32_bf16 v[70:73], v[176:179], v[224:227], v[70:73]
	s_setprio 0
	s_setprio 1
	v_mfma_f32_16x16x32_bf16 v[126:129], v[180:183], v[196:199], v[126:129]
	v_mfma_f32_16x16x32_bf16 v[114:117], v[188:191], v[196:199], v[114:117]
	v_mfma_f32_16x16x32_bf16 v[106:109], v[180:183], v[204:207], v[106:109]
	v_mfma_f32_16x16x32_bf16 v[98:101], v[188:191], v[204:207], v[98:101]
	v_mfma_f32_16x16x32_bf16 v[90:93], v[180:183], v[212:215], v[90:93]
	v_mfma_f32_16x16x32_bf16 v[82:85], v[188:191], v[212:215], v[82:85]
	v_mfma_f32_16x16x32_bf16 v[74:77], v[180:183], v[220:223], v[74:77]
	v_mfma_f32_16x16x32_bf16 v[66:69], v[188:191], v[220:223], v[66:69]
	v_mfma_f32_16x16x32_bf16 v[126:129], v[184:187], v[200:203], v[126:129]
	v_mfma_f32_16x16x32_bf16 v[114:117], v[192:195], v[200:203], v[114:117]
	v_mfma_f32_16x16x32_bf16 v[106:109], v[184:187], v[208:211], v[106:109]
	v_mfma_f32_16x16x32_bf16 v[98:101], v[192:195], v[208:211], v[98:101]
	v_mfma_f32_16x16x32_bf16 v[90:93], v[184:187], v[216:219], v[90:93]
	v_mfma_f32_16x16x32_bf16 v[82:85], v[192:195], v[216:219], v[82:85]
	v_mfma_f32_16x16x32_bf16 v[74:77], v[184:187], v[224:227], v[74:77]
	v_mfma_f32_16x16x32_bf16 v[66:69], v[192:195], v[224:227], v[66:69]
	s_barrier
	s_setprio 0
	s_add_u32 s96, s96, 0x80
	s_addc_u32 s97, s97, 0
	s_add_u32 s98, s96, 0x40000
	s_addc_u32 s99, s97, 0
	s_add_u32 s94, s94, 0x80
	s_addc_u32 s95, s95, 0
	s_add_i32 s5, s5, s25
	s_mov_b32 m0, s5
	s_nop 0
	global_load_lds_dwordx4 v132, s[96:97]
	s_add_i32 m0, s5, 0x2000
	s_add_i32 s5, s47, s25
	global_load_lds_dwordx4 v136, s[96:97]
	s_mov_b32 m0, s5
	s_nop 0
	global_load_lds_dwordx4 v132, s[98:99]
	s_add_i32 m0, s5, 0x2000
	s_nop 0
	global_load_lds_dwordx4 v136, s[98:99]
	s_mov_b32 m0, s61
	s_nop 0
	global_load_lds_dwordx4 v130, s[94:95]
	s_mov_b32 m0, s62
	s_nop 0
	global_load_lds_dwordx4 v134, s[94:95]
	ds_read_b128 v[196:199], v160 offset:49152
	ds_read_b128 v[200:203], v160 offset:50176
	ds_read_b128 v[204:207], v160 offset:51200
	ds_read_b128 v[208:211], v160 offset:52224
	ds_read_b128 v[212:215], v160 offset:53248
	ds_read_b128 v[216:219], v160 offset:54272
	ds_read_b128 v[220:223], v160 offset:55296
	ds_read_b128 v[224:227], v160 offset:56320
	s_waitcnt vmcnt(8)
	s_waitcnt lgkmcnt(0)
	.p2align 3
	s_setprio 1
	s_barrier
	v_mfma_f32_16x16x32_bf16 v[62:65], v[164:167], v[196:199], v[62:65]
	v_mfma_f32_16x16x32_bf16 v[54:57], v[172:175], v[196:199], v[54:57]
	v_mfma_f32_16x16x32_bf16 v[46:49], v[164:167], v[204:207], v[46:49]
	v_mfma_f32_16x16x32_bf16 v[38:41], v[172:175], v[204:207], v[38:41]
	v_mfma_f32_16x16x32_bf16 v[30:33], v[164:167], v[212:215], v[30:33]
	v_mfma_f32_16x16x32_bf16 v[22:25], v[172:175], v[212:215], v[22:25]
	v_mfma_f32_16x16x32_bf16 v[14:17], v[164:167], v[220:223], v[14:17]
	v_mfma_f32_16x16x32_bf16 v[6:9], v[172:175], v[220:223], v[6:9]
	v_mfma_f32_16x16x32_bf16 v[62:65], v[168:171], v[200:203], v[62:65]
	v_mfma_f32_16x16x32_bf16 v[54:57], v[176:179], v[200:203], v[54:57]
	v_mfma_f32_16x16x32_bf16 v[46:49], v[168:171], v[208:211], v[46:49]
	v_mfma_f32_16x16x32_bf16 v[38:41], v[176:179], v[208:211], v[38:41]
	v_mfma_f32_16x16x32_bf16 v[30:33], v[168:171], v[216:219], v[30:33]
	v_mfma_f32_16x16x32_bf16 v[22:25], v[176:179], v[216:219], v[22:25]
	v_mfma_f32_16x16x32_bf16 v[14:17], v[168:171], v[224:227], v[14:17]
	v_mfma_f32_16x16x32_bf16 v[6:9], v[176:179], v[224:227], v[6:9]
	s_setprio 0
	s_setprio 1
	v_mfma_f32_16x16x32_bf16 v[58:61], v[180:183], v[196:199], v[58:61]
	v_mfma_f32_16x16x32_bf16 v[50:53], v[188:191], v[196:199], v[50:53]
	v_mfma_f32_16x16x32_bf16 v[42:45], v[180:183], v[204:207], v[42:45]
	v_mfma_f32_16x16x32_bf16 v[34:37], v[188:191], v[204:207], v[34:37]
	v_mfma_f32_16x16x32_bf16 v[26:29], v[180:183], v[212:215], v[26:29]
	v_mfma_f32_16x16x32_bf16 v[18:21], v[188:191], v[212:215], v[18:21]
	v_mfma_f32_16x16x32_bf16 v[10:13], v[180:183], v[220:223], v[10:13]
	v_mfma_f32_16x16x32_bf16 v[2:5], v[188:191], v[220:223], v[2:5]
	v_mfma_f32_16x16x32_bf16 v[58:61], v[184:187], v[200:203], v[58:61]
	v_mfma_f32_16x16x32_bf16 v[50:53], v[192:195], v[200:203], v[50:53]
	v_mfma_f32_16x16x32_bf16 v[42:45], v[184:187], v[208:211], v[42:45]
	v_mfma_f32_16x16x32_bf16 v[34:37], v[192:195], v[208:211], v[34:37]
	v_mfma_f32_16x16x32_bf16 v[26:29], v[184:187], v[216:219], v[26:29]
	v_mfma_f32_16x16x32_bf16 v[18:21], v[192:195], v[216:219], v[18:21]
	v_mfma_f32_16x16x32_bf16 v[10:13], v[184:187], v[224:227], v[10:13]
	v_mfma_f32_16x16x32_bf16 v[2:5], v[192:195], v[224:227], v[2:5]
	s_barrier
	s_setprio 0
	s_mov_b32 s5, s45
	s_add_u32 s88, s88, 0x100
	s_addc_u32 s89, s89, 0
	s_add_u32 s86, s86, 0x100
	s_addc_u32 s87, s87, 0
	s_cmp_ge_i32 s45, s101
	s_cbranch_scc0 .LBB0_1944

.Lmy_nb_11:
	s_nop 0
	v_readfirstlane_b32 s86, v150
	v_readfirstlane_b32 s87, v151
	v_readfirstlane_b32 s88, v152
	v_readfirstlane_b32 s89, v153
	v_readfirstlane_b32 s90, v146
	v_readfirstlane_b32 s91, v147
	v_readfirstlane_b32 s92, v148
	v_readfirstlane_b32 s93, v149
	v_readfirstlane_b32 s100, v138
	v_readfirstlane_b32 s101, v156
	v_add_u32_e32 v230, s65, v141
	v_add_u32_e32 v231, s66, v141
	v_add_u32_e32 v232, 0x18000, v141
	v_add_u32_e32 v233, 0x1c000, v141
	s_add_u32 s98, s86, 0x100
	s_addc_u32 s99, s87, 0
	s_cmp_eq_u32 s4, s100
	s_cselect_b64 s[94:95], s[90:91], s[98:99]
	s_cselect_b64 s[96:97], s[92:93], s[88:89]
	s_add_i32 s5, s4, 2
	s_nop 0
	s_add_i32 m0, s44, 0xc000
	s_nop 0
	global_load_lds_dwordx4 v144, s[86:87]
	s_add_i32 m0, s44, 0xe000
	s_nop 0
	global_load_lds_dwordx4 v142, s[86:87]
	ds_read_b128 v[164:167], v230
	ds_read_b128 v[168:171], v230 offset:1024
	ds_read_b128 v[172:175], v230 offset:2048
	ds_read_b128 v[176:179], v230 offset:3072
	ds_read_b128 v[180:183], v231
	ds_read_b128 v[184:187], v231 offset:1024
	ds_read_b128 v[188:191], v231 offset:2048
	ds_read_b128 v[192:195], v231 offset:3072
	ds_read_b128 v[196:199], v160
	ds_read_b128 v[200:203], v160 offset:1024
	ds_read_b128 v[204:207], v160 offset:2048
	ds_read_b128 v[208:211], v160 offset:3072
	ds_read_b128 v[212:215], v160 offset:4096
	ds_read_b128 v[216:219], v160 offset:5120
	ds_read_b128 v[220:223], v160 offset:6144
	ds_read_b128 v[224:227], v160 offset:7168
	s_waitcnt vmcnt(8)
	s_waitcnt lgkmcnt(0)
	.p2align 3
	s_setprio 1
	s_barrier
	v_mfma_f32_16x16x32_bf16 v[122:125], v[164:167], v[196:199], 0
	v_mfma_f32_16x16x32_bf16 v[118:121], v[172:175], v[196:199], 0
	v_mfma_f32_16x16x32_bf16 v[110:113], v[164:167], v[204:207], 0
	v_mfma_f32_16x16x32_bf16 v[102:105], v[172:175], v[204:207], 0
	v_mfma_f32_16x16x32_bf16 v[94:97], v[164:167], v[212:215], 0
	v_mfma_f32_16x16x32_bf16 v[86:89], v[172:175], v[212:215], 0
	v_mfma_f32_16x16x32_bf16 v[78:81], v[164:167], v[220:223], 0
	v_mfma_f32_16x16x32_bf16 v[70:73], v[172:175], v[220:223], 0
	v_mfma_f32_16x16x32_bf16 v[122:125], v[168:171], v[200:203], v[122:125]
	v_mfma_f32_16x16x32_bf16 v[118:121], v[176:179], v[200:203], v[118:121]
	v_mfma_f32_16x16x32_bf16 v[110:113], v[168:171], v[208:211], v[110:113]
	v_mfma_f32_16x16x32_bf16 v[102:105], v[176:179], v[208:211], v[102:105]
	v_mfma_f32_16x16x32_bf16 v[94:97], v[168:171], v[216:219], v[94:97]
	v_mfma_f32_16x16x32_bf16 v[86:89], v[176:179], v[216:219], v[86:89]
	v_mfma_f32_16x16x32_bf16 v[78:81], v[168:171], v[224:227], v[78:81]
	v_mfma_f32_16x16x32_bf16 v[70:73], v[176:179], v[224:227], v[70:73]
	s_setprio 0
	s_setprio 1
	v_mfma_f32_16x16x32_bf16 v[126:129], v[180:183], v[196:199], 0
	v_mfma_f32_16x16x32_bf16 v[114:117], v[188:191], v[196:199], 0
	v_mfma_f32_16x16x32_bf16 v[106:109], v[180:183], v[204:207], 0
	v_mfma_f32_16x16x32_bf16 v[98:101], v[188:191], v[204:207], 0
	v_mfma_f32_16x16x32_bf16 v[90:93], v[180:183], v[212:215], 0
	v_mfma_f32_16x16x32_bf16 v[82:85], v[188:191], v[212:215], 0
	v_mfma_f32_16x16x32_bf16 v[74:77], v[180:183], v[220:223], 0
	v_mfma_f32_16x16x32_bf16 v[66:69], v[188:191], v[220:223], 0
	v_mfma_f32_16x16x32_bf16 v[126:129], v[184:187], v[200:203], v[126:129]
	v_mfma_f32_16x16x32_bf16 v[114:117], v[192:195], v[200:203], v[114:117]
	v_mfma_f32_16x16x32_bf16 v[106:109], v[184:187], v[208:211], v[106:109]
	v_mfma_f32_16x16x32_bf16 v[98:101], v[192:195], v[208:211], v[98:101]
	v_mfma_f32_16x16x32_bf16 v[90:93], v[184:187], v[216:219], v[90:93]
	v_mfma_f32_16x16x32_bf16 v[82:85], v[192:195], v[216:219], v[82:85]
	v_mfma_f32_16x16x32_bf16 v[74:77], v[184:187], v[224:227], v[74:77]
	v_mfma_f32_16x16x32_bf16 v[66:69], v[192:195], v[224:227], v[66:69]
	s_barrier
	s_setprio 0
	s_add_u32 s98, s96, 0xb0000
	s_addc_u32 s99, s97, 0
	s_add_i32 s4, s65, s21
	s_mov_b32 m0, s4
	s_nop 0
	global_load_lds_dwordx4 v132, s[96:97]
	s_add_i32 m0, s4, 0x2000
	s_add_i32 s4, s66, s21
	global_load_lds_dwordx4 v136, s[96:97]
	s_mov_b32 m0, s4
	s_nop 0
	global_load_lds_dwordx4 v132, s[98:99]
	s_add_i32 m0, s4, 0x2000
	s_nop 0
	global_load_lds_dwordx4 v136, s[98:99]
	s_mov_b32 m0, s44
	s_nop 0
	global_load_lds_dwordx4 v130, s[94:95]
	s_mov_b32 m0, s45
	s_nop 0
	global_load_lds_dwordx4 v134, s[94:95]
	ds_read_b128 v[196:199], v160 offset:16384
	ds_read_b128 v[200:203], v160 offset:17408
	ds_read_b128 v[204:207], v160 offset:18432
	ds_read_b128 v[208:211], v160 offset:19456
	ds_read_b128 v[212:215], v160 offset:20480
	ds_read_b128 v[216:219], v160 offset:21504
	ds_read_b128 v[220:223], v160 offset:22528
	ds_read_b128 v[224:227], v160 offset:23552
	s_waitcnt vmcnt(8)
	s_waitcnt lgkmcnt(0)
	.p2align 3
	s_setprio 1
	s_barrier
	v_mfma_f32_16x16x32_bf16 v[62:65], v[164:167], v[196:199], 0
	v_mfma_f32_16x16x32_bf16 v[54:57], v[172:175], v[196:199], 0
	v_mfma_f32_16x16x32_bf16 v[46:49], v[164:167], v[204:207], 0
	v_mfma_f32_16x16x32_bf16 v[38:41], v[172:175], v[204:207], 0
	v_mfma_f32_16x16x32_bf16 v[30:33], v[164:167], v[212:215], 0
	v_mfma_f32_16x16x32_bf16 v[22:25], v[172:175], v[212:215], 0
	v_mfma_f32_16x16x32_bf16 v[14:17], v[164:167], v[220:223], 0
	v_mfma_f32_16x16x32_bf16 v[6:9], v[172:175], v[220:223], 0
	v_mfma_f32_16x16x32_bf16 v[62:65], v[168:171], v[200:203], v[62:65]
	v_mfma_f32_16x16x32_bf16 v[54:57], v[176:179], v[200:203], v[54:57]
	v_mfma_f32_16x16x32_bf16 v[46:49], v[168:171], v[208:211], v[46:49]
	v_mfma_f32_16x16x32_bf16 v[38:41], v[176:179], v[208:211], v[38:41]
	v_mfma_f32_16x16x32_bf16 v[30:33], v[168:171], v[216:219], v[30:33]
	v_mfma_f32_16x16x32_bf16 v[22:25], v[176:179], v[216:219], v[22:25]
	v_mfma_f32_16x16x32_bf16 v[14:17], v[168:171], v[224:227], v[14:17]
	v_mfma_f32_16x16x32_bf16 v[6:9], v[176:179], v[224:227], v[6:9]
	s_setprio 0
	s_setprio 1
	v_mfma_f32_16x16x32_bf16 v[58:61], v[180:183], v[196:199], 0
	v_mfma_f32_16x16x32_bf16 v[50:53], v[188:191], v[196:199], 0
	v_mfma_f32_16x16x32_bf16 v[42:45], v[180:183], v[204:207], 0
	v_mfma_f32_16x16x32_bf16 v[34:37], v[188:191], v[204:207], 0
	v_mfma_f32_16x16x32_bf16 v[26:29], v[180:183], v[212:215], 0
	v_mfma_f32_16x16x32_bf16 v[18:21], v[188:191], v[212:215], 0
	v_mfma_f32_16x16x32_bf16 v[10:13], v[180:183], v[220:223], 0
	v_mfma_f32_16x16x32_bf16 v[2:5], v[188:191], v[220:223], 0
	v_mfma_f32_16x16x32_bf16 v[58:61], v[184:187], v[200:203], v[58:61]
	v_mfma_f32_16x16x32_bf16 v[50:53], v[192:195], v[200:203], v[50:53]
	v_mfma_f32_16x16x32_bf16 v[42:45], v[184:187], v[208:211], v[42:45]
	v_mfma_f32_16x16x32_bf16 v[34:37], v[192:195], v[208:211], v[34:37]
	v_mfma_f32_16x16x32_bf16 v[26:29], v[184:187], v[216:219], v[26:29]
	v_mfma_f32_16x16x32_bf16 v[18:21], v[192:195], v[216:219], v[18:21]
	v_mfma_f32_16x16x32_bf16 v[10:13], v[184:187], v[224:227], v[10:13]
	v_mfma_f32_16x16x32_bf16 v[2:5], v[192:195], v[224:227], v[2:5]
	s_barrier
	s_setprio 0
	s_add_u32 s98, s94, 0xb0000
	s_addc_u32 s99, s95, 0
	s_add_i32 s4, 0, 0x18000
	s_add_i32 s25, 0, 0x1c000
	s_mov_b32 m0, s46
	s_nop 0
	global_load_lds_dwordx4 v130, s[98:99]
	s_mov_b32 m0, s47
	s_nop 0
	global_load_lds_dwordx4 v134, s[98:99]
	ds_read_b128 v[164:167], v232
	ds_read_b128 v[168:171], v232 offset:1024
	ds_read_b128 v[172:175], v232 offset:2048
	ds_read_b128 v[176:179], v232 offset:3072
	ds_read_b128 v[180:183], v233
	ds_read_b128 v[184:187], v233 offset:1024
	ds_read_b128 v[188:191], v233 offset:2048
	ds_read_b128 v[192:195], v233 offset:3072
	ds_read_b128 v[196:199], v160 offset:32768
	ds_read_b128 v[200:203], v160 offset:33792
	ds_read_b128 v[204:207], v160 offset:34816
	ds_read_b128 v[208:211], v160 offset:35840
	ds_read_b128 v[212:215], v160 offset:36864
	ds_read_b128 v[216:219], v160 offset:37888
	ds_read_b128 v[220:223], v160 offset:38912
	ds_read_b128 v[224:227], v160 offset:39936
	s_waitcnt vmcnt(8)
	s_waitcnt lgkmcnt(0)
	.p2align 3
	s_setprio 1
	s_barrier
	v_mfma_f32_16x16x32_bf16 v[122:125], v[164:167], v[196:199], v[122:125]
	v_mfma_f32_16x16x32_bf16 v[118:121], v[172:175], v[196:199], v[118:121]
	v_mfma_f32_16x16x32_bf16 v[110:113], v[164:167], v[204:207], v[110:113]
	v_mfma_f32_16x16x32_bf16 v[102:105], v[172:175], v[204:207], v[102:105]
	v_mfma_f32_16x16x32_bf16 v[94:97], v[164:167], v[212:215], v[94:97]
	v_mfma_f32_16x16x32_bf16 v[86:89], v[172:175], v[212:215], v[86:89]
	v_mfma_f32_16x16x32_bf16 v[78:81], v[164:167], v[220:223], v[78:81]
	v_mfma_f32_16x16x32_bf16 v[70:73], v[172:175], v[220:223], v[70:73]
	v_mfma_f32_16x16x32_bf16 v[122:125], v[168:171], v[200:203], v[122:125]
	v_mfma_f32_16x16x32_bf16 v[118:121], v[176:179], v[200:203], v[118:121]
	v_mfma_f32_16x16x32_bf16 v[110:113], v[168:171], v[208:211], v[110:113]
	v_mfma_f32_16x16x32_bf16 v[102:105], v[176:179], v[208:211], v[102:105]
	v_mfma_f32_16x16x32_bf16 v[94:97], v[168:171], v[216:219], v[94:97]
	v_mfma_f32_16x16x32_bf16 v[86:89], v[176:179], v[216:219], v[86:89]
	v_mfma_f32_16x16x32_bf16 v[78:81], v[168:171], v[224:227], v[78:81]
	v_mfma_f32_16x16x32_bf16 v[70:73], v[176:179], v[224:227], v[70:73]
	s_setprio 0
	s_setprio 1
	v_mfma_f32_16x16x32_bf16 v[126:129], v[180:183], v[196:199], v[126:129]
	v_mfma_f32_16x16x32_bf16 v[114:117], v[188:191], v[196:199], v[114:117]
	v_mfma_f32_16x16x32_bf16 v[106:109], v[180:183], v[204:207], v[106:109]
	v_mfma_f32_16x16x32_bf16 v[98:101], v[188:191], v[204:207], v[98:101]
	v_mfma_f32_16x16x32_bf16 v[90:93], v[180:183], v[212:215], v[90:93]
	v_mfma_f32_16x16x32_bf16 v[82:85], v[188:191], v[212:215], v[82:85]
	v_mfma_f32_16x16x32_bf16 v[74:77], v[180:183], v[220:223], v[74:77]
	v_mfma_f32_16x16x32_bf16 v[66:69], v[188:191], v[220:223], v[66:69]
	v_mfma_f32_16x16x32_bf16 v[126:129], v[184:187], v[200:203], v[126:129]
	v_mfma_f32_16x16x32_bf16 v[114:117], v[192:195], v[200:203], v[114:117]
	v_mfma_f32_16x16x32_bf16 v[106:109], v[184:187], v[208:211], v[106:109]
	v_mfma_f32_16x16x32_bf16 v[98:101], v[192:195], v[208:211], v[98:101]
	v_mfma_f32_16x16x32_bf16 v[90:93], v[184:187], v[216:219], v[90:93]
	v_mfma_f32_16x16x32_bf16 v[82:85], v[192:195], v[216:219], v[82:85]
	v_mfma_f32_16x16x32_bf16 v[74:77], v[184:187], v[224:227], v[74:77]
	v_mfma_f32_16x16x32_bf16 v[66:69], v[192:195], v[224:227], v[66:69]
	s_barrier
	s_setprio 0
	s_add_u32 s96, s96, 0x80
	s_addc_u32 s97, s97, 0
	s_add_u32 s98, s96, 0xb0000
	s_addc_u32 s99, s97, 0
	s_add_u32 s94, s94, 0x80
	s_addc_u32 s95, s95, 0
	s_add_i32 s4, s4, s21
	s_mov_b32 m0, s4
	s_nop 0
	global_load_lds_dwordx4 v132, s[96:97]
	s_add_i32 m0, s4, 0x2000
	s_add_i32 s4, s25, s21
	global_load_lds_dwordx4 v136, s[96:97]
	s_mov_b32 m0, s4
	s_nop 0
	global_load_lds_dwordx4 v132, s[98:99]
	s_add_i32 m0, s4, 0x2000
	s_nop 0
	global_load_lds_dwordx4 v136, s[98:99]
	s_mov_b32 m0, s57
	s_nop 0
	global_load_lds_dwordx4 v130, s[94:95]
	s_mov_b32 m0, s58
	s_nop 0
	global_load_lds_dwordx4 v134, s[94:95]
	ds_read_b128 v[196:199], v160 offset:49152
	ds_read_b128 v[200:203], v160 offset:50176
	ds_read_b128 v[204:207], v160 offset:51200
	ds_read_b128 v[208:211], v160 offset:52224
	ds_read_b128 v[212:215], v160 offset:53248
	ds_read_b128 v[216:219], v160 offset:54272
	ds_read_b128 v[220:223], v160 offset:55296
	ds_read_b128 v[224:227], v160 offset:56320
	s_waitcnt vmcnt(8)
	s_waitcnt lgkmcnt(0)
	.p2align 3
	s_setprio 1
	s_barrier
	v_mfma_f32_16x16x32_bf16 v[62:65], v[164:167], v[196:199], v[62:65]
	v_mfma_f32_16x16x32_bf16 v[54:57], v[172:175], v[196:199], v[54:57]
	v_mfma_f32_16x16x32_bf16 v[46:49], v[164:167], v[204:207], v[46:49]
	v_mfma_f32_16x16x32_bf16 v[38:41], v[172:175], v[204:207], v[38:41]
	v_mfma_f32_16x16x32_bf16 v[30:33], v[164:167], v[212:215], v[30:33]
	v_mfma_f32_16x16x32_bf16 v[22:25], v[172:175], v[212:215], v[22:25]
	v_mfma_f32_16x16x32_bf16 v[14:17], v[164:167], v[220:223], v[14:17]
	v_mfma_f32_16x16x32_bf16 v[6:9], v[172:175], v[220:223], v[6:9]
	v_mfma_f32_16x16x32_bf16 v[62:65], v[168:171], v[200:203], v[62:65]
	v_mfma_f32_16x16x32_bf16 v[54:57], v[176:179], v[200:203], v[54:57]
	v_mfma_f32_16x16x32_bf16 v[46:49], v[168:171], v[208:211], v[46:49]
	v_mfma_f32_16x16x32_bf16 v[38:41], v[176:179], v[208:211], v[38:41]
	v_mfma_f32_16x16x32_bf16 v[30:33], v[168:171], v[216:219], v[30:33]
	v_mfma_f32_16x16x32_bf16 v[22:25], v[176:179], v[216:219], v[22:25]
	v_mfma_f32_16x16x32_bf16 v[14:17], v[168:171], v[224:227], v[14:17]
	v_mfma_f32_16x16x32_bf16 v[6:9], v[176:179], v[224:227], v[6:9]
	s_setprio 0
	s_setprio 1
	v_mfma_f32_16x16x32_bf16 v[58:61], v[180:183], v[196:199], v[58:61]
	v_mfma_f32_16x16x32_bf16 v[50:53], v[188:191], v[196:199], v[50:53]
	v_mfma_f32_16x16x32_bf16 v[42:45], v[180:183], v[204:207], v[42:45]
	v_mfma_f32_16x16x32_bf16 v[34:37], v[188:191], v[204:207], v[34:37]
	v_mfma_f32_16x16x32_bf16 v[26:29], v[180:183], v[212:215], v[26:29]
	v_mfma_f32_16x16x32_bf16 v[18:21], v[188:191], v[212:215], v[18:21]
	v_mfma_f32_16x16x32_bf16 v[10:13], v[180:183], v[220:223], v[10:13]
	v_mfma_f32_16x16x32_bf16 v[2:5], v[188:191], v[220:223], v[2:5]
	v_mfma_f32_16x16x32_bf16 v[58:61], v[184:187], v[200:203], v[58:61]
	v_mfma_f32_16x16x32_bf16 v[50:53], v[192:195], v[200:203], v[50:53]
	v_mfma_f32_16x16x32_bf16 v[42:45], v[184:187], v[208:211], v[42:45]
	v_mfma_f32_16x16x32_bf16 v[34:37], v[192:195], v[208:211], v[34:37]
	v_mfma_f32_16x16x32_bf16 v[26:29], v[184:187], v[216:219], v[26:29]
	v_mfma_f32_16x16x32_bf16 v[18:21], v[192:195], v[216:219], v[18:21]
	v_mfma_f32_16x16x32_bf16 v[10:13], v[184:187], v[224:227], v[10:13]
	v_mfma_f32_16x16x32_bf16 v[2:5], v[192:195], v[224:227], v[2:5]
	s_barrier
	s_setprio 0
	s_mov_b32 s4, s5
	s_add_u32 s88, s88, 0x100
	s_addc_u32 s89, s89, 0
	s_add_u32 s86, s86, 0x100
	s_addc_u32 s87, s87, 0
	s_cmp_ge_i32 s5, s101
	s_cbranch_scc1 .Lmy_kexit_11
.LBB0_2075:
	s_add_u32 s98, s86, 0x100
	s_addc_u32 s99, s87, 0
	s_cmp_eq_u32 s4, s100
	s_cselect_b64 s[94:95], s[90:91], s[98:99]
	s_cselect_b64 s[96:97], s[92:93], s[88:89]
	s_add_i32 s5, s4, 2
	s_nop 0
	s_add_i32 m0, s44, 0xc000
	s_nop 0
	global_load_lds_dwordx4 v144, s[86:87]
	s_add_i32 m0, s44, 0xe000
	s_nop 0
	global_load_lds_dwordx4 v142, s[86:87]
	ds_read_b128 v[164:167], v230
	ds_read_b128 v[168:171], v230 offset:1024
	ds_read_b128 v[172:175], v230 offset:2048
	ds_read_b128 v[176:179], v230 offset:3072
	ds_read_b128 v[180:183], v231
	ds_read_b128 v[184:187], v231 offset:1024
	ds_read_b128 v[188:191], v231 offset:2048
	ds_read_b128 v[192:195], v231 offset:3072
	ds_read_b128 v[196:199], v160
	ds_read_b128 v[200:203], v160 offset:1024
	ds_read_b128 v[204:207], v160 offset:2048
	ds_read_b128 v[208:211], v160 offset:3072
	ds_read_b128 v[212:215], v160 offset:4096
	ds_read_b128 v[216:219], v160 offset:5120
	ds_read_b128 v[220:223], v160 offset:6144
	ds_read_b128 v[224:227], v160 offset:7168
	s_waitcnt vmcnt(8)
	s_waitcnt lgkmcnt(0)
	.p2align 3
	s_setprio 1
	s_barrier
	v_mfma_f32_16x16x32_bf16 v[122:125], v[164:167], v[196:199], v[122:125]
	v_mfma_f32_16x16x32_bf16 v[118:121], v[172:175], v[196:199], v[118:121]
	v_mfma_f32_16x16x32_bf16 v[110:113], v[164:167], v[204:207], v[110:113]
	v_mfma_f32_16x16x32_bf16 v[102:105], v[172:175], v[204:207], v[102:105]
	v_mfma_f32_16x16x32_bf16 v[94:97], v[164:167], v[212:215], v[94:97]
	v_mfma_f32_16x16x32_bf16 v[86:89], v[172:175], v[212:215], v[86:89]
	v_mfma_f32_16x16x32_bf16 v[78:81], v[164:167], v[220:223], v[78:81]
	v_mfma_f32_16x16x32_bf16 v[70:73], v[172:175], v[220:223], v[70:73]
	v_mfma_f32_16x16x32_bf16 v[122:125], v[168:171], v[200:203], v[122:125]
	v_mfma_f32_16x16x32_bf16 v[118:121], v[176:179], v[200:203], v[118:121]
	v_mfma_f32_16x16x32_bf16 v[110:113], v[168:171], v[208:211], v[110:113]
	v_mfma_f32_16x16x32_bf16 v[102:105], v[176:179], v[208:211], v[102:105]
	v_mfma_f32_16x16x32_bf16 v[94:97], v[168:171], v[216:219], v[94:97]
	v_mfma_f32_16x16x32_bf16 v[86:89], v[176:179], v[216:219], v[86:89]
	v_mfma_f32_16x16x32_bf16 v[78:81], v[168:171], v[224:227], v[78:81]
	v_mfma_f32_16x16x32_bf16 v[70:73], v[176:179], v[224:227], v[70:73]
	s_setprio 0
	s_setprio 1
	v_mfma_f32_16x16x32_bf16 v[126:129], v[180:183], v[196:199], v[126:129]
	v_mfma_f32_16x16x32_bf16 v[114:117], v[188:191], v[196:199], v[114:117]
	v_mfma_f32_16x16x32_bf16 v[106:109], v[180:183], v[204:207], v[106:109]
	v_mfma_f32_16x16x32_bf16 v[98:101], v[188:191], v[204:207], v[98:101]
	v_mfma_f32_16x16x32_bf16 v[90:93], v[180:183], v[212:215], v[90:93]
	v_mfma_f32_16x16x32_bf16 v[82:85], v[188:191], v[212:215], v[82:85]
	v_mfma_f32_16x16x32_bf16 v[74:77], v[180:183], v[220:223], v[74:77]
	v_mfma_f32_16x16x32_bf16 v[66:69], v[188:191], v[220:223], v[66:69]
	v_mfma_f32_16x16x32_bf16 v[126:129], v[184:187], v[200:203], v[126:129]
	v_mfma_f32_16x16x32_bf16 v[114:117], v[192:195], v[200:203], v[114:117]
	v_mfma_f32_16x16x32_bf16 v[106:109], v[184:187], v[208:211], v[106:109]
	v_mfma_f32_16x16x32_bf16 v[98:101], v[192:195], v[208:211], v[98:101]
	v_mfma_f32_16x16x32_bf16 v[90:93], v[184:187], v[216:219], v[90:93]
	v_mfma_f32_16x16x32_bf16 v[82:85], v[192:195], v[216:219], v[82:85]
	v_mfma_f32_16x16x32_bf16 v[74:77], v[184:187], v[224:227], v[74:77]
	v_mfma_f32_16x16x32_bf16 v[66:69], v[192:195], v[224:227], v[66:69]
	s_barrier
	s_setprio 0
	s_add_u32 s98, s96, 0xb0000
	s_addc_u32 s99, s97, 0
	s_add_i32 s4, s65, s21
	s_mov_b32 m0, s4
	s_nop 0
	global_load_lds_dwordx4 v132, s[96:97]
	s_add_i32 m0, s4, 0x2000
	s_add_i32 s4, s66, s21
	global_load_lds_dwordx4 v136, s[96:97]
	s_mov_b32 m0, s4
	s_nop 0
	global_load_lds_dwordx4 v132, s[98:99]
	s_add_i32 m0, s4, 0x2000
	s_nop 0
	global_load_lds_dwordx4 v136, s[98:99]
	s_mov_b32 m0, s44
	s_nop 0
	global_load_lds_dwordx4 v130, s[94:95]
	s_mov_b32 m0, s45
	s_nop 0
	global_load_lds_dwordx4 v134, s[94:95]
	ds_read_b128 v[196:199], v160 offset:16384
	ds_read_b128 v[200:203], v160 offset:17408
	ds_read_b128 v[204:207], v160 offset:18432
	ds_read_b128 v[208:211], v160 offset:19456
	ds_read_b128 v[212:215], v160 offset:20480
	ds_read_b128 v[216:219], v160 offset:21504
	ds_read_b128 v[220:223], v160 offset:22528
	ds_read_b128 v[224:227], v160 offset:23552
	s_waitcnt vmcnt(8)
	s_waitcnt lgkmcnt(0)
	.p2align 3
	s_setprio 1
	s_barrier
	v_mfma_f32_16x16x32_bf16 v[62:65], v[164:167], v[196:199], v[62:65]
	v_mfma_f32_16x16x32_bf16 v[54:57], v[172:175], v[196:199], v[54:57]
	v_mfma_f32_16x16x32_bf16 v[46:49], v[164:167], v[204:207], v[46:49]
	v_mfma_f32_16x16x32_bf16 v[38:41], v[172:175], v[204:207], v[38:41]
	v_mfma_f32_16x16x32_bf16 v[30:33], v[164:167], v[212:215], v[30:33]
	v_mfma_f32_16x16x32_bf16 v[22:25], v[172:175], v[212:215], v[22:25]
	v_mfma_f32_16x16x32_bf16 v[14:17], v[164:167], v[220:223], v[14:17]
	v_mfma_f32_16x16x32_bf16 v[6:9], v[172:175], v[220:223], v[6:9]
	v_mfma_f32_16x16x32_bf16 v[62:65], v[168:171], v[200:203], v[62:65]
	v_mfma_f32_16x16x32_bf16 v[54:57], v[176:179], v[200:203], v[54:57]
	v_mfma_f32_16x16x32_bf16 v[46:49], v[168:171], v[208:211], v[46:49]
	v_mfma_f32_16x16x32_bf16 v[38:41], v[176:179], v[208:211], v[38:41]
	v_mfma_f32_16x16x32_bf16 v[30:33], v[168:171], v[216:219], v[30:33]
	v_mfma_f32_16x16x32_bf16 v[22:25], v[176:179], v[216:219], v[22:25]
	v_mfma_f32_16x16x32_bf16 v[14:17], v[168:171], v[224:227], v[14:17]
	v_mfma_f32_16x16x32_bf16 v[6:9], v[176:179], v[224:227], v[6:9]
	s_setprio 0
	s_setprio 1
	v_mfma_f32_16x16x32_bf16 v[58:61], v[180:183], v[196:199], v[58:61]
	v_mfma_f32_16x16x32_bf16 v[50:53], v[188:191], v[196:199], v[50:53]
	v_mfma_f32_16x16x32_bf16 v[42:45], v[180:183], v[204:207], v[42:45]
	v_mfma_f32_16x16x32_bf16 v[34:37], v[188:191], v[204:207], v[34:37]
	v_mfma_f32_16x16x32_bf16 v[26:29], v[180:183], v[212:215], v[26:29]
	v_mfma_f32_16x16x32_bf16 v[18:21], v[188:191], v[212:215], v[18:21]
	v_mfma_f32_16x16x32_bf16 v[10:13], v[180:183], v[220:223], v[10:13]
	v_mfma_f32_16x16x32_bf16 v[2:5], v[188:191], v[220:223], v[2:5]
	v_mfma_f32_16x16x32_bf16 v[58:61], v[184:187], v[200:203], v[58:61]
	v_mfma_f32_16x16x32_bf16 v[50:53], v[192:195], v[200:203], v[50:53]
	v_mfma_f32_16x16x32_bf16 v[42:45], v[184:187], v[208:211], v[42:45]
	v_mfma_f32_16x16x32_bf16 v[34:37], v[192:195], v[208:211], v[34:37]
	v_mfma_f32_16x16x32_bf16 v[26:29], v[184:187], v[216:219], v[26:29]
	v_mfma_f32_16x16x32_bf16 v[18:21], v[192:195], v[216:219], v[18:21]
	v_mfma_f32_16x16x32_bf16 v[10:13], v[184:187], v[224:227], v[10:13]
	v_mfma_f32_16x16x32_bf16 v[2:5], v[192:195], v[224:227], v[2:5]
	s_barrier
	s_setprio 0
	s_add_u32 s98, s94, 0xb0000
	s_addc_u32 s99, s95, 0
	s_add_i32 s4, 0, 0x18000
	s_add_i32 s25, 0, 0x1c000
	s_mov_b32 m0, s46
	s_nop 0
	global_load_lds_dwordx4 v130, s[98:99]
	s_mov_b32 m0, s47
	s_nop 0
	global_load_lds_dwordx4 v134, s[98:99]
	ds_read_b128 v[164:167], v232
	ds_read_b128 v[168:171], v232 offset:1024
	ds_read_b128 v[172:175], v232 offset:2048
	ds_read_b128 v[176:179], v232 offset:3072
	ds_read_b128 v[180:183], v233
	ds_read_b128 v[184:187], v233 offset:1024
	ds_read_b128 v[188:191], v233 offset:2048
	ds_read_b128 v[192:195], v233 offset:3072
	ds_read_b128 v[196:199], v160 offset:32768
	ds_read_b128 v[200:203], v160 offset:33792
	ds_read_b128 v[204:207], v160 offset:34816
	ds_read_b128 v[208:211], v160 offset:35840
	ds_read_b128 v[212:215], v160 offset:36864
	ds_read_b128 v[216:219], v160 offset:37888
	ds_read_b128 v[220:223], v160 offset:38912
	ds_read_b128 v[224:227], v160 offset:39936
	s_waitcnt vmcnt(8)
	s_waitcnt lgkmcnt(0)
	.p2align 3
	s_setprio 1
	s_barrier
	v_mfma_f32_16x16x32_bf16 v[122:125], v[164:167], v[196:199], v[122:125]
	v_mfma_f32_16x16x32_bf16 v[118:121], v[172:175], v[196:199], v[118:121]
	v_mfma_f32_16x16x32_bf16 v[110:113], v[164:167], v[204:207], v[110:113]
	v_mfma_f32_16x16x32_bf16 v[102:105], v[172:175], v[204:207], v[102:105]
	v_mfma_f32_16x16x32_bf16 v[94:97], v[164:167], v[212:215], v[94:97]
	v_mfma_f32_16x16x32_bf16 v[86:89], v[172:175], v[212:215], v[86:89]
	v_mfma_f32_16x16x32_bf16 v[78:81], v[164:167], v[220:223], v[78:81]
	v_mfma_f32_16x16x32_bf16 v[70:73], v[172:175], v[220:223], v[70:73]
	v_mfma_f32_16x16x32_bf16 v[122:125], v[168:171], v[200:203], v[122:125]
	v_mfma_f32_16x16x32_bf16 v[118:121], v[176:179], v[200:203], v[118:121]
	v_mfma_f32_16x16x32_bf16 v[110:113], v[168:171], v[208:211], v[110:113]
	v_mfma_f32_16x16x32_bf16 v[102:105], v[176:179], v[208:211], v[102:105]
	v_mfma_f32_16x16x32_bf16 v[94:97], v[168:171], v[216:219], v[94:97]
	v_mfma_f32_16x16x32_bf16 v[86:89], v[176:179], v[216:219], v[86:89]
	v_mfma_f32_16x16x32_bf16 v[78:81], v[168:171], v[224:227], v[78:81]
	v_mfma_f32_16x16x32_bf16 v[70:73], v[176:179], v[224:227], v[70:73]
	s_setprio 0
	s_setprio 1
	v_mfma_f32_16x16x32_bf16 v[126:129], v[180:183], v[196:199], v[126:129]
	v_mfma_f32_16x16x32_bf16 v[114:117], v[188:191], v[196:199], v[114:117]
	v_mfma_f32_16x16x32_bf16 v[106:109], v[180:183], v[204:207], v[106:109]
	v_mfma_f32_16x16x32_bf16 v[98:101], v[188:191], v[204:207], v[98:101]
	v_mfma_f32_16x16x32_bf16 v[90:93], v[180:183], v[212:215], v[90:93]
	v_mfma_f32_16x16x32_bf16 v[82:85], v[188:191], v[212:215], v[82:85]
	v_mfma_f32_16x16x32_bf16 v[74:77], v[180:183], v[220:223], v[74:77]
	v_mfma_f32_16x16x32_bf16 v[66:69], v[188:191], v[220:223], v[66:69]
	v_mfma_f32_16x16x32_bf16 v[126:129], v[184:187], v[200:203], v[126:129]
	v_mfma_f32_16x16x32_bf16 v[114:117], v[192:195], v[200:203], v[114:117]
	v_mfma_f32_16x16x32_bf16 v[106:109], v[184:187], v[208:211], v[106:109]
	v_mfma_f32_16x16x32_bf16 v[98:101], v[192:195], v[208:211], v[98:101]
	v_mfma_f32_16x16x32_bf16 v[90:93], v[184:187], v[216:219], v[90:93]
	v_mfma_f32_16x16x32_bf16 v[82:85], v[192:195], v[216:219], v[82:85]
	v_mfma_f32_16x16x32_bf16 v[74:77], v[184:187], v[224:227], v[74:77]
	v_mfma_f32_16x16x32_bf16 v[66:69], v[192:195], v[224:227], v[66:69]
	s_barrier
	s_setprio 0
	s_add_u32 s96, s96, 0x80
	s_addc_u32 s97, s97, 0
	s_add_u32 s98, s96, 0xb0000
	s_addc_u32 s99, s97, 0
	s_add_u32 s94, s94, 0x80
	s_addc_u32 s95, s95, 0
	s_add_i32 s4, s4, s21
	s_mov_b32 m0, s4
	s_nop 0
	global_load_lds_dwordx4 v132, s[96:97]
	s_add_i32 m0, s4, 0x2000
	s_add_i32 s4, s25, s21
	global_load_lds_dwordx4 v136, s[96:97]
	s_mov_b32 m0, s4
	s_nop 0
	global_load_lds_dwordx4 v132, s[98:99]
	s_add_i32 m0, s4, 0x2000
	s_nop 0
	global_load_lds_dwordx4 v136, s[98:99]
	s_mov_b32 m0, s57
	s_nop 0
	global_load_lds_dwordx4 v130, s[94:95]
	s_mov_b32 m0, s58
	s_nop 0
	global_load_lds_dwordx4 v134, s[94:95]
	ds_read_b128 v[196:199], v160 offset:49152
	ds_read_b128 v[200:203], v160 offset:50176
	ds_read_b128 v[204:207], v160 offset:51200
	ds_read_b128 v[208:211], v160 offset:52224
	ds_read_b128 v[212:215], v160 offset:53248
	ds_read_b128 v[216:219], v160 offset:54272
	ds_read_b128 v[220:223], v160 offset:55296
	ds_read_b128 v[224:227], v160 offset:56320
	s_waitcnt vmcnt(8)
	s_waitcnt lgkmcnt(0)
	.p2align 3
	s_setprio 1
	s_barrier
	v_mfma_f32_16x16x32_bf16 v[62:65], v[164:167], v[196:199], v[62:65]
	v_mfma_f32_16x16x32_bf16 v[54:57], v[172:175], v[196:199], v[54:57]
	v_mfma_f32_16x16x32_bf16 v[46:49], v[164:167], v[204:207], v[46:49]
	v_mfma_f32_16x16x32_bf16 v[38:41], v[172:175], v[204:207], v[38:41]
	v_mfma_f32_16x16x32_bf16 v[30:33], v[164:167], v[212:215], v[30:33]
	v_mfma_f32_16x16x32_bf16 v[22:25], v[172:175], v[212:215], v[22:25]
	v_mfma_f32_16x16x32_bf16 v[14:17], v[164:167], v[220:223], v[14:17]
	v_mfma_f32_16x16x32_bf16 v[6:9], v[172:175], v[220:223], v[6:9]
	v_mfma_f32_16x16x32_bf16 v[62:65], v[168:171], v[200:203], v[62:65]
	v_mfma_f32_16x16x32_bf16 v[54:57], v[176:179], v[200:203], v[54:57]
	v_mfma_f32_16x16x32_bf16 v[46:49], v[168:171], v[208:211], v[46:49]
	v_mfma_f32_16x16x32_bf16 v[38:41], v[176:179], v[208:211], v[38:41]
	v_mfma_f32_16x16x32_bf16 v[30:33], v[168:171], v[216:219], v[30:33]
	v_mfma_f32_16x16x32_bf16 v[22:25], v[176:179], v[216:219], v[22:25]
	v_mfma_f32_16x16x32_bf16 v[14:17], v[168:171], v[224:227], v[14:17]
	v_mfma_f32_16x16x32_bf16 v[6:9], v[176:179], v[224:227], v[6:9]
	s_setprio 0
	s_setprio 1
	v_mfma_f32_16x16x32_bf16 v[58:61], v[180:183], v[196:199], v[58:61]
	v_mfma_f32_16x16x32_bf16 v[50:53], v[188:191], v[196:199], v[50:53]
	v_mfma_f32_16x16x32_bf16 v[42:45], v[180:183], v[204:207], v[42:45]
	v_mfma_f32_16x16x32_bf16 v[34:37], v[188:191], v[204:207], v[34:37]
	v_mfma_f32_16x16x32_bf16 v[26:29], v[180:183], v[212:215], v[26:29]
	v_mfma_f32_16x16x32_bf16 v[18:21], v[188:191], v[212:215], v[18:21]
	v_mfma_f32_16x16x32_bf16 v[10:13], v[180:183], v[220:223], v[10:13]
	v_mfma_f32_16x16x32_bf16 v[2:5], v[188:191], v[220:223], v[2:5]
	v_mfma_f32_16x16x32_bf16 v[58:61], v[184:187], v[200:203], v[58:61]
	v_mfma_f32_16x16x32_bf16 v[50:53], v[192:195], v[200:203], v[50:53]
	v_mfma_f32_16x16x32_bf16 v[42:45], v[184:187], v[208:211], v[42:45]
	v_mfma_f32_16x16x32_bf16 v[34:37], v[192:195], v[208:211], v[34:37]
	v_mfma_f32_16x16x32_bf16 v[26:29], v[184:187], v[216:219], v[26:29]
	v_mfma_f32_16x16x32_bf16 v[18:21], v[192:195], v[216:219], v[18:21]
	v_mfma_f32_16x16x32_bf16 v[10:13], v[184:187], v[224:227], v[10:13]
	v_mfma_f32_16x16x32_bf16 v[2:5], v[192:195], v[224:227], v[2:5]
	s_barrier
	s_setprio 0
	s_mov_b32 s4, s5
	s_add_u32 s88, s88, 0x100
	s_addc_u32 s89, s89, 0
	s_add_u32 s86, s86, 0x100
	s_addc_u32 s87, s87, 0
	s_cmp_ge_i32 s5, s101
	s_cbranch_scc0 .LBB0_2075
